# speedup vs baseline: 1.0153x; 1.0144x over previous
; #define WAIT_V(n) asm volatile("s_waitcnt vmcnt(%0)" ::"n"(n) : "memory")
; #define WAIT_L(n) asm volatile("s_waitcnt lgkmcnt(%0)" ::"n"(n) : "memory")
; #define SBAR() __builtin_amdgcn_sched_barrier(0)
; #define LDA8(dst, b, h) _Pragma("unroll") for (int m = 0; m < 4; ++m) _Pragma("unroll") for (int k = 0; k < 2; ++k) \
;     dst[m][k] = *(const bf16x8*)(abase + SAo(b, h) + m * 2048 + k * 1024)
; #define LDB8(dst, b, h) _Pragma("unroll") for (int n = 0; n < 2; ++n) _Pragma("unroll") for (int k = 0; k < 2; ++k) \
;     dst[n][k] = *(const bf16x8*)(bbase + SAo(b, h) + n * 2048 + k * 1024)
; #define BAR8 __builtin_amdgcn_s_barrier()
; __device__ __forceinline__ void gemm_main8(const u16* __restrict__ Ab, int lda, const u16* __restrict__ Bb, int ldb, int K,
;                                            char* shm, f32x4 (&acc)[2][2][4][2]) {
;     ...
;   for (int t = 0; t < nt - 2; t += 2) {
;     LDB8(B0, 0, 0); SBAR(); LDA8(At, 0, 0); STG_A(1, 1, t + 1);
;     WAIT_L(8); BAR8; WAIT_L(0); MMA8(0, 0, At, B0); BAR8; SBAR();
;     LDB8(B1, 0, 1); STG_B(0, 0, t + 2);
;     BAR8; WAIT_L(0); MMA8(0, 1, At, B1); BAR8;
;     LDA8(At, 0, 1); STG_A(0, 0, t + 2);
;     BAR8; WAIT_L(0); MMA8(1, 0, At, B0); BAR8; SBAR();
;     STG_B(0, 1, t + 2);
;     WAIT_V(6); BAR8; MMA8(1, 1, At, B1); BAR8;
.LBB0_223:
	ds_read_b128 v[152:155], v142
	ds_read_b128 v[164:167], v142 offset:1024
	ds_read_b128 v[180:183], v142 offset:2048
	ds_read_b128 v[184:187], v142 offset:3072
	v_lshl_add_u64 v[168:169], s[88:89], 0, v[134:135]
	v_readfirstlane_b32 s25, v179
	v_lshl_add_u64 v[220:221], v[168:169], 0, s[54:55]
	s_mov_b32 m0, s25
	v_readfirstlane_b32 s25, v178
	ds_read_b128 v[188:191], v141
	ds_read_b128 v[192:195], v141 offset:1024
	ds_read_b128 v[196:199], v141 offset:2048
	ds_read_b128 v[200:203], v141 offset:3072
	ds_read_b128 v[204:207], v141 offset:4096
	ds_read_b128 v[208:211], v141 offset:5120
	ds_read_b128 v[212:215], v141 offset:6144
	ds_read_b128 v[216:219], v141 offset:7168
	global_load_lds_dwordx4 v[220:221], off
	v_lshl_add_u64 v[220:221], v[168:169], 0, s[56:57]
	s_mov_b32 m0, s25
	s_nop 0
	global_load_lds_dwordx4 v[220:221], off
	s_waitcnt lgkmcnt(8)
	s_barrier
	s_waitcnt lgkmcnt(0)
	s_waitcnt lgkmcnt(0)
	v_mfma_f32_16x16x32_bf16 v[126:129], v[152:155], v[188:191], v[126:129]
	v_mfma_f32_16x16x32_bf16 v[122:125], v[180:183], v[188:191], v[122:125]
	v_mfma_f32_16x16x32_bf16 v[118:121], v[152:155], v[196:199], v[118:121]
	v_mfma_f32_16x16x32_bf16 v[114:117], v[180:183], v[196:199], v[114:117]
	v_mfma_f32_16x16x32_bf16 v[110:113], v[152:155], v[204:207], v[110:113]
	v_mfma_f32_16x16x32_bf16 v[106:109], v[180:183], v[204:207], v[106:109]
	v_mfma_f32_16x16x32_bf16 v[102:105], v[152:155], v[212:215], v[102:105]
	v_mfma_f32_16x16x32_bf16 v[98:101], v[180:183], v[212:215], v[98:101]
	v_mfma_f32_16x16x32_bf16 v[126:129], v[164:167], v[192:195], v[126:129]
	v_mfma_f32_16x16x32_bf16 v[122:125], v[184:187], v[192:195], v[122:125]
	v_mfma_f32_16x16x32_bf16 v[118:121], v[164:167], v[200:203], v[118:121]
	v_mfma_f32_16x16x32_bf16 v[114:117], v[184:187], v[200:203], v[114:117]
	v_mfma_f32_16x16x32_bf16 v[110:113], v[164:167], v[208:211], v[110:113]
	v_mfma_f32_16x16x32_bf16 v[106:109], v[184:187], v[208:211], v[106:109]
	v_mfma_f32_16x16x32_bf16 v[102:105], v[164:167], v[216:219], v[102:105]
	v_mfma_f32_16x16x32_bf16 v[98:101], v[184:187], v[216:219], v[98:101]
	s_barrier
	v_lshl_add_u64 v[236:237], s[14:15], 0, v[134:135]
	s_mov_b64 s[90:91], 0x2000100
	v_readfirstlane_b32 s25, v144
	v_lshl_add_u64 v[238:239], v[236:237], 0, s[90:91]
	s_mov_b32 m0, s25
	s_mov_b64 s[90:91], 0x2040100
	v_readfirstlane_b32 s25, v145
	ds_read_b128 v[220:223], v142 offset:16384
	ds_read_b128 v[224:227], v142 offset:17408
	ds_read_b128 v[228:231], v142 offset:18432
	ds_read_b128 v[232:235], v142 offset:19456
	global_load_lds_dwordx4 v[238:239], off
	v_lshl_add_u64 v[238:239], v[236:237], 0, s[90:91]
	s_mov_b32 m0, s25
	s_nop 0
	global_load_lds_dwordx4 v[238:239], off
	s_barrier
	s_waitcnt lgkmcnt(0)
	s_waitcnt lgkmcnt(0)
	v_mfma_f32_16x16x32_bf16 v[94:97], v[220:223], v[188:191], v[94:97]
	v_mfma_f32_16x16x32_bf16 v[90:93], v[228:231], v[188:191], v[90:93]
	v_mfma_f32_16x16x32_bf16 v[86:89], v[220:223], v[196:199], v[86:89]
	v_mfma_f32_16x16x32_bf16 v[82:85], v[228:231], v[196:199], v[82:85]
	v_mfma_f32_16x16x32_bf16 v[78:81], v[220:223], v[204:207], v[78:81]
	v_mfma_f32_16x16x32_bf16 v[74:77], v[228:231], v[204:207], v[74:77]
	v_mfma_f32_16x16x32_bf16 v[70:73], v[220:223], v[212:215], v[70:73]
	v_mfma_f32_16x16x32_bf16 v[66:69], v[228:231], v[212:215], v[66:69]
	v_mfma_f32_16x16x32_bf16 v[94:97], v[224:227], v[192:195], v[94:97]
	v_mfma_f32_16x16x32_bf16 v[90:93], v[232:235], v[192:195], v[90:93]
	v_mfma_f32_16x16x32_bf16 v[86:89], v[224:227], v[200:203], v[86:89]
	v_mfma_f32_16x16x32_bf16 v[82:85], v[232:235], v[200:203], v[82:85]
	v_mfma_f32_16x16x32_bf16 v[78:81], v[224:227], v[208:211], v[78:81]
	v_mfma_f32_16x16x32_bf16 v[74:77], v[232:235], v[208:211], v[74:77]
	v_mfma_f32_16x16x32_bf16 v[70:73], v[224:227], v[216:219], v[70:73]
	v_mfma_f32_16x16x32_bf16 v[66:69], v[232:235], v[216:219], v[66:69]
	v_readfirstlane_b32 s25, v143
	v_lshl_add_u64 v[238:239], v[168:169], 0, s[58:59]
	s_mov_b32 m0, s25
	v_readfirstlane_b32 s25, v146
	s_barrier
	ds_read_b128 v[188:191], v141 offset:16384
	ds_read_b128 v[192:195], v141 offset:17408
	ds_read_b128 v[196:199], v141 offset:18432
	ds_read_b128 v[200:203], v141 offset:19456
	ds_read_b128 v[204:207], v141 offset:20480
	ds_read_b128 v[208:211], v141 offset:21504
	ds_read_b128 v[212:215], v141 offset:22528
	ds_read_b128 v[216:219], v141 offset:23552
	global_load_lds_dwordx4 v[238:239], off
	v_lshl_add_u64 v[238:239], v[168:169], 0, s[60:61]
	s_mov_b32 m0, s25
	s_nop 0
	global_load_lds_dwordx4 v[238:239], off
	s_barrier
	s_waitcnt lgkmcnt(0)
	s_waitcnt lgkmcnt(0)
	v_mfma_f32_16x16x32_bf16 v[62:65], v[152:155], v[188:191], v[62:65]
	v_mfma_f32_16x16x32_bf16 v[58:61], v[180:183], v[188:191], v[58:61]
	v_mfma_f32_16x16x32_bf16 v[54:57], v[152:155], v[196:199], v[54:57]
	v_mfma_f32_16x16x32_bf16 v[50:53], v[180:183], v[196:199], v[50:53]
	v_mfma_f32_16x16x32_bf16 v[46:49], v[152:155], v[204:207], v[46:49]
	v_mfma_f32_16x16x32_bf16 v[42:45], v[180:183], v[204:207], v[42:45]
	v_mfma_f32_16x16x32_bf16 v[38:41], v[152:155], v[212:215], v[38:41]
	v_mfma_f32_16x16x32_bf16 v[34:37], v[180:183], v[212:215], v[34:37]
	v_mfma_f32_16x16x32_bf16 v[62:65], v[164:167], v[192:195], v[62:65]
	v_mfma_f32_16x16x32_bf16 v[58:61], v[184:187], v[192:195], v[58:61]
	v_mfma_f32_16x16x32_bf16 v[54:57], v[164:167], v[200:203], v[54:57]
	v_mfma_f32_16x16x32_bf16 v[50:53], v[184:187], v[200:203], v[50:53]
	v_mfma_f32_16x16x32_bf16 v[46:49], v[164:167], v[208:211], v[46:49]
	v_mfma_f32_16x16x32_bf16 v[42:45], v[184:187], v[208:211], v[42:45]
	v_mfma_f32_16x16x32_bf16 v[38:41], v[164:167], v[216:219], v[38:41]
	v_mfma_f32_16x16x32_bf16 v[34:37], v[184:187], v[216:219], v[34:37]
	s_barrier
; #define WAIT_V(n) asm volatile("s_waitcnt vmcnt(%0)" ::"n"(n) : "memory")
; #define WAIT_L(n) asm volatile("s_waitcnt lgkmcnt(%0)" ::"n"(n) : "memory")
; #define SBAR() __builtin_amdgcn_sched_barrier(0)
; #define LDA8(dst, b, h) _Pragma("unroll") for (int m = 0; m < 4; ++m) _Pragma("unroll") for (int k = 0; k < 2; ++k) \
;     dst[m][k] = *(const bf16x8*)(abase + SAo(b, h) + m * 2048 + k * 1024)
; #define LDB8(dst, b, h) _Pragma("unroll") for (int n = 0; n < 2; ++n) _Pragma("unroll") for (int k = 0; k < 2; ++k) \
;     dst[n][k] = *(const bf16x8*)(bbase + SAo(b, h) + n * 2048 + k * 1024)
; #define BAR8 __builtin_amdgcn_s_barrier()
; __device__ __forceinline__ void gemm_main8(const u16* __restrict__ Ab, int lda, const u16* __restrict__ Bb, int ldb, int K,
;                                            char* shm, f32x4 (&acc)[2][2][4][2]) {
;     ...
;     STG_B(0, 1, t + 2);
;     WAIT_V(6); BAR8; MMA8(1, 1, At, B1); BAR8;
;     LDB8(B0, 1, 0); SBAR(); LDA8(At, 1, 0); STG_A(0, 1, t + 2);
;     WAIT_L(8); BAR8; WAIT_L(0); MMA8(0, 0, At, B0); BAR8; SBAR();
;     LDB8(B1, 1, 1); STG_B(1, 0, t + 3);
;     BAR8; WAIT_L(0); MMA8(0, 1, At, B1); BAR8;
;     LDA8(At, 1, 1); STG_A(1, 0, t + 3);
;     BAR8; WAIT_L(0); MMA8(1, 0, At, B0); BAR8; SBAR();
	s_mov_b64 s[90:91], 0x2080100
	v_readfirstlane_b32 s25, v147
	v_lshl_add_u64 v[152:153], v[236:237], 0, s[90:91]
	s_mov_b32 m0, s25
	s_mov_b64 s[90:91], 0x20c0100
	v_readfirstlane_b32 s25, v148
	global_load_lds_dwordx4 v[152:153], off
	v_lshl_add_u64 v[152:153], v[236:237], 0, s[90:91]
	s_mov_b32 m0, s25
	s_nop 0
	global_load_lds_dwordx4 v[152:153], off
	s_waitcnt vmcnt(6)
	s_barrier
	v_mfma_f32_16x16x32_bf16 v[30:33], v[220:223], v[188:191], v[30:33]
	v_mfma_f32_16x16x32_bf16 v[26:29], v[228:231], v[188:191], v[26:29]
	v_mfma_f32_16x16x32_bf16 v[22:25], v[220:223], v[196:199], v[22:25]
	v_mfma_f32_16x16x32_bf16 v[18:21], v[228:231], v[196:199], v[18:21]
	v_mfma_f32_16x16x32_bf16 v[14:17], v[220:223], v[204:207], v[14:17]
	v_mfma_f32_16x16x32_bf16 v[10:13], v[228:231], v[204:207], v[10:13]
	v_mfma_f32_16x16x32_bf16 v[6:9], v[220:223], v[212:215], v[6:9]
	v_mfma_f32_16x16x32_bf16 v[2:5], v[228:231], v[212:215], v[2:5]
	v_mfma_f32_16x16x32_bf16 v[30:33], v[224:227], v[192:195], v[30:33]
	v_mfma_f32_16x16x32_bf16 v[26:29], v[232:235], v[192:195], v[26:29]
	v_mfma_f32_16x16x32_bf16 v[22:25], v[224:227], v[200:203], v[22:25]
	v_mfma_f32_16x16x32_bf16 v[18:21], v[232:235], v[200:203], v[18:21]
	v_mfma_f32_16x16x32_bf16 v[14:17], v[224:227], v[208:211], v[14:17]
	v_mfma_f32_16x16x32_bf16 v[10:13], v[232:235], v[208:211], v[10:13]
	v_mfma_f32_16x16x32_bf16 v[6:9], v[224:227], v[216:219], v[6:9]
	v_mfma_f32_16x16x32_bf16 v[2:5], v[232:235], v[216:219], v[2:5]
	s_barrier
	ds_read_b128 v[152:155], v142 offset:32768
	ds_read_b128 v[164:167], v142 offset:33792
	ds_read_b128 v[180:183], v142 offset:34816
	ds_read_b128 v[184:187], v142 offset:35840
	v_readfirstlane_b32 s25, v149
	v_lshl_add_u64 v[220:221], v[168:169], 0, s[62:63]
	s_mov_b32 m0, s25
	v_readfirstlane_b32 s25, v171
	ds_read_b128 v[188:191], v141 offset:32768
	ds_read_b128 v[192:195], v141 offset:33792
	ds_read_b128 v[196:199], v141 offset:34816
	ds_read_b128 v[200:203], v141 offset:35840
	ds_read_b128 v[204:207], v141 offset:36864
	ds_read_b128 v[208:211], v141 offset:37888
	ds_read_b128 v[212:215], v141 offset:38912
	ds_read_b128 v[216:219], v141 offset:39936
	global_load_lds_dwordx4 v[220:221], off
	v_lshl_add_u64 v[220:221], v[168:169], 0, s[64:65]
	s_mov_b32 m0, s25
	s_nop 0
	global_load_lds_dwordx4 v[220:221], off
	s_waitcnt lgkmcnt(8)
	s_barrier
	s_waitcnt lgkmcnt(0)
	s_waitcnt lgkmcnt(0)
	v_mfma_f32_16x16x32_bf16 v[126:129], v[152:155], v[188:191], v[126:129]
	v_mfma_f32_16x16x32_bf16 v[122:125], v[180:183], v[188:191], v[122:125]
	v_mfma_f32_16x16x32_bf16 v[118:121], v[152:155], v[196:199], v[118:121]
	v_mfma_f32_16x16x32_bf16 v[114:117], v[180:183], v[196:199], v[114:117]
	v_mfma_f32_16x16x32_bf16 v[110:113], v[152:155], v[204:207], v[110:113]
	v_mfma_f32_16x16x32_bf16 v[106:109], v[180:183], v[204:207], v[106:109]
	v_mfma_f32_16x16x32_bf16 v[102:105], v[152:155], v[212:215], v[102:105]
	v_mfma_f32_16x16x32_bf16 v[98:101], v[180:183], v[212:215], v[98:101]
	v_mfma_f32_16x16x32_bf16 v[126:129], v[164:167], v[192:195], v[126:129]
	v_mfma_f32_16x16x32_bf16 v[122:125], v[184:187], v[192:195], v[122:125]
	v_mfma_f32_16x16x32_bf16 v[118:121], v[164:167], v[200:203], v[118:121]
	v_mfma_f32_16x16x32_bf16 v[114:117], v[184:187], v[200:203], v[114:117]
	v_mfma_f32_16x16x32_bf16 v[110:113], v[164:167], v[208:211], v[110:113]
	v_mfma_f32_16x16x32_bf16 v[106:109], v[184:187], v[208:211], v[106:109]
	v_mfma_f32_16x16x32_bf16 v[102:105], v[164:167], v[216:219], v[102:105]
	v_mfma_f32_16x16x32_bf16 v[98:101], v[184:187], v[216:219], v[98:101]
	s_barrier
	s_mov_b64 s[90:91], 0x2000180
	v_readfirstlane_b32 s25, v172
	v_lshl_add_u64 v[238:239], v[236:237], 0, s[90:91]
	s_mov_b32 m0, s25
	s_mov_b64 s[90:91], 0x2040180
	v_readfirstlane_b32 s25, v173
	ds_read_b128 v[220:223], v142 offset:49152
	ds_read_b128 v[224:227], v142 offset:50176
	ds_read_b128 v[228:231], v142 offset:51200
	ds_read_b128 v[232:235], v142 offset:52224
	global_load_lds_dwordx4 v[238:239], off
	v_lshl_add_u64 v[238:239], v[236:237], 0, s[90:91]
	s_mov_b32 m0, s25
	s_nop 0
	global_load_lds_dwordx4 v[238:239], off
	s_barrier
	s_waitcnt lgkmcnt(0)
	s_waitcnt lgkmcnt(0)
	v_mfma_f32_16x16x32_bf16 v[94:97], v[220:223], v[188:191], v[94:97]
	v_mfma_f32_16x16x32_bf16 v[90:93], v[228:231], v[188:191], v[90:93]
	v_mfma_f32_16x16x32_bf16 v[86:89], v[220:223], v[196:199], v[86:89]
	v_mfma_f32_16x16x32_bf16 v[82:85], v[228:231], v[196:199], v[82:85]
	v_mfma_f32_16x16x32_bf16 v[78:81], v[220:223], v[204:207], v[78:81]
	v_mfma_f32_16x16x32_bf16 v[74:77], v[228:231], v[204:207], v[74:77]
	v_mfma_f32_16x16x32_bf16 v[70:73], v[220:223], v[212:215], v[70:73]
	v_mfma_f32_16x16x32_bf16 v[66:69], v[228:231], v[212:215], v[66:69]
	v_mfma_f32_16x16x32_bf16 v[94:97], v[224:227], v[192:195], v[94:97]
	v_mfma_f32_16x16x32_bf16 v[90:93], v[232:235], v[192:195], v[90:93]
	v_mfma_f32_16x16x32_bf16 v[86:89], v[224:227], v[200:203], v[86:89]
	v_mfma_f32_16x16x32_bf16 v[82:85], v[232:235], v[200:203], v[82:85]
	v_mfma_f32_16x16x32_bf16 v[78:81], v[224:227], v[208:211], v[78:81]
	v_mfma_f32_16x16x32_bf16 v[74:77], v[232:235], v[208:211], v[74:77]
	v_mfma_f32_16x16x32_bf16 v[70:73], v[224:227], v[216:219], v[70:73]
	v_mfma_f32_16x16x32_bf16 v[66:69], v[232:235], v[216:219], v[66:69]
	v_readfirstlane_b32 s25, v174
	v_lshl_add_u64 v[238:239], v[168:169], 0, s[66:67]
	s_mov_b32 m0, s25
	v_readfirstlane_b32 s25, v175
	s_barrier
; #define WAIT_V(n) asm volatile("s_waitcnt vmcnt(%0)" ::"n"(n) : "memory")
; #define WAIT_L(n) asm volatile("s_waitcnt lgkmcnt(%0)" ::"n"(n) : "memory")
; #define SBAR() __builtin_amdgcn_sched_barrier(0)
; #define LDA8(dst, b, h) _Pragma("unroll") for (int m = 0; m < 4; ++m) _Pragma("unroll") for (int k = 0; k < 2; ++k) \
;     dst[m][k] = *(const bf16x8*)(abase + SAo(b, h) + m * 2048 + k * 1024)
; #define LDB8(dst, b, h) _Pragma("unroll") for (int n = 0; n < 2; ++n) _Pragma("unroll") for (int k = 0; k < 2; ++k) \
;     dst[n][k] = *(const bf16x8*)(bbase + SAo(b, h) + n * 2048 + k * 1024)
; #define BAR8 __builtin_amdgcn_s_barrier()
; __device__ __forceinline__ void gemm_main8(const u16* __restrict__ Ab, int lda, const u16* __restrict__ Bb, int ldb, int K,
;                                            char* shm, f32x4 (&acc)[2][2][4][2]) {
;     ...
;     LDA8(At, 1, 1); STG_A(1, 0, t + 3);
;     BAR8; WAIT_L(0); MMA8(1, 0, At, B0); BAR8; SBAR();
;     STG_B(1, 1, t + 3);
;     WAIT_V(6); BAR8; MMA8(1, 1, At, B1); BAR8;
;   }
;   { LDB8(B0, 0, 0); LDA8(At, 0, 0); STG_A(1, 1, nt - 1);
;     BAR8; WAIT_L(0); MMA8(0, 0, At, B0); BAR8;
;     LDB8(B1, 0, 1); BAR8; WAIT_L(0); MMA8(0, 1, At, B1); BAR8;
	ds_read_b128 v[188:191], v141 offset:49152
	ds_read_b128 v[192:195], v141 offset:50176
	ds_read_b128 v[196:199], v141 offset:51200
	ds_read_b128 v[200:203], v141 offset:52224
	ds_read_b128 v[204:207], v141 offset:53248
	ds_read_b128 v[208:211], v141 offset:54272
	ds_read_b128 v[212:215], v141 offset:55296
	ds_read_b128 v[216:219], v141 offset:56320
	global_load_lds_dwordx4 v[238:239], off
	v_lshl_add_u64 v[168:169], v[168:169], 0, s[68:69]
	s_mov_b32 m0, s25
	s_nop 0
	global_load_lds_dwordx4 v[168:169], off
	s_barrier
	s_waitcnt lgkmcnt(0)
	s_waitcnt lgkmcnt(0)
	v_mfma_f32_16x16x32_bf16 v[62:65], v[152:155], v[188:191], v[62:65]
	v_mfma_f32_16x16x32_bf16 v[58:61], v[180:183], v[188:191], v[58:61]
	v_mfma_f32_16x16x32_bf16 v[54:57], v[152:155], v[196:199], v[54:57]
	v_mfma_f32_16x16x32_bf16 v[50:53], v[180:183], v[196:199], v[50:53]
	v_mfma_f32_16x16x32_bf16 v[46:49], v[152:155], v[204:207], v[46:49]
	v_mfma_f32_16x16x32_bf16 v[42:45], v[180:183], v[204:207], v[42:45]
	v_mfma_f32_16x16x32_bf16 v[38:41], v[152:155], v[212:215], v[38:41]
	v_mfma_f32_16x16x32_bf16 v[34:37], v[180:183], v[212:215], v[34:37]
	v_mfma_f32_16x16x32_bf16 v[62:65], v[164:167], v[192:195], v[62:65]
	v_mfma_f32_16x16x32_bf16 v[58:61], v[184:187], v[192:195], v[58:61]
	v_mfma_f32_16x16x32_bf16 v[54:57], v[164:167], v[200:203], v[54:57]
	v_mfma_f32_16x16x32_bf16 v[50:53], v[184:187], v[200:203], v[50:53]
	v_mfma_f32_16x16x32_bf16 v[46:49], v[164:167], v[208:211], v[46:49]
	v_mfma_f32_16x16x32_bf16 v[42:45], v[184:187], v[208:211], v[42:45]
	v_mfma_f32_16x16x32_bf16 v[38:41], v[164:167], v[216:219], v[38:41]
	v_mfma_f32_16x16x32_bf16 v[34:37], v[184:187], v[216:219], v[34:37]
	s_barrier
	s_mov_b64 s[90:91], 0x2080180
	v_readfirstlane_b32 s25, v176
	v_lshl_add_u64 v[152:153], v[236:237], 0, s[90:91]
	s_mov_b32 m0, s25
	s_mov_b64 s[90:91], 0x20c0180
	v_readfirstlane_b32 s25, v177
	global_load_lds_dwordx4 v[152:153], off
	v_lshl_add_u64 v[152:153], v[236:237], 0, s[90:91]
	s_mov_b32 m0, s25
	s_nop 0
	global_load_lds_dwordx4 v[152:153], off
	s_waitcnt vmcnt(6)
	s_barrier
	v_mfma_f32_16x16x32_bf16 v[30:33], v[220:223], v[188:191], v[30:33]
	v_mfma_f32_16x16x32_bf16 v[26:29], v[228:231], v[188:191], v[26:29]
	v_mfma_f32_16x16x32_bf16 v[22:25], v[220:223], v[196:199], v[22:25]
	v_mfma_f32_16x16x32_bf16 v[18:21], v[228:231], v[196:199], v[18:21]
	v_mfma_f32_16x16x32_bf16 v[14:17], v[220:223], v[204:207], v[14:17]
	v_mfma_f32_16x16x32_bf16 v[10:13], v[228:231], v[204:207], v[10:13]
	v_mfma_f32_16x16x32_bf16 v[6:9], v[220:223], v[212:215], v[6:9]
	v_mfma_f32_16x16x32_bf16 v[2:5], v[228:231], v[212:215], v[2:5]
	v_mfma_f32_16x16x32_bf16 v[30:33], v[224:227], v[192:195], v[30:33]
	v_mfma_f32_16x16x32_bf16 v[26:29], v[232:235], v[192:195], v[26:29]
	v_mfma_f32_16x16x32_bf16 v[22:25], v[224:227], v[200:203], v[22:25]
	v_mfma_f32_16x16x32_bf16 v[18:21], v[232:235], v[200:203], v[18:21]
	v_mfma_f32_16x16x32_bf16 v[14:17], v[224:227], v[208:211], v[14:17]
	v_mfma_f32_16x16x32_bf16 v[10:13], v[232:235], v[208:211], v[10:13]
	v_mfma_f32_16x16x32_bf16 v[6:9], v[224:227], v[216:219], v[6:9]
	v_mfma_f32_16x16x32_bf16 v[2:5], v[232:235], v[216:219], v[2:5]
	s_add_i32 s5, s5, 2
	s_add_u32 s14, s14, 0x100
	s_addc_u32 s15, s15, 0
	s_add_u32 s88, s88, 0x100
	s_addc_u32 s89, s89, 0
	s_cmp_lt_u32 s5, 28
	s_barrier
	s_cbranch_scc1 .LBB0_223
	s_mov_b64 s[14:15], 0x80f80
	v_readfirstlane_b32 s5, v179
	v_lshl_add_u64 v[134:135], v[132:133], 0, s[14:15]
	s_mov_b32 m0, s5
	s_mov_b64 s[14:15], 0xc0f80
	v_readfirstlane_b32 s5, v178
	ds_read_b128 v[144:147], v142
	ds_read_b128 v[152:155], v142 offset:1024
	ds_read_b128 v[164:167], v142 offset:2048
	ds_read_b128 v[168:171], v142 offset:3072
	ds_read_b128 v[172:175], v141
	ds_read_b128 v[180:183], v141 offset:1024
	ds_read_b128 v[184:187], v141 offset:2048
	ds_read_b128 v[188:191], v141 offset:3072
	ds_read_b128 v[192:195], v141 offset:4096
	ds_read_b128 v[196:199], v141 offset:5120
	ds_read_b128 v[200:203], v141 offset:6144
	ds_read_b128 v[204:207], v141 offset:7168
	global_load_lds_dwordx4 v[134:135], off
	v_lshl_add_u64 v[132:133], v[132:133], 0, s[14:15]
	s_mov_b32 m0, s5
	s_nop 0
	global_load_lds_dwordx4 v[132:133], off
	s_barrier
	s_waitcnt lgkmcnt(0)
	s_waitcnt lgkmcnt(0)
	v_mfma_f32_16x16x32_bf16 v[126:129], v[144:147], v[172:175], v[126:129]
	v_mfma_f32_16x16x32_bf16 v[122:125], v[164:167], v[172:175], v[122:125]
	v_mfma_f32_16x16x32_bf16 v[118:121], v[144:147], v[184:187], v[118:121]
	v_mfma_f32_16x16x32_bf16 v[114:117], v[164:167], v[184:187], v[114:117]
	v_mfma_f32_16x16x32_bf16 v[102:105], v[144:147], v[200:203], v[102:105]
	v_mfma_f32_16x16x32_bf16 v[98:101], v[164:167], v[200:203], v[98:101]
	v_mfma_f32_16x16x32_bf16 v[126:129], v[152:155], v[180:183], v[126:129]
	v_mfma_f32_16x16x32_bf16 v[122:125], v[168:171], v[180:183], v[122:125]
	v_mfma_f32_16x16x32_bf16 v[118:121], v[152:155], v[188:191], v[118:121]
	v_mfma_f32_16x16x32_bf16 v[114:117], v[168:171], v[188:191], v[114:117]
	v_mfma_f32_16x16x32_bf16 v[110:113], v[144:147], v[192:195], v[110:113]
	v_mfma_f32_16x16x32_bf16 v[106:109], v[164:167], v[192:195], v[106:109]
	v_mfma_f32_16x16x32_bf16 v[102:105], v[152:155], v[204:207], v[102:105]
	v_mfma_f32_16x16x32_bf16 v[98:101], v[168:171], v[204:207], v[98:101]
	v_mfma_f32_16x16x32_bf16 v[132:135], v[152:155], v[196:199], v[110:113]
	v_mfma_f32_16x16x32_bf16 v[176:179], v[168:171], v[196:199], v[106:109]
	s_barrier
	s_nop 1
	ds_read_b128 v[106:109], v142 offset:16384
	ds_read_b128 v[110:113], v142 offset:17408
	ds_read_b128 v[208:211], v142 offset:18432
	ds_read_b128 v[212:215], v142 offset:19456
	s_barrier
; #define WAIT_V(n) asm volatile("s_waitcnt vmcnt(%0)" ::"n"(n) : "memory")
; #define WAIT_L(n) asm volatile("s_waitcnt lgkmcnt(%0)" ::"n"(n) : "memory")
; #define LDA8(dst, b, h) _Pragma("unroll") for (int m = 0; m < 4; ++m) _Pragma("unroll") for (int k = 0; k < 2; ++k) \
;     dst[m][k] = *(const bf16x8*)(abase + SAo(b, h) + m * 2048 + k * 1024)
; #define LDB8(dst, b, h) _Pragma("unroll") for (int n = 0; n < 2; ++n) _Pragma("unroll") for (int k = 0; k < 2; ++k) \
;     dst[n][k] = *(const bf16x8*)(bbase + SAo(b, h) + n * 2048 + k * 1024)
; #define BAR8 __builtin_amdgcn_s_barrier()
; __device__ __forceinline__ void gemm_main8(const u16* __restrict__ Ab, int lda, const u16* __restrict__ Bb, int ldb, int K,
;                                            char* shm, f32x4 (&acc)[2][2][4][2]) {
;     ...
;     LDB8(B1, 0, 1); BAR8; WAIT_L(0); MMA8(0, 1, At, B1); BAR8;
;     LDA8(At, 0, 1); WAIT_V(4); BAR8; WAIT_L(0); MMA8(1, 0, At, B0); MMA8(1, 1, At, B1); BAR8; }
;   { LDB8(B0, 1, 0); LDA8(At, 1, 0); WAIT_V(2); BAR8; WAIT_L(0); MMA8(0, 0, At, B0); BAR8;
;     LDB8(B1, 1, 1); WAIT_V(0); BAR8; WAIT_L(0); MMA8(0, 1, At, B1); BAR8;
	s_waitcnt lgkmcnt(0)
	s_waitcnt lgkmcnt(0)
	v_mfma_f32_16x16x32_bf16 v[86:89], v[106:109], v[184:187], v[86:89]
	v_mfma_f32_16x16x32_bf16 v[82:85], v[208:211], v[184:187], v[82:85]
	v_mfma_f32_16x16x32_bf16 v[70:73], v[106:109], v[200:203], v[70:73]
	v_mfma_f32_16x16x32_bf16 v[66:69], v[208:211], v[200:203], v[66:69]
	v_mfma_f32_16x16x32_bf16 v[94:97], v[106:109], v[172:175], v[94:97]
	v_mfma_f32_16x16x32_bf16 v[90:93], v[208:211], v[172:175], v[90:93]
	v_mfma_f32_16x16x32_bf16 v[86:89], v[110:113], v[188:191], v[86:89]
	v_mfma_f32_16x16x32_bf16 v[82:85], v[212:215], v[188:191], v[82:85]
	v_mfma_f32_16x16x32_bf16 v[78:81], v[106:109], v[192:195], v[78:81]
	v_mfma_f32_16x16x32_bf16 v[74:77], v[208:211], v[192:195], v[74:77]
	v_mfma_f32_16x16x32_bf16 v[70:73], v[110:113], v[204:207], v[70:73]
	v_mfma_f32_16x16x32_bf16 v[66:69], v[212:215], v[204:207], v[66:69]
	v_mfma_f32_16x16x32_bf16 v[216:219], v[110:113], v[180:183], v[94:97]
	v_mfma_f32_16x16x32_bf16 v[172:175], v[212:215], v[180:183], v[90:93]
	v_mfma_f32_16x16x32_bf16 v[180:183], v[110:113], v[196:199], v[78:81]
	v_mfma_f32_16x16x32_bf16 v[184:187], v[212:215], v[196:199], v[74:77]
	s_barrier
	s_nop 0
	ds_read_b128 v[74:77], v141 offset:16384
	ds_read_b128 v[78:81], v141 offset:17408
	ds_read_b128 v[90:93], v141 offset:18432
	ds_read_b128 v[94:97], v141 offset:19456
	ds_read_b128 v[188:191], v141 offset:20480
	ds_read_b128 v[192:195], v141 offset:21504
	ds_read_b128 v[196:199], v141 offset:22528
	ds_read_b128 v[200:203], v141 offset:23552
	s_waitcnt vmcnt(4)
	s_barrier
	s_waitcnt lgkmcnt(0)
	s_waitcnt lgkmcnt(0)
	v_mfma_f32_16x16x32_bf16 v[62:65], v[144:147], v[74:77], v[62:65]
	v_mfma_f32_16x16x32_bf16 v[58:61], v[164:167], v[74:77], v[58:61]
	v_mfma_f32_16x16x32_bf16 v[54:57], v[144:147], v[90:93], v[54:57]
	v_mfma_f32_16x16x32_bf16 v[50:53], v[164:167], v[90:93], v[50:53]
	v_mfma_f32_16x16x32_bf16 v[38:41], v[144:147], v[196:199], v[38:41]
	v_mfma_f32_16x16x32_bf16 v[34:37], v[164:167], v[196:199], v[34:37]
	v_mfma_f32_16x16x32_bf16 v[62:65], v[152:155], v[78:81], v[62:65]
	v_mfma_f32_16x16x32_bf16 v[58:61], v[168:171], v[78:81], v[58:61]
	v_mfma_f32_16x16x32_bf16 v[54:57], v[152:155], v[94:97], v[54:57]
	v_mfma_f32_16x16x32_bf16 v[50:53], v[168:171], v[94:97], v[50:53]
	v_mfma_f32_16x16x32_bf16 v[46:49], v[144:147], v[188:191], v[46:49]
	v_mfma_f32_16x16x32_bf16 v[42:45], v[164:167], v[188:191], v[42:45]
	v_mfma_f32_16x16x32_bf16 v[38:41], v[152:155], v[200:203], v[38:41]
	v_mfma_f32_16x16x32_bf16 v[34:37], v[168:171], v[200:203], v[34:37]
	v_mfma_f32_16x16x32_bf16 v[204:207], v[152:155], v[192:195], v[46:49]
	v_mfma_f32_16x16x32_bf16 v[220:223], v[168:171], v[192:195], v[42:45]
	v_mfma_f32_16x16x32_bf16 v[22:25], v[106:109], v[90:93], v[22:25]
	v_mfma_f32_16x16x32_bf16 v[18:21], v[208:211], v[90:93], v[18:21]
	v_mfma_f32_16x16x32_bf16 v[6:9], v[106:109], v[196:199], v[6:9]
	v_mfma_f32_16x16x32_bf16 v[2:5], v[208:211], v[196:199], v[2:5]
	v_mfma_f32_16x16x32_bf16 v[30:33], v[106:109], v[74:77], v[30:33]
	v_mfma_f32_16x16x32_bf16 v[26:29], v[208:211], v[74:77], v[26:29]
	v_mfma_f32_16x16x32_bf16 v[22:25], v[110:113], v[94:97], v[22:25]
	v_mfma_f32_16x16x32_bf16 v[18:21], v[212:215], v[94:97], v[18:21]
	v_mfma_f32_16x16x32_bf16 v[14:17], v[106:109], v[188:191], v[14:17]
	v_mfma_f32_16x16x32_bf16 v[10:13], v[208:211], v[188:191], v[10:13]
	v_mfma_f32_16x16x32_bf16 v[6:9], v[110:113], v[200:203], v[6:9]
	v_mfma_f32_16x16x32_bf16 v[2:5], v[212:215], v[200:203], v[2:5]
	v_mfma_f32_16x16x32_bf16 v[144:147], v[110:113], v[78:81], v[30:33]
	v_mfma_f32_16x16x32_bf16 v[152:155], v[212:215], v[78:81], v[26:29]
	v_mfma_f32_16x16x32_bf16 v[164:167], v[110:113], v[192:195], v[14:17]
	v_mfma_f32_16x16x32_bf16 v[168:171], v[212:215], v[192:195], v[10:13]
	s_barrier
	s_nop 0
	ds_read_b128 v[10:13], v142 offset:32768
	ds_read_b128 v[14:17], v142 offset:33792
	ds_read_b128 v[188:191], v142 offset:34816
	ds_read_b128 v[192:195], v142 offset:35840
	ds_read_b128 v[26:29], v141 offset:32768
	ds_read_b128 v[30:33], v141 offset:33792
	ds_read_b128 v[42:45], v141 offset:34816
	ds_read_b128 v[46:49], v141 offset:35840
	ds_read_b128 v[196:199], v141 offset:36864
	ds_read_b128 v[200:203], v141 offset:37888
	ds_read_b128 v[208:211], v141 offset:38912
	ds_read_b128 v[212:215], v141 offset:39936
	s_waitcnt vmcnt(2)
	s_barrier
; #define WAIT_V(n) asm volatile("s_waitcnt vmcnt(%0)" ::"n"(n) : "memory")
; #define WAIT_L(n) asm volatile("s_waitcnt lgkmcnt(%0)" ::"n"(n) : "memory")
; #define LDA8(dst, b, h) _Pragma("unroll") for (int m = 0; m < 4; ++m) _Pragma("unroll") for (int k = 0; k < 2; ++k) \
;     dst[m][k] = *(const bf16x8*)(abase + SAo(b, h) + m * 2048 + k * 1024)
; #define LDB8(dst, b, h) _Pragma("unroll") for (int n = 0; n < 2; ++n) _Pragma("unroll") for (int k = 0; k < 2; ++k) \
;     dst[n][k] = *(const bf16x8*)(bbase + SAo(b, h) + n * 2048 + k * 1024)
; #define BAR8 __builtin_amdgcn_s_barrier()
; __device__ __forceinline__ void gemm_main8(const u16* __restrict__ Ab, int lda, const u16* __restrict__ Bb, int ldb, int K,
;                                            char* shm, f32x4 (&acc)[2][2][4][2]) {
;     ...
;   { LDB8(B0, 1, 0); LDA8(At, 1, 0); WAIT_V(2); BAR8; WAIT_L(0); MMA8(0, 0, At, B0); BAR8;
;     LDB8(B1, 1, 1); WAIT_V(0); BAR8; WAIT_L(0); MMA8(0, 1, At, B1); BAR8;
;     LDA8(At, 1, 1); BAR8; WAIT_L(0); MMA8(1, 0, At, B0); MMA8(1, 1, At, B1); BAR8; }
;   if (wr == 0) BAR8;
	s_waitcnt lgkmcnt(0)
	s_waitcnt lgkmcnt(0)
	v_mfma_f32_16x16x32_bf16 v[74:77], v[10:13], v[26:29], v[126:129]
	v_mfma_f32_16x16x32_bf16 v[126:129], v[14:17], v[30:33], v[74:77]
	v_mfma_f32_16x16x32_bf16 v[74:77], v[188:191], v[26:29], v[122:125]
	v_mfma_f32_16x16x32_bf16 v[122:125], v[192:195], v[30:33], v[74:77]
	v_mfma_f32_16x16x32_bf16 v[74:77], v[10:13], v[42:45], v[118:121]
	v_mfma_f32_16x16x32_bf16 v[110:113], v[14:17], v[46:49], v[74:77]
	v_mfma_f32_16x16x32_bf16 v[74:77], v[188:191], v[42:45], v[114:117]
	v_mfma_f32_16x16x32_bf16 v[106:109], v[192:195], v[46:49], v[74:77]
	v_mfma_f32_16x16x32_bf16 v[74:77], v[10:13], v[196:199], v[132:135]
	v_mfma_f32_16x16x32_bf16 v[94:97], v[14:17], v[200:203], v[74:77]
	v_mfma_f32_16x16x32_bf16 v[74:77], v[188:191], v[196:199], v[176:179]
	v_mfma_f32_16x16x32_bf16 v[90:93], v[192:195], v[200:203], v[74:77]
	v_mfma_f32_16x16x32_bf16 v[74:77], v[10:13], v[208:211], v[102:105]
	v_mfma_f32_16x16x32_bf16 v[78:81], v[14:17], v[212:215], v[74:77]
	v_mfma_f32_16x16x32_bf16 v[74:77], v[188:191], v[208:211], v[98:101]
	v_mfma_f32_16x16x32_bf16 v[74:77], v[192:195], v[212:215], v[74:77]
	s_barrier
	ds_read_b128 v[132:135], v142 offset:49152
	ds_read_b128 v[176:179], v142 offset:50176
	ds_read_b128 v[224:227], v142 offset:51200
	ds_read_b128 v[228:231], v142 offset:52224
	s_waitcnt vmcnt(0)
	s_barrier
	s_waitcnt lgkmcnt(0)
	s_waitcnt lgkmcnt(0)
	v_mfma_f32_16x16x32_bf16 v[98:101], v[132:135], v[26:29], v[216:219]
	v_mfma_f32_16x16x32_bf16 v[26:29], v[224:227], v[26:29], v[172:175]
	v_mfma_f32_16x16x32_bf16 v[114:117], v[228:231], v[30:33], v[26:29]
	v_mfma_f32_16x16x32_bf16 v[26:29], v[132:135], v[42:45], v[86:89]
	v_mfma_f32_16x16x32_bf16 v[102:105], v[176:179], v[46:49], v[26:29]
	v_mfma_f32_16x16x32_bf16 v[26:29], v[224:227], v[42:45], v[82:85]
	v_mfma_f32_16x16x32_bf16 v[118:121], v[176:179], v[30:33], v[98:101]
	v_mfma_f32_16x16x32_bf16 v[98:101], v[228:231], v[46:49], v[26:29]
	v_mfma_f32_16x16x32_bf16 v[26:29], v[132:135], v[196:199], v[180:183]
	v_mfma_f32_16x16x32_bf16 v[86:89], v[176:179], v[200:203], v[26:29]
	v_mfma_f32_16x16x32_bf16 v[26:29], v[224:227], v[196:199], v[184:187]
	v_mfma_f32_16x16x32_bf16 v[82:85], v[228:231], v[200:203], v[26:29]
	v_mfma_f32_16x16x32_bf16 v[26:29], v[132:135], v[208:211], v[70:73]
	v_mfma_f32_16x16x32_bf16 v[70:73], v[176:179], v[212:215], v[26:29]
	v_mfma_f32_16x16x32_bf16 v[26:29], v[224:227], v[208:211], v[66:69]
	v_mfma_f32_16x16x32_bf16 v[66:69], v[228:231], v[212:215], v[26:29]
	s_barrier
	ds_read_b128 v[172:175], v141 offset:49152
	ds_read_b128 v[180:183], v141 offset:50176
	ds_read_b128 v[184:187], v141 offset:51200
	ds_read_b128 v[196:199], v141 offset:52224
	ds_read_b128 v[200:203], v141 offset:53248
	ds_read_b128 v[208:211], v141 offset:54272
	ds_read_b128 v[212:215], v141 offset:55296
	ds_read_b128 v[216:219], v141 offset:56320
	s_barrier
	s_waitcnt lgkmcnt(0)
	s_waitcnt lgkmcnt(0)
	v_mfma_f32_16x16x32_bf16 v[26:29], v[10:13], v[172:175], v[62:65]
	v_mfma_f32_16x16x32_bf16 v[62:65], v[14:17], v[180:183], v[26:29]
	v_mfma_f32_16x16x32_bf16 v[26:29], v[188:191], v[172:175], v[58:61]
	v_mfma_f32_16x16x32_bf16 v[58:61], v[192:195], v[180:183], v[26:29]
	v_mfma_f32_16x16x32_bf16 v[26:29], v[10:13], v[184:187], v[54:57]
	v_mfma_f32_16x16x32_bf16 v[46:49], v[14:17], v[196:199], v[26:29]
	v_mfma_f32_16x16x32_bf16 v[26:29], v[188:191], v[184:187], v[50:53]
	v_mfma_f32_16x16x32_bf16 v[42:45], v[192:195], v[196:199], v[26:29]
	v_mfma_f32_16x16x32_bf16 v[26:29], v[10:13], v[200:203], v[204:207]
	v_mfma_f32_16x16x32_bf16 v[10:13], v[10:13], v[212:215], v[38:41]
	v_mfma_f32_16x16x32_bf16 v[30:33], v[14:17], v[208:211], v[26:29]
	v_mfma_f32_16x16x32_bf16 v[26:29], v[188:191], v[200:203], v[220:223]
	v_mfma_f32_16x16x32_bf16 v[14:17], v[14:17], v[216:219], v[10:13]
	v_mfma_f32_16x16x32_bf16 v[10:13], v[188:191], v[212:215], v[34:37]
	v_mfma_f32_16x16x32_bf16 v[26:29], v[192:195], v[208:211], v[26:29]
	v_mfma_f32_16x16x32_bf16 v[10:13], v[192:195], v[216:219], v[10:13]
	v_mfma_f32_16x16x32_bf16 v[34:37], v[132:135], v[172:175], v[144:147]
	v_mfma_f32_16x16x32_bf16 v[54:57], v[176:179], v[180:183], v[34:37]
	v_mfma_f32_16x16x32_bf16 v[34:37], v[224:227], v[172:175], v[152:155]
	v_mfma_f32_16x16x32_bf16 v[18:21], v[224:227], v[184:187], v[18:21]
	v_mfma_f32_16x16x32_bf16 v[50:53], v[228:231], v[180:183], v[34:37]
	v_mfma_f32_16x16x32_bf16 v[22:25], v[132:135], v[184:187], v[22:25]
	v_mfma_f32_16x16x32_bf16 v[34:37], v[228:231], v[196:199], v[18:21]
	v_mfma_f32_16x16x32_bf16 v[18:21], v[132:135], v[200:203], v[164:167]
	v_mfma_f32_16x16x32_bf16 v[38:41], v[176:179], v[196:199], v[22:25]
	v_mfma_f32_16x16x32_bf16 v[22:25], v[176:179], v[208:211], v[18:21]
	v_mfma_f32_16x16x32_bf16 v[18:21], v[224:227], v[200:203], v[168:171]
	v_mfma_f32_16x16x32_bf16 v[6:9], v[132:135], v[212:215], v[6:9]
	v_mfma_f32_16x16x32_bf16 v[2:5], v[224:227], v[212:215], v[2:5]
	v_mfma_f32_16x16x32_bf16 v[18:21], v[228:231], v[208:211], v[18:21]
	v_mfma_f32_16x16x32_bf16 v[6:9], v[176:179], v[216:219], v[6:9]
	v_mfma_f32_16x16x32_bf16 v[2:5], v[228:231], v[216:219], v[2:5]
	v_cmp_gt_u32_e32 vcc, s97, v131
	s_barrier
	s_and_saveexec_b64 s[14:15], vcc
	s_cbranch_execz .LBB0_226
	s_barrier

; #define WAIT_V(n) asm volatile("s_waitcnt vmcnt(%0)" ::"n"(n) : "memory")
; #define WAIT_L(n) asm volatile("s_waitcnt lgkmcnt(%0)" ::"n"(n) : "memory")
; #define SBAR() __builtin_amdgcn_sched_barrier(0)
; #define LDA8(dst, b, h) _Pragma("unroll") for (int m = 0; m < 4; ++m) _Pragma("unroll") for (int k = 0; k < 2; ++k) \
;     dst[m][k] = *(const bf16x8*)(abase + SAo(b, h) + m * 2048 + k * 1024)
; #define LDB8(dst, b, h) _Pragma("unroll") for (int n = 0; n < 2; ++n) _Pragma("unroll") for (int k = 0; k < 2; ++k) \
;     dst[n][k] = *(const bf16x8*)(bbase + SAo(b, h) + n * 2048 + k * 1024)
; #define BAR8 __builtin_amdgcn_s_barrier()
; __device__ __forceinline__ void gemm_main8(const u16* __restrict__ Ab, int lda, const u16* __restrict__ Bb, int ldb, int K,
;                                            char* shm, f32x4 (&acc)[2][2][4][2]) {
;     ...
;   for (int t = 0; t < nt - 2; t += 2) {
;     LDB8(B0, 0, 0); SBAR(); LDA8(At, 0, 0); STG_A(1, 1, t + 1);
;     WAIT_L(8); BAR8; WAIT_L(0); MMA8(0, 0, At, B0); BAR8; SBAR();
;     LDB8(B1, 0, 1); STG_B(0, 0, t + 2);
;     BAR8; WAIT_L(0); MMA8(0, 1, At, B1); BAR8;
;     LDA8(At, 0, 1); STG_A(0, 0, t + 2);
;     BAR8; WAIT_L(0); MMA8(1, 0, At, B0); BAR8; SBAR();
;     STG_B(0, 1, t + 2);
;     WAIT_V(6); BAR8; MMA8(1, 1, At, B1); BAR8;
.LBB0_368:
	ds_read_b128 v[152:155], v137
	ds_read_b128 v[164:167], v137 offset:1024
	ds_read_b128 v[176:179], v137 offset:2048
	ds_read_b128 v[180:183], v137 offset:3072
	v_add_u32_e32 v173, 0xc000, v138
	v_lshl_add_u64 v[168:169], s[20:21], 0, v[0:1]
	v_readfirstlane_b32 s15, v173
	v_lshl_add_u64 v[174:175], v[168:169], 0, s[54:55]
	s_mov_b32 m0, s15
	ds_read_b128 v[184:187], v136
	ds_read_b128 v[188:191], v136 offset:1024
	ds_read_b128 v[192:195], v136 offset:2048
	ds_read_b128 v[196:199], v136 offset:3072
	ds_read_b128 v[200:203], v136 offset:4096
	ds_read_b128 v[204:207], v136 offset:5120
	ds_read_b128 v[208:211], v136 offset:6144
	ds_read_b128 v[212:215], v136 offset:7168
	global_load_lds_dwordx4 v[174:175], off
	v_add_u32_e32 v174, 0xe000, v138
	v_lshl_add_u64 v[216:217], v[168:169], 0, s[56:57]
	v_readfirstlane_b32 s15, v174
	s_mov_b32 m0, s15
	s_nop 0
	global_load_lds_dwordx4 v[216:217], off
	s_waitcnt lgkmcnt(8)
	s_barrier
	s_waitcnt lgkmcnt(0)
	s_waitcnt lgkmcnt(0)
	v_mfma_f32_16x16x32_bf16 v[126:129], v[152:155], v[184:187], v[126:129]
	v_mfma_f32_16x16x32_bf16 v[122:125], v[176:179], v[184:187], v[122:125]
	v_mfma_f32_16x16x32_bf16 v[118:121], v[152:155], v[192:195], v[118:121]
	v_mfma_f32_16x16x32_bf16 v[114:117], v[176:179], v[192:195], v[114:117]
	v_mfma_f32_16x16x32_bf16 v[110:113], v[152:155], v[200:203], v[110:113]
	v_mfma_f32_16x16x32_bf16 v[106:109], v[176:179], v[200:203], v[106:109]
	v_mfma_f32_16x16x32_bf16 v[102:105], v[152:155], v[208:211], v[102:105]
	v_mfma_f32_16x16x32_bf16 v[98:101], v[176:179], v[208:211], v[98:101]
	v_mfma_f32_16x16x32_bf16 v[126:129], v[164:167], v[188:191], v[126:129]
	v_mfma_f32_16x16x32_bf16 v[122:125], v[180:183], v[188:191], v[122:125]
	v_mfma_f32_16x16x32_bf16 v[118:121], v[164:167], v[196:199], v[118:121]
	v_mfma_f32_16x16x32_bf16 v[114:117], v[180:183], v[196:199], v[114:117]
	v_mfma_f32_16x16x32_bf16 v[110:113], v[164:167], v[204:207], v[110:113]
	v_mfma_f32_16x16x32_bf16 v[106:109], v[180:183], v[204:207], v[106:109]
	v_mfma_f32_16x16x32_bf16 v[102:105], v[164:167], v[212:215], v[102:105]
	v_mfma_f32_16x16x32_bf16 v[98:101], v[180:183], v[212:215], v[98:101]
	s_barrier
	v_lshl_add_u64 v[232:233], s[18:19], 0, v[0:1]
	s_mov_b64 s[24:25], 0x3800100
	v_readfirstlane_b32 s15, v139
	v_lshl_add_u64 v[234:235], v[232:233], 0, s[24:25]
	s_mov_b32 m0, s15
	s_mov_b64 s[24:25], 0x3840100
	v_readfirstlane_b32 s15, v140
	ds_read_b128 v[216:219], v137 offset:16384
	ds_read_b128 v[220:223], v137 offset:17408
	ds_read_b128 v[224:227], v137 offset:18432
	ds_read_b128 v[228:231], v137 offset:19456
	global_load_lds_dwordx4 v[234:235], off
	v_lshl_add_u64 v[234:235], v[232:233], 0, s[24:25]
	s_mov_b32 m0, s15
	s_nop 0
	global_load_lds_dwordx4 v[234:235], off
	s_barrier
	s_waitcnt lgkmcnt(0)
	s_waitcnt lgkmcnt(0)
	v_mfma_f32_16x16x32_bf16 v[94:97], v[216:219], v[184:187], v[94:97]
	v_mfma_f32_16x16x32_bf16 v[90:93], v[224:227], v[184:187], v[90:93]
	v_mfma_f32_16x16x32_bf16 v[86:89], v[216:219], v[192:195], v[86:89]
	v_mfma_f32_16x16x32_bf16 v[82:85], v[224:227], v[192:195], v[82:85]
	v_mfma_f32_16x16x32_bf16 v[78:81], v[216:219], v[200:203], v[78:81]
	v_mfma_f32_16x16x32_bf16 v[74:77], v[224:227], v[200:203], v[74:77]
	v_mfma_f32_16x16x32_bf16 v[70:73], v[216:219], v[208:211], v[70:73]
	v_mfma_f32_16x16x32_bf16 v[66:69], v[224:227], v[208:211], v[66:69]
	v_mfma_f32_16x16x32_bf16 v[94:97], v[220:223], v[188:191], v[94:97]
	v_mfma_f32_16x16x32_bf16 v[90:93], v[228:231], v[188:191], v[90:93]
	v_mfma_f32_16x16x32_bf16 v[86:89], v[220:223], v[196:199], v[86:89]
	v_mfma_f32_16x16x32_bf16 v[82:85], v[228:231], v[196:199], v[82:85]
	v_mfma_f32_16x16x32_bf16 v[78:81], v[220:223], v[204:207], v[78:81]
	v_mfma_f32_16x16x32_bf16 v[74:77], v[228:231], v[204:207], v[74:77]
	v_mfma_f32_16x16x32_bf16 v[70:73], v[220:223], v[212:215], v[70:73]
	v_mfma_f32_16x16x32_bf16 v[66:69], v[228:231], v[212:215], v[66:69]
	v_readfirstlane_b32 s15, v138
	v_lshl_add_u64 v[234:235], v[168:169], 0, s[58:59]
	s_mov_b32 m0, s15
	v_readfirstlane_b32 s15, v141
	s_barrier
	ds_read_b128 v[184:187], v136 offset:16384
	ds_read_b128 v[188:191], v136 offset:17408
	ds_read_b128 v[192:195], v136 offset:18432
	ds_read_b128 v[196:199], v136 offset:19456
	ds_read_b128 v[200:203], v136 offset:20480
	ds_read_b128 v[204:207], v136 offset:21504
	ds_read_b128 v[208:211], v136 offset:22528
	ds_read_b128 v[212:215], v136 offset:23552
	global_load_lds_dwordx4 v[234:235], off
	v_lshl_add_u64 v[234:235], v[168:169], 0, s[60:61]
	s_mov_b32 m0, s15
	s_nop 0
	global_load_lds_dwordx4 v[234:235], off
	s_barrier
	s_waitcnt lgkmcnt(0)
	s_waitcnt lgkmcnt(0)
	v_mfma_f32_16x16x32_bf16 v[62:65], v[152:155], v[184:187], v[62:65]
	v_mfma_f32_16x16x32_bf16 v[58:61], v[176:179], v[184:187], v[58:61]
	v_mfma_f32_16x16x32_bf16 v[54:57], v[152:155], v[192:195], v[54:57]
	v_mfma_f32_16x16x32_bf16 v[50:53], v[176:179], v[192:195], v[50:53]
	v_mfma_f32_16x16x32_bf16 v[46:49], v[152:155], v[200:203], v[46:49]
	v_mfma_f32_16x16x32_bf16 v[42:45], v[176:179], v[200:203], v[42:45]
	v_mfma_f32_16x16x32_bf16 v[38:41], v[152:155], v[208:211], v[38:41]
	v_mfma_f32_16x16x32_bf16 v[34:37], v[176:179], v[208:211], v[34:37]
	v_mfma_f32_16x16x32_bf16 v[62:65], v[164:167], v[188:191], v[62:65]
	v_mfma_f32_16x16x32_bf16 v[58:61], v[180:183], v[188:191], v[58:61]
	v_mfma_f32_16x16x32_bf16 v[54:57], v[164:167], v[196:199], v[54:57]
	v_mfma_f32_16x16x32_bf16 v[50:53], v[180:183], v[196:199], v[50:53]
	v_mfma_f32_16x16x32_bf16 v[46:49], v[164:167], v[204:207], v[46:49]
	v_mfma_f32_16x16x32_bf16 v[42:45], v[180:183], v[204:207], v[42:45]
	v_mfma_f32_16x16x32_bf16 v[38:41], v[164:167], v[212:215], v[38:41]
	v_mfma_f32_16x16x32_bf16 v[34:37], v[180:183], v[212:215], v[34:37]
	s_barrier
; #define WAIT_V(n) asm volatile("s_waitcnt vmcnt(%0)" ::"n"(n) : "memory")
; #define WAIT_L(n) asm volatile("s_waitcnt lgkmcnt(%0)" ::"n"(n) : "memory")
; #define SBAR() __builtin_amdgcn_sched_barrier(0)
; #define LDA8(dst, b, h) _Pragma("unroll") for (int m = 0; m < 4; ++m) _Pragma("unroll") for (int k = 0; k < 2; ++k) \
;     dst[m][k] = *(const bf16x8*)(abase + SAo(b, h) + m * 2048 + k * 1024)
; #define LDB8(dst, b, h) _Pragma("unroll") for (int n = 0; n < 2; ++n) _Pragma("unroll") for (int k = 0; k < 2; ++k) \
;     dst[n][k] = *(const bf16x8*)(bbase + SAo(b, h) + n * 2048 + k * 1024)
; #define BAR8 __builtin_amdgcn_s_barrier()
; __device__ __forceinline__ void gemm_main8(const u16* __restrict__ Ab, int lda, const u16* __restrict__ Bb, int ldb, int K,
;                                            char* shm, f32x4 (&acc)[2][2][4][2]) {
;     ...
;     STG_B(0, 1, t + 2);
;     WAIT_V(6); BAR8; MMA8(1, 1, At, B1); BAR8;
;     LDB8(B0, 1, 0); SBAR(); LDA8(At, 1, 0); STG_A(0, 1, t + 2);
;     WAIT_L(8); BAR8; WAIT_L(0); MMA8(0, 0, At, B0); BAR8; SBAR();
;     LDB8(B1, 1, 1); STG_B(1, 0, t + 3);
;     BAR8; WAIT_L(0); MMA8(0, 1, At, B1); BAR8;
;     LDA8(At, 1, 1); STG_A(1, 0, t + 3);
;     BAR8; WAIT_L(0); MMA8(1, 0, At, B0); BAR8; SBAR();
	s_mov_b64 s[24:25], 0x3880100
	v_readfirstlane_b32 s15, v142
	v_lshl_add_u64 v[152:153], v[232:233], 0, s[24:25]
	s_mov_b32 m0, s15
	s_mov_b64 s[24:25], 0x38c0100
	v_readfirstlane_b32 s15, v143
	global_load_lds_dwordx4 v[152:153], off
	v_lshl_add_u64 v[152:153], v[232:233], 0, s[24:25]
	s_mov_b32 m0, s15
	s_nop 0
	global_load_lds_dwordx4 v[152:153], off
	s_waitcnt vmcnt(6)
	s_barrier
	v_mfma_f32_16x16x32_bf16 v[30:33], v[216:219], v[184:187], v[30:33]
	v_mfma_f32_16x16x32_bf16 v[26:29], v[224:227], v[184:187], v[26:29]
	v_mfma_f32_16x16x32_bf16 v[22:25], v[216:219], v[192:195], v[22:25]
	v_mfma_f32_16x16x32_bf16 v[18:21], v[224:227], v[192:195], v[18:21]
	v_mfma_f32_16x16x32_bf16 v[14:17], v[216:219], v[200:203], v[14:17]
	v_mfma_f32_16x16x32_bf16 v[10:13], v[224:227], v[200:203], v[10:13]
	v_mfma_f32_16x16x32_bf16 v[6:9], v[216:219], v[208:211], v[6:9]
	v_mfma_f32_16x16x32_bf16 v[2:5], v[224:227], v[208:211], v[2:5]
	v_mfma_f32_16x16x32_bf16 v[30:33], v[220:223], v[188:191], v[30:33]
	v_mfma_f32_16x16x32_bf16 v[26:29], v[228:231], v[188:191], v[26:29]
	v_mfma_f32_16x16x32_bf16 v[22:25], v[220:223], v[196:199], v[22:25]
	v_mfma_f32_16x16x32_bf16 v[18:21], v[228:231], v[196:199], v[18:21]
	v_mfma_f32_16x16x32_bf16 v[14:17], v[220:223], v[204:207], v[14:17]
	v_mfma_f32_16x16x32_bf16 v[10:13], v[228:231], v[204:207], v[10:13]
	v_mfma_f32_16x16x32_bf16 v[6:9], v[220:223], v[212:215], v[6:9]
	v_mfma_f32_16x16x32_bf16 v[2:5], v[228:231], v[212:215], v[2:5]
	s_barrier
	ds_read_b128 v[152:155], v137 offset:32768
	ds_read_b128 v[164:167], v137 offset:33792
	ds_read_b128 v[176:179], v137 offset:34816
	ds_read_b128 v[180:183], v137 offset:35840
	v_readfirstlane_b32 s15, v144
	v_lshl_add_u64 v[216:217], v[168:169], 0, s[62:63]
	s_mov_b32 m0, s15
	v_readfirstlane_b32 s15, v145
	ds_read_b128 v[184:187], v136 offset:32768
	ds_read_b128 v[188:191], v136 offset:33792
	ds_read_b128 v[192:195], v136 offset:34816
	ds_read_b128 v[196:199], v136 offset:35840
	ds_read_b128 v[200:203], v136 offset:36864
	ds_read_b128 v[204:207], v136 offset:37888
	ds_read_b128 v[208:211], v136 offset:38912
	ds_read_b128 v[212:215], v136 offset:39936
	global_load_lds_dwordx4 v[216:217], off
	v_lshl_add_u64 v[216:217], v[168:169], 0, s[64:65]
	s_mov_b32 m0, s15
	s_nop 0
	global_load_lds_dwordx4 v[216:217], off
	s_waitcnt lgkmcnt(8)
	s_barrier
	s_waitcnt lgkmcnt(0)
	s_waitcnt lgkmcnt(0)
	v_mfma_f32_16x16x32_bf16 v[126:129], v[152:155], v[184:187], v[126:129]
	v_mfma_f32_16x16x32_bf16 v[122:125], v[176:179], v[184:187], v[122:125]
	v_mfma_f32_16x16x32_bf16 v[118:121], v[152:155], v[192:195], v[118:121]
	v_mfma_f32_16x16x32_bf16 v[114:117], v[176:179], v[192:195], v[114:117]
	v_mfma_f32_16x16x32_bf16 v[110:113], v[152:155], v[200:203], v[110:113]
	v_mfma_f32_16x16x32_bf16 v[106:109], v[176:179], v[200:203], v[106:109]
	v_mfma_f32_16x16x32_bf16 v[102:105], v[152:155], v[208:211], v[102:105]
	v_mfma_f32_16x16x32_bf16 v[98:101], v[176:179], v[208:211], v[98:101]
	v_mfma_f32_16x16x32_bf16 v[126:129], v[164:167], v[188:191], v[126:129]
	v_mfma_f32_16x16x32_bf16 v[122:125], v[180:183], v[188:191], v[122:125]
	v_mfma_f32_16x16x32_bf16 v[118:121], v[164:167], v[196:199], v[118:121]
	v_mfma_f32_16x16x32_bf16 v[114:117], v[180:183], v[196:199], v[114:117]
	v_mfma_f32_16x16x32_bf16 v[110:113], v[164:167], v[204:207], v[110:113]
	v_mfma_f32_16x16x32_bf16 v[106:109], v[180:183], v[204:207], v[106:109]
	v_mfma_f32_16x16x32_bf16 v[102:105], v[164:167], v[212:215], v[102:105]
	v_mfma_f32_16x16x32_bf16 v[98:101], v[180:183], v[212:215], v[98:101]
	s_barrier
	s_mov_b64 s[24:25], 0x3800180
	v_readfirstlane_b32 s15, v146
	v_lshl_add_u64 v[234:235], v[232:233], 0, s[24:25]
	s_mov_b32 m0, s15
	s_mov_b64 s[24:25], 0x3840180
	v_readfirstlane_b32 s15, v147
	ds_read_b128 v[216:219], v137 offset:49152
	ds_read_b128 v[220:223], v137 offset:50176
	ds_read_b128 v[224:227], v137 offset:51200
	ds_read_b128 v[228:231], v137 offset:52224
	global_load_lds_dwordx4 v[234:235], off
	v_lshl_add_u64 v[234:235], v[232:233], 0, s[24:25]
	s_mov_b32 m0, s15
	s_nop 0
	global_load_lds_dwordx4 v[234:235], off
	s_barrier
	s_waitcnt lgkmcnt(0)
	s_waitcnt lgkmcnt(0)
	v_mfma_f32_16x16x32_bf16 v[94:97], v[216:219], v[184:187], v[94:97]
	v_mfma_f32_16x16x32_bf16 v[90:93], v[224:227], v[184:187], v[90:93]
	v_mfma_f32_16x16x32_bf16 v[86:89], v[216:219], v[192:195], v[86:89]
	v_mfma_f32_16x16x32_bf16 v[82:85], v[224:227], v[192:195], v[82:85]
	v_mfma_f32_16x16x32_bf16 v[78:81], v[216:219], v[200:203], v[78:81]
	v_mfma_f32_16x16x32_bf16 v[74:77], v[224:227], v[200:203], v[74:77]
	v_mfma_f32_16x16x32_bf16 v[70:73], v[216:219], v[208:211], v[70:73]
	v_mfma_f32_16x16x32_bf16 v[66:69], v[224:227], v[208:211], v[66:69]
	v_mfma_f32_16x16x32_bf16 v[94:97], v[220:223], v[188:191], v[94:97]
	v_mfma_f32_16x16x32_bf16 v[90:93], v[228:231], v[188:191], v[90:93]
	v_mfma_f32_16x16x32_bf16 v[86:89], v[220:223], v[196:199], v[86:89]
	v_mfma_f32_16x16x32_bf16 v[82:85], v[228:231], v[196:199], v[82:85]
	v_mfma_f32_16x16x32_bf16 v[78:81], v[220:223], v[204:207], v[78:81]
	v_mfma_f32_16x16x32_bf16 v[74:77], v[228:231], v[204:207], v[74:77]
	v_mfma_f32_16x16x32_bf16 v[70:73], v[220:223], v[212:215], v[70:73]
	v_mfma_f32_16x16x32_bf16 v[66:69], v[228:231], v[212:215], v[66:69]
	v_readfirstlane_b32 s15, v148
	v_lshl_add_u64 v[234:235], v[168:169], 0, s[66:67]
	s_mov_b32 m0, s15
	v_readfirstlane_b32 s15, v149
	s_barrier
; #define WAIT_V(n) asm volatile("s_waitcnt vmcnt(%0)" ::"n"(n) : "memory")
; #define WAIT_L(n) asm volatile("s_waitcnt lgkmcnt(%0)" ::"n"(n) : "memory")
; #define SBAR() __builtin_amdgcn_sched_barrier(0)
; #define LDA8(dst, b, h) _Pragma("unroll") for (int m = 0; m < 4; ++m) _Pragma("unroll") for (int k = 0; k < 2; ++k) \
;     dst[m][k] = *(const bf16x8*)(abase + SAo(b, h) + m * 2048 + k * 1024)
; #define LDB8(dst, b, h) _Pragma("unroll") for (int n = 0; n < 2; ++n) _Pragma("unroll") for (int k = 0; k < 2; ++k) \
;     dst[n][k] = *(const bf16x8*)(bbase + SAo(b, h) + n * 2048 + k * 1024)
; #define BAR8 __builtin_amdgcn_s_barrier()
; __device__ __forceinline__ void gemm_main8(const u16* __restrict__ Ab, int lda, const u16* __restrict__ Bb, int ldb, int K,
;                                            char* shm, f32x4 (&acc)[2][2][4][2]) {
;     ...
;     LDA8(At, 1, 1); STG_A(1, 0, t + 3);
;     BAR8; WAIT_L(0); MMA8(1, 0, At, B0); BAR8; SBAR();
;     STG_B(1, 1, t + 3);
;     WAIT_V(6); BAR8; MMA8(1, 1, At, B1); BAR8;
;   }
;   { LDB8(B0, 0, 0); LDA8(At, 0, 0); STG_A(1, 1, nt - 1);
;     BAR8; WAIT_L(0); MMA8(0, 0, At, B0); BAR8;
;     LDB8(B1, 0, 1); BAR8; WAIT_L(0); MMA8(0, 1, At, B1); BAR8;
	ds_read_b128 v[184:187], v136 offset:49152
	ds_read_b128 v[188:191], v136 offset:50176
	ds_read_b128 v[192:195], v136 offset:51200
	ds_read_b128 v[196:199], v136 offset:52224
	ds_read_b128 v[200:203], v136 offset:53248
	ds_read_b128 v[204:207], v136 offset:54272
	ds_read_b128 v[208:211], v136 offset:55296
	ds_read_b128 v[212:215], v136 offset:56320
	global_load_lds_dwordx4 v[234:235], off
	v_lshl_add_u64 v[168:169], v[168:169], 0, s[68:69]
	s_mov_b32 m0, s15
	s_nop 0
	global_load_lds_dwordx4 v[168:169], off
	s_barrier
	s_waitcnt lgkmcnt(0)
	s_waitcnt lgkmcnt(0)
	v_mfma_f32_16x16x32_bf16 v[62:65], v[152:155], v[184:187], v[62:65]
	v_mfma_f32_16x16x32_bf16 v[58:61], v[176:179], v[184:187], v[58:61]
	v_mfma_f32_16x16x32_bf16 v[54:57], v[152:155], v[192:195], v[54:57]
	v_mfma_f32_16x16x32_bf16 v[50:53], v[176:179], v[192:195], v[50:53]
	v_mfma_f32_16x16x32_bf16 v[46:49], v[152:155], v[200:203], v[46:49]
	v_mfma_f32_16x16x32_bf16 v[42:45], v[176:179], v[200:203], v[42:45]
	v_mfma_f32_16x16x32_bf16 v[38:41], v[152:155], v[208:211], v[38:41]
	v_mfma_f32_16x16x32_bf16 v[34:37], v[176:179], v[208:211], v[34:37]
	v_mfma_f32_16x16x32_bf16 v[62:65], v[164:167], v[188:191], v[62:65]
	v_mfma_f32_16x16x32_bf16 v[58:61], v[180:183], v[188:191], v[58:61]
	v_mfma_f32_16x16x32_bf16 v[54:57], v[164:167], v[196:199], v[54:57]
	v_mfma_f32_16x16x32_bf16 v[50:53], v[180:183], v[196:199], v[50:53]
	v_mfma_f32_16x16x32_bf16 v[46:49], v[164:167], v[204:207], v[46:49]
	v_mfma_f32_16x16x32_bf16 v[42:45], v[180:183], v[204:207], v[42:45]
	v_mfma_f32_16x16x32_bf16 v[38:41], v[164:167], v[212:215], v[38:41]
	v_mfma_f32_16x16x32_bf16 v[34:37], v[180:183], v[212:215], v[34:37]
	s_barrier
	s_mov_b64 s[24:25], 0x3880180
	v_readfirstlane_b32 s15, v171
	v_lshl_add_u64 v[152:153], v[232:233], 0, s[24:25]
	s_mov_b32 m0, s15
	s_mov_b64 s[24:25], 0x38c0180
	v_readfirstlane_b32 s15, v172
	global_load_lds_dwordx4 v[152:153], off
	v_lshl_add_u64 v[152:153], v[232:233], 0, s[24:25]
	s_mov_b32 m0, s15
	s_nop 0
	global_load_lds_dwordx4 v[152:153], off
	s_waitcnt vmcnt(6)
	s_barrier
	v_mfma_f32_16x16x32_bf16 v[30:33], v[216:219], v[184:187], v[30:33]
	v_mfma_f32_16x16x32_bf16 v[26:29], v[224:227], v[184:187], v[26:29]
	v_mfma_f32_16x16x32_bf16 v[22:25], v[216:219], v[192:195], v[22:25]
	v_mfma_f32_16x16x32_bf16 v[18:21], v[224:227], v[192:195], v[18:21]
	v_mfma_f32_16x16x32_bf16 v[14:17], v[216:219], v[200:203], v[14:17]
	v_mfma_f32_16x16x32_bf16 v[10:13], v[224:227], v[200:203], v[10:13]
	v_mfma_f32_16x16x32_bf16 v[6:9], v[216:219], v[208:211], v[6:9]
	v_mfma_f32_16x16x32_bf16 v[2:5], v[224:227], v[208:211], v[2:5]
	v_mfma_f32_16x16x32_bf16 v[30:33], v[220:223], v[188:191], v[30:33]
	v_mfma_f32_16x16x32_bf16 v[26:29], v[228:231], v[188:191], v[26:29]
	v_mfma_f32_16x16x32_bf16 v[22:25], v[220:223], v[196:199], v[22:25]
	v_mfma_f32_16x16x32_bf16 v[18:21], v[228:231], v[196:199], v[18:21]
	v_mfma_f32_16x16x32_bf16 v[14:17], v[220:223], v[204:207], v[14:17]
	v_mfma_f32_16x16x32_bf16 v[10:13], v[228:231], v[204:207], v[10:13]
	v_mfma_f32_16x16x32_bf16 v[6:9], v[220:223], v[212:215], v[6:9]
	v_mfma_f32_16x16x32_bf16 v[2:5], v[228:231], v[212:215], v[2:5]
	s_add_i32 s13, s13, 2
	s_add_u32 s18, s18, 0x100
	s_addc_u32 s19, s19, 0
	s_add_u32 s20, s20, 0x100
	s_addc_u32 s21, s21, 0
	s_cmp_lt_u32 s13, 28
	s_barrier
	s_cbranch_scc1 .LBB0_368
	s_mov_b64 s[18:19], 0x80f80
	v_readfirstlane_b32 s13, v173
	v_lshl_add_u64 v[200:201], v[130:131], 0, s[18:19]
	s_mov_b32 m0, s13
	s_mov_b64 s[18:19], 0xc0f80
	v_readfirstlane_b32 s13, v174
	ds_read_b128 v[138:141], v137
	ds_read_b128 v[142:145], v137 offset:1024
	ds_read_b128 v[146:149], v137 offset:2048
	ds_read_b128 v[152:155], v137 offset:3072
	ds_read_b128 v[164:167], v136
	ds_read_b128 v[168:171], v136 offset:1024
	ds_read_b128 v[176:179], v136 offset:2048
	ds_read_b128 v[180:183], v136 offset:3072
	ds_read_b128 v[184:187], v136 offset:4096
	ds_read_b128 v[188:191], v136 offset:5120
	ds_read_b128 v[192:195], v136 offset:6144
	ds_read_b128 v[196:199], v136 offset:7168
	global_load_lds_dwordx4 v[200:201], off
	v_lshl_add_u64 v[130:131], v[130:131], 0, s[18:19]
	s_mov_b32 m0, s13
	s_nop 0
	global_load_lds_dwordx4 v[130:131], off
	s_barrier
	s_waitcnt lgkmcnt(0)
	s_waitcnt lgkmcnt(0)
	v_mfma_f32_16x16x32_bf16 v[126:129], v[138:141], v[164:167], v[126:129]
	v_mfma_f32_16x16x32_bf16 v[118:121], v[138:141], v[176:179], v[118:121]
	v_mfma_f32_16x16x32_bf16 v[110:113], v[138:141], v[184:187], v[110:113]
	v_mfma_f32_16x16x32_bf16 v[102:105], v[138:141], v[192:195], v[102:105]
	v_mfma_f32_16x16x32_bf16 v[126:129], v[142:145], v[168:171], v[126:129]
	v_mfma_f32_16x16x32_bf16 v[122:125], v[146:149], v[164:167], v[122:125]
	v_mfma_f32_16x16x32_bf16 v[118:121], v[142:145], v[180:183], v[118:121]
	v_mfma_f32_16x16x32_bf16 v[114:117], v[146:149], v[176:179], v[114:117]
	v_mfma_f32_16x16x32_bf16 v[110:113], v[142:145], v[188:191], v[110:113]
	v_mfma_f32_16x16x32_bf16 v[106:109], v[146:149], v[184:187], v[106:109]
	v_mfma_f32_16x16x32_bf16 v[102:105], v[142:145], v[196:199], v[102:105]
	v_mfma_f32_16x16x32_bf16 v[98:101], v[146:149], v[192:195], v[98:101]
	v_mfma_f32_16x16x32_bf16 v[172:175], v[152:155], v[168:171], v[122:125]
	v_mfma_f32_16x16x32_bf16 v[200:203], v[152:155], v[180:183], v[114:117]
	v_mfma_f32_16x16x32_bf16 v[204:207], v[152:155], v[188:191], v[106:109]
	v_mfma_f32_16x16x32_bf16 v[208:211], v[152:155], v[196:199], v[98:101]
	s_barrier
	s_nop 1
	ds_read_b128 v[98:101], v137 offset:16384
	ds_read_b128 v[106:109], v137 offset:17408
	ds_read_b128 v[114:117], v137 offset:18432
	ds_read_b128 v[122:125], v137 offset:19456
	s_barrier
; #define WAIT_V(n) asm volatile("s_waitcnt vmcnt(%0)" ::"n"(n) : "memory")
; #define WAIT_L(n) asm volatile("s_waitcnt lgkmcnt(%0)" ::"n"(n) : "memory")
; #define LDA8(dst, b, h) _Pragma("unroll") for (int m = 0; m < 4; ++m) _Pragma("unroll") for (int k = 0; k < 2; ++k) \
;     dst[m][k] = *(const bf16x8*)(abase + SAo(b, h) + m * 2048 + k * 1024)
; #define LDB8(dst, b, h) _Pragma("unroll") for (int n = 0; n < 2; ++n) _Pragma("unroll") for (int k = 0; k < 2; ++k) \
;     dst[n][k] = *(const bf16x8*)(bbase + SAo(b, h) + n * 2048 + k * 1024)
; #define BAR8 __builtin_amdgcn_s_barrier()
; __device__ __forceinline__ void gemm_main8(const u16* __restrict__ Ab, int lda, const u16* __restrict__ Bb, int ldb, int K,
;                                            char* shm, f32x4 (&acc)[2][2][4][2]) {
;     ...
;     LDB8(B1, 0, 1); BAR8; WAIT_L(0); MMA8(0, 1, At, B1); BAR8;
;     LDA8(At, 0, 1); WAIT_V(4); BAR8; WAIT_L(0); MMA8(1, 0, At, B0); MMA8(1, 1, At, B1); BAR8; }
;   { LDB8(B0, 1, 0); LDA8(At, 1, 0); WAIT_V(2); BAR8; WAIT_L(0); MMA8(0, 0, At, B0); BAR8;
;     LDB8(B1, 1, 1); WAIT_V(0); BAR8; WAIT_L(0); MMA8(0, 1, At, B1); BAR8;
	s_waitcnt lgkmcnt(0)
	s_waitcnt lgkmcnt(0)
	v_mfma_f32_16x16x32_bf16 v[94:97], v[98:101], v[164:167], v[94:97]
	v_mfma_f32_16x16x32_bf16 v[86:89], v[98:101], v[176:179], v[86:89]
	v_mfma_f32_16x16x32_bf16 v[78:81], v[98:101], v[184:187], v[78:81]
	v_mfma_f32_16x16x32_bf16 v[70:73], v[98:101], v[192:195], v[70:73]
	v_mfma_f32_16x16x32_bf16 v[94:97], v[106:109], v[168:171], v[94:97]
	v_mfma_f32_16x16x32_bf16 v[90:93], v[114:117], v[164:167], v[90:93]
	v_mfma_f32_16x16x32_bf16 v[86:89], v[106:109], v[180:183], v[86:89]
	v_mfma_f32_16x16x32_bf16 v[82:85], v[114:117], v[176:179], v[82:85]
	v_mfma_f32_16x16x32_bf16 v[78:81], v[106:109], v[188:191], v[78:81]
	v_mfma_f32_16x16x32_bf16 v[74:77], v[114:117], v[184:187], v[74:77]
	v_mfma_f32_16x16x32_bf16 v[70:73], v[106:109], v[196:199], v[70:73]
	v_mfma_f32_16x16x32_bf16 v[66:69], v[114:117], v[192:195], v[66:69]
	v_mfma_f32_16x16x32_bf16 v[164:167], v[122:125], v[168:171], v[90:93]
	v_mfma_f32_16x16x32_bf16 v[168:171], v[122:125], v[180:183], v[82:85]
	v_mfma_f32_16x16x32_bf16 v[176:179], v[122:125], v[188:191], v[74:77]
	v_mfma_f32_16x16x32_bf16 v[180:183], v[122:125], v[196:199], v[66:69]
	s_barrier
	s_nop 1
	ds_read_b128 v[66:69], v136 offset:16384
	ds_read_b128 v[74:77], v136 offset:17408
	ds_read_b128 v[82:85], v136 offset:18432
	ds_read_b128 v[90:93], v136 offset:19456
	ds_read_b128 v[184:187], v136 offset:20480
	ds_read_b128 v[188:191], v136 offset:21504
	ds_read_b128 v[192:195], v136 offset:22528
	ds_read_b128 v[196:199], v136 offset:23552
	s_waitcnt vmcnt(4)
	s_barrier
	s_waitcnt lgkmcnt(0)
	s_waitcnt lgkmcnt(0)
	v_mfma_f32_16x16x32_bf16 v[62:65], v[138:141], v[66:69], v[62:65]
	v_mfma_f32_16x16x32_bf16 v[58:61], v[146:149], v[66:69], v[58:61]
	v_mfma_f32_16x16x32_bf16 v[50:53], v[146:149], v[82:85], v[50:53]
	v_mfma_f32_16x16x32_bf16 v[42:45], v[146:149], v[184:187], v[42:45]
	v_mfma_f32_16x16x32_bf16 v[34:37], v[146:149], v[192:195], v[34:37]
	v_mfma_f32_16x16x32_bf16 v[62:65], v[142:145], v[74:77], v[62:65]
	v_mfma_f32_16x16x32_bf16 v[58:61], v[152:155], v[74:77], v[58:61]
	v_mfma_f32_16x16x32_bf16 v[54:57], v[138:141], v[82:85], v[54:57]
	v_mfma_f32_16x16x32_bf16 v[50:53], v[152:155], v[90:93], v[50:53]
	v_mfma_f32_16x16x32_bf16 v[46:49], v[138:141], v[184:187], v[46:49]
	v_mfma_f32_16x16x32_bf16 v[42:45], v[152:155], v[188:191], v[42:45]
	v_mfma_f32_16x16x32_bf16 v[38:41], v[138:141], v[192:195], v[38:41]
	v_mfma_f32_16x16x32_bf16 v[34:37], v[152:155], v[196:199], v[34:37]
	v_mfma_f32_16x16x32_bf16 v[212:215], v[142:145], v[90:93], v[54:57]
	v_mfma_f32_16x16x32_bf16 v[216:219], v[142:145], v[188:191], v[46:49]
	v_mfma_f32_16x16x32_bf16 v[138:141], v[142:145], v[196:199], v[38:41]
	v_mfma_f32_16x16x32_bf16 v[26:29], v[114:117], v[66:69], v[26:29]
	v_mfma_f32_16x16x32_bf16 v[18:21], v[114:117], v[82:85], v[18:21]
	v_mfma_f32_16x16x32_bf16 v[10:13], v[114:117], v[184:187], v[10:13]
	v_mfma_f32_16x16x32_bf16 v[2:5], v[114:117], v[192:195], v[2:5]
	v_mfma_f32_16x16x32_bf16 v[30:33], v[98:101], v[66:69], v[30:33]
	v_mfma_f32_16x16x32_bf16 v[26:29], v[122:125], v[74:77], v[26:29]
	v_mfma_f32_16x16x32_bf16 v[22:25], v[98:101], v[82:85], v[22:25]
	v_mfma_f32_16x16x32_bf16 v[18:21], v[122:125], v[90:93], v[18:21]
	v_mfma_f32_16x16x32_bf16 v[14:17], v[98:101], v[184:187], v[14:17]
	v_mfma_f32_16x16x32_bf16 v[10:13], v[122:125], v[188:191], v[10:13]
	v_mfma_f32_16x16x32_bf16 v[6:9], v[98:101], v[192:195], v[6:9]
	v_mfma_f32_16x16x32_bf16 v[2:5], v[122:125], v[196:199], v[2:5]
	v_mfma_f32_16x16x32_bf16 v[142:145], v[106:109], v[74:77], v[30:33]
	v_mfma_f32_16x16x32_bf16 v[146:149], v[106:109], v[90:93], v[22:25]
	v_mfma_f32_16x16x32_bf16 v[152:155], v[106:109], v[188:191], v[14:17]
	v_mfma_f32_16x16x32_bf16 v[184:187], v[106:109], v[196:199], v[6:9]
	s_barrier
	s_nop 0
	ds_read_b128 v[6:9], v137 offset:32768
	ds_read_b128 v[14:17], v137 offset:33792
	ds_read_b128 v[188:191], v137 offset:34816
	ds_read_b128 v[192:195], v137 offset:35840
	ds_read_b128 v[22:25], v136 offset:32768
	ds_read_b128 v[30:33], v136 offset:33792
	ds_read_b128 v[38:41], v136 offset:34816
	ds_read_b128 v[46:49], v136 offset:35840
	ds_read_b128 v[54:57], v136 offset:36864
	ds_read_b128 v[196:199], v136 offset:37888
	ds_read_b128 v[220:223], v136 offset:38912
	ds_read_b128 v[224:227], v136 offset:39936
	s_waitcnt vmcnt(2)
	s_barrier
; #define WAIT_V(n) asm volatile("s_waitcnt vmcnt(%0)" ::"n"(n) : "memory")
; #define WAIT_L(n) asm volatile("s_waitcnt lgkmcnt(%0)" ::"n"(n) : "memory")
; #define LDA8(dst, b, h) _Pragma("unroll") for (int m = 0; m < 4; ++m) _Pragma("unroll") for (int k = 0; k < 2; ++k) \
;     dst[m][k] = *(const bf16x8*)(abase + SAo(b, h) + m * 2048 + k * 1024)
; #define LDB8(dst, b, h) _Pragma("unroll") for (int n = 0; n < 2; ++n) _Pragma("unroll") for (int k = 0; k < 2; ++k) \
;     dst[n][k] = *(const bf16x8*)(bbase + SAo(b, h) + n * 2048 + k * 1024)
; #define BAR8 __builtin_amdgcn_s_barrier()
; __device__ __forceinline__ void gemm_main8(const u16* __restrict__ Ab, int lda, const u16* __restrict__ Bb, int ldb, int K,
;                                            char* shm, f32x4 (&acc)[2][2][4][2]) {
;     ...
;   { LDB8(B0, 1, 0); LDA8(At, 1, 0); WAIT_V(2); BAR8; WAIT_L(0); MMA8(0, 0, At, B0); BAR8;
;     LDB8(B1, 1, 1); WAIT_V(0); BAR8; WAIT_L(0); MMA8(0, 1, At, B1); BAR8;
;     LDA8(At, 1, 1); BAR8; WAIT_L(0); MMA8(1, 0, At, B0); MMA8(1, 1, At, B1); BAR8; }
;   if (wr == 0) BAR8;
	s_waitcnt lgkmcnt(0)
	s_waitcnt lgkmcnt(0)
	v_mfma_f32_16x16x32_bf16 v[66:69], v[6:9], v[22:25], v[126:129]
	v_mfma_f32_16x16x32_bf16 v[122:125], v[14:17], v[30:33], v[66:69]
	v_mfma_f32_16x16x32_bf16 v[66:69], v[188:191], v[22:25], v[172:175]
	v_mfma_f32_16x16x32_bf16 v[114:117], v[192:195], v[30:33], v[66:69]
	v_mfma_f32_16x16x32_bf16 v[66:69], v[6:9], v[38:41], v[118:121]
	v_mfma_f32_16x16x32_bf16 v[106:109], v[14:17], v[46:49], v[66:69]
	v_mfma_f32_16x16x32_bf16 v[66:69], v[188:191], v[38:41], v[200:203]
	v_mfma_f32_16x16x32_bf16 v[98:101], v[192:195], v[46:49], v[66:69]
	v_mfma_f32_16x16x32_bf16 v[66:69], v[6:9], v[54:57], v[110:113]
	v_mfma_f32_16x16x32_bf16 v[90:93], v[14:17], v[196:199], v[66:69]
	v_mfma_f32_16x16x32_bf16 v[66:69], v[188:191], v[54:57], v[204:207]
	v_mfma_f32_16x16x32_bf16 v[82:85], v[192:195], v[196:199], v[66:69]
	v_mfma_f32_16x16x32_bf16 v[66:69], v[6:9], v[220:223], v[102:105]
	v_mfma_f32_16x16x32_bf16 v[74:77], v[14:17], v[224:227], v[66:69]
	v_mfma_f32_16x16x32_bf16 v[66:69], v[188:191], v[220:223], v[208:211]
	v_mfma_f32_16x16x32_bf16 v[66:69], v[192:195], v[224:227], v[66:69]
	s_barrier
	ds_read_b128 v[172:175], v137 offset:49152
	ds_read_b128 v[200:203], v137 offset:50176
	ds_read_b128 v[204:207], v137 offset:51200
	ds_read_b128 v[208:211], v137 offset:52224
	s_waitcnt vmcnt(0)
	s_barrier
	s_waitcnt lgkmcnt(0)
	s_waitcnt lgkmcnt(0)
	v_mfma_f32_16x16x32_bf16 v[94:97], v[172:175], v[22:25], v[94:97]
	v_mfma_f32_16x16x32_bf16 v[22:25], v[204:207], v[22:25], v[164:167]
	v_mfma_f32_16x16x32_bf16 v[118:121], v[208:211], v[30:33], v[22:25]
	v_mfma_f32_16x16x32_bf16 v[22:25], v[172:175], v[38:41], v[86:89]
	v_mfma_f32_16x16x32_bf16 v[110:113], v[200:203], v[46:49], v[22:25]
	v_mfma_f32_16x16x32_bf16 v[22:25], v[204:207], v[38:41], v[168:171]
	v_mfma_f32_16x16x32_bf16 v[102:105], v[208:211], v[46:49], v[22:25]
	v_mfma_f32_16x16x32_bf16 v[22:25], v[172:175], v[54:57], v[78:81]
	v_mfma_f32_16x16x32_bf16 v[126:129], v[200:203], v[30:33], v[94:97]
	v_mfma_f32_16x16x32_bf16 v[94:97], v[200:203], v[196:199], v[22:25]
	v_mfma_f32_16x16x32_bf16 v[22:25], v[204:207], v[54:57], v[176:179]
	v_mfma_f32_16x16x32_bf16 v[86:89], v[208:211], v[196:199], v[22:25]
	v_mfma_f32_16x16x32_bf16 v[22:25], v[172:175], v[220:223], v[70:73]
	v_mfma_f32_16x16x32_bf16 v[78:81], v[200:203], v[224:227], v[22:25]
	v_mfma_f32_16x16x32_bf16 v[22:25], v[204:207], v[220:223], v[180:183]
	v_mfma_f32_16x16x32_bf16 v[70:73], v[208:211], v[224:227], v[22:25]
	s_barrier
	ds_read_b128 v[164:167], v136 offset:49152
	ds_read_b128 v[168:171], v136 offset:50176
	ds_read_b128 v[176:179], v136 offset:51200
	ds_read_b128 v[180:183], v136 offset:52224
	ds_read_b128 v[196:199], v136 offset:53248
	ds_read_b128 v[220:223], v136 offset:54272
	ds_read_b128 v[224:227], v136 offset:55296
	ds_read_b128 v[228:231], v136 offset:56320
	s_barrier
	s_waitcnt lgkmcnt(0)
	s_waitcnt lgkmcnt(0)
	v_mfma_f32_16x16x32_bf16 v[22:25], v[6:9], v[164:167], v[62:65]
	v_mfma_f32_16x16x32_bf16 v[62:65], v[14:17], v[168:171], v[22:25]
	v_mfma_f32_16x16x32_bf16 v[22:25], v[188:191], v[164:167], v[58:61]
	v_mfma_f32_16x16x32_bf16 v[54:57], v[192:195], v[168:171], v[22:25]
	v_mfma_f32_16x16x32_bf16 v[22:25], v[6:9], v[176:179], v[212:215]
	v_mfma_f32_16x16x32_bf16 v[46:49], v[14:17], v[180:183], v[22:25]
	v_mfma_f32_16x16x32_bf16 v[22:25], v[188:191], v[176:179], v[50:53]
	v_mfma_f32_16x16x32_bf16 v[38:41], v[192:195], v[180:183], v[22:25]
	v_mfma_f32_16x16x32_bf16 v[22:25], v[6:9], v[196:199], v[216:219]
	v_mfma_f32_16x16x32_bf16 v[6:9], v[6:9], v[224:227], v[138:141]
	v_mfma_f32_16x16x32_bf16 v[30:33], v[14:17], v[220:223], v[22:25]
	v_mfma_f32_16x16x32_bf16 v[22:25], v[188:191], v[196:199], v[42:45]
	v_mfma_f32_16x16x32_bf16 v[14:17], v[14:17], v[228:231], v[6:9]
	v_mfma_f32_16x16x32_bf16 v[6:9], v[188:191], v[224:227], v[34:37]
	v_mfma_f32_16x16x32_bf16 v[22:25], v[192:195], v[220:223], v[22:25]
	v_mfma_f32_16x16x32_bf16 v[6:9], v[192:195], v[228:231], v[6:9]
	v_mfma_f32_16x16x32_bf16 v[34:37], v[172:175], v[164:167], v[142:145]
	v_mfma_f32_16x16x32_bf16 v[26:29], v[204:207], v[164:167], v[26:29]
	v_mfma_f32_16x16x32_bf16 v[18:21], v[204:207], v[176:179], v[18:21]
	v_mfma_f32_16x16x32_bf16 v[58:61], v[200:203], v[168:171], v[34:37]
	v_mfma_f32_16x16x32_bf16 v[50:53], v[208:211], v[168:171], v[26:29]
	v_mfma_f32_16x16x32_bf16 v[26:29], v[172:175], v[176:179], v[146:149]
	v_mfma_f32_16x16x32_bf16 v[34:37], v[208:211], v[180:183], v[18:21]
	v_mfma_f32_16x16x32_bf16 v[18:21], v[172:175], v[196:199], v[152:155]
	v_mfma_f32_16x16x32_bf16 v[10:13], v[204:207], v[196:199], v[10:13]
	v_mfma_f32_16x16x32_bf16 v[42:45], v[200:203], v[180:183], v[26:29]
	v_mfma_f32_16x16x32_bf16 v[26:29], v[200:203], v[220:223], v[18:21]
	v_mfma_f32_16x16x32_bf16 v[18:21], v[208:211], v[220:223], v[10:13]
	v_mfma_f32_16x16x32_bf16 v[10:13], v[172:175], v[224:227], v[184:187]
	v_mfma_f32_16x16x32_bf16 v[2:5], v[204:207], v[224:227], v[2:5]
	v_mfma_f32_16x16x32_bf16 v[10:13], v[200:203], v[228:231], v[10:13]
	v_mfma_f32_16x16x32_bf16 v[2:5], v[208:211], v[228:231], v[2:5]
	v_cmp_gt_u32_e32 vcc, s97, v135
	s_barrier
	s_and_saveexec_b64 s[18:19], vcc
	s_cbranch_execz .LBB0_364
	s_barrier
	s_branch .LBB0_364

; #define WAIT_V(n) asm volatile("s_waitcnt vmcnt(%0)" ::"n"(n) : "memory")
; #define WAIT_L(n) asm volatile("s_waitcnt lgkmcnt(%0)" ::"n"(n) : "memory")
; #define SBAR() __builtin_amdgcn_sched_barrier(0)
; #define LDA8(dst, b, h) _Pragma("unroll") for (int m = 0; m < 4; ++m) _Pragma("unroll") for (int k = 0; k < 2; ++k) \
;     dst[m][k] = *(const bf16x8*)(abase + SAo(b, h) + m * 2048 + k * 1024)
; #define LDB8(dst, b, h) _Pragma("unroll") for (int n = 0; n < 2; ++n) _Pragma("unroll") for (int k = 0; k < 2; ++k) \
;     dst[n][k] = *(const bf16x8*)(bbase + SAo(b, h) + n * 2048 + k * 1024)
; #define BAR8 __builtin_amdgcn_s_barrier()
; __device__ __forceinline__ void gemm_main8(const u16* __restrict__ Ab, int lda, const u16* __restrict__ Bb, int ldb, int K,
;                                            char* shm, f32x4 (&acc)[2][2][4][2]) {
;     ...
;   WAIT_V(4); BAR8;
;   STG_B(1, 0, 1); STG_A(1, 0, 1); STG_B(1, 1, 1);
;   WAIT_V(6); BAR8;
;   for (int t = 0; t < nt - 2; t += 2) {
;     LDB8(B0, 0, 0); SBAR(); LDA8(At, 0, 0); STG_A(1, 1, t + 1);
;     WAIT_L(8); BAR8; WAIT_L(0); MMA8(0, 0, At, B0); BAR8; SBAR();
.LBB0_415:
	s_or_b64 exec, exec, s[10:11]
	v_and_b32_e32 v0, 15, v130
	v_lshlrev_b32_e32 v18, 2, v130
	v_and_b32_e32 v16, 48, v130
	v_lshlrev_b32_e32 v0, 6, v0
	v_and_b32_e32 v18, 32, v18
	v_or_b32_e32 v17, v0, v16
	v_bitop3_b32 v0, v0, v18, v16 bitop3:0x36
	v_lshlrev_b32_e32 v14, 12, v14
	v_and_or_b32 v131, v14, s7, v0
	v_add_u32_e32 v0, 0x18000, v8
	v_lshlrev_b32_e32 v16, 13, v15
	v_readfirstlane_b32 s72, v0
	v_add_u32_e32 v0, 0x1a000, v8
	v_lshl_add_u64 v[14:15], v[4:5], 0, s[46:47]
	s_mov_b32 m0, s72
	s_mov_b64 s[10:11], 0x8080
	v_readfirstlane_b32 s25, v0
	v_add_u32_e32 v0, 0x8000, v8
	s_waitcnt vmcnt(4)
	s_barrier
	global_load_lds_dwordx4 v[14:15], off
	v_lshl_add_u64 v[14:15], v[4:5], 0, s[10:11]
	s_mov_b32 m0, s25
	v_readfirstlane_b32 s13, v0
	v_add_u32_e32 v0, 0xa000, v8
	global_load_lds_dwordx4 v[14:15], off
	v_lshl_add_u64 v[14:15], v[2:3], 0, s[46:47]
	s_mov_b32 m0, s13
	s_mov_b64 s[74:75], 0x10080
	v_readfirstlane_b32 s11, v0
	v_add_u32_e32 v0, 0x1c000, v8
	global_load_lds_dwordx4 v[14:15], off
	v_lshl_add_u64 v[14:15], v[2:3], 0, s[74:75]
	s_mov_b32 m0, s11
	v_readfirstlane_b32 s10, v0
	v_add_u32_e32 v0, 0x1e000, v8
	global_load_lds_dwordx4 v[14:15], off
	v_lshl_add_u64 v[14:15], v[4:5], 0, s[74:75]
	s_mov_b32 m0, s10
	s_mov_b64 s[74:75], 0x18080
	v_readfirstlane_b32 s5, v0
	global_load_lds_dwordx4 v[14:15], off
	v_lshl_add_u64 v[14:15], v[4:5], 0, s[74:75]
	s_mov_b32 m0, s5
	v_or_b32_e32 v135, 0x10000, v131
	global_load_lds_dwordx4 v[14:15], off
	v_or_b32_e32 v148, 0x10400, v131
	v_or_b32_e32 v149, 0x10800, v131
	v_or_b32_e32 v164, 0x10c00, v131
	s_waitcnt vmcnt(6)
	s_barrier
	v_bitop3_b32 v0, v17, v16, v18 bitop3:0xde
	ds_read_b128 v[14:17], v135
	ds_read_b128 v[18:21], v148
	ds_read_b128 v[22:25], v149
	ds_read_b128 v[26:29], v164
	v_add_u32_e32 v64, 0xc000, v8
	s_mov_b64 s[74:75], 0x20080
	v_readfirstlane_b32 s36, v64
	v_add_u32_e32 v64, 0xe000, v8
	v_lshl_add_u64 v[62:63], v[2:3], 0, s[74:75]
	s_mov_b32 m0, s36
	s_mov_b64 s[74:75], 0x30080
	v_readfirstlane_b32 s15, v64
	ds_read_b128 v[30:33], v0
	ds_read_b128 v[34:37], v0 offset:1024
	ds_read_b128 v[38:41], v0 offset:2048
	ds_read_b128 v[42:45], v0 offset:3072
	ds_read_b128 v[46:49], v0 offset:4096
	ds_read_b128 v[50:53], v0 offset:5120
	ds_read_b128 v[54:57], v0 offset:6144
	ds_read_b128 v[58:61], v0 offset:7168
	global_load_lds_dwordx4 v[62:63], off
	v_lshl_add_u64 v[62:63], v[2:3], 0, s[74:75]
	s_mov_b32 m0, s15
	s_nop 0
	global_load_lds_dwordx4 v[62:63], off
	s_waitcnt lgkmcnt(8)
	s_barrier
	s_waitcnt lgkmcnt(0)
	s_waitcnt lgkmcnt(0)
	v_mfma_f32_16x16x32_bf16 v[62:65], v[14:17], v[30:33], 0
	v_mfma_f32_16x16x32_bf16 v[66:69], v[22:25], v[30:33], 0
	v_mfma_f32_16x16x32_bf16 v[70:73], v[14:17], v[38:41], 0
	v_mfma_f32_16x16x32_bf16 v[74:77], v[22:25], v[38:41], 0
	v_mfma_f32_16x16x32_bf16 v[78:81], v[14:17], v[46:49], 0
	v_mfma_f32_16x16x32_bf16 v[82:85], v[22:25], v[46:49], 0
	v_mfma_f32_16x16x32_bf16 v[86:89], v[14:17], v[54:57], 0
	v_mfma_f32_16x16x32_bf16 v[90:93], v[22:25], v[54:57], 0
	v_mfma_f32_16x16x32_bf16 v[62:65], v[18:21], v[34:37], v[62:65]
	v_mfma_f32_16x16x32_bf16 v[66:69], v[26:29], v[34:37], v[66:69]
	v_mfma_f32_16x16x32_bf16 v[70:73], v[18:21], v[42:45], v[70:73]
	v_mfma_f32_16x16x32_bf16 v[74:77], v[26:29], v[42:45], v[74:77]
	v_mfma_f32_16x16x32_bf16 v[78:81], v[18:21], v[50:53], v[78:81]
	v_mfma_f32_16x16x32_bf16 v[82:85], v[26:29], v[50:53], v[82:85]
	v_mfma_f32_16x16x32_bf16 v[86:89], v[18:21], v[58:61], v[86:89]
	v_mfma_f32_16x16x32_bf16 v[90:93], v[26:29], v[58:61], v[90:93]
	s_barrier
	v_readfirstlane_b32 s73, v12
	v_or_b32_e32 v165, 0x14000, v131
	v_or_b32_e32 v167, 0x14800, v131
	v_lshl_add_u64 v[110:111], v[4:5], 0, s[70:71]
	s_mov_b32 m0, s73
	s_mov_b64 s[74:75], 0x8100
	v_readfirstlane_b32 s73, v13
	v_or_b32_e32 v166, 0x14400, v131
	ds_read_b128 v[94:97], v165
	ds_read_b128 v[98:101], v166
	v_or_b32_e32 v224, 0x14c00, v131
	ds_read_b128 v[102:105], v167
	ds_read_b128 v[106:109], v224
	global_load_lds_dwordx4 v[110:111], off
	v_lshl_add_u64 v[110:111], v[4:5], 0, s[74:75]
	s_mov_b32 m0, s73
	s_nop 0
	global_load_lds_dwordx4 v[110:111], off
	s_barrier
	s_waitcnt lgkmcnt(0)
	s_waitcnt lgkmcnt(0)
	v_mfma_f32_16x16x32_bf16 v[110:113], v[94:97], v[30:33], 0
	v_mfma_f32_16x16x32_bf16 v[30:33], v[102:105], v[30:33], 0
	v_mfma_f32_16x16x32_bf16 v[110:113], v[98:101], v[34:37], v[110:113]
	v_mfma_f32_16x16x32_bf16 v[30:33], v[106:109], v[34:37], v[30:33]
	v_mfma_f32_16x16x32_bf16 v[34:37], v[94:97], v[38:41], 0
	v_mfma_f32_16x16x32_bf16 v[38:41], v[102:105], v[38:41], 0
	v_mfma_f32_16x16x32_bf16 v[34:37], v[98:101], v[42:45], v[34:37]
	v_mfma_f32_16x16x32_bf16 v[38:41], v[106:109], v[42:45], v[38:41]
	v_mfma_f32_16x16x32_bf16 v[42:45], v[94:97], v[46:49], 0
	v_mfma_f32_16x16x32_bf16 v[46:49], v[102:105], v[46:49], 0
	v_mfma_f32_16x16x32_bf16 v[42:45], v[98:101], v[50:53], v[42:45]
	v_mfma_f32_16x16x32_bf16 v[46:49], v[106:109], v[50:53], v[46:49]
	v_mfma_f32_16x16x32_bf16 v[50:53], v[94:97], v[54:57], 0
	v_mfma_f32_16x16x32_bf16 v[54:57], v[102:105], v[54:57], 0
	v_mfma_f32_16x16x32_bf16 v[50:53], v[98:101], v[58:61], v[50:53]
	v_mfma_f32_16x16x32_bf16 v[54:57], v[106:109], v[58:61], v[54:57]
	v_readfirstlane_b32 s73, v8
	v_lshl_add_u64 v[12:13], v[2:3], 0, s[70:71]
	s_mov_b32 m0, s73
	s_mov_b64 s[74:75], 0x10100
	v_readfirstlane_b32 s73, v11
	s_barrier
	ds_read_b128 v[58:61], v0 offset:16384
	ds_read_b128 v[114:117], v0 offset:17408
	ds_read_b128 v[118:121], v0 offset:18432
	ds_read_b128 v[122:125], v0 offset:19456
	ds_read_b128 v[126:129], v0 offset:20480
	ds_read_b128 v[136:139], v0 offset:21504
	ds_read_b128 v[140:143], v0 offset:22528
	ds_read_b128 v[144:147], v0 offset:23552
	global_load_lds_dwordx4 v[12:13], off
	v_lshl_add_u64 v[12:13], v[2:3], 0, s[74:75]
	s_mov_b32 m0, s73
	s_nop 0
	global_load_lds_dwordx4 v[12:13], off
	s_barrier
; #define WAIT_V(n) asm volatile("s_waitcnt vmcnt(%0)" ::"n"(n) : "memory")
; #define WAIT_L(n) asm volatile("s_waitcnt lgkmcnt(%0)" ::"n"(n) : "memory")
; #define SBAR() __builtin_amdgcn_sched_barrier(0)
; #define LDA8(dst, b, h) _Pragma("unroll") for (int m = 0; m < 4; ++m) _Pragma("unroll") for (int k = 0; k < 2; ++k) \
;     dst[m][k] = *(const bf16x8*)(abase + SAo(b, h) + m * 2048 + k * 1024)
; #define LDB8(dst, b, h) _Pragma("unroll") for (int n = 0; n < 2; ++n) _Pragma("unroll") for (int k = 0; k < 2; ++k) \
;     dst[n][k] = *(const bf16x8*)(bbase + SAo(b, h) + n * 2048 + k * 1024)
; #define BAR8 __builtin_amdgcn_s_barrier()
; __device__ __forceinline__ void gemm_main8(const u16* __restrict__ Ab, int lda, const u16* __restrict__ Bb, int ldb, int K,
;                                            char* shm, f32x4 (&acc)[2][2][4][2]) {
;     ...
;     LDB8(B1, 0, 1); STG_B(0, 0, t + 2);
;     BAR8; WAIT_L(0); MMA8(0, 1, At, B1); BAR8;
;     LDA8(At, 0, 1); STG_A(0, 0, t + 2);
;     BAR8; WAIT_L(0); MMA8(1, 0, At, B0); BAR8; SBAR();
;     STG_B(0, 1, t + 2);
;     WAIT_V(6); BAR8; MMA8(1, 1, At, B1); BAR8;
;     LDB8(B0, 1, 0); SBAR(); LDA8(At, 1, 0); STG_A(0, 1, t + 2);
;     WAIT_L(8); BAR8; WAIT_L(0); MMA8(0, 0, At, B0); BAR8; SBAR();
	s_waitcnt lgkmcnt(0)
	s_waitcnt lgkmcnt(0)
	v_mfma_f32_16x16x32_bf16 v[152:155], v[14:17], v[58:61], 0
	v_mfma_f32_16x16x32_bf16 v[172:175], v[14:17], v[118:121], 0
	v_mfma_f32_16x16x32_bf16 v[180:183], v[14:17], v[126:129], 0
	v_mfma_f32_16x16x32_bf16 v[12:15], v[14:17], v[140:143], 0
	v_mfma_f32_16x16x32_bf16 v[152:155], v[18:21], v[114:117], v[152:155]
	v_mfma_f32_16x16x32_bf16 v[172:175], v[18:21], v[122:125], v[172:175]
	v_mfma_f32_16x16x32_bf16 v[180:183], v[18:21], v[136:139], v[180:183]
	v_mfma_f32_16x16x32_bf16 v[12:15], v[18:21], v[144:147], v[12:15]
	v_mfma_f32_16x16x32_bf16 v[16:19], v[22:25], v[140:143], 0
	v_mfma_f32_16x16x32_bf16 v[168:171], v[22:25], v[58:61], 0
	v_mfma_f32_16x16x32_bf16 v[176:179], v[22:25], v[118:121], 0
	v_mfma_f32_16x16x32_bf16 v[184:187], v[22:25], v[126:129], 0
	v_mfma_f32_16x16x32_bf16 v[16:19], v[26:29], v[144:147], v[16:19]
	v_mfma_f32_16x16x32_bf16 v[168:171], v[26:29], v[114:117], v[168:171]
	v_mfma_f32_16x16x32_bf16 v[176:179], v[26:29], v[122:125], v[176:179]
	v_mfma_f32_16x16x32_bf16 v[184:187], v[26:29], v[136:139], v[184:187]
	s_barrier
	v_readfirstlane_b32 s73, v9
	v_lshl_add_u64 v[20:21], v[4:5], 0, s[74:75]
	s_mov_b32 m0, s73
	s_mov_b64 s[74:75], 0x18100
	v_readfirstlane_b32 s73, v10
	global_load_lds_dwordx4 v[20:21], off
	v_lshl_add_u64 v[8:9], v[4:5], 0, s[74:75]
	s_mov_b32 m0, s73
	s_nop 0
	global_load_lds_dwordx4 v[8:9], off
	s_waitcnt vmcnt(6)
	s_barrier
	v_mfma_f32_16x16x32_bf16 v[8:11], v[94:97], v[58:61], 0
	v_mfma_f32_16x16x32_bf16 v[20:23], v[102:105], v[58:61], 0
	v_mfma_f32_16x16x32_bf16 v[8:11], v[98:101], v[114:117], v[8:11]
	v_mfma_f32_16x16x32_bf16 v[20:23], v[106:109], v[114:117], v[20:23]
	v_mfma_f32_16x16x32_bf16 v[24:27], v[94:97], v[118:121], 0
	v_mfma_f32_16x16x32_bf16 v[114:117], v[94:97], v[126:129], 0
	v_mfma_f32_16x16x32_bf16 v[94:97], v[94:97], v[140:143], 0
	v_mfma_f32_16x16x32_bf16 v[24:27], v[98:101], v[122:125], v[24:27]
	v_mfma_f32_16x16x32_bf16 v[58:61], v[102:105], v[118:121], 0
	v_mfma_f32_16x16x32_bf16 v[114:117], v[98:101], v[136:139], v[114:117]
	v_mfma_f32_16x16x32_bf16 v[118:121], v[102:105], v[126:129], 0
	v_mfma_f32_16x16x32_bf16 v[94:97], v[98:101], v[144:147], v[94:97]
	v_mfma_f32_16x16x32_bf16 v[98:101], v[102:105], v[140:143], 0
	v_mfma_f32_16x16x32_bf16 v[58:61], v[106:109], v[122:125], v[58:61]
	v_mfma_f32_16x16x32_bf16 v[118:121], v[106:109], v[136:139], v[118:121]
	v_mfma_f32_16x16x32_bf16 v[98:101], v[106:109], v[144:147], v[98:101]
	v_or_b32_e32 v228, 0x18000, v131
	v_or_b32_e32 v230, 0x18800, v131
	s_barrier
	v_or_b32_e32 v229, 0x18400, v131
	ds_read_b128 v[102:105], v228
	ds_read_b128 v[106:109], v229
	v_or_b32_e32 v231, 0x18c00, v131
	ds_read_b128 v[122:125], v230
	ds_read_b128 v[126:129], v231
	s_mov_b64 s[74:75], 0x20100
	v_readfirstlane_b32 s73, v6
	v_lshl_add_u64 v[28:29], v[2:3], 0, s[74:75]
	s_mov_b32 m0, s73
	s_mov_b64 s[74:75], 0x30100
	v_readfirstlane_b32 s73, v7
	ds_read_b128 v[136:139], v0 offset:32768
	ds_read_b128 v[140:143], v0 offset:33792
	ds_read_b128 v[144:147], v0 offset:34816
	ds_read_b128 v[188:191], v0 offset:35840
	ds_read_b128 v[192:195], v0 offset:36864
	ds_read_b128 v[196:199], v0 offset:37888
	ds_read_b128 v[200:203], v0 offset:38912
	ds_read_b128 v[204:207], v0 offset:39936
	global_load_lds_dwordx4 v[28:29], off
	v_lshl_add_u64 v[28:29], v[2:3], 0, s[74:75]
	s_mov_b32 m0, s73
	s_nop 0
	global_load_lds_dwordx4 v[28:29], off
	s_waitcnt lgkmcnt(8)
	s_barrier
	s_waitcnt lgkmcnt(0)
	s_waitcnt lgkmcnt(0)
	v_mfma_f32_16x16x32_bf16 v[62:65], v[102:105], v[136:139], v[62:65]
	v_mfma_f32_16x16x32_bf16 v[66:69], v[122:125], v[136:139], v[66:69]
	v_mfma_f32_16x16x32_bf16 v[70:73], v[102:105], v[144:147], v[70:73]
	v_mfma_f32_16x16x32_bf16 v[74:77], v[122:125], v[144:147], v[74:77]
	v_mfma_f32_16x16x32_bf16 v[78:81], v[102:105], v[192:195], v[78:81]
	v_mfma_f32_16x16x32_bf16 v[82:85], v[122:125], v[192:195], v[82:85]
	v_mfma_f32_16x16x32_bf16 v[86:89], v[102:105], v[200:203], v[86:89]
	v_mfma_f32_16x16x32_bf16 v[90:93], v[122:125], v[200:203], v[90:93]
	v_mfma_f32_16x16x32_bf16 v[62:65], v[106:109], v[140:143], v[62:65]
	v_mfma_f32_16x16x32_bf16 v[66:69], v[126:129], v[140:143], v[66:69]
	v_mfma_f32_16x16x32_bf16 v[70:73], v[106:109], v[188:191], v[70:73]
	v_mfma_f32_16x16x32_bf16 v[74:77], v[126:129], v[188:191], v[74:77]
	v_mfma_f32_16x16x32_bf16 v[78:81], v[106:109], v[196:199], v[78:81]
	v_mfma_f32_16x16x32_bf16 v[82:85], v[126:129], v[196:199], v[82:85]
	v_mfma_f32_16x16x32_bf16 v[86:89], v[106:109], v[204:207], v[86:89]
	v_mfma_f32_16x16x32_bf16 v[90:93], v[126:129], v[204:207], v[90:93]
	s_barrier
	s_mov_b32 m0, s72
	v_or_b32_e32 v240, 0x1c000, v131
	v_or_b32_e32 v244, 0x1c800, v131
	v_lshl_add_u64 v[6:7], v[4:5], 0, s[8:9]
	s_mov_b64 s[72:73], 0x8180
	v_or_b32_e32 v241, 0x1c400, v131
	ds_read_b128 v[208:211], v240
	ds_read_b128 v[212:215], v241
	v_or_b32_e32 v131, 0x1cc00, v131
	ds_read_b128 v[216:219], v244
	ds_read_b128 v[220:223], v131
	global_load_lds_dwordx4 v[6:7], off
	v_lshl_add_u64 v[6:7], v[4:5], 0, s[72:73]
	s_mov_b32 m0, s25
	s_nop 0
	global_load_lds_dwordx4 v[6:7], off
	s_barrier
; #define WAIT_V(n) asm volatile("s_waitcnt vmcnt(%0)" ::"n"(n) : "memory")
; #define WAIT_L(n) asm volatile("s_waitcnt lgkmcnt(%0)" ::"n"(n) : "memory")
; #define SBAR() __builtin_amdgcn_sched_barrier(0)
; #define LDA8(dst, b, h) _Pragma("unroll") for (int m = 0; m < 4; ++m) _Pragma("unroll") for (int k = 0; k < 2; ++k) \
;     dst[m][k] = *(const bf16x8*)(abase + SAo(b, h) + m * 2048 + k * 1024)
; #define LDB8(dst, b, h) _Pragma("unroll") for (int n = 0; n < 2; ++n) _Pragma("unroll") for (int k = 0; k < 2; ++k) \
;     dst[n][k] = *(const bf16x8*)(bbase + SAo(b, h) + n * 2048 + k * 1024)
; #define BAR8 __builtin_amdgcn_s_barrier()
; __device__ __forceinline__ void gemm_main8(const u16* __restrict__ Ab, int lda, const u16* __restrict__ Bb, int ldb, int K,
;                                            char* shm, f32x4 (&acc)[2][2][4][2]) {
;     ...
;     LDB8(B1, 1, 1); STG_B(1, 0, t + 3);
;     BAR8; WAIT_L(0); MMA8(0, 1, At, B1); BAR8;
;     LDA8(At, 1, 1); STG_A(1, 0, t + 3);
;     BAR8; WAIT_L(0); MMA8(1, 0, At, B0); BAR8; SBAR();
;     STG_B(1, 1, t + 3);
;     WAIT_V(6); BAR8; MMA8(1, 1, At, B1); BAR8;
;   }
;   { LDB8(B0, 0, 0); LDA8(At, 0, 0); STG_A(1, 1, nt - 1);
;     BAR8; WAIT_L(0); MMA8(0, 0, At, B0); BAR8;
	s_waitcnt lgkmcnt(0)
	s_waitcnt lgkmcnt(0)
	v_mfma_f32_16x16x32_bf16 v[110:113], v[208:211], v[136:139], v[110:113]
	v_mfma_f32_16x16x32_bf16 v[28:31], v[216:219], v[136:139], v[30:33]
	v_mfma_f32_16x16x32_bf16 v[32:35], v[208:211], v[144:147], v[34:37]
	v_mfma_f32_16x16x32_bf16 v[36:39], v[216:219], v[144:147], v[38:41]
	v_mfma_f32_16x16x32_bf16 v[40:43], v[208:211], v[192:195], v[42:45]
	v_mfma_f32_16x16x32_bf16 v[44:47], v[216:219], v[192:195], v[46:49]
	v_mfma_f32_16x16x32_bf16 v[48:51], v[208:211], v[200:203], v[50:53]
	v_mfma_f32_16x16x32_bf16 v[52:55], v[216:219], v[200:203], v[54:57]
	v_mfma_f32_16x16x32_bf16 v[110:113], v[212:215], v[140:143], v[110:113]
	v_mfma_f32_16x16x32_bf16 v[28:31], v[220:223], v[140:143], v[28:31]
	v_mfma_f32_16x16x32_bf16 v[32:35], v[212:215], v[188:191], v[32:35]
	v_mfma_f32_16x16x32_bf16 v[36:39], v[220:223], v[188:191], v[36:39]
	v_mfma_f32_16x16x32_bf16 v[40:43], v[212:215], v[196:199], v[40:43]
	v_mfma_f32_16x16x32_bf16 v[44:47], v[220:223], v[196:199], v[44:47]
	v_mfma_f32_16x16x32_bf16 v[48:51], v[212:215], v[204:207], v[48:51]
	v_mfma_f32_16x16x32_bf16 v[52:55], v[220:223], v[204:207], v[52:55]
	s_mov_b32 m0, s13
	v_lshl_add_u64 v[6:7], v[2:3], 0, s[8:9]
	s_mov_b64 s[72:73], 0x10180
	s_barrier
	ds_read_b128 v[136:139], v0 offset:49152
	ds_read_b128 v[140:143], v0 offset:50176
	ds_read_b128 v[144:147], v0 offset:51200
	ds_read_b128 v[188:191], v0 offset:52224
	ds_read_b128 v[192:195], v0 offset:53248
	ds_read_b128 v[196:199], v0 offset:54272
	ds_read_b128 v[200:203], v0 offset:55296
	ds_read_b128 v[204:207], v0 offset:56320
	global_load_lds_dwordx4 v[6:7], off
	v_lshl_add_u64 v[6:7], v[2:3], 0, s[72:73]
	s_mov_b32 m0, s11
	s_nop 0
	global_load_lds_dwordx4 v[6:7], off
	s_barrier
	s_waitcnt lgkmcnt(0)
	s_waitcnt lgkmcnt(0)
	v_mfma_f32_16x16x32_bf16 v[12:15], v[102:105], v[200:203], v[12:15]
	v_mfma_f32_16x16x32_bf16 v[16:19], v[122:125], v[200:203], v[16:19]
	v_mfma_f32_16x16x32_bf16 v[152:155], v[102:105], v[136:139], v[152:155]
	v_mfma_f32_16x16x32_bf16 v[168:171], v[122:125], v[136:139], v[168:171]
	v_mfma_f32_16x16x32_bf16 v[172:175], v[102:105], v[144:147], v[172:175]
	v_mfma_f32_16x16x32_bf16 v[176:179], v[122:125], v[144:147], v[176:179]
	v_mfma_f32_16x16x32_bf16 v[180:183], v[102:105], v[192:195], v[180:183]
	v_mfma_f32_16x16x32_bf16 v[184:187], v[122:125], v[192:195], v[184:187]
	v_mfma_f32_16x16x32_bf16 v[12:15], v[106:109], v[204:207], v[12:15]
	v_mfma_f32_16x16x32_bf16 v[16:19], v[126:129], v[204:207], v[16:19]
	v_mfma_f32_16x16x32_bf16 v[152:155], v[106:109], v[140:143], v[152:155]
	v_mfma_f32_16x16x32_bf16 v[168:171], v[126:129], v[140:143], v[168:171]
	v_mfma_f32_16x16x32_bf16 v[172:175], v[106:109], v[188:191], v[172:175]
	v_mfma_f32_16x16x32_bf16 v[176:179], v[126:129], v[188:191], v[176:179]
	v_mfma_f32_16x16x32_bf16 v[180:183], v[106:109], v[196:199], v[180:183]
	v_mfma_f32_16x16x32_bf16 v[184:187], v[126:129], v[196:199], v[184:187]
	s_barrier
	s_mov_b32 m0, s10
	v_lshl_add_u64 v[6:7], v[4:5], 0, s[72:73]
	s_mov_b64 s[10:11], 0x18180
	global_load_lds_dwordx4 v[6:7], off
	v_lshl_add_u64 v[4:5], v[4:5], 0, s[10:11]
	s_mov_b32 m0, s5
	s_nop 0
	global_load_lds_dwordx4 v[4:5], off
	s_waitcnt vmcnt(6)
	s_barrier
	v_mfma_f32_16x16x32_bf16 v[4:7], v[208:211], v[136:139], v[8:11]
	v_mfma_f32_16x16x32_bf16 v[8:11], v[216:219], v[136:139], v[20:23]
	v_mfma_f32_16x16x32_bf16 v[20:23], v[208:211], v[144:147], v[24:27]
	v_mfma_f32_16x16x32_bf16 v[24:27], v[216:219], v[144:147], v[58:61]
	v_mfma_f32_16x16x32_bf16 v[56:59], v[208:211], v[192:195], v[114:117]
	v_mfma_f32_16x16x32_bf16 v[102:105], v[216:219], v[192:195], v[118:121]
	v_mfma_f32_16x16x32_bf16 v[94:97], v[208:211], v[200:203], v[94:97]
	v_mfma_f32_16x16x32_bf16 v[98:101], v[216:219], v[200:203], v[98:101]
	v_mfma_f32_16x16x32_bf16 v[4:7], v[212:215], v[140:143], v[4:7]
	v_mfma_f32_16x16x32_bf16 v[8:11], v[220:223], v[140:143], v[8:11]
	v_mfma_f32_16x16x32_bf16 v[20:23], v[212:215], v[188:191], v[20:23]
	v_mfma_f32_16x16x32_bf16 v[24:27], v[220:223], v[188:191], v[24:27]
	v_mfma_f32_16x16x32_bf16 v[56:59], v[212:215], v[196:199], v[56:59]
	v_mfma_f32_16x16x32_bf16 v[102:105], v[220:223], v[196:199], v[102:105]
	v_mfma_f32_16x16x32_bf16 v[94:97], v[212:215], v[204:207], v[94:97]
	v_mfma_f32_16x16x32_bf16 v[98:101], v[220:223], v[204:207], v[98:101]
	s_mov_b64 s[10:11], 0x20180
	s_mov_b32 m0, s36
	v_lshl_add_u64 v[60:61], v[2:3], 0, s[10:11]
	s_mov_b64 s[10:11], 0x30180
	s_barrier
	ds_read_b128 v[106:109], v149
	ds_read_b128 v[114:117], v164
	ds_read_b128 v[118:121], v135
	ds_read_b128 v[122:125], v0
	ds_read_b128 v[126:129], v0 offset:1024
	ds_read_b128 v[136:139], v0 offset:2048
	ds_read_b128 v[140:143], v0 offset:3072
	ds_read_b128 v[144:147], v0 offset:4096
	ds_read_b128 v[188:191], v0 offset:5120
	ds_read_b128 v[192:195], v0 offset:6144
	ds_read_b128 v[196:199], v148
	ds_read_b128 v[200:203], v0 offset:7168
	global_load_lds_dwordx4 v[60:61], off
	v_lshl_add_u64 v[2:3], v[2:3], 0, s[10:11]
	s_mov_b32 m0, s15
	s_nop 0
	global_load_lds_dwordx4 v[2:3], off
	s_barrier
; #define WAIT_V(n) asm volatile("s_waitcnt vmcnt(%0)" ::"n"(n) : "memory")
; #define WAIT_L(n) asm volatile("s_waitcnt lgkmcnt(%0)" ::"n"(n) : "memory")
; #define LDA8(dst, b, h) _Pragma("unroll") for (int m = 0; m < 4; ++m) _Pragma("unroll") for (int k = 0; k < 2; ++k) \
;     dst[m][k] = *(const bf16x8*)(abase + SAo(b, h) + m * 2048 + k * 1024)
; #define LDB8(dst, b, h) _Pragma("unroll") for (int n = 0; n < 2; ++n) _Pragma("unroll") for (int k = 0; k < 2; ++k) \
;     dst[n][k] = *(const bf16x8*)(bbase + SAo(b, h) + n * 2048 + k * 1024)
; #define BAR8 __builtin_amdgcn_s_barrier()
; __device__ __forceinline__ void gemm_main8(const u16* __restrict__ Ab, int lda, const u16* __restrict__ Bb, int ldb, int K,
;                                            char* shm, f32x4 (&acc)[2][2][4][2]) {
;     ...
;   { LDB8(B0, 0, 0); LDA8(At, 0, 0); STG_A(1, 1, nt - 1);
;     BAR8; WAIT_L(0); MMA8(0, 0, At, B0); BAR8;
;     LDB8(B1, 0, 1); BAR8; WAIT_L(0); MMA8(0, 1, At, B1); BAR8;
;     LDA8(At, 0, 1); WAIT_V(4); BAR8; WAIT_L(0); MMA8(1, 0, At, B0); MMA8(1, 1, At, B1); BAR8; }
;   { LDB8(B0, 1, 0); LDA8(At, 1, 0); WAIT_V(2); BAR8; WAIT_L(0); MMA8(0, 0, At, B0); BAR8;
	s_waitcnt lgkmcnt(0)
	s_waitcnt lgkmcnt(0)
	v_mfma_f32_16x16x32_bf16 v[60:63], v[118:121], v[122:125], v[62:65]
	v_mfma_f32_16x16x32_bf16 v[64:67], v[106:109], v[122:125], v[66:69]
	v_mfma_f32_16x16x32_bf16 v[68:71], v[118:121], v[136:139], v[70:73]
	v_mfma_f32_16x16x32_bf16 v[72:75], v[106:109], v[136:139], v[74:77]
	v_mfma_f32_16x16x32_bf16 v[76:79], v[118:121], v[144:147], v[78:81]
	v_mfma_f32_16x16x32_bf16 v[80:83], v[106:109], v[144:147], v[82:85]
	v_mfma_f32_16x16x32_bf16 v[84:87], v[118:121], v[192:195], v[86:89]
	v_mfma_f32_16x16x32_bf16 v[60:63], v[196:199], v[126:129], v[60:63]
	v_mfma_f32_16x16x32_bf16 v[64:67], v[114:117], v[126:129], v[64:67]
	v_mfma_f32_16x16x32_bf16 v[68:71], v[196:199], v[140:143], v[68:71]
	v_mfma_f32_16x16x32_bf16 v[72:75], v[114:117], v[140:143], v[72:75]
	v_mfma_f32_16x16x32_bf16 v[76:79], v[196:199], v[188:191], v[76:79]
	v_mfma_f32_16x16x32_bf16 v[80:83], v[114:117], v[188:191], v[80:83]
	v_mfma_f32_16x16x32_bf16 v[86:89], v[196:199], v[200:203], v[84:87]
	v_mfma_f32_16x16x32_bf16 v[90:93], v[106:109], v[192:195], v[90:93]
	v_mfma_f32_16x16x32_bf16 v[204:207], v[114:117], v[200:203], v[90:93]
	s_barrier
	s_nop 4
	ds_read_b128 v[90:93], v165
	ds_read_b128 v[208:211], v166
	ds_read_b128 v[212:215], v167
	ds_read_b128 v[216:219], v224
	s_barrier
	s_waitcnt lgkmcnt(0)
	s_waitcnt lgkmcnt(0)
	v_mfma_f32_16x16x32_bf16 v[110:113], v[90:93], v[122:125], v[110:113]
	v_mfma_f32_16x16x32_bf16 v[28:31], v[212:215], v[122:125], v[28:31]
	v_mfma_f32_16x16x32_bf16 v[32:35], v[90:93], v[136:139], v[32:35]
	v_mfma_f32_16x16x32_bf16 v[36:39], v[212:215], v[136:139], v[36:39]
	v_mfma_f32_16x16x32_bf16 v[40:43], v[90:93], v[144:147], v[40:43]
	v_mfma_f32_16x16x32_bf16 v[44:47], v[212:215], v[144:147], v[44:47]
	v_mfma_f32_16x16x32_bf16 v[48:51], v[90:93], v[192:195], v[48:51]
	v_mfma_f32_16x16x32_bf16 v[52:55], v[212:215], v[192:195], v[52:55]
	v_mfma_f32_16x16x32_bf16 v[110:113], v[208:211], v[126:129], v[110:113]
	v_mfma_f32_16x16x32_bf16 v[28:31], v[216:219], v[126:129], v[28:31]
	v_mfma_f32_16x16x32_bf16 v[32:35], v[208:211], v[140:143], v[32:35]
	v_mfma_f32_16x16x32_bf16 v[36:39], v[216:219], v[140:143], v[36:39]
	v_mfma_f32_16x16x32_bf16 v[40:43], v[208:211], v[188:191], v[40:43]
	v_mfma_f32_16x16x32_bf16 v[44:47], v[216:219], v[188:191], v[44:47]
	v_mfma_f32_16x16x32_bf16 v[48:51], v[208:211], v[200:203], v[48:51]
	v_mfma_f32_16x16x32_bf16 v[52:55], v[216:219], v[200:203], v[52:55]
	s_barrier
	ds_read_b128 v[122:125], v0 offset:16384
	ds_read_b128 v[126:129], v0 offset:17408
	ds_read_b128 v[136:139], v0 offset:18432
	ds_read_b128 v[140:143], v0 offset:19456
	ds_read_b128 v[144:147], v0 offset:20480
	ds_read_b128 v[188:191], v0 offset:21504
	ds_read_b128 v[192:195], v0 offset:22528
	ds_read_b128 v[200:203], v0 offset:23552
	s_waitcnt vmcnt(4)
	s_barrier
	s_waitcnt lgkmcnt(0)
	s_waitcnt lgkmcnt(0)
	v_mfma_f32_16x16x32_bf16 v[12:15], v[118:121], v[192:195], v[12:15]
	v_mfma_f32_16x16x32_bf16 v[152:155], v[118:121], v[122:125], v[152:155]
	v_mfma_f32_16x16x32_bf16 v[168:171], v[106:109], v[122:125], v[168:171]
	v_mfma_f32_16x16x32_bf16 v[172:175], v[118:121], v[136:139], v[172:175]
	v_mfma_f32_16x16x32_bf16 v[176:179], v[106:109], v[136:139], v[176:179]
	v_mfma_f32_16x16x32_bf16 v[180:183], v[118:121], v[144:147], v[180:183]
	v_mfma_f32_16x16x32_bf16 v[184:187], v[106:109], v[144:147], v[184:187]
	v_mfma_f32_16x16x32_bf16 v[12:15], v[196:199], v[200:203], v[12:15]
	v_mfma_f32_16x16x32_bf16 v[16:19], v[106:109], v[192:195], v[16:19]
	v_mfma_f32_16x16x32_bf16 v[152:155], v[196:199], v[126:129], v[152:155]
	v_mfma_f32_16x16x32_bf16 v[168:171], v[114:117], v[126:129], v[168:171]
	v_mfma_f32_16x16x32_bf16 v[172:175], v[196:199], v[140:143], v[172:175]
	v_mfma_f32_16x16x32_bf16 v[176:179], v[114:117], v[140:143], v[176:179]
	v_mfma_f32_16x16x32_bf16 v[180:183], v[196:199], v[188:191], v[180:183]
	v_mfma_f32_16x16x32_bf16 v[184:187], v[114:117], v[188:191], v[184:187]
	v_mfma_f32_16x16x32_bf16 v[196:199], v[114:117], v[200:203], v[16:19]
	v_mfma_f32_16x16x32_bf16 v[2:5], v[90:93], v[122:125], v[4:7]
	v_mfma_f32_16x16x32_bf16 v[220:223], v[208:211], v[126:129], v[2:5]
	v_mfma_f32_16x16x32_bf16 v[2:5], v[212:215], v[122:125], v[8:11]
	v_mfma_f32_16x16x32_bf16 v[6:9], v[216:219], v[126:129], v[2:5]
	v_mfma_f32_16x16x32_bf16 v[2:5], v[90:93], v[136:139], v[20:23]
	v_mfma_f32_16x16x32_bf16 v[224:227], v[208:211], v[140:143], v[2:5]
	v_mfma_f32_16x16x32_bf16 v[2:5], v[212:215], v[136:139], v[24:27]
	v_mfma_f32_16x16x32_bf16 v[22:25], v[216:219], v[140:143], v[2:5]
	v_mfma_f32_16x16x32_bf16 v[2:5], v[90:93], v[144:147], v[56:59]
	v_mfma_f32_16x16x32_bf16 v[136:139], v[208:211], v[188:191], v[2:5]
	v_mfma_f32_16x16x32_bf16 v[2:5], v[212:215], v[144:147], v[102:105]
	v_mfma_f32_16x16x32_bf16 v[140:143], v[216:219], v[188:191], v[2:5]
	v_mfma_f32_16x16x32_bf16 v[2:5], v[90:93], v[192:195], v[94:97]
	v_mfma_f32_16x16x32_bf16 v[144:147], v[208:211], v[200:203], v[2:5]
	v_mfma_f32_16x16x32_bf16 v[2:5], v[212:215], v[192:195], v[98:101]
	v_mfma_f32_16x16x32_bf16 v[188:191], v[216:219], v[200:203], v[2:5]
	s_barrier
	s_nop 4
	ds_read_b128 v[2:5], v228
	ds_read_b128 v[192:195], v229
	ds_read_b128 v[200:203], v230
	ds_read_b128 v[208:211], v231
	ds_read_b128 v[16:19], v0 offset:32768
	ds_read_b128 v[94:97], v0 offset:33792
	ds_read_b128 v[102:105], v0 offset:34816
	ds_read_b128 v[212:215], v0 offset:35840
	ds_read_b128 v[216:219], v0 offset:36864
	ds_read_b128 v[228:231], v0 offset:37888
	ds_read_b128 v[232:235], v0 offset:38912
	ds_read_b128 v[236:239], v0 offset:39936
	s_waitcnt vmcnt(2)
	s_barrier
; #define WAIT_V(n) asm volatile("s_waitcnt vmcnt(%0)" ::"n"(n) : "memory")
; #define WAIT_L(n) asm volatile("s_waitcnt lgkmcnt(%0)" ::"n"(n) : "memory")
; #define LDA8(dst, b, h) _Pragma("unroll") for (int m = 0; m < 4; ++m) _Pragma("unroll") for (int k = 0; k < 2; ++k) \
;     dst[m][k] = *(const bf16x8*)(abase + SAo(b, h) + m * 2048 + k * 1024)
; #define LDB8(dst, b, h) _Pragma("unroll") for (int n = 0; n < 2; ++n) _Pragma("unroll") for (int k = 0; k < 2; ++k) \
;     dst[n][k] = *(const bf16x8*)(bbase + SAo(b, h) + n * 2048 + k * 1024)
; #define BAR8 __builtin_amdgcn_s_barrier()
; __device__ __forceinline__ void gemm_main8(const u16* __restrict__ Ab, int lda, const u16* __restrict__ Bb, int ldb, int K,
;                                            char* shm, f32x4 (&acc)[2][2][4][2]) {
;     ...
;   { LDB8(B0, 1, 0); LDA8(At, 1, 0); WAIT_V(2); BAR8; WAIT_L(0); MMA8(0, 0, At, B0); BAR8;
;     LDB8(B1, 1, 1); WAIT_V(0); BAR8; WAIT_L(0); MMA8(0, 1, At, B1); BAR8;
;     LDA8(At, 1, 1); BAR8; WAIT_L(0); MMA8(1, 0, At, B0); MMA8(1, 1, At, B1); BAR8; }
;   if (wr == 0) BAR8;
	s_waitcnt lgkmcnt(0)
	s_waitcnt lgkmcnt(0)
	v_mfma_f32_16x16x32_bf16 v[56:59], v[2:5], v[16:19], v[60:63]
	v_mfma_f32_16x16x32_bf16 v[122:125], v[192:195], v[94:97], v[56:59]
	v_mfma_f32_16x16x32_bf16 v[56:59], v[200:203], v[16:19], v[64:67]
	v_mfma_f32_16x16x32_bf16 v[114:117], v[208:211], v[94:97], v[56:59]
	v_mfma_f32_16x16x32_bf16 v[56:59], v[2:5], v[102:105], v[68:71]
	v_mfma_f32_16x16x32_bf16 v[106:109], v[192:195], v[212:215], v[56:59]
	v_mfma_f32_16x16x32_bf16 v[56:59], v[200:203], v[102:105], v[72:75]
	v_mfma_f32_16x16x32_bf16 v[98:101], v[208:211], v[212:215], v[56:59]
	v_mfma_f32_16x16x32_bf16 v[56:59], v[2:5], v[216:219], v[76:79]
	v_mfma_f32_16x16x32_bf16 v[90:93], v[192:195], v[228:231], v[56:59]
	v_mfma_f32_16x16x32_bf16 v[56:59], v[200:203], v[216:219], v[80:83]
	v_mfma_f32_16x16x32_bf16 v[82:85], v[208:211], v[228:231], v[56:59]
	v_mfma_f32_16x16x32_bf16 v[56:59], v[2:5], v[232:235], v[86:89]
	v_mfma_f32_16x16x32_bf16 v[74:77], v[192:195], v[236:239], v[56:59]
	v_mfma_f32_16x16x32_bf16 v[56:59], v[200:203], v[232:235], v[204:207]
	v_mfma_f32_16x16x32_bf16 v[58:61], v[208:211], v[236:239], v[56:59]
	s_barrier
	ds_read_b128 v[204:207], v240
	ds_read_b128 v[240:243], v241
	ds_read_b128 v[244:247], v244
	ds_read_b128 v[248:251], v131
	s_waitcnt vmcnt(0)
	s_barrier
	s_waitcnt lgkmcnt(0)
	s_waitcnt lgkmcnt(0)
	v_mfma_f32_16x16x32_bf16 v[62:65], v[204:207], v[16:19], v[110:113]
	v_mfma_f32_16x16x32_bf16 v[16:19], v[244:247], v[16:19], v[28:31]
	v_mfma_f32_16x16x32_bf16 v[118:121], v[248:251], v[94:97], v[16:19]
	v_mfma_f32_16x16x32_bf16 v[16:19], v[204:207], v[102:105], v[32:35]
	v_mfma_f32_16x16x32_bf16 v[110:113], v[240:243], v[212:215], v[16:19]
	v_mfma_f32_16x16x32_bf16 v[16:19], v[244:247], v[102:105], v[36:39]
	v_mfma_f32_16x16x32_bf16 v[102:105], v[248:251], v[212:215], v[16:19]
	v_mfma_f32_16x16x32_bf16 v[16:19], v[204:207], v[216:219], v[40:43]
	v_mfma_f32_16x16x32_bf16 v[126:129], v[240:243], v[94:97], v[62:65]
	v_mfma_f32_16x16x32_bf16 v[94:97], v[240:243], v[228:231], v[16:19]
	v_mfma_f32_16x16x32_bf16 v[16:19], v[244:247], v[216:219], v[44:47]
	v_mfma_f32_16x16x32_bf16 v[86:89], v[248:251], v[228:231], v[16:19]
	v_mfma_f32_16x16x32_bf16 v[16:19], v[204:207], v[232:235], v[48:51]
	v_mfma_f32_16x16x32_bf16 v[78:81], v[240:243], v[236:239], v[16:19]
	v_mfma_f32_16x16x32_bf16 v[16:19], v[244:247], v[232:235], v[52:55]
	v_mfma_f32_16x16x32_bf16 v[66:69], v[248:251], v[236:239], v[16:19]
	s_barrier
	ds_read_b128 v[26:29], v0 offset:49152
	ds_read_b128 v[38:41], v0 offset:50176
	ds_read_b128 v[212:215], v0 offset:51200
	ds_read_b128 v[216:219], v0 offset:52224
	ds_read_b128 v[228:231], v0 offset:53248
	ds_read_b128 v[232:235], v0 offset:54272
	ds_read_b128 v[236:239], v0 offset:55296
	ds_read_b128 v[164:167], v0 offset:56320
	s_barrier
	s_waitcnt lgkmcnt(0)
	s_waitcnt lgkmcnt(0)
	v_mfma_f32_16x16x32_bf16 v[16:19], v[2:5], v[26:29], v[152:155]
	v_mfma_f32_16x16x32_bf16 v[70:73], v[192:195], v[38:41], v[16:19]
	v_mfma_f32_16x16x32_bf16 v[16:19], v[200:203], v[26:29], v[168:171]
	v_mfma_f32_16x16x32_bf16 v[50:53], v[208:211], v[38:41], v[16:19]
	v_mfma_f32_16x16x32_bf16 v[16:19], v[2:5], v[212:215], v[172:175]
	v_mfma_f32_16x16x32_bf16 v[46:49], v[192:195], v[216:219], v[16:19]
	v_mfma_f32_16x16x32_bf16 v[16:19], v[200:203], v[212:215], v[176:179]
	v_mfma_f32_16x16x32_bf16 v[34:37], v[208:211], v[216:219], v[16:19]
	v_mfma_f32_16x16x32_bf16 v[16:19], v[2:5], v[228:231], v[180:183]
	v_mfma_f32_16x16x32_bf16 v[30:33], v[192:195], v[232:235], v[16:19]
	v_mfma_f32_16x16x32_bf16 v[16:19], v[200:203], v[228:231], v[184:187]
	v_mfma_f32_16x16x32_bf16 v[2:5], v[2:5], v[236:239], v[12:15]
	v_mfma_f32_16x16x32_bf16 v[18:21], v[208:211], v[232:235], v[16:19]
	v_mfma_f32_16x16x32_bf16 v[14:17], v[192:195], v[164:167], v[2:5]
	v_mfma_f32_16x16x32_bf16 v[2:5], v[200:203], v[236:239], v[196:199]
	v_mfma_f32_16x16x32_bf16 v[2:5], v[208:211], v[164:167], v[2:5]
	v_mfma_f32_16x16x32_bf16 v[6:9], v[244:247], v[26:29], v[6:9]
	v_mfma_f32_16x16x32_bf16 v[54:57], v[248:251], v[38:41], v[6:9]
	v_mfma_f32_16x16x32_bf16 v[6:9], v[204:207], v[212:215], v[224:227]
	v_mfma_f32_16x16x32_bf16 v[10:13], v[204:207], v[26:29], v[220:223]
	v_mfma_f32_16x16x32_bf16 v[42:45], v[240:243], v[216:219], v[6:9]
	v_mfma_f32_16x16x32_bf16 v[6:9], v[244:247], v[212:215], v[22:25]
	v_mfma_f32_16x16x32_bf16 v[62:65], v[240:243], v[38:41], v[10:13]
	v_mfma_f32_16x16x32_bf16 v[38:41], v[248:251], v[216:219], v[6:9]
	v_mfma_f32_16x16x32_bf16 v[6:9], v[204:207], v[228:231], v[136:139]
	v_mfma_f32_16x16x32_bf16 v[26:29], v[240:243], v[232:235], v[6:9]
	v_mfma_f32_16x16x32_bf16 v[6:9], v[244:247], v[228:231], v[140:143]
	v_mfma_f32_16x16x32_bf16 v[22:25], v[248:251], v[232:235], v[6:9]
	v_mfma_f32_16x16x32_bf16 v[6:9], v[204:207], v[236:239], v[144:147]
	v_mfma_f32_16x16x32_bf16 v[10:13], v[240:243], v[164:167], v[6:9]
	v_mfma_f32_16x16x32_bf16 v[6:9], v[244:247], v[236:239], v[188:191]
	v_mfma_f32_16x16x32_bf16 v[6:9], v[248:251], v[164:167], v[6:9]
	v_cmp_gt_u32_e32 vcc, s97, v130
	s_barrier
	s_and_saveexec_b64 s[10:11], vcc
	s_cbranch_execz .LBB0_412
	s_barrier
	s_branch .LBB0_412

; #define WAIT_V(n) asm volatile("s_waitcnt vmcnt(%0)" ::"n"(n) : "memory")
; #define WAIT_L(n) asm volatile("s_waitcnt lgkmcnt(%0)" ::"n"(n) : "memory")
; #define SBAR() __builtin_amdgcn_sched_barrier(0)
; #define LDA8(dst, b, h) _Pragma("unroll") for (int m = 0; m < 4; ++m) _Pragma("unroll") for (int k = 0; k < 2; ++k) \
;     dst[m][k] = *(const bf16x8*)(abase + SAo(b, h) + m * 2048 + k * 1024)
; #define LDB8(dst, b, h) _Pragma("unroll") for (int n = 0; n < 2; ++n) _Pragma("unroll") for (int k = 0; k < 2; ++k) \
;     dst[n][k] = *(const bf16x8*)(bbase + SAo(b, h) + n * 2048 + k * 1024)
; #define BAR8 __builtin_amdgcn_s_barrier()
; __device__ __forceinline__ void gemm_main8(const u16* __restrict__ Ab, int lda, const u16* __restrict__ Bb, int ldb, int K,
;                                            char* shm, f32x4 (&acc)[2][2][4][2]) {
;     ...
;   for (int t = 0; t < nt - 2; t += 2) {
;     LDB8(B0, 0, 0); SBAR(); LDA8(At, 0, 0); STG_A(1, 1, t + 1);
;     WAIT_L(8); BAR8; WAIT_L(0); MMA8(0, 0, At, B0); BAR8; SBAR();
;     LDB8(B1, 0, 1); STG_B(0, 0, t + 2);
;     BAR8; WAIT_L(0); MMA8(0, 1, At, B1); BAR8;
;     LDA8(At, 0, 1); STG_A(0, 0, t + 2);
;     BAR8; WAIT_L(0); MMA8(1, 0, At, B0); BAR8; SBAR();
;     STG_B(0, 1, t + 2);
;     WAIT_V(6); BAR8; MMA8(1, 1, At, B1); BAR8;
.LBB0_510:
	ds_read_b128 v[152:155], v137
	ds_read_b128 v[164:167], v137 offset:1024
	ds_read_b128 v[176:179], v137 offset:2048
	ds_read_b128 v[180:183], v137 offset:3072
	v_add_u32_e32 v173, 0xc000, v138
	v_lshl_add_u64 v[168:169], s[24:25], 0, v[0:1]
	s_mov_b64 s[88:89], 0x17320080
	v_readfirstlane_b32 s5, v173
	v_lshl_add_u64 v[174:175], v[168:169], 0, s[88:89]
	s_mov_b32 m0, s5
	ds_read_b128 v[184:187], v136
	ds_read_b128 v[188:191], v136 offset:1024
	ds_read_b128 v[192:195], v136 offset:2048
	ds_read_b128 v[196:199], v136 offset:3072
	ds_read_b128 v[200:203], v136 offset:4096
	ds_read_b128 v[204:207], v136 offset:5120
	ds_read_b128 v[208:211], v136 offset:6144
	ds_read_b128 v[212:215], v136 offset:7168
	global_load_lds_dwordx4 v[174:175], off
	v_add_u32_e32 v174, 0xe000, v138
	s_mov_b64 s[88:89], 0x17330080
	v_readfirstlane_b32 s5, v174
	v_lshl_add_u64 v[216:217], v[168:169], 0, s[88:89]
	s_mov_b32 m0, s5
	s_nop 0
	global_load_lds_dwordx4 v[216:217], off
	s_waitcnt lgkmcnt(8)
	s_barrier
	s_waitcnt lgkmcnt(0)
	s_waitcnt lgkmcnt(0)
	v_mfma_f32_16x16x32_bf16 v[126:129], v[152:155], v[184:187], v[126:129]
	v_mfma_f32_16x16x32_bf16 v[122:125], v[176:179], v[184:187], v[122:125]
	v_mfma_f32_16x16x32_bf16 v[118:121], v[152:155], v[192:195], v[118:121]
	v_mfma_f32_16x16x32_bf16 v[114:117], v[176:179], v[192:195], v[114:117]
	v_mfma_f32_16x16x32_bf16 v[110:113], v[152:155], v[200:203], v[110:113]
	v_mfma_f32_16x16x32_bf16 v[106:109], v[176:179], v[200:203], v[106:109]
	v_mfma_f32_16x16x32_bf16 v[102:105], v[152:155], v[208:211], v[102:105]
	v_mfma_f32_16x16x32_bf16 v[98:101], v[176:179], v[208:211], v[98:101]
	v_mfma_f32_16x16x32_bf16 v[126:129], v[164:167], v[188:191], v[126:129]
	v_mfma_f32_16x16x32_bf16 v[122:125], v[180:183], v[188:191], v[122:125]
	v_mfma_f32_16x16x32_bf16 v[118:121], v[164:167], v[196:199], v[118:121]
	v_mfma_f32_16x16x32_bf16 v[114:117], v[180:183], v[196:199], v[114:117]
	v_mfma_f32_16x16x32_bf16 v[110:113], v[164:167], v[204:207], v[110:113]
	v_mfma_f32_16x16x32_bf16 v[106:109], v[180:183], v[204:207], v[106:109]
	v_mfma_f32_16x16x32_bf16 v[102:105], v[164:167], v[212:215], v[102:105]
	v_mfma_f32_16x16x32_bf16 v[98:101], v[180:183], v[212:215], v[98:101]
	s_barrier
	v_lshl_add_u64 v[232:233], s[20:21], 0, v[0:1]
	s_mov_b64 s[88:89], 0x11300100
	v_readfirstlane_b32 s5, v139
	v_lshl_add_u64 v[234:235], v[232:233], 0, s[88:89]
	s_mov_b32 m0, s5
	s_mov_b64 s[88:89], 0x11310100
	v_readfirstlane_b32 s5, v140
	ds_read_b128 v[216:219], v137 offset:16384
	ds_read_b128 v[220:223], v137 offset:17408
	ds_read_b128 v[224:227], v137 offset:18432
	ds_read_b128 v[228:231], v137 offset:19456
	global_load_lds_dwordx4 v[234:235], off
	v_lshl_add_u64 v[234:235], v[232:233], 0, s[88:89]
	s_mov_b32 m0, s5
	s_nop 0
	global_load_lds_dwordx4 v[234:235], off
	s_barrier
	s_waitcnt lgkmcnt(0)
	s_waitcnt lgkmcnt(0)
	v_mfma_f32_16x16x32_bf16 v[94:97], v[216:219], v[184:187], v[94:97]
	v_mfma_f32_16x16x32_bf16 v[90:93], v[224:227], v[184:187], v[90:93]
	v_mfma_f32_16x16x32_bf16 v[86:89], v[216:219], v[192:195], v[86:89]
	v_mfma_f32_16x16x32_bf16 v[82:85], v[224:227], v[192:195], v[82:85]
	v_mfma_f32_16x16x32_bf16 v[78:81], v[216:219], v[200:203], v[78:81]
	v_mfma_f32_16x16x32_bf16 v[74:77], v[224:227], v[200:203], v[74:77]
	v_mfma_f32_16x16x32_bf16 v[70:73], v[216:219], v[208:211], v[70:73]
	v_mfma_f32_16x16x32_bf16 v[66:69], v[224:227], v[208:211], v[66:69]
	v_mfma_f32_16x16x32_bf16 v[94:97], v[220:223], v[188:191], v[94:97]
	v_mfma_f32_16x16x32_bf16 v[90:93], v[228:231], v[188:191], v[90:93]
	v_mfma_f32_16x16x32_bf16 v[86:89], v[220:223], v[196:199], v[86:89]
	v_mfma_f32_16x16x32_bf16 v[82:85], v[228:231], v[196:199], v[82:85]
	v_mfma_f32_16x16x32_bf16 v[78:81], v[220:223], v[204:207], v[78:81]
	v_mfma_f32_16x16x32_bf16 v[74:77], v[228:231], v[204:207], v[74:77]
	v_mfma_f32_16x16x32_bf16 v[70:73], v[220:223], v[212:215], v[70:73]
	v_mfma_f32_16x16x32_bf16 v[66:69], v[228:231], v[212:215], v[66:69]
	v_readfirstlane_b32 s5, v138
	v_lshl_add_u64 v[234:235], v[168:169], 0, s[30:31]
	s_mov_b32 m0, s5
	s_mov_b64 s[88:89], 0x17310100
	v_readfirstlane_b32 s5, v141
	s_barrier
	ds_read_b128 v[184:187], v136 offset:16384
	ds_read_b128 v[188:191], v136 offset:17408
	ds_read_b128 v[192:195], v136 offset:18432
	ds_read_b128 v[196:199], v136 offset:19456
	ds_read_b128 v[200:203], v136 offset:20480
	ds_read_b128 v[204:207], v136 offset:21504
	ds_read_b128 v[208:211], v136 offset:22528
	ds_read_b128 v[212:215], v136 offset:23552
	global_load_lds_dwordx4 v[234:235], off
	v_lshl_add_u64 v[234:235], v[168:169], 0, s[88:89]
	s_mov_b32 m0, s5
	s_nop 0
	global_load_lds_dwordx4 v[234:235], off
	s_barrier
	s_waitcnt lgkmcnt(0)
	s_waitcnt lgkmcnt(0)
	v_mfma_f32_16x16x32_bf16 v[62:65], v[152:155], v[184:187], v[62:65]
	v_mfma_f32_16x16x32_bf16 v[58:61], v[176:179], v[184:187], v[58:61]
	v_mfma_f32_16x16x32_bf16 v[54:57], v[152:155], v[192:195], v[54:57]
	v_mfma_f32_16x16x32_bf16 v[50:53], v[176:179], v[192:195], v[50:53]
	v_mfma_f32_16x16x32_bf16 v[46:49], v[152:155], v[200:203], v[46:49]
	v_mfma_f32_16x16x32_bf16 v[42:45], v[176:179], v[200:203], v[42:45]
	v_mfma_f32_16x16x32_bf16 v[38:41], v[152:155], v[208:211], v[38:41]
	v_mfma_f32_16x16x32_bf16 v[34:37], v[176:179], v[208:211], v[34:37]
	v_mfma_f32_16x16x32_bf16 v[62:65], v[164:167], v[188:191], v[62:65]
	v_mfma_f32_16x16x32_bf16 v[58:61], v[180:183], v[188:191], v[58:61]
	v_mfma_f32_16x16x32_bf16 v[54:57], v[164:167], v[196:199], v[54:57]
	v_mfma_f32_16x16x32_bf16 v[50:53], v[180:183], v[196:199], v[50:53]
	v_mfma_f32_16x16x32_bf16 v[46:49], v[164:167], v[204:207], v[46:49]
	v_mfma_f32_16x16x32_bf16 v[42:45], v[180:183], v[204:207], v[42:45]
	v_mfma_f32_16x16x32_bf16 v[38:41], v[164:167], v[212:215], v[38:41]
	v_mfma_f32_16x16x32_bf16 v[34:37], v[180:183], v[212:215], v[34:37]
	s_barrier
; #define WAIT_V(n) asm volatile("s_waitcnt vmcnt(%0)" ::"n"(n) : "memory")
; #define WAIT_L(n) asm volatile("s_waitcnt lgkmcnt(%0)" ::"n"(n) : "memory")
; #define SBAR() __builtin_amdgcn_sched_barrier(0)
; #define LDA8(dst, b, h) _Pragma("unroll") for (int m = 0; m < 4; ++m) _Pragma("unroll") for (int k = 0; k < 2; ++k) \
;     dst[m][k] = *(const bf16x8*)(abase + SAo(b, h) + m * 2048 + k * 1024)
; #define LDB8(dst, b, h) _Pragma("unroll") for (int n = 0; n < 2; ++n) _Pragma("unroll") for (int k = 0; k < 2; ++k) \
;     dst[n][k] = *(const bf16x8*)(bbase + SAo(b, h) + n * 2048 + k * 1024)
; #define BAR8 __builtin_amdgcn_s_barrier()
; __device__ __forceinline__ void gemm_main8(const u16* __restrict__ Ab, int lda, const u16* __restrict__ Bb, int ldb, int K,
;                                            char* shm, f32x4 (&acc)[2][2][4][2]) {
;     ...
;     STG_B(0, 1, t + 2);
;     WAIT_V(6); BAR8; MMA8(1, 1, At, B1); BAR8;
;     LDB8(B0, 1, 0); SBAR(); LDA8(At, 1, 0); STG_A(0, 1, t + 2);
;     WAIT_L(8); BAR8; WAIT_L(0); MMA8(0, 0, At, B0); BAR8; SBAR();
;     LDB8(B1, 1, 1); STG_B(1, 0, t + 3);
;     BAR8; WAIT_L(0); MMA8(0, 1, At, B1); BAR8;
;     LDA8(At, 1, 1); STG_A(1, 0, t + 3);
;     BAR8; WAIT_L(0); MMA8(1, 0, At, B0); BAR8; SBAR();
	s_mov_b64 s[88:89], 0x11320100
	v_readfirstlane_b32 s5, v142
	v_lshl_add_u64 v[152:153], v[232:233], 0, s[88:89]
	s_mov_b32 m0, s5
	s_mov_b64 s[88:89], 0x11330100
	v_readfirstlane_b32 s5, v143
	global_load_lds_dwordx4 v[152:153], off
	v_lshl_add_u64 v[152:153], v[232:233], 0, s[88:89]
	s_mov_b32 m0, s5
	s_nop 0
	global_load_lds_dwordx4 v[152:153], off
	s_waitcnt vmcnt(6)
	s_barrier
	v_mfma_f32_16x16x32_bf16 v[30:33], v[216:219], v[184:187], v[30:33]
	v_mfma_f32_16x16x32_bf16 v[26:29], v[224:227], v[184:187], v[26:29]
	v_mfma_f32_16x16x32_bf16 v[22:25], v[216:219], v[192:195], v[22:25]
	v_mfma_f32_16x16x32_bf16 v[18:21], v[224:227], v[192:195], v[18:21]
	v_mfma_f32_16x16x32_bf16 v[14:17], v[216:219], v[200:203], v[14:17]
	v_mfma_f32_16x16x32_bf16 v[10:13], v[224:227], v[200:203], v[10:13]
	v_mfma_f32_16x16x32_bf16 v[6:9], v[216:219], v[208:211], v[6:9]
	v_mfma_f32_16x16x32_bf16 v[2:5], v[224:227], v[208:211], v[2:5]
	v_mfma_f32_16x16x32_bf16 v[30:33], v[220:223], v[188:191], v[30:33]
	v_mfma_f32_16x16x32_bf16 v[26:29], v[228:231], v[188:191], v[26:29]
	v_mfma_f32_16x16x32_bf16 v[22:25], v[220:223], v[196:199], v[22:25]
	v_mfma_f32_16x16x32_bf16 v[18:21], v[228:231], v[196:199], v[18:21]
	v_mfma_f32_16x16x32_bf16 v[14:17], v[220:223], v[204:207], v[14:17]
	v_mfma_f32_16x16x32_bf16 v[10:13], v[228:231], v[204:207], v[10:13]
	v_mfma_f32_16x16x32_bf16 v[6:9], v[220:223], v[212:215], v[6:9]
	v_mfma_f32_16x16x32_bf16 v[2:5], v[228:231], v[212:215], v[2:5]
	s_barrier
	ds_read_b128 v[152:155], v137 offset:32768
	ds_read_b128 v[164:167], v137 offset:33792
	ds_read_b128 v[176:179], v137 offset:34816
	ds_read_b128 v[180:183], v137 offset:35840
	s_mov_b64 s[88:89], 0x17320100
	v_readfirstlane_b32 s5, v144
	v_lshl_add_u64 v[216:217], v[168:169], 0, s[88:89]
	s_mov_b32 m0, s5
	s_mov_b64 s[88:89], 0x17330100
	v_readfirstlane_b32 s5, v145
	ds_read_b128 v[184:187], v136 offset:32768
	ds_read_b128 v[188:191], v136 offset:33792
	ds_read_b128 v[192:195], v136 offset:34816
	ds_read_b128 v[196:199], v136 offset:35840
	ds_read_b128 v[200:203], v136 offset:36864
	ds_read_b128 v[204:207], v136 offset:37888
	ds_read_b128 v[208:211], v136 offset:38912
	ds_read_b128 v[212:215], v136 offset:39936
	global_load_lds_dwordx4 v[216:217], off
	v_lshl_add_u64 v[216:217], v[168:169], 0, s[88:89]
	s_mov_b32 m0, s5
	s_nop 0
	global_load_lds_dwordx4 v[216:217], off
	s_waitcnt lgkmcnt(8)
	s_barrier
	s_waitcnt lgkmcnt(0)
	s_waitcnt lgkmcnt(0)
	v_mfma_f32_16x16x32_bf16 v[126:129], v[152:155], v[184:187], v[126:129]
	v_mfma_f32_16x16x32_bf16 v[122:125], v[176:179], v[184:187], v[122:125]
	v_mfma_f32_16x16x32_bf16 v[118:121], v[152:155], v[192:195], v[118:121]
	v_mfma_f32_16x16x32_bf16 v[114:117], v[176:179], v[192:195], v[114:117]
	v_mfma_f32_16x16x32_bf16 v[110:113], v[152:155], v[200:203], v[110:113]
	v_mfma_f32_16x16x32_bf16 v[106:109], v[176:179], v[200:203], v[106:109]
	v_mfma_f32_16x16x32_bf16 v[102:105], v[152:155], v[208:211], v[102:105]
	v_mfma_f32_16x16x32_bf16 v[98:101], v[176:179], v[208:211], v[98:101]
	v_mfma_f32_16x16x32_bf16 v[126:129], v[164:167], v[188:191], v[126:129]
	v_mfma_f32_16x16x32_bf16 v[122:125], v[180:183], v[188:191], v[122:125]
	v_mfma_f32_16x16x32_bf16 v[118:121], v[164:167], v[196:199], v[118:121]
	v_mfma_f32_16x16x32_bf16 v[114:117], v[180:183], v[196:199], v[114:117]
	v_mfma_f32_16x16x32_bf16 v[110:113], v[164:167], v[204:207], v[110:113]
	v_mfma_f32_16x16x32_bf16 v[106:109], v[180:183], v[204:207], v[106:109]
	v_mfma_f32_16x16x32_bf16 v[102:105], v[164:167], v[212:215], v[102:105]
	v_mfma_f32_16x16x32_bf16 v[98:101], v[180:183], v[212:215], v[98:101]
	s_barrier
	s_mov_b64 s[88:89], 0x11300180
	v_readfirstlane_b32 s5, v146
	v_lshl_add_u64 v[234:235], v[232:233], 0, s[88:89]
	s_mov_b32 m0, s5
	s_mov_b64 s[88:89], 0x11310180
	v_readfirstlane_b32 s5, v147
	ds_read_b128 v[216:219], v137 offset:49152
	ds_read_b128 v[220:223], v137 offset:50176
	ds_read_b128 v[224:227], v137 offset:51200
	ds_read_b128 v[228:231], v137 offset:52224
	global_load_lds_dwordx4 v[234:235], off
	v_lshl_add_u64 v[234:235], v[232:233], 0, s[88:89]
	s_mov_b32 m0, s5
	s_nop 0
	global_load_lds_dwordx4 v[234:235], off
	s_barrier
	s_waitcnt lgkmcnt(0)
	s_waitcnt lgkmcnt(0)
	v_mfma_f32_16x16x32_bf16 v[94:97], v[216:219], v[184:187], v[94:97]
	v_mfma_f32_16x16x32_bf16 v[90:93], v[224:227], v[184:187], v[90:93]
	v_mfma_f32_16x16x32_bf16 v[86:89], v[216:219], v[192:195], v[86:89]
	v_mfma_f32_16x16x32_bf16 v[82:85], v[224:227], v[192:195], v[82:85]
	v_mfma_f32_16x16x32_bf16 v[78:81], v[216:219], v[200:203], v[78:81]
	v_mfma_f32_16x16x32_bf16 v[74:77], v[224:227], v[200:203], v[74:77]
	v_mfma_f32_16x16x32_bf16 v[70:73], v[216:219], v[208:211], v[70:73]
	v_mfma_f32_16x16x32_bf16 v[66:69], v[224:227], v[208:211], v[66:69]
	v_mfma_f32_16x16x32_bf16 v[94:97], v[220:223], v[188:191], v[94:97]
	v_mfma_f32_16x16x32_bf16 v[90:93], v[228:231], v[188:191], v[90:93]
	v_mfma_f32_16x16x32_bf16 v[86:89], v[220:223], v[196:199], v[86:89]
	v_mfma_f32_16x16x32_bf16 v[82:85], v[228:231], v[196:199], v[82:85]
	v_mfma_f32_16x16x32_bf16 v[78:81], v[220:223], v[204:207], v[78:81]
	v_mfma_f32_16x16x32_bf16 v[74:77], v[228:231], v[204:207], v[74:77]
	v_mfma_f32_16x16x32_bf16 v[70:73], v[220:223], v[212:215], v[70:73]
	v_mfma_f32_16x16x32_bf16 v[66:69], v[228:231], v[212:215], v[66:69]
	v_readfirstlane_b32 s5, v148
	v_lshl_add_u64 v[234:235], v[168:169], 0, s[16:17]
	s_mov_b32 m0, s5
	s_mov_b64 s[88:89], 0x17310180
	v_readfirstlane_b32 s5, v149
	s_barrier
; #define WAIT_V(n) asm volatile("s_waitcnt vmcnt(%0)" ::"n"(n) : "memory")
; #define WAIT_L(n) asm volatile("s_waitcnt lgkmcnt(%0)" ::"n"(n) : "memory")
; #define SBAR() __builtin_amdgcn_sched_barrier(0)
; #define LDA8(dst, b, h) _Pragma("unroll") for (int m = 0; m < 4; ++m) _Pragma("unroll") for (int k = 0; k < 2; ++k) \
;     dst[m][k] = *(const bf16x8*)(abase + SAo(b, h) + m * 2048 + k * 1024)
; #define LDB8(dst, b, h) _Pragma("unroll") for (int n = 0; n < 2; ++n) _Pragma("unroll") for (int k = 0; k < 2; ++k) \
;     dst[n][k] = *(const bf16x8*)(bbase + SAo(b, h) + n * 2048 + k * 1024)
; #define BAR8 __builtin_amdgcn_s_barrier()
; __device__ __forceinline__ void gemm_main8(const u16* __restrict__ Ab, int lda, const u16* __restrict__ Bb, int ldb, int K,
;                                            char* shm, f32x4 (&acc)[2][2][4][2]) {
;     ...
;     LDB8(B1, 1, 1); STG_B(1, 0, t + 3);
;     BAR8; WAIT_L(0); MMA8(0, 1, At, B1); BAR8;
;     LDA8(At, 1, 1); STG_A(1, 0, t + 3);
;     BAR8; WAIT_L(0); MMA8(1, 0, At, B0); BAR8; SBAR();
;     STG_B(1, 1, t + 3);
;     WAIT_V(6); BAR8; MMA8(1, 1, At, B1); BAR8;
;   }
;   { LDB8(B0, 0, 0); LDA8(At, 0, 0); STG_A(1, 1, nt - 1);
;     BAR8; WAIT_L(0); MMA8(0, 0, At, B0); BAR8;
	ds_read_b128 v[184:187], v136 offset:49152
	ds_read_b128 v[188:191], v136 offset:50176
	ds_read_b128 v[192:195], v136 offset:51200
	ds_read_b128 v[196:199], v136 offset:52224
	ds_read_b128 v[200:203], v136 offset:53248
	ds_read_b128 v[204:207], v136 offset:54272
	ds_read_b128 v[208:211], v136 offset:55296
	ds_read_b128 v[212:215], v136 offset:56320
	global_load_lds_dwordx4 v[234:235], off
	v_lshl_add_u64 v[168:169], v[168:169], 0, s[88:89]
	s_mov_b32 m0, s5
	s_nop 0
	global_load_lds_dwordx4 v[168:169], off
	s_barrier
	s_waitcnt lgkmcnt(0)
	s_waitcnt lgkmcnt(0)
	v_mfma_f32_16x16x32_bf16 v[62:65], v[152:155], v[184:187], v[62:65]
	v_mfma_f32_16x16x32_bf16 v[58:61], v[176:179], v[184:187], v[58:61]
	v_mfma_f32_16x16x32_bf16 v[54:57], v[152:155], v[192:195], v[54:57]
	v_mfma_f32_16x16x32_bf16 v[50:53], v[176:179], v[192:195], v[50:53]
	v_mfma_f32_16x16x32_bf16 v[46:49], v[152:155], v[200:203], v[46:49]
	v_mfma_f32_16x16x32_bf16 v[42:45], v[176:179], v[200:203], v[42:45]
	v_mfma_f32_16x16x32_bf16 v[38:41], v[152:155], v[208:211], v[38:41]
	v_mfma_f32_16x16x32_bf16 v[34:37], v[176:179], v[208:211], v[34:37]
	v_mfma_f32_16x16x32_bf16 v[62:65], v[164:167], v[188:191], v[62:65]
	v_mfma_f32_16x16x32_bf16 v[58:61], v[180:183], v[188:191], v[58:61]
	v_mfma_f32_16x16x32_bf16 v[54:57], v[164:167], v[196:199], v[54:57]
	v_mfma_f32_16x16x32_bf16 v[50:53], v[180:183], v[196:199], v[50:53]
	v_mfma_f32_16x16x32_bf16 v[46:49], v[164:167], v[204:207], v[46:49]
	v_mfma_f32_16x16x32_bf16 v[42:45], v[180:183], v[204:207], v[42:45]
	v_mfma_f32_16x16x32_bf16 v[38:41], v[164:167], v[212:215], v[38:41]
	v_mfma_f32_16x16x32_bf16 v[34:37], v[180:183], v[212:215], v[34:37]
	s_barrier
	s_mov_b64 s[88:89], 0x11320180
	v_readfirstlane_b32 s5, v171
	v_lshl_add_u64 v[152:153], v[232:233], 0, s[88:89]
	s_mov_b32 m0, s5
	s_mov_b64 s[88:89], 0x11330180
	v_readfirstlane_b32 s5, v172
	global_load_lds_dwordx4 v[152:153], off
	v_lshl_add_u64 v[152:153], v[232:233], 0, s[88:89]
	s_mov_b32 m0, s5
	s_nop 0
	global_load_lds_dwordx4 v[152:153], off
	s_waitcnt vmcnt(6)
	s_barrier
	v_mfma_f32_16x16x32_bf16 v[30:33], v[216:219], v[184:187], v[30:33]
	v_mfma_f32_16x16x32_bf16 v[26:29], v[224:227], v[184:187], v[26:29]
	v_mfma_f32_16x16x32_bf16 v[22:25], v[216:219], v[192:195], v[22:25]
	v_mfma_f32_16x16x32_bf16 v[18:21], v[224:227], v[192:195], v[18:21]
	v_mfma_f32_16x16x32_bf16 v[14:17], v[216:219], v[200:203], v[14:17]
	v_mfma_f32_16x16x32_bf16 v[10:13], v[224:227], v[200:203], v[10:13]
	v_mfma_f32_16x16x32_bf16 v[6:9], v[216:219], v[208:211], v[6:9]
	v_mfma_f32_16x16x32_bf16 v[2:5], v[224:227], v[208:211], v[2:5]
	v_mfma_f32_16x16x32_bf16 v[30:33], v[220:223], v[188:191], v[30:33]
	v_mfma_f32_16x16x32_bf16 v[26:29], v[228:231], v[188:191], v[26:29]
	v_mfma_f32_16x16x32_bf16 v[22:25], v[220:223], v[196:199], v[22:25]
	v_mfma_f32_16x16x32_bf16 v[18:21], v[228:231], v[196:199], v[18:21]
	v_mfma_f32_16x16x32_bf16 v[14:17], v[220:223], v[204:207], v[14:17]
	v_mfma_f32_16x16x32_bf16 v[10:13], v[228:231], v[204:207], v[10:13]
	v_mfma_f32_16x16x32_bf16 v[6:9], v[220:223], v[212:215], v[6:9]
	v_mfma_f32_16x16x32_bf16 v[2:5], v[228:231], v[212:215], v[2:5]
	s_add_i32 s3, s3, 2
	s_add_u32 s20, s20, 0x100
	s_addc_u32 s21, s21, 0
	s_add_u32 s24, s24, 0x100
	s_addc_u32 s25, s25, 0
	s_cmp_lt_u32 s3, 4
	s_barrier
	s_cbranch_scc1 .LBB0_510
	s_mov_b64 s[20:21], 0x20380
	v_readfirstlane_b32 s3, v173
	v_lshl_add_u64 v[200:201], v[130:131], 0, s[20:21]
	s_mov_b32 m0, s3
	s_mov_b64 s[20:21], 0x30380
	v_readfirstlane_b32 s3, v174
	ds_read_b128 v[138:141], v137
	ds_read_b128 v[142:145], v137 offset:1024
	ds_read_b128 v[146:149], v137 offset:2048
	ds_read_b128 v[152:155], v137 offset:3072
	ds_read_b128 v[164:167], v136
	ds_read_b128 v[168:171], v136 offset:1024
	ds_read_b128 v[176:179], v136 offset:2048
	ds_read_b128 v[180:183], v136 offset:3072
	ds_read_b128 v[184:187], v136 offset:4096
	ds_read_b128 v[188:191], v136 offset:5120
	ds_read_b128 v[192:195], v136 offset:6144
	ds_read_b128 v[196:199], v136 offset:7168
	global_load_lds_dwordx4 v[200:201], off
	v_lshl_add_u64 v[130:131], v[130:131], 0, s[20:21]
	s_mov_b32 m0, s3
	s_nop 0
	global_load_lds_dwordx4 v[130:131], off
	s_barrier
	s_waitcnt lgkmcnt(0)
	s_waitcnt lgkmcnt(0)
	v_mfma_f32_16x16x32_bf16 v[126:129], v[138:141], v[164:167], v[126:129]
	v_mfma_f32_16x16x32_bf16 v[122:125], v[146:149], v[164:167], v[122:125]
	v_mfma_f32_16x16x32_bf16 v[118:121], v[138:141], v[176:179], v[118:121]
	v_mfma_f32_16x16x32_bf16 v[114:117], v[146:149], v[176:179], v[114:117]
	v_mfma_f32_16x16x32_bf16 v[102:105], v[138:141], v[192:195], v[102:105]
	v_mfma_f32_16x16x32_bf16 v[98:101], v[146:149], v[192:195], v[98:101]
	v_mfma_f32_16x16x32_bf16 v[126:129], v[142:145], v[168:171], v[126:129]
	v_mfma_f32_16x16x32_bf16 v[122:125], v[152:155], v[168:171], v[122:125]
	v_mfma_f32_16x16x32_bf16 v[118:121], v[142:145], v[180:183], v[118:121]
	v_mfma_f32_16x16x32_bf16 v[114:117], v[152:155], v[180:183], v[114:117]
	v_mfma_f32_16x16x32_bf16 v[110:113], v[138:141], v[184:187], v[110:113]
	v_mfma_f32_16x16x32_bf16 v[106:109], v[146:149], v[184:187], v[106:109]
	v_mfma_f32_16x16x32_bf16 v[102:105], v[142:145], v[196:199], v[102:105]
	v_mfma_f32_16x16x32_bf16 v[98:101], v[152:155], v[196:199], v[98:101]
	v_mfma_f32_16x16x32_bf16 v[172:175], v[142:145], v[188:191], v[110:113]
	v_mfma_f32_16x16x32_bf16 v[200:203], v[152:155], v[188:191], v[106:109]
	s_barrier
	s_nop 1
	ds_read_b128 v[106:109], v137 offset:16384
	ds_read_b128 v[110:113], v137 offset:17408
	ds_read_b128 v[204:207], v137 offset:18432
	ds_read_b128 v[208:211], v137 offset:19456
	s_barrier
; #define WAIT_V(n) asm volatile("s_waitcnt vmcnt(%0)" ::"n"(n) : "memory")
; #define WAIT_L(n) asm volatile("s_waitcnt lgkmcnt(%0)" ::"n"(n) : "memory")
; #define LDA8(dst, b, h) _Pragma("unroll") for (int m = 0; m < 4; ++m) _Pragma("unroll") for (int k = 0; k < 2; ++k) \
;     dst[m][k] = *(const bf16x8*)(abase + SAo(b, h) + m * 2048 + k * 1024)
; #define LDB8(dst, b, h) _Pragma("unroll") for (int n = 0; n < 2; ++n) _Pragma("unroll") for (int k = 0; k < 2; ++k) \
;     dst[n][k] = *(const bf16x8*)(bbase + SAo(b, h) + n * 2048 + k * 1024)
; #define BAR8 __builtin_amdgcn_s_barrier()
; __device__ __forceinline__ void gemm_main8(const u16* __restrict__ Ab, int lda, const u16* __restrict__ Bb, int ldb, int K,
;                                            char* shm, f32x4 (&acc)[2][2][4][2]) {
;     ...
;     LDB8(B1, 0, 1); BAR8; WAIT_L(0); MMA8(0, 1, At, B1); BAR8;
;     LDA8(At, 0, 1); WAIT_V(4); BAR8; WAIT_L(0); MMA8(1, 0, At, B0); MMA8(1, 1, At, B1); BAR8; }
;   { LDB8(B0, 1, 0); LDA8(At, 1, 0); WAIT_V(2); BAR8; WAIT_L(0); MMA8(0, 0, At, B0); BAR8;
	s_waitcnt lgkmcnt(0)
	s_waitcnt lgkmcnt(0)
	v_mfma_f32_16x16x32_bf16 v[86:89], v[106:109], v[176:179], v[86:89]
	v_mfma_f32_16x16x32_bf16 v[82:85], v[204:207], v[176:179], v[82:85]
	v_mfma_f32_16x16x32_bf16 v[70:73], v[106:109], v[192:195], v[70:73]
	v_mfma_f32_16x16x32_bf16 v[66:69], v[204:207], v[192:195], v[66:69]
	v_mfma_f32_16x16x32_bf16 v[94:97], v[106:109], v[164:167], v[94:97]
	v_mfma_f32_16x16x32_bf16 v[90:93], v[204:207], v[164:167], v[90:93]
	v_mfma_f32_16x16x32_bf16 v[86:89], v[110:113], v[180:183], v[86:89]
	v_mfma_f32_16x16x32_bf16 v[82:85], v[208:211], v[180:183], v[82:85]
	v_mfma_f32_16x16x32_bf16 v[78:81], v[106:109], v[184:187], v[78:81]
	v_mfma_f32_16x16x32_bf16 v[74:77], v[204:207], v[184:187], v[74:77]
	v_mfma_f32_16x16x32_bf16 v[70:73], v[110:113], v[196:199], v[70:73]
	v_mfma_f32_16x16x32_bf16 v[66:69], v[208:211], v[196:199], v[66:69]
	v_mfma_f32_16x16x32_bf16 v[212:215], v[110:113], v[168:171], v[94:97]
	v_mfma_f32_16x16x32_bf16 v[164:167], v[208:211], v[168:171], v[90:93]
	v_mfma_f32_16x16x32_bf16 v[168:171], v[110:113], v[188:191], v[78:81]
	v_mfma_f32_16x16x32_bf16 v[176:179], v[208:211], v[188:191], v[74:77]
	s_barrier
	s_nop 0
	ds_read_b128 v[74:77], v136 offset:16384
	ds_read_b128 v[78:81], v136 offset:17408
	ds_read_b128 v[90:93], v136 offset:18432
	ds_read_b128 v[94:97], v136 offset:19456
	ds_read_b128 v[180:183], v136 offset:20480
	ds_read_b128 v[184:187], v136 offset:21504
	ds_read_b128 v[188:191], v136 offset:22528
	ds_read_b128 v[192:195], v136 offset:23552
	s_waitcnt vmcnt(4)
	s_barrier
	s_waitcnt lgkmcnt(0)
	s_waitcnt lgkmcnt(0)
	v_mfma_f32_16x16x32_bf16 v[62:65], v[138:141], v[74:77], v[62:65]
	v_mfma_f32_16x16x32_bf16 v[58:61], v[146:149], v[74:77], v[58:61]
	v_mfma_f32_16x16x32_bf16 v[54:57], v[138:141], v[90:93], v[54:57]
	v_mfma_f32_16x16x32_bf16 v[50:53], v[146:149], v[90:93], v[50:53]
	v_mfma_f32_16x16x32_bf16 v[38:41], v[138:141], v[188:191], v[38:41]
	v_mfma_f32_16x16x32_bf16 v[34:37], v[146:149], v[188:191], v[34:37]
	v_mfma_f32_16x16x32_bf16 v[62:65], v[142:145], v[78:81], v[62:65]
	v_mfma_f32_16x16x32_bf16 v[58:61], v[152:155], v[78:81], v[58:61]
	v_mfma_f32_16x16x32_bf16 v[54:57], v[142:145], v[94:97], v[54:57]
	v_mfma_f32_16x16x32_bf16 v[50:53], v[152:155], v[94:97], v[50:53]
	v_mfma_f32_16x16x32_bf16 v[46:49], v[138:141], v[180:183], v[46:49]
	v_mfma_f32_16x16x32_bf16 v[42:45], v[146:149], v[180:183], v[42:45]
	v_mfma_f32_16x16x32_bf16 v[38:41], v[142:145], v[192:195], v[38:41]
	v_mfma_f32_16x16x32_bf16 v[34:37], v[152:155], v[192:195], v[34:37]
	v_mfma_f32_16x16x32_bf16 v[196:199], v[142:145], v[184:187], v[46:49]
	v_mfma_f32_16x16x32_bf16 v[216:219], v[152:155], v[184:187], v[42:45]
	v_mfma_f32_16x16x32_bf16 v[22:25], v[106:109], v[90:93], v[22:25]
	v_mfma_f32_16x16x32_bf16 v[18:21], v[204:207], v[90:93], v[18:21]
	v_mfma_f32_16x16x32_bf16 v[6:9], v[106:109], v[188:191], v[6:9]
	v_mfma_f32_16x16x32_bf16 v[2:5], v[204:207], v[188:191], v[2:5]
	v_mfma_f32_16x16x32_bf16 v[30:33], v[106:109], v[74:77], v[30:33]
	v_mfma_f32_16x16x32_bf16 v[26:29], v[204:207], v[74:77], v[26:29]
	v_mfma_f32_16x16x32_bf16 v[22:25], v[110:113], v[94:97], v[22:25]
	v_mfma_f32_16x16x32_bf16 v[18:21], v[208:211], v[94:97], v[18:21]
	v_mfma_f32_16x16x32_bf16 v[14:17], v[106:109], v[180:183], v[14:17]
	v_mfma_f32_16x16x32_bf16 v[10:13], v[204:207], v[180:183], v[10:13]
	v_mfma_f32_16x16x32_bf16 v[6:9], v[110:113], v[192:195], v[6:9]
	v_mfma_f32_16x16x32_bf16 v[2:5], v[208:211], v[192:195], v[2:5]
	v_mfma_f32_16x16x32_bf16 v[138:141], v[110:113], v[78:81], v[30:33]
	v_mfma_f32_16x16x32_bf16 v[142:145], v[208:211], v[78:81], v[26:29]
	v_mfma_f32_16x16x32_bf16 v[146:149], v[110:113], v[184:187], v[14:17]
	v_mfma_f32_16x16x32_bf16 v[152:155], v[208:211], v[184:187], v[10:13]
	s_barrier
	s_nop 0
	ds_read_b128 v[10:13], v137 offset:32768
	ds_read_b128 v[14:17], v137 offset:33792
	ds_read_b128 v[180:183], v137 offset:34816
	ds_read_b128 v[184:187], v137 offset:35840
	ds_read_b128 v[26:29], v136 offset:32768
	ds_read_b128 v[30:33], v136 offset:33792
	ds_read_b128 v[42:45], v136 offset:34816
	ds_read_b128 v[46:49], v136 offset:35840
	ds_read_b128 v[188:191], v136 offset:36864
	ds_read_b128 v[192:195], v136 offset:37888
	ds_read_b128 v[204:207], v136 offset:38912
	ds_read_b128 v[208:211], v136 offset:39936
	s_waitcnt vmcnt(2)
	s_barrier
; #define WAIT_V(n) asm volatile("s_waitcnt vmcnt(%0)" ::"n"(n) : "memory")
; #define WAIT_L(n) asm volatile("s_waitcnt lgkmcnt(%0)" ::"n"(n) : "memory")
; #define LDA8(dst, b, h) _Pragma("unroll") for (int m = 0; m < 4; ++m) _Pragma("unroll") for (int k = 0; k < 2; ++k) \
;     dst[m][k] = *(const bf16x8*)(abase + SAo(b, h) + m * 2048 + k * 1024)
; #define LDB8(dst, b, h) _Pragma("unroll") for (int n = 0; n < 2; ++n) _Pragma("unroll") for (int k = 0; k < 2; ++k) \
;     dst[n][k] = *(const bf16x8*)(bbase + SAo(b, h) + n * 2048 + k * 1024)
; #define BAR8 __builtin_amdgcn_s_barrier()
; __device__ __forceinline__ void gemm_main8(const u16* __restrict__ Ab, int lda, const u16* __restrict__ Bb, int ldb, int K,
;                                            char* shm, f32x4 (&acc)[2][2][4][2]) {
;     ...
;   { LDB8(B0, 1, 0); LDA8(At, 1, 0); WAIT_V(2); BAR8; WAIT_L(0); MMA8(0, 0, At, B0); BAR8;
;     LDB8(B1, 1, 1); WAIT_V(0); BAR8; WAIT_L(0); MMA8(0, 1, At, B1); BAR8;
;     LDA8(At, 1, 1); BAR8; WAIT_L(0); MMA8(1, 0, At, B0); MMA8(1, 1, At, B1); BAR8; }
;   if (wr == 0) BAR8;
	s_waitcnt lgkmcnt(0)
	s_waitcnt lgkmcnt(0)
	v_mfma_f32_16x16x32_bf16 v[74:77], v[10:13], v[26:29], v[126:129]
	v_mfma_f32_16x16x32_bf16 v[126:129], v[14:17], v[30:33], v[74:77]
	v_mfma_f32_16x16x32_bf16 v[74:77], v[180:183], v[26:29], v[122:125]
	v_mfma_f32_16x16x32_bf16 v[122:125], v[184:187], v[30:33], v[74:77]
	v_mfma_f32_16x16x32_bf16 v[74:77], v[10:13], v[42:45], v[118:121]
	v_mfma_f32_16x16x32_bf16 v[110:113], v[14:17], v[46:49], v[74:77]
	v_mfma_f32_16x16x32_bf16 v[74:77], v[180:183], v[42:45], v[114:117]
	v_mfma_f32_16x16x32_bf16 v[106:109], v[184:187], v[46:49], v[74:77]
	v_mfma_f32_16x16x32_bf16 v[74:77], v[10:13], v[188:191], v[172:175]
	v_mfma_f32_16x16x32_bf16 v[94:97], v[14:17], v[192:195], v[74:77]
	v_mfma_f32_16x16x32_bf16 v[74:77], v[180:183], v[188:191], v[200:203]
	v_mfma_f32_16x16x32_bf16 v[90:93], v[184:187], v[192:195], v[74:77]
	v_mfma_f32_16x16x32_bf16 v[74:77], v[10:13], v[204:207], v[102:105]
	v_mfma_f32_16x16x32_bf16 v[78:81], v[14:17], v[208:211], v[74:77]
	v_mfma_f32_16x16x32_bf16 v[74:77], v[180:183], v[204:207], v[98:101]
	v_mfma_f32_16x16x32_bf16 v[74:77], v[184:187], v[208:211], v[74:77]
	s_barrier
	ds_read_b128 v[172:175], v137 offset:49152
	ds_read_b128 v[200:203], v137 offset:50176
	ds_read_b128 v[220:223], v137 offset:51200
	ds_read_b128 v[224:227], v137 offset:52224
	s_waitcnt vmcnt(0)
	s_barrier
	s_waitcnt lgkmcnt(0)
	s_waitcnt lgkmcnt(0)
	v_mfma_f32_16x16x32_bf16 v[98:101], v[172:175], v[26:29], v[212:215]
	v_mfma_f32_16x16x32_bf16 v[26:29], v[220:223], v[26:29], v[164:167]
	v_mfma_f32_16x16x32_bf16 v[114:117], v[224:227], v[30:33], v[26:29]
	v_mfma_f32_16x16x32_bf16 v[26:29], v[172:175], v[42:45], v[86:89]
	v_mfma_f32_16x16x32_bf16 v[102:105], v[200:203], v[46:49], v[26:29]
	v_mfma_f32_16x16x32_bf16 v[26:29], v[220:223], v[42:45], v[82:85]
	v_mfma_f32_16x16x32_bf16 v[118:121], v[200:203], v[30:33], v[98:101]
	v_mfma_f32_16x16x32_bf16 v[98:101], v[224:227], v[46:49], v[26:29]
	v_mfma_f32_16x16x32_bf16 v[26:29], v[172:175], v[188:191], v[168:171]
	v_mfma_f32_16x16x32_bf16 v[86:89], v[200:203], v[192:195], v[26:29]
	v_mfma_f32_16x16x32_bf16 v[26:29], v[220:223], v[188:191], v[176:179]
	v_mfma_f32_16x16x32_bf16 v[82:85], v[224:227], v[192:195], v[26:29]
	v_mfma_f32_16x16x32_bf16 v[26:29], v[172:175], v[204:207], v[70:73]
	v_mfma_f32_16x16x32_bf16 v[70:73], v[200:203], v[208:211], v[26:29]
	v_mfma_f32_16x16x32_bf16 v[26:29], v[220:223], v[204:207], v[66:69]
	v_mfma_f32_16x16x32_bf16 v[66:69], v[224:227], v[208:211], v[26:29]
	s_barrier
	ds_read_b128 v[164:167], v136 offset:49152
	ds_read_b128 v[168:171], v136 offset:50176
	ds_read_b128 v[176:179], v136 offset:51200
	ds_read_b128 v[188:191], v136 offset:52224
	ds_read_b128 v[192:195], v136 offset:53248
	ds_read_b128 v[204:207], v136 offset:54272
	ds_read_b128 v[208:211], v136 offset:55296
	ds_read_b128 v[212:215], v136 offset:56320
	s_barrier
	s_waitcnt lgkmcnt(0)
	s_waitcnt lgkmcnt(0)
	v_mfma_f32_16x16x32_bf16 v[26:29], v[10:13], v[164:167], v[62:65]
	v_mfma_f32_16x16x32_bf16 v[62:65], v[14:17], v[168:171], v[26:29]
	v_mfma_f32_16x16x32_bf16 v[26:29], v[180:183], v[164:167], v[58:61]
	v_mfma_f32_16x16x32_bf16 v[58:61], v[184:187], v[168:171], v[26:29]
	v_mfma_f32_16x16x32_bf16 v[26:29], v[10:13], v[176:179], v[54:57]
	v_mfma_f32_16x16x32_bf16 v[46:49], v[14:17], v[188:191], v[26:29]
	v_mfma_f32_16x16x32_bf16 v[26:29], v[180:183], v[176:179], v[50:53]
	v_mfma_f32_16x16x32_bf16 v[42:45], v[184:187], v[188:191], v[26:29]
	v_mfma_f32_16x16x32_bf16 v[26:29], v[10:13], v[192:195], v[196:199]
	v_mfma_f32_16x16x32_bf16 v[10:13], v[10:13], v[208:211], v[38:41]
	v_mfma_f32_16x16x32_bf16 v[30:33], v[14:17], v[204:207], v[26:29]
	v_mfma_f32_16x16x32_bf16 v[26:29], v[180:183], v[192:195], v[216:219]
	v_mfma_f32_16x16x32_bf16 v[14:17], v[14:17], v[212:215], v[10:13]
	v_mfma_f32_16x16x32_bf16 v[10:13], v[180:183], v[208:211], v[34:37]
	v_mfma_f32_16x16x32_bf16 v[26:29], v[184:187], v[204:207], v[26:29]
	v_mfma_f32_16x16x32_bf16 v[10:13], v[184:187], v[212:215], v[10:13]
	v_mfma_f32_16x16x32_bf16 v[34:37], v[172:175], v[164:167], v[138:141]
	v_mfma_f32_16x16x32_bf16 v[54:57], v[200:203], v[168:171], v[34:37]
	v_mfma_f32_16x16x32_bf16 v[34:37], v[220:223], v[164:167], v[142:145]
	v_mfma_f32_16x16x32_bf16 v[18:21], v[220:223], v[176:179], v[18:21]
	v_mfma_f32_16x16x32_bf16 v[50:53], v[224:227], v[168:171], v[34:37]
	v_mfma_f32_16x16x32_bf16 v[22:25], v[172:175], v[176:179], v[22:25]
	v_mfma_f32_16x16x32_bf16 v[34:37], v[224:227], v[188:191], v[18:21]
	v_mfma_f32_16x16x32_bf16 v[18:21], v[172:175], v[192:195], v[146:149]
	v_mfma_f32_16x16x32_bf16 v[38:41], v[200:203], v[188:191], v[22:25]
	v_mfma_f32_16x16x32_bf16 v[22:25], v[200:203], v[204:207], v[18:21]
	v_mfma_f32_16x16x32_bf16 v[18:21], v[220:223], v[192:195], v[152:155]
	v_mfma_f32_16x16x32_bf16 v[6:9], v[172:175], v[208:211], v[6:9]
	v_mfma_f32_16x16x32_bf16 v[2:5], v[220:223], v[208:211], v[2:5]
	v_mfma_f32_16x16x32_bf16 v[18:21], v[224:227], v[204:207], v[18:21]
	v_mfma_f32_16x16x32_bf16 v[6:9], v[200:203], v[212:215], v[6:9]
	v_mfma_f32_16x16x32_bf16 v[2:5], v[224:227], v[212:215], v[2:5]
	v_cmp_gt_u32_e32 vcc, s97, v135
	s_barrier
	s_and_saveexec_b64 s[20:21], vcc
	s_cbranch_execz .LBB0_506
	s_barrier
	s_branch .LBB0_506

; #define WAIT_V(n) asm volatile("s_waitcnt vmcnt(%0)" ::"n"(n) : "memory")
; #define WAIT_L(n) asm volatile("s_waitcnt lgkmcnt(%0)" ::"n"(n) : "memory")
; #define SBAR() __builtin_amdgcn_sched_barrier(0)
; #define LDA8(dst, b, h) _Pragma("unroll") for (int m = 0; m < 4; ++m) _Pragma("unroll") for (int k = 0; k < 2; ++k) \
;     dst[m][k] = *(const bf16x8*)(abase + SAo(b, h) + m * 2048 + k * 1024)
; #define LDB8(dst, b, h) _Pragma("unroll") for (int n = 0; n < 2; ++n) _Pragma("unroll") for (int k = 0; k < 2; ++k) \
;     dst[n][k] = *(const bf16x8*)(bbase + SAo(b, h) + n * 2048 + k * 1024)
; #define BAR8 __builtin_amdgcn_s_barrier()
; __device__ __forceinline__ void gemm_main8(const u16* __restrict__ Ab, int lda, const u16* __restrict__ Bb, int ldb, int K,
;                                            char* shm, f32x4 (&acc)[2][2][4][2]) {
;     ...
;     LDB8(B0, 0, 0); SBAR(); LDA8(At, 0, 0); STG_A(1, 1, t + 1);
;     WAIT_L(8); BAR8; WAIT_L(0); MMA8(0, 0, At, B0); BAR8; SBAR();
;     LDB8(B1, 0, 1); STG_B(0, 0, t + 2);
;     BAR8; WAIT_L(0); MMA8(0, 1, At, B1); BAR8;
;     LDA8(At, 0, 1); STG_A(0, 0, t + 2);
;     BAR8; WAIT_L(0); MMA8(1, 0, At, B0); BAR8; SBAR();
;     STG_B(0, 1, t + 2);
;     WAIT_V(6); BAR8; MMA8(1, 1, At, B1); BAR8;
.LBB0_556:
	ds_read_b128 v[152:155], v132
	ds_read_b128 v[164:167], v132 offset:1024
	ds_read_b128 v[176:179], v132 offset:2048
	ds_read_b128 v[180:183], v132 offset:3072
	v_add_u32_e32 v174, 0xc000, v133
	v_lshl_add_u64 v[168:169], s[20:21], 0, v[0:1]
	v_readfirstlane_b32 s15, v174
	v_add_u32_e32 v175, 0xe000, v133
	v_lshl_add_u64 v[216:217], v[168:169], 0, s[54:55]
	s_mov_b32 m0, s15
	v_readfirstlane_b32 s15, v175
	ds_read_b128 v[184:187], v139
	ds_read_b128 v[188:191], v139 offset:1024
	ds_read_b128 v[192:195], v139 offset:2048
	ds_read_b128 v[196:199], v139 offset:3072
	ds_read_b128 v[200:203], v139 offset:4096
	ds_read_b128 v[204:207], v139 offset:5120
	ds_read_b128 v[208:211], v139 offset:6144
	ds_read_b128 v[212:215], v139 offset:7168
	global_load_lds_dwordx4 v[216:217], off
	v_lshl_add_u64 v[216:217], v[168:169], 0, s[56:57]
	s_mov_b32 m0, s15
	s_nop 0
	global_load_lds_dwordx4 v[216:217], off
	s_waitcnt lgkmcnt(8)
	s_barrier
	s_waitcnt lgkmcnt(0)
	s_waitcnt lgkmcnt(0)
	v_mfma_f32_16x16x32_bf16 v[126:129], v[152:155], v[184:187], v[126:129]
	v_mfma_f32_16x16x32_bf16 v[122:125], v[176:179], v[184:187], v[122:125]
	v_mfma_f32_16x16x32_bf16 v[118:121], v[152:155], v[192:195], v[118:121]
	v_mfma_f32_16x16x32_bf16 v[114:117], v[176:179], v[192:195], v[114:117]
	v_mfma_f32_16x16x32_bf16 v[110:113], v[152:155], v[200:203], v[110:113]
	v_mfma_f32_16x16x32_bf16 v[106:109], v[176:179], v[200:203], v[106:109]
	v_mfma_f32_16x16x32_bf16 v[102:105], v[152:155], v[208:211], v[102:105]
	v_mfma_f32_16x16x32_bf16 v[98:101], v[176:179], v[208:211], v[98:101]
	v_mfma_f32_16x16x32_bf16 v[126:129], v[164:167], v[188:191], v[126:129]
	v_mfma_f32_16x16x32_bf16 v[122:125], v[180:183], v[188:191], v[122:125]
	v_mfma_f32_16x16x32_bf16 v[118:121], v[164:167], v[196:199], v[118:121]
	v_mfma_f32_16x16x32_bf16 v[114:117], v[180:183], v[196:199], v[114:117]
	v_mfma_f32_16x16x32_bf16 v[110:113], v[164:167], v[204:207], v[110:113]
	v_mfma_f32_16x16x32_bf16 v[106:109], v[180:183], v[204:207], v[106:109]
	v_mfma_f32_16x16x32_bf16 v[102:105], v[164:167], v[212:215], v[102:105]
	v_mfma_f32_16x16x32_bf16 v[98:101], v[180:183], v[212:215], v[98:101]
	s_barrier
	v_lshl_add_u64 v[232:233], s[18:19], 0, v[0:1]
	s_mov_b64 s[24:25], 0x1000100
	v_readfirstlane_b32 s15, v134
	v_lshl_add_u64 v[234:235], v[232:233], 0, s[24:25]
	s_mov_b32 m0, s15
	s_mov_b64 s[24:25], 0x1040100
	v_readfirstlane_b32 s15, v135
	ds_read_b128 v[216:219], v132 offset:16384
	ds_read_b128 v[220:223], v132 offset:17408
	ds_read_b128 v[224:227], v132 offset:18432
	ds_read_b128 v[228:231], v132 offset:19456
	global_load_lds_dwordx4 v[234:235], off
	v_lshl_add_u64 v[234:235], v[232:233], 0, s[24:25]
	s_mov_b32 m0, s15
	s_nop 0
	global_load_lds_dwordx4 v[234:235], off
	s_barrier
	s_waitcnt lgkmcnt(0)
	s_waitcnt lgkmcnt(0)
	v_mfma_f32_16x16x32_bf16 v[94:97], v[216:219], v[184:187], v[94:97]
	v_mfma_f32_16x16x32_bf16 v[90:93], v[224:227], v[184:187], v[90:93]
	v_mfma_f32_16x16x32_bf16 v[86:89], v[216:219], v[192:195], v[86:89]
	v_mfma_f32_16x16x32_bf16 v[82:85], v[224:227], v[192:195], v[82:85]
	v_mfma_f32_16x16x32_bf16 v[78:81], v[216:219], v[200:203], v[78:81]
	v_mfma_f32_16x16x32_bf16 v[74:77], v[224:227], v[200:203], v[74:77]
	v_mfma_f32_16x16x32_bf16 v[70:73], v[216:219], v[208:211], v[70:73]
	v_mfma_f32_16x16x32_bf16 v[66:69], v[224:227], v[208:211], v[66:69]
	v_mfma_f32_16x16x32_bf16 v[94:97], v[220:223], v[188:191], v[94:97]
	v_mfma_f32_16x16x32_bf16 v[90:93], v[228:231], v[188:191], v[90:93]
	v_mfma_f32_16x16x32_bf16 v[86:89], v[220:223], v[196:199], v[86:89]
	v_mfma_f32_16x16x32_bf16 v[82:85], v[228:231], v[196:199], v[82:85]
	v_mfma_f32_16x16x32_bf16 v[78:81], v[220:223], v[204:207], v[78:81]
	v_mfma_f32_16x16x32_bf16 v[74:77], v[228:231], v[204:207], v[74:77]
	v_mfma_f32_16x16x32_bf16 v[70:73], v[220:223], v[212:215], v[70:73]
	v_mfma_f32_16x16x32_bf16 v[66:69], v[228:231], v[212:215], v[66:69]
	v_readfirstlane_b32 s15, v133
	v_lshl_add_u64 v[234:235], v[168:169], 0, s[58:59]
	s_mov_b32 m0, s15
	v_readfirstlane_b32 s15, v136
	s_barrier
	ds_read_b128 v[184:187], v139 offset:16384
	ds_read_b128 v[188:191], v139 offset:17408
	ds_read_b128 v[192:195], v139 offset:18432
	ds_read_b128 v[196:199], v139 offset:19456
	ds_read_b128 v[200:203], v139 offset:20480
	ds_read_b128 v[204:207], v139 offset:21504
	ds_read_b128 v[208:211], v139 offset:22528
	ds_read_b128 v[212:215], v139 offset:23552
	global_load_lds_dwordx4 v[234:235], off
	v_lshl_add_u64 v[234:235], v[168:169], 0, s[60:61]
	s_mov_b32 m0, s15
	s_nop 0
	global_load_lds_dwordx4 v[234:235], off
	s_barrier
	s_waitcnt lgkmcnt(0)
	s_waitcnt lgkmcnt(0)
	v_mfma_f32_16x16x32_bf16 v[62:65], v[152:155], v[184:187], v[62:65]
	v_mfma_f32_16x16x32_bf16 v[58:61], v[176:179], v[184:187], v[58:61]
	v_mfma_f32_16x16x32_bf16 v[54:57], v[152:155], v[192:195], v[54:57]
	v_mfma_f32_16x16x32_bf16 v[50:53], v[176:179], v[192:195], v[50:53]
	v_mfma_f32_16x16x32_bf16 v[46:49], v[152:155], v[200:203], v[46:49]
	v_mfma_f32_16x16x32_bf16 v[42:45], v[176:179], v[200:203], v[42:45]
	v_mfma_f32_16x16x32_bf16 v[38:41], v[152:155], v[208:211], v[38:41]
	v_mfma_f32_16x16x32_bf16 v[34:37], v[176:179], v[208:211], v[34:37]
	v_mfma_f32_16x16x32_bf16 v[62:65], v[164:167], v[188:191], v[62:65]
	v_mfma_f32_16x16x32_bf16 v[58:61], v[180:183], v[188:191], v[58:61]
	v_mfma_f32_16x16x32_bf16 v[54:57], v[164:167], v[196:199], v[54:57]
	v_mfma_f32_16x16x32_bf16 v[50:53], v[180:183], v[196:199], v[50:53]
	v_mfma_f32_16x16x32_bf16 v[46:49], v[164:167], v[204:207], v[46:49]
	v_mfma_f32_16x16x32_bf16 v[42:45], v[180:183], v[204:207], v[42:45]
	v_mfma_f32_16x16x32_bf16 v[38:41], v[164:167], v[212:215], v[38:41]
	v_mfma_f32_16x16x32_bf16 v[34:37], v[180:183], v[212:215], v[34:37]
	s_barrier
; #define WAIT_V(n) asm volatile("s_waitcnt vmcnt(%0)" ::"n"(n) : "memory")
; #define WAIT_L(n) asm volatile("s_waitcnt lgkmcnt(%0)" ::"n"(n) : "memory")
; #define SBAR() __builtin_amdgcn_sched_barrier(0)
; #define LDA8(dst, b, h) _Pragma("unroll") for (int m = 0; m < 4; ++m) _Pragma("unroll") for (int k = 0; k < 2; ++k) \
;     dst[m][k] = *(const bf16x8*)(abase + SAo(b, h) + m * 2048 + k * 1024)
; #define LDB8(dst, b, h) _Pragma("unroll") for (int n = 0; n < 2; ++n) _Pragma("unroll") for (int k = 0; k < 2; ++k) \
;     dst[n][k] = *(const bf16x8*)(bbase + SAo(b, h) + n * 2048 + k * 1024)
; #define BAR8 __builtin_amdgcn_s_barrier()
; __device__ __forceinline__ void gemm_main8(const u16* __restrict__ Ab, int lda, const u16* __restrict__ Bb, int ldb, int K,
;                                            char* shm, f32x4 (&acc)[2][2][4][2]) {
;     ...
;     STG_B(0, 1, t + 2);
;     WAIT_V(6); BAR8; MMA8(1, 1, At, B1); BAR8;
;     LDB8(B0, 1, 0); SBAR(); LDA8(At, 1, 0); STG_A(0, 1, t + 2);
;     WAIT_L(8); BAR8; WAIT_L(0); MMA8(0, 0, At, B0); BAR8; SBAR();
;     LDB8(B1, 1, 1); STG_B(1, 0, t + 3);
;     BAR8; WAIT_L(0); MMA8(0, 1, At, B1); BAR8;
;     LDA8(At, 1, 1); STG_A(1, 0, t + 3);
	s_mov_b64 s[24:25], 0x1080100
	v_readfirstlane_b32 s15, v137
	v_lshl_add_u64 v[152:153], v[232:233], 0, s[24:25]
	s_mov_b32 m0, s15
	s_mov_b64 s[24:25], 0x10c0100
	v_readfirstlane_b32 s15, v140
	global_load_lds_dwordx4 v[152:153], off
	v_lshl_add_u64 v[152:153], v[232:233], 0, s[24:25]
	s_mov_b32 m0, s15
	s_nop 0
	global_load_lds_dwordx4 v[152:153], off
	s_waitcnt vmcnt(6)
	s_barrier
	v_mfma_f32_16x16x32_bf16 v[30:33], v[216:219], v[184:187], v[30:33]
	v_mfma_f32_16x16x32_bf16 v[26:29], v[224:227], v[184:187], v[26:29]
	v_mfma_f32_16x16x32_bf16 v[22:25], v[216:219], v[192:195], v[22:25]
	v_mfma_f32_16x16x32_bf16 v[18:21], v[224:227], v[192:195], v[18:21]
	v_mfma_f32_16x16x32_bf16 v[14:17], v[216:219], v[200:203], v[14:17]
	v_mfma_f32_16x16x32_bf16 v[10:13], v[224:227], v[200:203], v[10:13]
	v_mfma_f32_16x16x32_bf16 v[6:9], v[216:219], v[208:211], v[6:9]
	v_mfma_f32_16x16x32_bf16 v[2:5], v[224:227], v[208:211], v[2:5]
	v_mfma_f32_16x16x32_bf16 v[30:33], v[220:223], v[188:191], v[30:33]
	v_mfma_f32_16x16x32_bf16 v[26:29], v[228:231], v[188:191], v[26:29]
	v_mfma_f32_16x16x32_bf16 v[22:25], v[220:223], v[196:199], v[22:25]
	v_mfma_f32_16x16x32_bf16 v[18:21], v[228:231], v[196:199], v[18:21]
	v_mfma_f32_16x16x32_bf16 v[14:17], v[220:223], v[204:207], v[14:17]
	v_mfma_f32_16x16x32_bf16 v[10:13], v[228:231], v[204:207], v[10:13]
	v_mfma_f32_16x16x32_bf16 v[6:9], v[220:223], v[212:215], v[6:9]
	v_mfma_f32_16x16x32_bf16 v[2:5], v[228:231], v[212:215], v[2:5]
	s_barrier
	ds_read_b128 v[152:155], v132 offset:32768
	ds_read_b128 v[164:167], v132 offset:33792
	ds_read_b128 v[176:179], v132 offset:34816
	ds_read_b128 v[180:183], v132 offset:35840
	v_readfirstlane_b32 s15, v141
	v_lshl_add_u64 v[216:217], v[168:169], 0, s[62:63]
	s_mov_b32 m0, s15
	v_readfirstlane_b32 s15, v142
	ds_read_b128 v[184:187], v139 offset:32768
	ds_read_b128 v[188:191], v139 offset:33792
	ds_read_b128 v[192:195], v139 offset:34816
	ds_read_b128 v[196:199], v139 offset:35840
	ds_read_b128 v[200:203], v139 offset:36864
	ds_read_b128 v[204:207], v139 offset:37888
	ds_read_b128 v[208:211], v139 offset:38912
	ds_read_b128 v[212:215], v139 offset:39936
	global_load_lds_dwordx4 v[216:217], off
	v_lshl_add_u64 v[216:217], v[168:169], 0, s[64:65]
	s_mov_b32 m0, s15
	s_nop 0
	global_load_lds_dwordx4 v[216:217], off
	s_waitcnt lgkmcnt(8)
	s_barrier
	s_waitcnt lgkmcnt(0)
	s_waitcnt lgkmcnt(0)
	v_mfma_f32_16x16x32_bf16 v[126:129], v[152:155], v[184:187], v[126:129]
	v_mfma_f32_16x16x32_bf16 v[122:125], v[176:179], v[184:187], v[122:125]
	v_mfma_f32_16x16x32_bf16 v[118:121], v[152:155], v[192:195], v[118:121]
	v_mfma_f32_16x16x32_bf16 v[114:117], v[176:179], v[192:195], v[114:117]
	v_mfma_f32_16x16x32_bf16 v[110:113], v[152:155], v[200:203], v[110:113]
	v_mfma_f32_16x16x32_bf16 v[106:109], v[176:179], v[200:203], v[106:109]
	v_mfma_f32_16x16x32_bf16 v[102:105], v[152:155], v[208:211], v[102:105]
	v_mfma_f32_16x16x32_bf16 v[98:101], v[176:179], v[208:211], v[98:101]
	v_mfma_f32_16x16x32_bf16 v[126:129], v[164:167], v[188:191], v[126:129]
	v_mfma_f32_16x16x32_bf16 v[122:125], v[180:183], v[188:191], v[122:125]
	v_mfma_f32_16x16x32_bf16 v[118:121], v[164:167], v[196:199], v[118:121]
	v_mfma_f32_16x16x32_bf16 v[114:117], v[180:183], v[196:199], v[114:117]
	v_mfma_f32_16x16x32_bf16 v[110:113], v[164:167], v[204:207], v[110:113]
	v_mfma_f32_16x16x32_bf16 v[106:109], v[180:183], v[204:207], v[106:109]
	v_mfma_f32_16x16x32_bf16 v[102:105], v[164:167], v[212:215], v[102:105]
	v_mfma_f32_16x16x32_bf16 v[98:101], v[180:183], v[212:215], v[98:101]
	s_barrier
	s_mov_b64 s[24:25], 0x1000180
	v_readfirstlane_b32 s15, v143
	v_lshl_add_u64 v[234:235], v[232:233], 0, s[24:25]
	s_mov_b32 m0, s15
	s_mov_b64 s[24:25], 0x1040180
	v_readfirstlane_b32 s15, v144
	ds_read_b128 v[216:219], v132 offset:49152
	ds_read_b128 v[220:223], v132 offset:50176
	ds_read_b128 v[224:227], v132 offset:51200
	ds_read_b128 v[228:231], v132 offset:52224
	global_load_lds_dwordx4 v[234:235], off
	v_lshl_add_u64 v[234:235], v[232:233], 0, s[24:25]
	s_mov_b32 m0, s15
	s_nop 0
	global_load_lds_dwordx4 v[234:235], off
	s_barrier
	s_waitcnt lgkmcnt(0)
	s_waitcnt lgkmcnt(0)
	v_mfma_f32_16x16x32_bf16 v[94:97], v[216:219], v[184:187], v[94:97]
	v_mfma_f32_16x16x32_bf16 v[90:93], v[224:227], v[184:187], v[90:93]
	v_mfma_f32_16x16x32_bf16 v[86:89], v[216:219], v[192:195], v[86:89]
	v_mfma_f32_16x16x32_bf16 v[82:85], v[224:227], v[192:195], v[82:85]
	v_mfma_f32_16x16x32_bf16 v[78:81], v[216:219], v[200:203], v[78:81]
	v_mfma_f32_16x16x32_bf16 v[74:77], v[224:227], v[200:203], v[74:77]
	v_mfma_f32_16x16x32_bf16 v[70:73], v[216:219], v[208:211], v[70:73]
	v_mfma_f32_16x16x32_bf16 v[66:69], v[224:227], v[208:211], v[66:69]
	v_mfma_f32_16x16x32_bf16 v[94:97], v[220:223], v[188:191], v[94:97]
	v_mfma_f32_16x16x32_bf16 v[90:93], v[228:231], v[188:191], v[90:93]
	v_mfma_f32_16x16x32_bf16 v[86:89], v[220:223], v[196:199], v[86:89]
	v_mfma_f32_16x16x32_bf16 v[82:85], v[228:231], v[196:199], v[82:85]
	v_mfma_f32_16x16x32_bf16 v[78:81], v[220:223], v[204:207], v[78:81]
	v_mfma_f32_16x16x32_bf16 v[74:77], v[228:231], v[204:207], v[74:77]
	v_mfma_f32_16x16x32_bf16 v[70:73], v[220:223], v[212:215], v[70:73]
	v_mfma_f32_16x16x32_bf16 v[66:69], v[228:231], v[212:215], v[66:69]
	v_readfirstlane_b32 s15, v145
	v_lshl_add_u64 v[234:235], v[168:169], 0, s[66:67]
	s_mov_b32 m0, s15
	v_readfirstlane_b32 s15, v171
	s_barrier
; #define WAIT_V(n) asm volatile("s_waitcnt vmcnt(%0)" ::"n"(n) : "memory")
; #define WAIT_L(n) asm volatile("s_waitcnt lgkmcnt(%0)" ::"n"(n) : "memory")
; #define SBAR() __builtin_amdgcn_sched_barrier(0)
; #define LDA8(dst, b, h) _Pragma("unroll") for (int m = 0; m < 4; ++m) _Pragma("unroll") for (int k = 0; k < 2; ++k) \
;     dst[m][k] = *(const bf16x8*)(abase + SAo(b, h) + m * 2048 + k * 1024)
; #define LDB8(dst, b, h) _Pragma("unroll") for (int n = 0; n < 2; ++n) _Pragma("unroll") for (int k = 0; k < 2; ++k) \
;     dst[n][k] = *(const bf16x8*)(bbase + SAo(b, h) + n * 2048 + k * 1024)
; #define BAR8 __builtin_amdgcn_s_barrier()
; __device__ __forceinline__ void gemm_main8(const u16* __restrict__ Ab, int lda, const u16* __restrict__ Bb, int ldb, int K,
;                                            char* shm, f32x4 (&acc)[2][2][4][2]) {
;     ...
;     LDB8(B1, 1, 1); STG_B(1, 0, t + 3);
;     BAR8; WAIT_L(0); MMA8(0, 1, At, B1); BAR8;
;     LDA8(At, 1, 1); STG_A(1, 0, t + 3);
;     BAR8; WAIT_L(0); MMA8(1, 0, At, B0); BAR8; SBAR();
;     STG_B(1, 1, t + 3);
;     WAIT_V(6); BAR8; MMA8(1, 1, At, B1); BAR8;
;   }
;   { LDB8(B0, 0, 0); LDA8(At, 0, 0); STG_A(1, 1, nt - 1);
;     BAR8; WAIT_L(0); MMA8(0, 0, At, B0); BAR8;
	ds_read_b128 v[184:187], v139 offset:49152
	ds_read_b128 v[188:191], v139 offset:50176
	ds_read_b128 v[192:195], v139 offset:51200
	ds_read_b128 v[196:199], v139 offset:52224
	ds_read_b128 v[200:203], v139 offset:53248
	ds_read_b128 v[204:207], v139 offset:54272
	ds_read_b128 v[208:211], v139 offset:55296
	ds_read_b128 v[212:215], v139 offset:56320
	global_load_lds_dwordx4 v[234:235], off
	v_lshl_add_u64 v[168:169], v[168:169], 0, s[68:69]
	s_mov_b32 m0, s15
	s_nop 0
	global_load_lds_dwordx4 v[168:169], off
	s_barrier
	s_waitcnt lgkmcnt(0)
	s_waitcnt lgkmcnt(0)
	v_mfma_f32_16x16x32_bf16 v[62:65], v[152:155], v[184:187], v[62:65]
	v_mfma_f32_16x16x32_bf16 v[58:61], v[176:179], v[184:187], v[58:61]
	v_mfma_f32_16x16x32_bf16 v[54:57], v[152:155], v[192:195], v[54:57]
	v_mfma_f32_16x16x32_bf16 v[50:53], v[176:179], v[192:195], v[50:53]
	v_mfma_f32_16x16x32_bf16 v[46:49], v[152:155], v[200:203], v[46:49]
	v_mfma_f32_16x16x32_bf16 v[42:45], v[176:179], v[200:203], v[42:45]
	v_mfma_f32_16x16x32_bf16 v[38:41], v[152:155], v[208:211], v[38:41]
	v_mfma_f32_16x16x32_bf16 v[34:37], v[176:179], v[208:211], v[34:37]
	v_mfma_f32_16x16x32_bf16 v[62:65], v[164:167], v[188:191], v[62:65]
	v_mfma_f32_16x16x32_bf16 v[58:61], v[180:183], v[188:191], v[58:61]
	v_mfma_f32_16x16x32_bf16 v[54:57], v[164:167], v[196:199], v[54:57]
	v_mfma_f32_16x16x32_bf16 v[50:53], v[180:183], v[196:199], v[50:53]
	v_mfma_f32_16x16x32_bf16 v[46:49], v[164:167], v[204:207], v[46:49]
	v_mfma_f32_16x16x32_bf16 v[42:45], v[180:183], v[204:207], v[42:45]
	v_mfma_f32_16x16x32_bf16 v[38:41], v[164:167], v[212:215], v[38:41]
	v_mfma_f32_16x16x32_bf16 v[34:37], v[180:183], v[212:215], v[34:37]
	s_barrier
	s_mov_b64 s[24:25], 0x1080180
	v_readfirstlane_b32 s15, v172
	v_lshl_add_u64 v[152:153], v[232:233], 0, s[24:25]
	s_mov_b32 m0, s15
	s_mov_b64 s[24:25], 0x10c0180
	v_readfirstlane_b32 s15, v173
	global_load_lds_dwordx4 v[152:153], off
	v_lshl_add_u64 v[152:153], v[232:233], 0, s[24:25]
	s_mov_b32 m0, s15
	s_nop 0
	global_load_lds_dwordx4 v[152:153], off
	s_waitcnt vmcnt(6)
	s_barrier
	v_mfma_f32_16x16x32_bf16 v[30:33], v[216:219], v[184:187], v[30:33]
	v_mfma_f32_16x16x32_bf16 v[26:29], v[224:227], v[184:187], v[26:29]
	v_mfma_f32_16x16x32_bf16 v[22:25], v[216:219], v[192:195], v[22:25]
	v_mfma_f32_16x16x32_bf16 v[18:21], v[224:227], v[192:195], v[18:21]
	v_mfma_f32_16x16x32_bf16 v[14:17], v[216:219], v[200:203], v[14:17]
	v_mfma_f32_16x16x32_bf16 v[10:13], v[224:227], v[200:203], v[10:13]
	v_mfma_f32_16x16x32_bf16 v[6:9], v[216:219], v[208:211], v[6:9]
	v_mfma_f32_16x16x32_bf16 v[2:5], v[224:227], v[208:211], v[2:5]
	v_mfma_f32_16x16x32_bf16 v[30:33], v[220:223], v[188:191], v[30:33]
	v_mfma_f32_16x16x32_bf16 v[26:29], v[228:231], v[188:191], v[26:29]
	v_mfma_f32_16x16x32_bf16 v[22:25], v[220:223], v[196:199], v[22:25]
	v_mfma_f32_16x16x32_bf16 v[18:21], v[228:231], v[196:199], v[18:21]
	v_mfma_f32_16x16x32_bf16 v[14:17], v[220:223], v[204:207], v[14:17]
	v_mfma_f32_16x16x32_bf16 v[10:13], v[228:231], v[204:207], v[10:13]
	v_mfma_f32_16x16x32_bf16 v[6:9], v[220:223], v[212:215], v[6:9]
	v_mfma_f32_16x16x32_bf16 v[2:5], v[228:231], v[212:215], v[2:5]
	s_add_i32 s13, s13, 2
	s_add_u32 s18, s18, 0x100
	s_addc_u32 s19, s19, 0
	s_add_u32 s20, s20, 0x100
	s_addc_u32 s21, s21, 0
	s_cmp_lt_u32 s13, 28
	s_barrier
	s_cbranch_scc1 .LBB0_556
	s_mov_b64 s[18:19], 0x80f80
	v_readfirstlane_b32 s13, v174
	v_lshl_add_u64 v[144:145], v[130:131], 0, s[18:19]
	s_mov_b32 m0, s13
	s_mov_b64 s[18:19], 0xc0f80
	v_readfirstlane_b32 s13, v175
	ds_read_b128 v[134:137], v132
	ds_read_b128 v[140:143], v132 offset:1024
	ds_read_b128 v[152:155], v132 offset:2048
	ds_read_b128 v[164:167], v132 offset:3072
	ds_read_b128 v[168:171], v139
	ds_read_b128 v[176:179], v139 offset:1024
	ds_read_b128 v[180:183], v139 offset:2048
	ds_read_b128 v[184:187], v139 offset:3072
	ds_read_b128 v[188:191], v139 offset:4096
	ds_read_b128 v[192:195], v139 offset:5120
	ds_read_b128 v[196:199], v139 offset:6144
	ds_read_b128 v[200:203], v139 offset:7168
	global_load_lds_dwordx4 v[144:145], off
	v_lshl_add_u64 v[130:131], v[130:131], 0, s[18:19]
	s_mov_b32 m0, s13
	s_nop 0
	global_load_lds_dwordx4 v[130:131], off
	s_barrier
	s_waitcnt lgkmcnt(0)
	s_waitcnt lgkmcnt(0)
	v_mfma_f32_16x16x32_bf16 v[126:129], v[134:137], v[168:171], v[126:129]
	v_mfma_f32_16x16x32_bf16 v[122:125], v[152:155], v[168:171], v[122:125]
	v_mfma_f32_16x16x32_bf16 v[118:121], v[134:137], v[180:183], v[118:121]
	v_mfma_f32_16x16x32_bf16 v[114:117], v[152:155], v[180:183], v[114:117]
	v_mfma_f32_16x16x32_bf16 v[102:105], v[134:137], v[196:199], v[102:105]
	v_mfma_f32_16x16x32_bf16 v[126:129], v[140:143], v[176:179], v[126:129]
	v_mfma_f32_16x16x32_bf16 v[122:125], v[164:167], v[176:179], v[122:125]
	v_mfma_f32_16x16x32_bf16 v[118:121], v[140:143], v[184:187], v[118:121]
	v_mfma_f32_16x16x32_bf16 v[114:117], v[164:167], v[184:187], v[114:117]
	v_mfma_f32_16x16x32_bf16 v[110:113], v[134:137], v[188:191], v[110:113]
	v_mfma_f32_16x16x32_bf16 v[106:109], v[152:155], v[188:191], v[106:109]
	v_mfma_f32_16x16x32_bf16 v[102:105], v[140:143], v[200:203], v[102:105]
	v_mfma_f32_16x16x32_bf16 v[98:101], v[152:155], v[196:199], v[98:101]
	v_mfma_f32_16x16x32_bf16 v[172:175], v[140:143], v[192:195], v[110:113]
	v_mfma_f32_16x16x32_bf16 v[106:109], v[164:167], v[192:195], v[106:109]
	v_mfma_f32_16x16x32_bf16 v[204:207], v[164:167], v[200:203], v[98:101]
	s_barrier
	s_nop 2
	ds_read_b128 v[98:101], v132 offset:16384
	ds_read_b128 v[110:113], v132 offset:17408
	ds_read_b128 v[208:211], v132 offset:18432
	ds_read_b128 v[212:215], v132 offset:19456
	s_barrier
; #define WAIT_V(n) asm volatile("s_waitcnt vmcnt(%0)" ::"n"(n) : "memory")
; #define WAIT_L(n) asm volatile("s_waitcnt lgkmcnt(%0)" ::"n"(n) : "memory")
; #define LDA8(dst, b, h) _Pragma("unroll") for (int m = 0; m < 4; ++m) _Pragma("unroll") for (int k = 0; k < 2; ++k) \
;     dst[m][k] = *(const bf16x8*)(abase + SAo(b, h) + m * 2048 + k * 1024)
; #define LDB8(dst, b, h) _Pragma("unroll") for (int n = 0; n < 2; ++n) _Pragma("unroll") for (int k = 0; k < 2; ++k) \
;     dst[n][k] = *(const bf16x8*)(bbase + SAo(b, h) + n * 2048 + k * 1024)
; #define BAR8 __builtin_amdgcn_s_barrier()
; __device__ __forceinline__ void gemm_main8(const u16* __restrict__ Ab, int lda, const u16* __restrict__ Bb, int ldb, int K,
;                                            char* shm, f32x4 (&acc)[2][2][4][2]) {
;     ...
;     LDB8(B1, 0, 1); BAR8; WAIT_L(0); MMA8(0, 1, At, B1); BAR8;
;     LDA8(At, 0, 1); WAIT_V(4); BAR8; WAIT_L(0); MMA8(1, 0, At, B0); MMA8(1, 1, At, B1); BAR8; }
;   { LDB8(B0, 1, 0); LDA8(At, 1, 0); WAIT_V(2); BAR8; WAIT_L(0); MMA8(0, 0, At, B0); BAR8;
	s_waitcnt lgkmcnt(0)
	s_waitcnt lgkmcnt(0)
	v_mfma_f32_16x16x32_bf16 v[90:93], v[208:211], v[168:171], v[90:93]
	v_mfma_f32_16x16x32_bf16 v[82:85], v[208:211], v[180:183], v[82:85]
	v_mfma_f32_16x16x32_bf16 v[74:77], v[208:211], v[188:191], v[74:77]
	v_mfma_f32_16x16x32_bf16 v[94:97], v[98:101], v[168:171], v[94:97]
	v_mfma_f32_16x16x32_bf16 v[90:93], v[212:215], v[176:179], v[90:93]
	v_mfma_f32_16x16x32_bf16 v[86:89], v[98:101], v[180:183], v[86:89]
	v_mfma_f32_16x16x32_bf16 v[82:85], v[212:215], v[184:187], v[82:85]
	v_mfma_f32_16x16x32_bf16 v[78:81], v[98:101], v[188:191], v[78:81]
	v_mfma_f32_16x16x32_bf16 v[74:77], v[212:215], v[192:195], v[74:77]
	v_mfma_f32_16x16x32_bf16 v[70:73], v[98:101], v[196:199], v[70:73]
	v_mfma_f32_16x16x32_bf16 v[66:69], v[208:211], v[196:199], v[66:69]
	v_mfma_f32_16x16x32_bf16 v[94:97], v[110:113], v[176:179], v[94:97]
	v_mfma_f32_16x16x32_bf16 v[168:171], v[110:113], v[184:187], v[86:89]
	v_mfma_f32_16x16x32_bf16 v[176:179], v[110:113], v[192:195], v[78:81]
	v_mfma_f32_16x16x32_bf16 v[180:183], v[110:113], v[200:203], v[70:73]
	v_mfma_f32_16x16x32_bf16 v[184:187], v[212:215], v[200:203], v[66:69]
	s_barrier
	s_nop 0
	ds_read_b128 v[66:69], v139 offset:16384
	ds_read_b128 v[70:73], v139 offset:17408
	ds_read_b128 v[78:81], v139 offset:18432
	ds_read_b128 v[86:89], v139 offset:19456
	ds_read_b128 v[188:191], v139 offset:20480
	ds_read_b128 v[192:195], v139 offset:21504
	ds_read_b128 v[196:199], v139 offset:22528
	ds_read_b128 v[200:203], v139 offset:23552
	s_waitcnt vmcnt(4)
	s_barrier
	s_waitcnt lgkmcnt(0)
	s_waitcnt lgkmcnt(0)
	v_mfma_f32_16x16x32_bf16 v[62:65], v[134:137], v[66:69], v[62:65]
	v_mfma_f32_16x16x32_bf16 v[54:57], v[134:137], v[78:81], v[54:57]
	v_mfma_f32_16x16x32_bf16 v[50:53], v[152:155], v[78:81], v[50:53]
	v_mfma_f32_16x16x32_bf16 v[38:41], v[134:137], v[196:199], v[38:41]
	v_mfma_f32_16x16x32_bf16 v[34:37], v[152:155], v[196:199], v[34:37]
	v_mfma_f32_16x16x32_bf16 v[62:65], v[140:143], v[70:73], v[62:65]
	v_mfma_f32_16x16x32_bf16 v[58:61], v[152:155], v[66:69], v[58:61]
	v_mfma_f32_16x16x32_bf16 v[54:57], v[140:143], v[86:89], v[54:57]
	v_mfma_f32_16x16x32_bf16 v[50:53], v[164:167], v[86:89], v[50:53]
	v_mfma_f32_16x16x32_bf16 v[46:49], v[134:137], v[188:191], v[46:49]
	v_mfma_f32_16x16x32_bf16 v[42:45], v[152:155], v[188:191], v[42:45]
	v_mfma_f32_16x16x32_bf16 v[38:41], v[140:143], v[200:203], v[38:41]
	v_mfma_f32_16x16x32_bf16 v[34:37], v[164:167], v[200:203], v[34:37]
	v_mfma_f32_16x16x32_bf16 v[216:219], v[164:167], v[70:73], v[58:61]
	v_mfma_f32_16x16x32_bf16 v[220:223], v[140:143], v[192:195], v[46:49]
	v_mfma_f32_16x16x32_bf16 v[224:227], v[164:167], v[192:195], v[42:45]
	v_mfma_f32_16x16x32_bf16 v[22:25], v[98:101], v[78:81], v[22:25]
	v_mfma_f32_16x16x32_bf16 v[18:21], v[208:211], v[78:81], v[18:21]
	v_mfma_f32_16x16x32_bf16 v[10:13], v[208:211], v[188:191], v[10:13]
	v_mfma_f32_16x16x32_bf16 v[30:33], v[98:101], v[66:69], v[30:33]
	v_mfma_f32_16x16x32_bf16 v[26:29], v[208:211], v[66:69], v[26:29]
	v_mfma_f32_16x16x32_bf16 v[22:25], v[110:113], v[86:89], v[22:25]
	v_mfma_f32_16x16x32_bf16 v[18:21], v[212:215], v[86:89], v[18:21]
	v_mfma_f32_16x16x32_bf16 v[14:17], v[98:101], v[188:191], v[14:17]
	v_mfma_f32_16x16x32_bf16 v[10:13], v[212:215], v[192:195], v[10:13]
	v_mfma_f32_16x16x32_bf16 v[6:9], v[98:101], v[196:199], v[6:9]
	v_mfma_f32_16x16x32_bf16 v[2:5], v[208:211], v[196:199], v[2:5]
	v_mfma_f32_16x16x32_bf16 v[140:143], v[110:113], v[70:73], v[30:33]
	v_mfma_f32_16x16x32_bf16 v[152:155], v[212:215], v[70:73], v[26:29]
	v_mfma_f32_16x16x32_bf16 v[164:167], v[110:113], v[192:195], v[14:17]
	v_mfma_f32_16x16x32_bf16 v[188:191], v[110:113], v[200:203], v[6:9]
	v_mfma_f32_16x16x32_bf16 v[192:195], v[212:215], v[200:203], v[2:5]
	s_barrier
	s_nop 0
	ds_read_b128 v[2:5], v132 offset:32768
	ds_read_b128 v[6:9], v132 offset:33792
	ds_read_b128 v[14:17], v132 offset:34816
	ds_read_b128 v[196:199], v132 offset:35840
	ds_read_b128 v[26:29], v139 offset:32768
	ds_read_b128 v[30:33], v139 offset:33792
	ds_read_b128 v[42:45], v139 offset:34816
	ds_read_b128 v[46:49], v139 offset:35840
	ds_read_b128 v[58:61], v139 offset:36864
	ds_read_b128 v[66:69], v139 offset:37888
	ds_read_b128 v[200:203], v139 offset:38912
	ds_read_b128 v[208:211], v139 offset:39936
	s_waitcnt vmcnt(2)
	s_barrier
; #define WAIT_V(n) asm volatile("s_waitcnt vmcnt(%0)" ::"n"(n) : "memory")
; #define WAIT_L(n) asm volatile("s_waitcnt lgkmcnt(%0)" ::"n"(n) : "memory")
; #define LDA8(dst, b, h) _Pragma("unroll") for (int m = 0; m < 4; ++m) _Pragma("unroll") for (int k = 0; k < 2; ++k) \
;     dst[m][k] = *(const bf16x8*)(abase + SAo(b, h) + m * 2048 + k * 1024)
; #define LDB8(dst, b, h) _Pragma("unroll") for (int n = 0; n < 2; ++n) _Pragma("unroll") for (int k = 0; k < 2; ++k) \
;     dst[n][k] = *(const bf16x8*)(bbase + SAo(b, h) + n * 2048 + k * 1024)
; #define BAR8 __builtin_amdgcn_s_barrier()
; __device__ __forceinline__ void gemm_main8(const u16* __restrict__ Ab, int lda, const u16* __restrict__ Bb, int ldb, int K,
;                                            char* shm, f32x4 (&acc)[2][2][4][2]) {
;     ...
;   { LDB8(B0, 1, 0); LDA8(At, 1, 0); WAIT_V(2); BAR8; WAIT_L(0); MMA8(0, 0, At, B0); BAR8;
;     LDB8(B1, 1, 1); WAIT_V(0); BAR8; WAIT_L(0); MMA8(0, 1, At, B1); BAR8;
;     LDA8(At, 1, 1); BAR8; WAIT_L(0); MMA8(1, 0, At, B0); MMA8(1, 1, At, B1); BAR8; }
;   if (wr == 0) BAR8;
	s_waitcnt lgkmcnt(0)
	s_waitcnt lgkmcnt(0)
	v_mfma_f32_16x16x32_bf16 v[70:73], v[2:5], v[26:29], v[126:129]
	v_mfma_f32_16x16x32_bf16 v[126:129], v[6:9], v[30:33], v[70:73]
	v_mfma_f32_16x16x32_bf16 v[70:73], v[14:17], v[26:29], v[122:125]
	v_mfma_f32_16x16x32_bf16 v[134:137], v[196:199], v[30:33], v[70:73]
	v_mfma_f32_16x16x32_bf16 v[70:73], v[2:5], v[42:45], v[118:121]
	v_mfma_f32_16x16x32_bf16 v[110:113], v[6:9], v[46:49], v[70:73]
	v_mfma_f32_16x16x32_bf16 v[70:73], v[14:17], v[42:45], v[114:117]
	v_mfma_f32_16x16x32_bf16 v[118:121], v[196:199], v[46:49], v[70:73]
	v_mfma_f32_16x16x32_bf16 v[70:73], v[2:5], v[58:61], v[172:175]
	v_mfma_f32_16x16x32_bf16 v[86:89], v[6:9], v[66:69], v[70:73]
	v_mfma_f32_16x16x32_bf16 v[70:73], v[14:17], v[58:61], v[106:109]
	v_mfma_f32_16x16x32_bf16 v[98:101], v[196:199], v[66:69], v[70:73]
	v_mfma_f32_16x16x32_bf16 v[70:73], v[2:5], v[200:203], v[102:105]
	v_mfma_f32_16x16x32_bf16 v[78:81], v[14:17], v[200:203], v[204:207]
	v_mfma_f32_16x16x32_bf16 v[70:73], v[6:9], v[208:211], v[70:73]
	v_mfma_f32_16x16x32_bf16 v[78:81], v[196:199], v[208:211], v[78:81]
	s_barrier
	ds_read_b128 v[106:109], v132 offset:49152
	ds_read_b128 v[172:175], v132 offset:50176
	ds_read_b128 v[204:207], v132 offset:51200
	ds_read_b128 v[212:215], v132 offset:52224
	s_waitcnt vmcnt(0)
	s_barrier
	s_waitcnt lgkmcnt(0)
	s_waitcnt lgkmcnt(0)
	v_mfma_f32_16x16x32_bf16 v[94:97], v[106:109], v[26:29], v[94:97]
	v_mfma_f32_16x16x32_bf16 v[26:29], v[204:207], v[26:29], v[90:93]
	v_mfma_f32_16x16x32_bf16 v[130:133], v[212:215], v[30:33], v[26:29]
	v_mfma_f32_16x16x32_bf16 v[26:29], v[106:109], v[42:45], v[168:171]
	v_mfma_f32_16x16x32_bf16 v[102:105], v[172:175], v[46:49], v[26:29]
	v_mfma_f32_16x16x32_bf16 v[26:29], v[204:207], v[42:45], v[82:85]
	v_mfma_f32_16x16x32_bf16 v[114:117], v[212:215], v[46:49], v[26:29]
	v_mfma_f32_16x16x32_bf16 v[26:29], v[106:109], v[58:61], v[176:179]
	v_mfma_f32_16x16x32_bf16 v[82:85], v[172:175], v[66:69], v[26:29]
	v_mfma_f32_16x16x32_bf16 v[26:29], v[204:207], v[58:61], v[74:77]
	v_mfma_f32_16x16x32_bf16 v[90:93], v[212:215], v[66:69], v[26:29]
	v_mfma_f32_16x16x32_bf16 v[26:29], v[106:109], v[200:203], v[180:183]
	v_mfma_f32_16x16x32_bf16 v[66:69], v[172:175], v[208:211], v[26:29]
	v_mfma_f32_16x16x32_bf16 v[26:29], v[204:207], v[200:203], v[184:187]
	v_mfma_f32_16x16x32_bf16 v[122:125], v[172:175], v[30:33], v[94:97]
	v_mfma_f32_16x16x32_bf16 v[74:77], v[212:215], v[208:211], v[26:29]
	s_barrier
	ds_read_b128 v[94:97], v139 offset:49152
	ds_read_b128 v[168:171], v139 offset:50176
	ds_read_b128 v[176:179], v139 offset:51200
	ds_read_b128 v[180:183], v139 offset:52224
	ds_read_b128 v[184:187], v139 offset:53248
	ds_read_b128 v[200:203], v139 offset:54272
	ds_read_b128 v[208:211], v139 offset:55296
	ds_read_b128 v[228:231], v139 offset:56320
	s_barrier
	s_waitcnt lgkmcnt(0)
	s_waitcnt lgkmcnt(0)
	v_mfma_f32_16x16x32_bf16 v[26:29], v[2:5], v[94:97], v[62:65]
	v_mfma_f32_16x16x32_bf16 v[58:61], v[6:9], v[168:171], v[26:29]
	v_mfma_f32_16x16x32_bf16 v[26:29], v[14:17], v[94:97], v[216:219]
	v_mfma_f32_16x16x32_bf16 v[62:65], v[196:199], v[168:171], v[26:29]
	v_mfma_f32_16x16x32_bf16 v[26:29], v[2:5], v[176:179], v[54:57]
	v_mfma_f32_16x16x32_bf16 v[42:45], v[6:9], v[180:183], v[26:29]
	v_mfma_f32_16x16x32_bf16 v[26:29], v[14:17], v[176:179], v[50:53]
	v_mfma_f32_16x16x32_bf16 v[46:49], v[196:199], v[180:183], v[26:29]
	v_mfma_f32_16x16x32_bf16 v[26:29], v[2:5], v[184:187], v[220:223]
	v_mfma_f32_16x16x32_bf16 v[2:5], v[2:5], v[208:211], v[38:41]
	v_mfma_f32_16x16x32_bf16 v[26:29], v[6:9], v[200:203], v[26:29]
	v_mfma_f32_16x16x32_bf16 v[30:33], v[14:17], v[184:187], v[224:227]
	v_mfma_f32_16x16x32_bf16 v[6:9], v[6:9], v[228:231], v[2:5]
	v_mfma_f32_16x16x32_bf16 v[2:5], v[14:17], v[208:211], v[34:37]
	v_mfma_f32_16x16x32_bf16 v[30:33], v[196:199], v[200:203], v[30:33]
	v_mfma_f32_16x16x32_bf16 v[14:17], v[196:199], v[228:231], v[2:5]
	v_mfma_f32_16x16x32_bf16 v[2:5], v[106:109], v[94:97], v[140:143]
	v_mfma_f32_16x16x32_bf16 v[50:53], v[172:175], v[168:171], v[2:5]
	v_mfma_f32_16x16x32_bf16 v[2:5], v[204:207], v[94:97], v[152:155]
	v_mfma_f32_16x16x32_bf16 v[54:57], v[212:215], v[168:171], v[2:5]
	v_mfma_f32_16x16x32_bf16 v[2:5], v[106:109], v[176:179], v[22:25]
	v_mfma_f32_16x16x32_bf16 v[34:37], v[172:175], v[180:183], v[2:5]
	v_mfma_f32_16x16x32_bf16 v[2:5], v[204:207], v[176:179], v[18:21]
	v_mfma_f32_16x16x32_bf16 v[38:41], v[212:215], v[180:183], v[2:5]
	v_mfma_f32_16x16x32_bf16 v[2:5], v[106:109], v[184:187], v[164:167]
	v_mfma_f32_16x16x32_bf16 v[18:21], v[172:175], v[200:203], v[2:5]
	v_mfma_f32_16x16x32_bf16 v[2:5], v[204:207], v[184:187], v[10:13]
	v_mfma_f32_16x16x32_bf16 v[22:25], v[212:215], v[200:203], v[2:5]
	v_mfma_f32_16x16x32_bf16 v[2:5], v[106:109], v[208:211], v[188:191]
	v_mfma_f32_16x16x32_bf16 v[10:13], v[204:207], v[208:211], v[192:195]
	v_mfma_f32_16x16x32_bf16 v[2:5], v[172:175], v[228:231], v[2:5]
	v_mfma_f32_16x16x32_bf16 v[10:13], v[212:215], v[228:231], v[10:13]
	v_cmp_gt_u32_e32 vcc, s97, v138
	s_barrier
	s_and_saveexec_b64 s[18:19], vcc
	s_cbranch_execz .LBB0_552
	s_barrier
	s_branch .LBB0_552

; #define WAIT_V(n) asm volatile("s_waitcnt vmcnt(%0)" ::"n"(n) : "memory")
; #define WAIT_L(n) asm volatile("s_waitcnt lgkmcnt(%0)" ::"n"(n) : "memory")
; #define SBAR() __builtin_amdgcn_sched_barrier(0)
; #define LDA8(dst, b, h) _Pragma("unroll") for (int m = 0; m < 4; ++m) _Pragma("unroll") for (int k = 0; k < 2; ++k) \
;     dst[m][k] = *(const bf16x8*)(abase + SAo(b, h) + m * 2048 + k * 1024)
; #define LDB8(dst, b, h) _Pragma("unroll") for (int n = 0; n < 2; ++n) _Pragma("unroll") for (int k = 0; k < 2; ++k) \
;     dst[n][k] = *(const bf16x8*)(bbase + SAo(b, h) + n * 2048 + k * 1024)
; #define BAR8 __builtin_amdgcn_s_barrier()
; __device__ __forceinline__ void gemm_main8(const u16* __restrict__ Ab, int lda, const u16* __restrict__ Bb, int ldb, int K,
;                                            char* shm, f32x4 (&acc)[2][2][4][2]) {
;     ...
;     LDB8(B0, 0, 0); SBAR(); LDA8(At, 0, 0); STG_A(1, 1, t + 1);
;     WAIT_L(8); BAR8; WAIT_L(0); MMA8(0, 0, At, B0); BAR8; SBAR();
;     LDB8(B1, 0, 1); STG_B(0, 0, t + 2);
;     BAR8; WAIT_L(0); MMA8(0, 1, At, B1); BAR8;
;     LDA8(At, 0, 1); STG_A(0, 0, t + 2);
;     BAR8; WAIT_L(0); MMA8(1, 0, At, B0); BAR8; SBAR();
;     STG_B(0, 1, t + 2);
;     WAIT_V(6); BAR8; MMA8(1, 1, At, B1); BAR8;
.LBB0_605:
	ds_read_b128 v[178:181], v140
	ds_read_b128 v[182:185], v140 offset:1024
	ds_read_b128 v[186:189], v140 offset:2048
	ds_read_b128 v[190:193], v140 offset:3072
	v_add_u32_e32 v176, 0xc000, v141
	v_lshl_add_u64 v[152:153], v[134:135], 0, s[24:25]
	s_mov_b64 s[88:89], 0x10220080
	v_readfirstlane_b32 s11, v176
	v_add_u32_e32 v177, 0xe000, v141
	v_lshl_add_u64 v[154:155], v[152:153], 0, s[88:89]
	s_mov_b32 m0, s11
	s_mov_b64 s[88:89], 0x10230080
	v_readfirstlane_b32 s11, v177
	ds_read_b128 v[194:197], v0
	ds_read_b128 v[198:201], v0 offset:1024
	ds_read_b128 v[202:205], v0 offset:2048
	ds_read_b128 v[206:209], v0 offset:3072
	ds_read_b128 v[210:213], v0 offset:4096
	ds_read_b128 v[214:217], v0 offset:5120
	ds_read_b128 v[218:221], v0 offset:6144
	ds_read_b128 v[222:225], v0 offset:7168
	global_load_lds_dwordx4 v[154:155], off
	v_lshl_add_u64 v[154:155], v[152:153], 0, s[88:89]
	s_mov_b32 m0, s11
	s_nop 0
	global_load_lds_dwordx4 v[154:155], off
	s_waitcnt lgkmcnt(8)
	s_barrier
	s_waitcnt lgkmcnt(0)
	s_waitcnt lgkmcnt(0)
	v_mfma_f32_16x16x32_bf16 v[126:129], v[178:181], v[194:197], v[126:129]
	v_mfma_f32_16x16x32_bf16 v[122:125], v[186:189], v[194:197], v[122:125]
	v_mfma_f32_16x16x32_bf16 v[118:121], v[178:181], v[202:205], v[118:121]
	v_mfma_f32_16x16x32_bf16 v[114:117], v[186:189], v[202:205], v[114:117]
	v_mfma_f32_16x16x32_bf16 v[110:113], v[178:181], v[210:213], v[110:113]
	v_mfma_f32_16x16x32_bf16 v[106:109], v[186:189], v[210:213], v[106:109]
	v_mfma_f32_16x16x32_bf16 v[102:105], v[178:181], v[218:221], v[102:105]
	v_mfma_f32_16x16x32_bf16 v[98:101], v[186:189], v[218:221], v[98:101]
	v_mfma_f32_16x16x32_bf16 v[126:129], v[182:185], v[198:201], v[126:129]
	v_mfma_f32_16x16x32_bf16 v[122:125], v[190:193], v[198:201], v[122:125]
	v_mfma_f32_16x16x32_bf16 v[118:121], v[182:185], v[206:209], v[118:121]
	v_mfma_f32_16x16x32_bf16 v[114:117], v[190:193], v[206:209], v[114:117]
	v_mfma_f32_16x16x32_bf16 v[110:113], v[182:185], v[214:217], v[110:113]
	v_mfma_f32_16x16x32_bf16 v[106:109], v[190:193], v[214:217], v[106:109]
	v_mfma_f32_16x16x32_bf16 v[102:105], v[182:185], v[222:225], v[102:105]
	v_mfma_f32_16x16x32_bf16 v[98:101], v[190:193], v[222:225], v[98:101]
	s_barrier
	v_lshl_add_u64 v[154:155], v[132:133], 0, s[24:25]
	v_readfirstlane_b32 s11, v142
	v_lshl_add_u64 v[164:165], v[154:155], 0, s[58:59]
	s_mov_b32 m0, s11
	v_readfirstlane_b32 s11, v143
	ds_read_b128 v[226:229], v140 offset:16384
	ds_read_b128 v[230:233], v140 offset:17408
	ds_read_b128 v[234:237], v140 offset:18432
	ds_read_b128 v[238:241], v140 offset:19456
	global_load_lds_dwordx4 v[164:165], off
	v_lshl_add_u64 v[164:165], v[154:155], 0, s[60:61]
	s_mov_b32 m0, s11
	s_nop 0
	global_load_lds_dwordx4 v[164:165], off
	s_barrier
	s_waitcnt lgkmcnt(0)
	s_waitcnt lgkmcnt(0)
	v_mfma_f32_16x16x32_bf16 v[94:97], v[226:229], v[194:197], v[94:97]
	v_mfma_f32_16x16x32_bf16 v[90:93], v[234:237], v[194:197], v[90:93]
	v_mfma_f32_16x16x32_bf16 v[86:89], v[226:229], v[202:205], v[86:89]
	v_mfma_f32_16x16x32_bf16 v[82:85], v[234:237], v[202:205], v[82:85]
	v_mfma_f32_16x16x32_bf16 v[78:81], v[226:229], v[210:213], v[78:81]
	v_mfma_f32_16x16x32_bf16 v[74:77], v[234:237], v[210:213], v[74:77]
	v_mfma_f32_16x16x32_bf16 v[70:73], v[226:229], v[218:221], v[70:73]
	v_mfma_f32_16x16x32_bf16 v[66:69], v[234:237], v[218:221], v[66:69]
	v_mfma_f32_16x16x32_bf16 v[94:97], v[230:233], v[198:201], v[94:97]
	v_mfma_f32_16x16x32_bf16 v[90:93], v[238:241], v[198:201], v[90:93]
	v_mfma_f32_16x16x32_bf16 v[86:89], v[230:233], v[206:209], v[86:89]
	v_mfma_f32_16x16x32_bf16 v[82:85], v[238:241], v[206:209], v[82:85]
	v_mfma_f32_16x16x32_bf16 v[78:81], v[230:233], v[214:217], v[78:81]
	v_mfma_f32_16x16x32_bf16 v[74:77], v[238:241], v[214:217], v[74:77]
	v_mfma_f32_16x16x32_bf16 v[70:73], v[230:233], v[222:225], v[70:73]
	v_mfma_f32_16x16x32_bf16 v[66:69], v[238:241], v[222:225], v[66:69]
	s_mov_b64 s[88:89], 0x10200100
	v_readfirstlane_b32 s11, v141
	v_lshl_add_u64 v[164:165], v[152:153], 0, s[88:89]
	s_mov_b32 m0, s11
	s_mov_b64 s[88:89], 0x10210100
	v_readfirstlane_b32 s11, v144
	s_barrier
	ds_read_b128 v[194:197], v0 offset:16384
	ds_read_b128 v[198:201], v0 offset:17408
	ds_read_b128 v[202:205], v0 offset:18432
	ds_read_b128 v[206:209], v0 offset:19456
	ds_read_b128 v[210:213], v0 offset:20480
	ds_read_b128 v[214:217], v0 offset:21504
	ds_read_b128 v[218:221], v0 offset:22528
	ds_read_b128 v[222:225], v0 offset:23552
	global_load_lds_dwordx4 v[164:165], off
	v_lshl_add_u64 v[164:165], v[152:153], 0, s[88:89]
	s_mov_b32 m0, s11
	s_nop 0
	global_load_lds_dwordx4 v[164:165], off
	s_barrier
	s_waitcnt lgkmcnt(0)
	s_waitcnt lgkmcnt(0)
	v_mfma_f32_16x16x32_bf16 v[62:65], v[178:181], v[194:197], v[62:65]
	v_mfma_f32_16x16x32_bf16 v[58:61], v[186:189], v[194:197], v[58:61]
	v_mfma_f32_16x16x32_bf16 v[54:57], v[178:181], v[202:205], v[54:57]
	v_mfma_f32_16x16x32_bf16 v[50:53], v[186:189], v[202:205], v[50:53]
	v_mfma_f32_16x16x32_bf16 v[46:49], v[178:181], v[210:213], v[46:49]
	v_mfma_f32_16x16x32_bf16 v[42:45], v[186:189], v[210:213], v[42:45]
	v_mfma_f32_16x16x32_bf16 v[38:41], v[178:181], v[218:221], v[38:41]
	v_mfma_f32_16x16x32_bf16 v[34:37], v[186:189], v[218:221], v[34:37]
	v_mfma_f32_16x16x32_bf16 v[62:65], v[182:185], v[198:201], v[62:65]
	v_mfma_f32_16x16x32_bf16 v[58:61], v[190:193], v[198:201], v[58:61]
	v_mfma_f32_16x16x32_bf16 v[54:57], v[182:185], v[206:209], v[54:57]
	v_mfma_f32_16x16x32_bf16 v[50:53], v[190:193], v[206:209], v[50:53]
	v_mfma_f32_16x16x32_bf16 v[46:49], v[182:185], v[214:217], v[46:49]
	v_mfma_f32_16x16x32_bf16 v[42:45], v[190:193], v[214:217], v[42:45]
	v_mfma_f32_16x16x32_bf16 v[38:41], v[182:185], v[222:225], v[38:41]
	v_mfma_f32_16x16x32_bf16 v[34:37], v[190:193], v[222:225], v[34:37]
	s_barrier
; #define WAIT_V(n) asm volatile("s_waitcnt vmcnt(%0)" ::"n"(n) : "memory")
; #define WAIT_L(n) asm volatile("s_waitcnt lgkmcnt(%0)" ::"n"(n) : "memory")
; #define SBAR() __builtin_amdgcn_sched_barrier(0)
; #define LDA8(dst, b, h) _Pragma("unroll") for (int m = 0; m < 4; ++m) _Pragma("unroll") for (int k = 0; k < 2; ++k) \
;     dst[m][k] = *(const bf16x8*)(abase + SAo(b, h) + m * 2048 + k * 1024)
; #define LDB8(dst, b, h) _Pragma("unroll") for (int n = 0; n < 2; ++n) _Pragma("unroll") for (int k = 0; k < 2; ++k) \
;     dst[n][k] = *(const bf16x8*)(bbase + SAo(b, h) + n * 2048 + k * 1024)
; #define BAR8 __builtin_amdgcn_s_barrier()
; __device__ __forceinline__ void gemm_main8(const u16* __restrict__ Ab, int lda, const u16* __restrict__ Bb, int ldb, int K,
;                                            char* shm, f32x4 (&acc)[2][2][4][2]) {
;     ...
;     STG_B(0, 1, t + 2);
;     WAIT_V(6); BAR8; MMA8(1, 1, At, B1); BAR8;
;     LDB8(B0, 1, 0); SBAR(); LDA8(At, 1, 0); STG_A(0, 1, t + 2);
;     WAIT_L(8); BAR8; WAIT_L(0); MMA8(0, 0, At, B0); BAR8; SBAR();
;     LDB8(B1, 1, 1); STG_B(1, 0, t + 3);
;     BAR8; WAIT_L(0); MMA8(0, 1, At, B1); BAR8;
;     LDA8(At, 1, 1); STG_A(1, 0, t + 3);
	v_readfirstlane_b32 s11, v145
	v_lshl_add_u64 v[164:165], v[154:155], 0, s[62:63]
	s_mov_b32 m0, s11
	v_readfirstlane_b32 s11, v146
	global_load_lds_dwordx4 v[164:165], off
	v_lshl_add_u64 v[164:165], v[154:155], 0, s[64:65]
	s_mov_b32 m0, s11
	s_nop 0
	global_load_lds_dwordx4 v[164:165], off
	s_waitcnt vmcnt(6)
	s_barrier
	v_mfma_f32_16x16x32_bf16 v[30:33], v[226:229], v[194:197], v[30:33]
	v_mfma_f32_16x16x32_bf16 v[26:29], v[234:237], v[194:197], v[26:29]
	v_mfma_f32_16x16x32_bf16 v[22:25], v[226:229], v[202:205], v[22:25]
	v_mfma_f32_16x16x32_bf16 v[18:21], v[234:237], v[202:205], v[18:21]
	v_mfma_f32_16x16x32_bf16 v[14:17], v[226:229], v[210:213], v[14:17]
	v_mfma_f32_16x16x32_bf16 v[10:13], v[234:237], v[210:213], v[10:13]
	v_mfma_f32_16x16x32_bf16 v[6:9], v[226:229], v[218:221], v[6:9]
	v_mfma_f32_16x16x32_bf16 v[2:5], v[234:237], v[218:221], v[2:5]
	v_mfma_f32_16x16x32_bf16 v[30:33], v[230:233], v[198:201], v[30:33]
	v_mfma_f32_16x16x32_bf16 v[26:29], v[238:241], v[198:201], v[26:29]
	v_mfma_f32_16x16x32_bf16 v[22:25], v[230:233], v[206:209], v[22:25]
	v_mfma_f32_16x16x32_bf16 v[18:21], v[238:241], v[206:209], v[18:21]
	v_mfma_f32_16x16x32_bf16 v[14:17], v[230:233], v[214:217], v[14:17]
	v_mfma_f32_16x16x32_bf16 v[10:13], v[238:241], v[214:217], v[10:13]
	v_mfma_f32_16x16x32_bf16 v[6:9], v[230:233], v[222:225], v[6:9]
	v_mfma_f32_16x16x32_bf16 v[2:5], v[238:241], v[222:225], v[2:5]
	s_barrier
	ds_read_b128 v[178:181], v140 offset:32768
	ds_read_b128 v[182:185], v140 offset:33792
	ds_read_b128 v[186:189], v140 offset:34816
	ds_read_b128 v[190:193], v140 offset:35840
	s_mov_b64 s[88:89], 0x10220100
	v_readfirstlane_b32 s11, v147
	v_lshl_add_u64 v[164:165], v[152:153], 0, s[88:89]
	s_mov_b32 m0, s11
	s_mov_b64 s[88:89], 0x10230100
	v_readfirstlane_b32 s11, v148
	ds_read_b128 v[194:197], v0 offset:32768
	ds_read_b128 v[198:201], v0 offset:33792
	ds_read_b128 v[202:205], v0 offset:34816
	ds_read_b128 v[206:209], v0 offset:35840
	ds_read_b128 v[210:213], v0 offset:36864
	ds_read_b128 v[214:217], v0 offset:37888
	ds_read_b128 v[218:221], v0 offset:38912
	ds_read_b128 v[222:225], v0 offset:39936
	global_load_lds_dwordx4 v[164:165], off
	v_lshl_add_u64 v[164:165], v[152:153], 0, s[88:89]
	s_mov_b32 m0, s11
	s_nop 0
	global_load_lds_dwordx4 v[164:165], off
	s_waitcnt lgkmcnt(8)
	s_barrier
	s_waitcnt lgkmcnt(0)
	s_waitcnt lgkmcnt(0)
	v_mfma_f32_16x16x32_bf16 v[126:129], v[178:181], v[194:197], v[126:129]
	v_mfma_f32_16x16x32_bf16 v[122:125], v[186:189], v[194:197], v[122:125]
	v_mfma_f32_16x16x32_bf16 v[118:121], v[178:181], v[202:205], v[118:121]
	v_mfma_f32_16x16x32_bf16 v[114:117], v[186:189], v[202:205], v[114:117]
	v_mfma_f32_16x16x32_bf16 v[110:113], v[178:181], v[210:213], v[110:113]
	v_mfma_f32_16x16x32_bf16 v[106:109], v[186:189], v[210:213], v[106:109]
	v_mfma_f32_16x16x32_bf16 v[102:105], v[178:181], v[218:221], v[102:105]
	v_mfma_f32_16x16x32_bf16 v[98:101], v[186:189], v[218:221], v[98:101]
	v_mfma_f32_16x16x32_bf16 v[126:129], v[182:185], v[198:201], v[126:129]
	v_mfma_f32_16x16x32_bf16 v[122:125], v[190:193], v[198:201], v[122:125]
	v_mfma_f32_16x16x32_bf16 v[118:121], v[182:185], v[206:209], v[118:121]
	v_mfma_f32_16x16x32_bf16 v[114:117], v[190:193], v[206:209], v[114:117]
	v_mfma_f32_16x16x32_bf16 v[110:113], v[182:185], v[214:217], v[110:113]
	v_mfma_f32_16x16x32_bf16 v[106:109], v[190:193], v[214:217], v[106:109]
	v_mfma_f32_16x16x32_bf16 v[102:105], v[182:185], v[222:225], v[102:105]
	v_mfma_f32_16x16x32_bf16 v[98:101], v[190:193], v[222:225], v[98:101]
	s_barrier
	v_readfirstlane_b32 s11, v149
	v_lshl_add_u64 v[164:165], v[154:155], 0, s[66:67]
	s_mov_b32 m0, s11
	v_readfirstlane_b32 s11, v171
	ds_read_b128 v[226:229], v140 offset:49152
	ds_read_b128 v[230:233], v140 offset:50176
	ds_read_b128 v[234:237], v140 offset:51200
	ds_read_b128 v[238:241], v140 offset:52224
	global_load_lds_dwordx4 v[164:165], off
	v_lshl_add_u64 v[164:165], v[154:155], 0, s[68:69]
	s_mov_b32 m0, s11
	s_nop 0
	global_load_lds_dwordx4 v[164:165], off
	s_barrier
	s_waitcnt lgkmcnt(0)
	s_waitcnt lgkmcnt(0)
	v_mfma_f32_16x16x32_bf16 v[94:97], v[226:229], v[194:197], v[94:97]
	v_mfma_f32_16x16x32_bf16 v[90:93], v[234:237], v[194:197], v[90:93]
	v_mfma_f32_16x16x32_bf16 v[86:89], v[226:229], v[202:205], v[86:89]
	v_mfma_f32_16x16x32_bf16 v[82:85], v[234:237], v[202:205], v[82:85]
	v_mfma_f32_16x16x32_bf16 v[78:81], v[226:229], v[210:213], v[78:81]
	v_mfma_f32_16x16x32_bf16 v[74:77], v[234:237], v[210:213], v[74:77]
	v_mfma_f32_16x16x32_bf16 v[70:73], v[226:229], v[218:221], v[70:73]
	v_mfma_f32_16x16x32_bf16 v[66:69], v[234:237], v[218:221], v[66:69]
	v_mfma_f32_16x16x32_bf16 v[94:97], v[230:233], v[198:201], v[94:97]
	v_mfma_f32_16x16x32_bf16 v[90:93], v[238:241], v[198:201], v[90:93]
	v_mfma_f32_16x16x32_bf16 v[86:89], v[230:233], v[206:209], v[86:89]
	v_mfma_f32_16x16x32_bf16 v[82:85], v[238:241], v[206:209], v[82:85]
	v_mfma_f32_16x16x32_bf16 v[78:81], v[230:233], v[214:217], v[78:81]
	v_mfma_f32_16x16x32_bf16 v[74:77], v[238:241], v[214:217], v[74:77]
	v_mfma_f32_16x16x32_bf16 v[70:73], v[230:233], v[222:225], v[70:73]
	v_mfma_f32_16x16x32_bf16 v[66:69], v[238:241], v[222:225], v[66:69]
	s_mov_b64 s[88:89], 0x10200180
	v_readfirstlane_b32 s11, v172
	v_lshl_add_u64 v[164:165], v[152:153], 0, s[88:89]
	s_mov_b32 m0, s11
	s_mov_b64 s[88:89], 0x10210180
	v_readfirstlane_b32 s11, v173
	s_barrier
; #define WAIT_V(n) asm volatile("s_waitcnt vmcnt(%0)" ::"n"(n) : "memory")
; #define WAIT_L(n) asm volatile("s_waitcnt lgkmcnt(%0)" ::"n"(n) : "memory")
; #define SBAR() __builtin_amdgcn_sched_barrier(0)
; #define LDA8(dst, b, h) _Pragma("unroll") for (int m = 0; m < 4; ++m) _Pragma("unroll") for (int k = 0; k < 2; ++k) \
;     dst[m][k] = *(const bf16x8*)(abase + SAo(b, h) + m * 2048 + k * 1024)
; #define LDB8(dst, b, h) _Pragma("unroll") for (int n = 0; n < 2; ++n) _Pragma("unroll") for (int k = 0; k < 2; ++k) \
;     dst[n][k] = *(const bf16x8*)(bbase + SAo(b, h) + n * 2048 + k * 1024)
; #define BAR8 __builtin_amdgcn_s_barrier()
; __device__ __forceinline__ void gemm_main8(const u16* __restrict__ Ab, int lda, const u16* __restrict__ Bb, int ldb, int K,
;                                            char* shm, f32x4 (&acc)[2][2][4][2]) {
;     ...
;     LDB8(B1, 1, 1); STG_B(1, 0, t + 3);
;     BAR8; WAIT_L(0); MMA8(0, 1, At, B1); BAR8;
;     LDA8(At, 1, 1); STG_A(1, 0, t + 3);
;     BAR8; WAIT_L(0); MMA8(1, 0, At, B0); BAR8; SBAR();
;     STG_B(1, 1, t + 3);
;     WAIT_V(6); BAR8; MMA8(1, 1, At, B1); BAR8;
;   }
;   { LDB8(B0, 0, 0); LDA8(At, 0, 0); STG_A(1, 1, nt - 1);
;     BAR8; WAIT_L(0); MMA8(0, 0, At, B0); BAR8;
	ds_read_b128 v[194:197], v0 offset:49152
	ds_read_b128 v[198:201], v0 offset:50176
	ds_read_b128 v[202:205], v0 offset:51200
	ds_read_b128 v[206:209], v0 offset:52224
	ds_read_b128 v[210:213], v0 offset:53248
	ds_read_b128 v[214:217], v0 offset:54272
	ds_read_b128 v[218:221], v0 offset:55296
	ds_read_b128 v[222:225], v0 offset:56320
	global_load_lds_dwordx4 v[164:165], off
	v_lshl_add_u64 v[152:153], v[152:153], 0, s[88:89]
	s_mov_b32 m0, s11
	s_nop 0
	global_load_lds_dwordx4 v[152:153], off
	s_barrier
	s_waitcnt lgkmcnt(0)
	s_waitcnt lgkmcnt(0)
	v_mfma_f32_16x16x32_bf16 v[62:65], v[178:181], v[194:197], v[62:65]
	v_mfma_f32_16x16x32_bf16 v[58:61], v[186:189], v[194:197], v[58:61]
	v_mfma_f32_16x16x32_bf16 v[54:57], v[178:181], v[202:205], v[54:57]
	v_mfma_f32_16x16x32_bf16 v[50:53], v[186:189], v[202:205], v[50:53]
	v_mfma_f32_16x16x32_bf16 v[46:49], v[178:181], v[210:213], v[46:49]
	v_mfma_f32_16x16x32_bf16 v[42:45], v[186:189], v[210:213], v[42:45]
	v_mfma_f32_16x16x32_bf16 v[38:41], v[178:181], v[218:221], v[38:41]
	v_mfma_f32_16x16x32_bf16 v[34:37], v[186:189], v[218:221], v[34:37]
	v_mfma_f32_16x16x32_bf16 v[62:65], v[182:185], v[198:201], v[62:65]
	v_mfma_f32_16x16x32_bf16 v[58:61], v[190:193], v[198:201], v[58:61]
	v_mfma_f32_16x16x32_bf16 v[54:57], v[182:185], v[206:209], v[54:57]
	v_mfma_f32_16x16x32_bf16 v[50:53], v[190:193], v[206:209], v[50:53]
	v_mfma_f32_16x16x32_bf16 v[46:49], v[182:185], v[214:217], v[46:49]
	v_mfma_f32_16x16x32_bf16 v[42:45], v[190:193], v[214:217], v[42:45]
	v_mfma_f32_16x16x32_bf16 v[38:41], v[182:185], v[222:225], v[38:41]
	v_mfma_f32_16x16x32_bf16 v[34:37], v[190:193], v[222:225], v[34:37]
	s_barrier
	s_mov_b64 s[88:89], 0x13380180
	v_readfirstlane_b32 s11, v174
	v_lshl_add_u64 v[152:153], v[154:155], 0, s[88:89]
	s_mov_b32 m0, s11
	s_mov_b64 s[88:89], 0x133c0180
	v_readfirstlane_b32 s11, v175
	global_load_lds_dwordx4 v[152:153], off
	v_lshl_add_u64 v[152:153], v[154:155], 0, s[88:89]
	s_mov_b32 m0, s11
	s_nop 0
	global_load_lds_dwordx4 v[152:153], off
	s_waitcnt vmcnt(6)
	s_barrier
	v_mfma_f32_16x16x32_bf16 v[30:33], v[226:229], v[194:197], v[30:33]
	v_mfma_f32_16x16x32_bf16 v[26:29], v[234:237], v[194:197], v[26:29]
	v_mfma_f32_16x16x32_bf16 v[22:25], v[226:229], v[202:205], v[22:25]
	v_mfma_f32_16x16x32_bf16 v[18:21], v[234:237], v[202:205], v[18:21]
	v_mfma_f32_16x16x32_bf16 v[14:17], v[226:229], v[210:213], v[14:17]
	v_mfma_f32_16x16x32_bf16 v[10:13], v[234:237], v[210:213], v[10:13]
	v_mfma_f32_16x16x32_bf16 v[6:9], v[226:229], v[218:221], v[6:9]
	v_mfma_f32_16x16x32_bf16 v[2:5], v[234:237], v[218:221], v[2:5]
	v_mfma_f32_16x16x32_bf16 v[30:33], v[230:233], v[198:201], v[30:33]
	v_mfma_f32_16x16x32_bf16 v[26:29], v[238:241], v[198:201], v[26:29]
	v_mfma_f32_16x16x32_bf16 v[22:25], v[230:233], v[206:209], v[22:25]
	v_mfma_f32_16x16x32_bf16 v[18:21], v[238:241], v[206:209], v[18:21]
	v_mfma_f32_16x16x32_bf16 v[14:17], v[230:233], v[214:217], v[14:17]
	v_mfma_f32_16x16x32_bf16 v[10:13], v[238:241], v[214:217], v[10:13]
	v_mfma_f32_16x16x32_bf16 v[6:9], v[230:233], v[222:225], v[6:9]
	v_mfma_f32_16x16x32_bf16 v[2:5], v[238:241], v[222:225], v[2:5]
	s_add_i32 s10, s10, 2
	s_add_u32 s24, s24, 0x100
	s_addc_u32 s25, s25, 0
	s_cmp_lt_u32 s10, 4
	s_barrier
	s_cbranch_scc1 .LBB0_605
	s_mov_b64 s[10:11], 0x20380
	v_lshl_add_u64 v[152:153], v[130:131], 0, s[10:11]
	v_readfirstlane_b32 s10, v176
	s_mov_b32 m0, s10
	s_mov_b64 s[10:11], 0x30380
	v_lshl_add_u64 v[130:131], v[130:131], 0, s[10:11]
	v_readfirstlane_b32 s10, v177
	ds_read_b128 v[132:135], v140
	ds_read_b128 v[142:145], v140 offset:1024
	ds_read_b128 v[146:149], v140 offset:2048
	ds_read_b128 v[172:175], v140 offset:3072
	ds_read_b128 v[178:181], v0
	ds_read_b128 v[182:185], v0 offset:1024
	ds_read_b128 v[186:189], v0 offset:2048
	ds_read_b128 v[190:193], v0 offset:3072
	ds_read_b128 v[194:197], v0 offset:4096
	ds_read_b128 v[198:201], v0 offset:5120
	ds_read_b128 v[202:205], v0 offset:6144
	ds_read_b128 v[206:209], v0 offset:7168
	global_load_lds_dwordx4 v[152:153], off
	s_mov_b32 m0, s10
	s_nop 0
	global_load_lds_dwordx4 v[130:131], off
	s_barrier
	s_waitcnt lgkmcnt(0)
	s_waitcnt lgkmcnt(0)
	v_mfma_f32_16x16x32_bf16 v[126:129], v[132:135], v[178:181], v[126:129]
	v_mfma_f32_16x16x32_bf16 v[122:125], v[146:149], v[178:181], v[122:125]
	v_mfma_f32_16x16x32_bf16 v[114:117], v[146:149], v[186:189], v[114:117]
	v_mfma_f32_16x16x32_bf16 v[106:109], v[146:149], v[194:197], v[106:109]
	v_mfma_f32_16x16x32_bf16 v[98:101], v[146:149], v[202:205], v[98:101]
	v_mfma_f32_16x16x32_bf16 v[126:129], v[142:145], v[182:185], v[126:129]
	v_mfma_f32_16x16x32_bf16 v[122:125], v[172:175], v[182:185], v[122:125]
	v_mfma_f32_16x16x32_bf16 v[118:121], v[132:135], v[186:189], v[118:121]
	v_mfma_f32_16x16x32_bf16 v[114:117], v[172:175], v[190:193], v[114:117]
	v_mfma_f32_16x16x32_bf16 v[110:113], v[132:135], v[194:197], v[110:113]
	v_mfma_f32_16x16x32_bf16 v[106:109], v[172:175], v[198:201], v[106:109]
	v_mfma_f32_16x16x32_bf16 v[102:105], v[132:135], v[202:205], v[102:105]
	v_mfma_f32_16x16x32_bf16 v[98:101], v[172:175], v[206:209], v[98:101]
	v_mfma_f32_16x16x32_bf16 v[210:213], v[142:145], v[190:193], v[118:121]
	v_mfma_f32_16x16x32_bf16 v[214:217], v[142:145], v[198:201], v[110:113]
	v_mfma_f32_16x16x32_bf16 v[218:221], v[142:145], v[206:209], v[102:105]
	s_barrier
	s_nop 1
	ds_read_b128 v[102:105], v140 offset:16384
	ds_read_b128 v[110:113], v140 offset:17408
	ds_read_b128 v[118:121], v140 offset:18432
	ds_read_b128 v[222:225], v140 offset:19456
	s_barrier
; #define WAIT_V(n) asm volatile("s_waitcnt vmcnt(%0)" ::"n"(n) : "memory")
; #define WAIT_L(n) asm volatile("s_waitcnt lgkmcnt(%0)" ::"n"(n) : "memory")
; #define LDA8(dst, b, h) _Pragma("unroll") for (int m = 0; m < 4; ++m) _Pragma("unroll") for (int k = 0; k < 2; ++k) \
;     dst[m][k] = *(const bf16x8*)(abase + SAo(b, h) + m * 2048 + k * 1024)
; #define LDB8(dst, b, h) _Pragma("unroll") for (int n = 0; n < 2; ++n) _Pragma("unroll") for (int k = 0; k < 2; ++k) \
;     dst[n][k] = *(const bf16x8*)(bbase + SAo(b, h) + n * 2048 + k * 1024)
; #define BAR8 __builtin_amdgcn_s_barrier()
; __device__ __forceinline__ void gemm_main8(const u16* __restrict__ Ab, int lda, const u16* __restrict__ Bb, int ldb, int K,
;                                            char* shm, f32x4 (&acc)[2][2][4][2]) {
;     ...
;     LDB8(B1, 0, 1); BAR8; WAIT_L(0); MMA8(0, 1, At, B1); BAR8;
;     LDA8(At, 0, 1); WAIT_V(4); BAR8; WAIT_L(0); MMA8(1, 0, At, B0); MMA8(1, 1, At, B1); BAR8; }
;   { LDB8(B0, 1, 0); LDA8(At, 1, 0); WAIT_V(2); BAR8; WAIT_L(0); MMA8(0, 0, At, B0); BAR8;
	s_waitcnt lgkmcnt(0)
	s_waitcnt lgkmcnt(0)
	v_mfma_f32_16x16x32_bf16 v[90:93], v[118:121], v[178:181], v[90:93]
	v_mfma_f32_16x16x32_bf16 v[82:85], v[118:121], v[186:189], v[82:85]
	v_mfma_f32_16x16x32_bf16 v[74:77], v[118:121], v[194:197], v[74:77]
	v_mfma_f32_16x16x32_bf16 v[66:69], v[118:121], v[202:205], v[66:69]
	v_mfma_f32_16x16x32_bf16 v[94:97], v[102:105], v[178:181], v[94:97]
	v_mfma_f32_16x16x32_bf16 v[90:93], v[222:225], v[182:185], v[90:93]
	v_mfma_f32_16x16x32_bf16 v[86:89], v[102:105], v[186:189], v[86:89]
	v_mfma_f32_16x16x32_bf16 v[82:85], v[222:225], v[190:193], v[82:85]
	v_mfma_f32_16x16x32_bf16 v[78:81], v[102:105], v[194:197], v[78:81]
	v_mfma_f32_16x16x32_bf16 v[74:77], v[222:225], v[198:201], v[74:77]
	v_mfma_f32_16x16x32_bf16 v[70:73], v[102:105], v[202:205], v[70:73]
	v_mfma_f32_16x16x32_bf16 v[66:69], v[222:225], v[206:209], v[66:69]
	v_mfma_f32_16x16x32_bf16 v[226:229], v[110:113], v[182:185], v[94:97]
	v_mfma_f32_16x16x32_bf16 v[176:179], v[110:113], v[190:193], v[86:89]
	v_mfma_f32_16x16x32_bf16 v[180:183], v[110:113], v[198:201], v[78:81]
	v_mfma_f32_16x16x32_bf16 v[184:187], v[110:113], v[206:209], v[70:73]
	s_barrier
	s_nop 0
	ds_read_b128 v[70:73], v0 offset:16384
	ds_read_b128 v[78:81], v0 offset:17408
	ds_read_b128 v[86:89], v0 offset:18432
	ds_read_b128 v[94:97], v0 offset:19456
	ds_read_b128 v[188:191], v0 offset:20480
	ds_read_b128 v[192:195], v0 offset:21504
	ds_read_b128 v[196:199], v0 offset:22528
	ds_read_b128 v[200:203], v0 offset:23552
	s_waitcnt vmcnt(4)
	s_barrier
	s_waitcnt lgkmcnt(0)
	s_waitcnt lgkmcnt(0)
	v_mfma_f32_16x16x32_bf16 v[62:65], v[132:135], v[70:73], v[62:65]
	v_mfma_f32_16x16x32_bf16 v[58:61], v[146:149], v[70:73], v[58:61]
	v_mfma_f32_16x16x32_bf16 v[54:57], v[132:135], v[86:89], v[54:57]
	v_mfma_f32_16x16x32_bf16 v[50:53], v[146:149], v[86:89], v[50:53]
	v_mfma_f32_16x16x32_bf16 v[38:41], v[132:135], v[196:199], v[38:41]
	v_mfma_f32_16x16x32_bf16 v[34:37], v[146:149], v[196:199], v[34:37]
	v_mfma_f32_16x16x32_bf16 v[62:65], v[142:145], v[78:81], v[62:65]
	v_mfma_f32_16x16x32_bf16 v[58:61], v[172:175], v[78:81], v[58:61]
	v_mfma_f32_16x16x32_bf16 v[54:57], v[142:145], v[94:97], v[54:57]
	v_mfma_f32_16x16x32_bf16 v[50:53], v[172:175], v[94:97], v[50:53]
	v_mfma_f32_16x16x32_bf16 v[46:49], v[132:135], v[188:191], v[46:49]
	v_mfma_f32_16x16x32_bf16 v[42:45], v[146:149], v[188:191], v[42:45]
	v_mfma_f32_16x16x32_bf16 v[38:41], v[142:145], v[200:203], v[38:41]
	v_mfma_f32_16x16x32_bf16 v[34:37], v[172:175], v[200:203], v[34:37]
	v_mfma_f32_16x16x32_bf16 v[204:207], v[142:145], v[192:195], v[46:49]
	v_mfma_f32_16x16x32_bf16 v[230:233], v[172:175], v[192:195], v[42:45]
	v_mfma_f32_16x16x32_bf16 v[22:25], v[102:105], v[86:89], v[22:25]
	v_mfma_f32_16x16x32_bf16 v[18:21], v[118:121], v[86:89], v[18:21]
	v_mfma_f32_16x16x32_bf16 v[6:9], v[102:105], v[196:199], v[6:9]
	v_mfma_f32_16x16x32_bf16 v[2:5], v[118:121], v[196:199], v[2:5]
	v_mfma_f32_16x16x32_bf16 v[30:33], v[102:105], v[70:73], v[30:33]
	v_mfma_f32_16x16x32_bf16 v[26:29], v[118:121], v[70:73], v[26:29]
	v_mfma_f32_16x16x32_bf16 v[22:25], v[110:113], v[94:97], v[22:25]
	v_mfma_f32_16x16x32_bf16 v[18:21], v[222:225], v[94:97], v[18:21]
	v_mfma_f32_16x16x32_bf16 v[14:17], v[102:105], v[188:191], v[14:17]
	v_mfma_f32_16x16x32_bf16 v[10:13], v[118:121], v[188:191], v[10:13]
	v_mfma_f32_16x16x32_bf16 v[6:9], v[110:113], v[200:203], v[6:9]
	v_mfma_f32_16x16x32_bf16 v[2:5], v[222:225], v[200:203], v[2:5]
	v_mfma_f32_16x16x32_bf16 v[130:133], v[110:113], v[78:81], v[30:33]
	v_mfma_f32_16x16x32_bf16 v[142:145], v[222:225], v[78:81], v[26:29]
	v_mfma_f32_16x16x32_bf16 v[146:149], v[110:113], v[192:195], v[14:17]
	v_mfma_f32_16x16x32_bf16 v[172:175], v[222:225], v[192:195], v[10:13]
	s_barrier
	s_nop 0
	ds_read_b128 v[10:13], v140 offset:32768
	ds_read_b128 v[14:17], v140 offset:33792
	ds_read_b128 v[188:191], v140 offset:34816
	ds_read_b128 v[192:195], v140 offset:35840
	ds_read_b128 v[26:29], v0 offset:32768
	ds_read_b128 v[30:33], v0 offset:33792
	ds_read_b128 v[42:45], v0 offset:34816
	ds_read_b128 v[46:49], v0 offset:35840
	ds_read_b128 v[196:199], v0 offset:36864
	ds_read_b128 v[200:203], v0 offset:37888
	ds_read_b128 v[222:225], v0 offset:38912
	ds_read_b128 v[234:237], v0 offset:39936
	s_waitcnt vmcnt(2)
	s_barrier
; #define WAIT_V(n) asm volatile("s_waitcnt vmcnt(%0)" ::"n"(n) : "memory")
; #define WAIT_L(n) asm volatile("s_waitcnt lgkmcnt(%0)" ::"n"(n) : "memory")
; #define LDA8(dst, b, h) _Pragma("unroll") for (int m = 0; m < 4; ++m) _Pragma("unroll") for (int k = 0; k < 2; ++k) \
;     dst[m][k] = *(const bf16x8*)(abase + SAo(b, h) + m * 2048 + k * 1024)
; #define LDB8(dst, b, h) _Pragma("unroll") for (int n = 0; n < 2; ++n) _Pragma("unroll") for (int k = 0; k < 2; ++k) \
;     dst[n][k] = *(const bf16x8*)(bbase + SAo(b, h) + n * 2048 + k * 1024)
; #define BAR8 __builtin_amdgcn_s_barrier()
; __device__ __forceinline__ void gemm_main8(const u16* __restrict__ Ab, int lda, const u16* __restrict__ Bb, int ldb, int K,
;                                            char* shm, f32x4 (&acc)[2][2][4][2]) {
;     ...
;   { LDB8(B0, 1, 0); LDA8(At, 1, 0); WAIT_V(2); BAR8; WAIT_L(0); MMA8(0, 0, At, B0); BAR8;
;     LDB8(B1, 1, 1); WAIT_V(0); BAR8; WAIT_L(0); MMA8(0, 1, At, B1); BAR8;
;     LDA8(At, 1, 1); BAR8; WAIT_L(0); MMA8(1, 0, At, B0); MMA8(1, 1, At, B1); BAR8; }
;   if (wr == 0) BAR8;
	s_waitcnt lgkmcnt(0)
	s_waitcnt lgkmcnt(0)
	v_mfma_f32_16x16x32_bf16 v[70:73], v[10:13], v[26:29], v[126:129]
	v_mfma_f32_16x16x32_bf16 v[126:129], v[14:17], v[30:33], v[70:73]
	v_mfma_f32_16x16x32_bf16 v[70:73], v[188:191], v[26:29], v[122:125]
	v_mfma_f32_16x16x32_bf16 v[118:121], v[192:195], v[30:33], v[70:73]
	v_mfma_f32_16x16x32_bf16 v[70:73], v[10:13], v[42:45], v[210:213]
	v_mfma_f32_16x16x32_bf16 v[110:113], v[14:17], v[46:49], v[70:73]
	v_mfma_f32_16x16x32_bf16 v[70:73], v[188:191], v[42:45], v[114:117]
	v_mfma_f32_16x16x32_bf16 v[102:105], v[192:195], v[46:49], v[70:73]
	v_mfma_f32_16x16x32_bf16 v[70:73], v[10:13], v[196:199], v[214:217]
	v_mfma_f32_16x16x32_bf16 v[94:97], v[14:17], v[200:203], v[70:73]
	v_mfma_f32_16x16x32_bf16 v[70:73], v[188:191], v[196:199], v[106:109]
	v_mfma_f32_16x16x32_bf16 v[86:89], v[192:195], v[200:203], v[70:73]
	v_mfma_f32_16x16x32_bf16 v[70:73], v[10:13], v[222:225], v[218:221]
	v_mfma_f32_16x16x32_bf16 v[78:81], v[14:17], v[234:237], v[70:73]
	v_mfma_f32_16x16x32_bf16 v[70:73], v[188:191], v[222:225], v[98:101]
	v_mfma_f32_16x16x32_bf16 v[70:73], v[192:195], v[234:237], v[70:73]
	s_barrier
	ds_read_b128 v[208:211], v140 offset:49152
	ds_read_b128 v[212:215], v140 offset:50176
	ds_read_b128 v[216:219], v140 offset:51200
	ds_read_b128 v[238:241], v140 offset:52224
	s_waitcnt vmcnt(0)
	s_barrier
	s_waitcnt lgkmcnt(0)
	s_waitcnt lgkmcnt(0)
	v_mfma_f32_16x16x32_bf16 v[98:101], v[208:211], v[26:29], v[226:229]
	v_mfma_f32_16x16x32_bf16 v[26:29], v[216:219], v[26:29], v[90:93]
	v_mfma_f32_16x16x32_bf16 v[114:117], v[238:241], v[30:33], v[26:29]
	v_mfma_f32_16x16x32_bf16 v[26:29], v[208:211], v[42:45], v[176:179]
	v_mfma_f32_16x16x32_bf16 v[106:109], v[212:215], v[46:49], v[26:29]
	v_mfma_f32_16x16x32_bf16 v[26:29], v[216:219], v[42:45], v[82:85]
	v_mfma_f32_16x16x32_bf16 v[122:125], v[212:215], v[30:33], v[98:101]
	v_mfma_f32_16x16x32_bf16 v[98:101], v[238:241], v[46:49], v[26:29]
	v_mfma_f32_16x16x32_bf16 v[26:29], v[208:211], v[196:199], v[180:183]
	v_mfma_f32_16x16x32_bf16 v[90:93], v[212:215], v[200:203], v[26:29]
	v_mfma_f32_16x16x32_bf16 v[26:29], v[216:219], v[196:199], v[74:77]
	v_mfma_f32_16x16x32_bf16 v[82:85], v[238:241], v[200:203], v[26:29]
	v_mfma_f32_16x16x32_bf16 v[26:29], v[208:211], v[222:225], v[184:187]
	v_mfma_f32_16x16x32_bf16 v[74:77], v[212:215], v[234:237], v[26:29]
	v_mfma_f32_16x16x32_bf16 v[26:29], v[216:219], v[222:225], v[66:69]
	v_mfma_f32_16x16x32_bf16 v[66:69], v[238:241], v[234:237], v[26:29]
	s_barrier
	ds_read_b128 v[176:179], v0 offset:49152
	ds_read_b128 v[180:183], v0 offset:50176
	ds_read_b128 v[184:187], v0 offset:51200
	ds_read_b128 v[196:199], v0 offset:52224
	ds_read_b128 v[200:203], v0 offset:53248
	ds_read_b128 v[220:223], v0 offset:54272
	ds_read_b128 v[224:227], v0 offset:55296
	ds_read_b128 v[234:237], v0 offset:56320
	s_barrier
	s_waitcnt lgkmcnt(0)
	s_waitcnt lgkmcnt(0)
	v_mfma_f32_16x16x32_bf16 v[26:29], v[10:13], v[176:179], v[62:65]
	v_mfma_f32_16x16x32_bf16 v[62:65], v[14:17], v[180:183], v[26:29]
	v_mfma_f32_16x16x32_bf16 v[26:29], v[188:191], v[176:179], v[58:61]
	v_mfma_f32_16x16x32_bf16 v[58:61], v[192:195], v[180:183], v[26:29]
	v_mfma_f32_16x16x32_bf16 v[26:29], v[10:13], v[184:187], v[54:57]
	v_mfma_f32_16x16x32_bf16 v[46:49], v[14:17], v[196:199], v[26:29]
	v_mfma_f32_16x16x32_bf16 v[26:29], v[188:191], v[184:187], v[50:53]
	v_mfma_f32_16x16x32_bf16 v[42:45], v[192:195], v[196:199], v[26:29]
	v_mfma_f32_16x16x32_bf16 v[26:29], v[10:13], v[200:203], v[204:207]
	v_mfma_f32_16x16x32_bf16 v[10:13], v[10:13], v[224:227], v[38:41]
	v_mfma_f32_16x16x32_bf16 v[30:33], v[14:17], v[220:223], v[26:29]
	v_mfma_f32_16x16x32_bf16 v[26:29], v[188:191], v[200:203], v[230:233]
	v_mfma_f32_16x16x32_bf16 v[14:17], v[14:17], v[234:237], v[10:13]
	v_mfma_f32_16x16x32_bf16 v[10:13], v[188:191], v[224:227], v[34:37]
	v_mfma_f32_16x16x32_bf16 v[26:29], v[192:195], v[220:223], v[26:29]
	v_mfma_f32_16x16x32_bf16 v[10:13], v[192:195], v[234:237], v[10:13]
	v_mfma_f32_16x16x32_bf16 v[34:37], v[208:211], v[176:179], v[130:133]
	v_mfma_f32_16x16x32_bf16 v[54:57], v[212:215], v[180:183], v[34:37]
	v_mfma_f32_16x16x32_bf16 v[34:37], v[216:219], v[176:179], v[142:145]
	v_mfma_f32_16x16x32_bf16 v[18:21], v[216:219], v[184:187], v[18:21]
	v_mfma_f32_16x16x32_bf16 v[50:53], v[238:241], v[180:183], v[34:37]
	v_mfma_f32_16x16x32_bf16 v[22:25], v[208:211], v[184:187], v[22:25]
	v_mfma_f32_16x16x32_bf16 v[34:37], v[238:241], v[196:199], v[18:21]
	v_mfma_f32_16x16x32_bf16 v[18:21], v[208:211], v[200:203], v[146:149]
	v_mfma_f32_16x16x32_bf16 v[38:41], v[212:215], v[196:199], v[22:25]
	v_mfma_f32_16x16x32_bf16 v[22:25], v[212:215], v[220:223], v[18:21]
	v_mfma_f32_16x16x32_bf16 v[18:21], v[216:219], v[200:203], v[172:175]
	v_mfma_f32_16x16x32_bf16 v[6:9], v[208:211], v[224:227], v[6:9]
	v_mfma_f32_16x16x32_bf16 v[2:5], v[216:219], v[224:227], v[2:5]
	v_mfma_f32_16x16x32_bf16 v[18:21], v[238:241], v[220:223], v[18:21]
	v_mfma_f32_16x16x32_bf16 v[6:9], v[212:215], v[234:237], v[6:9]
	v_mfma_f32_16x16x32_bf16 v[2:5], v[238:241], v[234:237], v[2:5]
	v_cmp_gt_u32_e32 vcc, s97, v139
	s_barrier
	s_and_saveexec_b64 s[10:11], vcc
	s_cbranch_execz .LBB0_601
	s_barrier
	s_branch .LBB0_601

; #define WAIT_V(n) asm volatile("s_waitcnt vmcnt(%0)" ::"n"(n) : "memory")
; #define WAIT_L(n) asm volatile("s_waitcnt lgkmcnt(%0)" ::"n"(n) : "memory")
; #define SBAR() __builtin_amdgcn_sched_barrier(0)
; #define LDA8(dst, b, h) _Pragma("unroll") for (int m = 0; m < 4; ++m) _Pragma("unroll") for (int k = 0; k < 2; ++k) \
;     dst[m][k] = *(const bf16x8*)(abase + SAo(b, h) + m * 2048 + k * 1024)
; #define LDB8(dst, b, h) _Pragma("unroll") for (int n = 0; n < 2; ++n) _Pragma("unroll") for (int k = 0; k < 2; ++k) \
;     dst[n][k] = *(const bf16x8*)(bbase + SAo(b, h) + n * 2048 + k * 1024)
; #define BAR8 __builtin_amdgcn_s_barrier()
; __device__ __forceinline__ void gemm_main8(const u16* __restrict__ Ab, int lda, const u16* __restrict__ Bb, int ldb, int K,
;                                            char* shm, f32x4 (&acc)[2][2][4][2]) {
;     ...
;     LDB8(B0, 0, 0); SBAR(); LDA8(At, 0, 0); STG_A(1, 1, t + 1);
;     WAIT_L(8); BAR8; WAIT_L(0); MMA8(0, 0, At, B0); BAR8; SBAR();
;     LDB8(B1, 0, 1); STG_B(0, 0, t + 2);
;     BAR8; WAIT_L(0); MMA8(0, 1, At, B1); BAR8;
;     LDA8(At, 0, 1); STG_A(0, 0, t + 2);
;     BAR8; WAIT_L(0); MMA8(1, 0, At, B0); BAR8; SBAR();
;     STG_B(0, 1, t + 2);
;     WAIT_V(6); BAR8; MMA8(1, 1, At, B1); BAR8;
.LBB0_662:
	ds_read_b128 v[178:181], v140
	ds_read_b128 v[182:185], v140 offset:1024
	ds_read_b128 v[186:189], v140 offset:2048
	ds_read_b128 v[190:193], v140 offset:3072
	v_add_u32_e32 v176, 0xc000, v141
	v_lshl_add_u64 v[152:153], v[134:135], 0, s[20:21]
	s_mov_b64 s[24:25], 0x8400080
	v_readfirstlane_b32 s11, v176
	v_add_u32_e32 v177, 0xe000, v141
	v_lshl_add_u64 v[154:155], v[152:153], 0, s[24:25]
	s_mov_b32 m0, s11
	s_mov_b64 s[24:25], 0x8500080
	v_readfirstlane_b32 s11, v177
	ds_read_b128 v[194:197], v0
	ds_read_b128 v[198:201], v0 offset:1024
	ds_read_b128 v[202:205], v0 offset:2048
	ds_read_b128 v[206:209], v0 offset:3072
	ds_read_b128 v[210:213], v0 offset:4096
	ds_read_b128 v[214:217], v0 offset:5120
	ds_read_b128 v[218:221], v0 offset:6144
	ds_read_b128 v[222:225], v0 offset:7168
	global_load_lds_dwordx4 v[154:155], off
	v_lshl_add_u64 v[154:155], v[152:153], 0, s[24:25]
	s_mov_b32 m0, s11
	s_nop 0
	global_load_lds_dwordx4 v[154:155], off
	s_waitcnt lgkmcnt(8)
	s_barrier
	s_waitcnt lgkmcnt(0)
	s_waitcnt lgkmcnt(0)
	v_mfma_f32_16x16x32_bf16 v[126:129], v[178:181], v[194:197], v[126:129]
	v_mfma_f32_16x16x32_bf16 v[122:125], v[186:189], v[194:197], v[122:125]
	v_mfma_f32_16x16x32_bf16 v[118:121], v[178:181], v[202:205], v[118:121]
	v_mfma_f32_16x16x32_bf16 v[114:117], v[186:189], v[202:205], v[114:117]
	v_mfma_f32_16x16x32_bf16 v[110:113], v[178:181], v[210:213], v[110:113]
	v_mfma_f32_16x16x32_bf16 v[106:109], v[186:189], v[210:213], v[106:109]
	v_mfma_f32_16x16x32_bf16 v[102:105], v[178:181], v[218:221], v[102:105]
	v_mfma_f32_16x16x32_bf16 v[98:101], v[186:189], v[218:221], v[98:101]
	v_mfma_f32_16x16x32_bf16 v[126:129], v[182:185], v[198:201], v[126:129]
	v_mfma_f32_16x16x32_bf16 v[122:125], v[190:193], v[198:201], v[122:125]
	v_mfma_f32_16x16x32_bf16 v[118:121], v[182:185], v[206:209], v[118:121]
	v_mfma_f32_16x16x32_bf16 v[114:117], v[190:193], v[206:209], v[114:117]
	v_mfma_f32_16x16x32_bf16 v[110:113], v[182:185], v[214:217], v[110:113]
	v_mfma_f32_16x16x32_bf16 v[106:109], v[190:193], v[214:217], v[106:109]
	v_mfma_f32_16x16x32_bf16 v[102:105], v[182:185], v[222:225], v[102:105]
	v_mfma_f32_16x16x32_bf16 v[98:101], v[190:193], v[222:225], v[98:101]
	s_barrier
	v_lshl_add_u64 v[154:155], v[132:133], 0, s[20:21]
	v_readfirstlane_b32 s11, v142
	v_lshl_add_u64 v[164:165], v[154:155], 0, s[30:31]
	s_mov_b32 m0, s11
	s_mov_b64 s[24:25], 0x17500100
	v_readfirstlane_b32 s11, v143
	ds_read_b128 v[226:229], v140 offset:16384
	ds_read_b128 v[230:233], v140 offset:17408
	ds_read_b128 v[234:237], v140 offset:18432
	ds_read_b128 v[238:241], v140 offset:19456
	global_load_lds_dwordx4 v[164:165], off
	v_lshl_add_u64 v[164:165], v[154:155], 0, s[24:25]
	s_mov_b32 m0, s11
	s_nop 0
	global_load_lds_dwordx4 v[164:165], off
	s_barrier
	s_waitcnt lgkmcnt(0)
	s_waitcnt lgkmcnt(0)
	v_mfma_f32_16x16x32_bf16 v[94:97], v[226:229], v[194:197], v[94:97]
	v_mfma_f32_16x16x32_bf16 v[90:93], v[234:237], v[194:197], v[90:93]
	v_mfma_f32_16x16x32_bf16 v[86:89], v[226:229], v[202:205], v[86:89]
	v_mfma_f32_16x16x32_bf16 v[82:85], v[234:237], v[202:205], v[82:85]
	v_mfma_f32_16x16x32_bf16 v[78:81], v[226:229], v[210:213], v[78:81]
	v_mfma_f32_16x16x32_bf16 v[74:77], v[234:237], v[210:213], v[74:77]
	v_mfma_f32_16x16x32_bf16 v[70:73], v[226:229], v[218:221], v[70:73]
	v_mfma_f32_16x16x32_bf16 v[66:69], v[234:237], v[218:221], v[66:69]
	v_mfma_f32_16x16x32_bf16 v[94:97], v[230:233], v[198:201], v[94:97]
	v_mfma_f32_16x16x32_bf16 v[90:93], v[238:241], v[198:201], v[90:93]
	v_mfma_f32_16x16x32_bf16 v[86:89], v[230:233], v[206:209], v[86:89]
	v_mfma_f32_16x16x32_bf16 v[82:85], v[238:241], v[206:209], v[82:85]
	v_mfma_f32_16x16x32_bf16 v[78:81], v[230:233], v[214:217], v[78:81]
	v_mfma_f32_16x16x32_bf16 v[74:77], v[238:241], v[214:217], v[74:77]
	v_mfma_f32_16x16x32_bf16 v[70:73], v[230:233], v[222:225], v[70:73]
	v_mfma_f32_16x16x32_bf16 v[66:69], v[238:241], v[222:225], v[66:69]
	s_mov_b64 s[24:25], 0x8200100
	v_readfirstlane_b32 s11, v141
	v_lshl_add_u64 v[164:165], v[152:153], 0, s[24:25]
	s_mov_b32 m0, s11
	s_mov_b64 s[24:25], 0x8300100
	v_readfirstlane_b32 s11, v144
	s_barrier
	ds_read_b128 v[194:197], v0 offset:16384
	ds_read_b128 v[198:201], v0 offset:17408
	ds_read_b128 v[202:205], v0 offset:18432
	ds_read_b128 v[206:209], v0 offset:19456
	ds_read_b128 v[210:213], v0 offset:20480
	ds_read_b128 v[214:217], v0 offset:21504
	ds_read_b128 v[218:221], v0 offset:22528
	ds_read_b128 v[222:225], v0 offset:23552
	global_load_lds_dwordx4 v[164:165], off
	v_lshl_add_u64 v[164:165], v[152:153], 0, s[24:25]
	s_mov_b32 m0, s11
	s_nop 0
	global_load_lds_dwordx4 v[164:165], off
	s_barrier
	s_waitcnt lgkmcnt(0)
	s_waitcnt lgkmcnt(0)
	v_mfma_f32_16x16x32_bf16 v[62:65], v[178:181], v[194:197], v[62:65]
	v_mfma_f32_16x16x32_bf16 v[58:61], v[186:189], v[194:197], v[58:61]
	v_mfma_f32_16x16x32_bf16 v[54:57], v[178:181], v[202:205], v[54:57]
	v_mfma_f32_16x16x32_bf16 v[50:53], v[186:189], v[202:205], v[50:53]
	v_mfma_f32_16x16x32_bf16 v[46:49], v[178:181], v[210:213], v[46:49]
	v_mfma_f32_16x16x32_bf16 v[42:45], v[186:189], v[210:213], v[42:45]
	v_mfma_f32_16x16x32_bf16 v[38:41], v[178:181], v[218:221], v[38:41]
	v_mfma_f32_16x16x32_bf16 v[34:37], v[186:189], v[218:221], v[34:37]
	v_mfma_f32_16x16x32_bf16 v[62:65], v[182:185], v[198:201], v[62:65]
	v_mfma_f32_16x16x32_bf16 v[58:61], v[190:193], v[198:201], v[58:61]
	v_mfma_f32_16x16x32_bf16 v[54:57], v[182:185], v[206:209], v[54:57]
	v_mfma_f32_16x16x32_bf16 v[50:53], v[190:193], v[206:209], v[50:53]
	v_mfma_f32_16x16x32_bf16 v[46:49], v[182:185], v[214:217], v[46:49]
	v_mfma_f32_16x16x32_bf16 v[42:45], v[190:193], v[214:217], v[42:45]
	v_mfma_f32_16x16x32_bf16 v[38:41], v[182:185], v[222:225], v[38:41]
	v_mfma_f32_16x16x32_bf16 v[34:37], v[190:193], v[222:225], v[34:37]
	s_barrier
; #define WAIT_V(n) asm volatile("s_waitcnt vmcnt(%0)" ::"n"(n) : "memory")
; #define WAIT_L(n) asm volatile("s_waitcnt lgkmcnt(%0)" ::"n"(n) : "memory")
; #define SBAR() __builtin_amdgcn_sched_barrier(0)
; #define LDA8(dst, b, h) _Pragma("unroll") for (int m = 0; m < 4; ++m) _Pragma("unroll") for (int k = 0; k < 2; ++k) \
;     dst[m][k] = *(const bf16x8*)(abase + SAo(b, h) + m * 2048 + k * 1024)
; #define LDB8(dst, b, h) _Pragma("unroll") for (int n = 0; n < 2; ++n) _Pragma("unroll") for (int k = 0; k < 2; ++k) \
;     dst[n][k] = *(const bf16x8*)(bbase + SAo(b, h) + n * 2048 + k * 1024)
; #define BAR8 __builtin_amdgcn_s_barrier()
; __device__ __forceinline__ void gemm_main8(const u16* __restrict__ Ab, int lda, const u16* __restrict__ Bb, int ldb, int K,
;                                            char* shm, f32x4 (&acc)[2][2][4][2]) {
;     ...
;     STG_B(0, 1, t + 2);
;     WAIT_V(6); BAR8; MMA8(1, 1, At, B1); BAR8;
;     LDB8(B0, 1, 0); SBAR(); LDA8(At, 1, 0); STG_A(0, 1, t + 2);
;     WAIT_L(8); BAR8; WAIT_L(0); MMA8(0, 0, At, B0); BAR8; SBAR();
;     LDB8(B1, 1, 1); STG_B(1, 0, t + 3);
;     BAR8; WAIT_L(0); MMA8(0, 1, At, B1); BAR8;
;     LDA8(At, 1, 1); STG_A(1, 0, t + 3);
	s_mov_b64 s[24:25], 0x17700100
	v_readfirstlane_b32 s11, v145
	v_lshl_add_u64 v[164:165], v[154:155], 0, s[24:25]
	s_mov_b32 m0, s11
	s_mov_b64 s[24:25], 0x17900100
	v_readfirstlane_b32 s11, v146
	global_load_lds_dwordx4 v[164:165], off
	v_lshl_add_u64 v[164:165], v[154:155], 0, s[24:25]
	s_mov_b32 m0, s11
	s_nop 0
	global_load_lds_dwordx4 v[164:165], off
	s_waitcnt vmcnt(6)
	s_barrier
	v_mfma_f32_16x16x32_bf16 v[30:33], v[226:229], v[194:197], v[30:33]
	v_mfma_f32_16x16x32_bf16 v[26:29], v[234:237], v[194:197], v[26:29]
	v_mfma_f32_16x16x32_bf16 v[22:25], v[226:229], v[202:205], v[22:25]
	v_mfma_f32_16x16x32_bf16 v[18:21], v[234:237], v[202:205], v[18:21]
	v_mfma_f32_16x16x32_bf16 v[14:17], v[226:229], v[210:213], v[14:17]
	v_mfma_f32_16x16x32_bf16 v[10:13], v[234:237], v[210:213], v[10:13]
	v_mfma_f32_16x16x32_bf16 v[6:9], v[226:229], v[218:221], v[6:9]
	v_mfma_f32_16x16x32_bf16 v[2:5], v[234:237], v[218:221], v[2:5]
	v_mfma_f32_16x16x32_bf16 v[30:33], v[230:233], v[198:201], v[30:33]
	v_mfma_f32_16x16x32_bf16 v[26:29], v[238:241], v[198:201], v[26:29]
	v_mfma_f32_16x16x32_bf16 v[22:25], v[230:233], v[206:209], v[22:25]
	v_mfma_f32_16x16x32_bf16 v[18:21], v[238:241], v[206:209], v[18:21]
	v_mfma_f32_16x16x32_bf16 v[14:17], v[230:233], v[214:217], v[14:17]
	v_mfma_f32_16x16x32_bf16 v[10:13], v[238:241], v[214:217], v[10:13]
	v_mfma_f32_16x16x32_bf16 v[6:9], v[230:233], v[222:225], v[6:9]
	v_mfma_f32_16x16x32_bf16 v[2:5], v[238:241], v[222:225], v[2:5]
	s_barrier
	ds_read_b128 v[178:181], v140 offset:32768
	ds_read_b128 v[182:185], v140 offset:33792
	ds_read_b128 v[186:189], v140 offset:34816
	ds_read_b128 v[190:193], v140 offset:35840
	s_mov_b64 s[24:25], 0x8400100
	v_readfirstlane_b32 s11, v147
	v_lshl_add_u64 v[164:165], v[152:153], 0, s[24:25]
	s_mov_b32 m0, s11
	s_mov_b64 s[24:25], 0x8500100
	v_readfirstlane_b32 s11, v148
	ds_read_b128 v[194:197], v0 offset:32768
	ds_read_b128 v[198:201], v0 offset:33792
	ds_read_b128 v[202:205], v0 offset:34816
	ds_read_b128 v[206:209], v0 offset:35840
	ds_read_b128 v[210:213], v0 offset:36864
	ds_read_b128 v[214:217], v0 offset:37888
	ds_read_b128 v[218:221], v0 offset:38912
	ds_read_b128 v[222:225], v0 offset:39936
	global_load_lds_dwordx4 v[164:165], off
	v_lshl_add_u64 v[164:165], v[152:153], 0, s[24:25]
	s_mov_b32 m0, s11
	s_nop 0
	global_load_lds_dwordx4 v[164:165], off
	s_waitcnt lgkmcnt(8)
	s_barrier
	s_waitcnt lgkmcnt(0)
	s_waitcnt lgkmcnt(0)
	v_mfma_f32_16x16x32_bf16 v[126:129], v[178:181], v[194:197], v[126:129]
	v_mfma_f32_16x16x32_bf16 v[122:125], v[186:189], v[194:197], v[122:125]
	v_mfma_f32_16x16x32_bf16 v[118:121], v[178:181], v[202:205], v[118:121]
	v_mfma_f32_16x16x32_bf16 v[114:117], v[186:189], v[202:205], v[114:117]
	v_mfma_f32_16x16x32_bf16 v[110:113], v[178:181], v[210:213], v[110:113]
	v_mfma_f32_16x16x32_bf16 v[106:109], v[186:189], v[210:213], v[106:109]
	v_mfma_f32_16x16x32_bf16 v[102:105], v[178:181], v[218:221], v[102:105]
	v_mfma_f32_16x16x32_bf16 v[98:101], v[186:189], v[218:221], v[98:101]
	v_mfma_f32_16x16x32_bf16 v[126:129], v[182:185], v[198:201], v[126:129]
	v_mfma_f32_16x16x32_bf16 v[122:125], v[190:193], v[198:201], v[122:125]
	v_mfma_f32_16x16x32_bf16 v[118:121], v[182:185], v[206:209], v[118:121]
	v_mfma_f32_16x16x32_bf16 v[114:117], v[190:193], v[206:209], v[114:117]
	v_mfma_f32_16x16x32_bf16 v[110:113], v[182:185], v[214:217], v[110:113]
	v_mfma_f32_16x16x32_bf16 v[106:109], v[190:193], v[214:217], v[106:109]
	v_mfma_f32_16x16x32_bf16 v[102:105], v[182:185], v[222:225], v[102:105]
	v_mfma_f32_16x16x32_bf16 v[98:101], v[190:193], v[222:225], v[98:101]
	s_barrier
	v_readfirstlane_b32 s11, v149
	v_lshl_add_u64 v[164:165], v[154:155], 0, s[16:17]
	s_mov_b32 m0, s11
	s_mov_b64 s[24:25], 0x17500180
	v_readfirstlane_b32 s11, v171
	ds_read_b128 v[226:229], v140 offset:49152
	ds_read_b128 v[230:233], v140 offset:50176
	ds_read_b128 v[234:237], v140 offset:51200
	ds_read_b128 v[238:241], v140 offset:52224
	global_load_lds_dwordx4 v[164:165], off
	v_lshl_add_u64 v[164:165], v[154:155], 0, s[24:25]
	s_mov_b32 m0, s11
	s_nop 0
	global_load_lds_dwordx4 v[164:165], off
	s_barrier
	s_waitcnt lgkmcnt(0)
	s_waitcnt lgkmcnt(0)
	v_mfma_f32_16x16x32_bf16 v[94:97], v[226:229], v[194:197], v[94:97]
	v_mfma_f32_16x16x32_bf16 v[90:93], v[234:237], v[194:197], v[90:93]
	v_mfma_f32_16x16x32_bf16 v[86:89], v[226:229], v[202:205], v[86:89]
	v_mfma_f32_16x16x32_bf16 v[82:85], v[234:237], v[202:205], v[82:85]
	v_mfma_f32_16x16x32_bf16 v[78:81], v[226:229], v[210:213], v[78:81]
	v_mfma_f32_16x16x32_bf16 v[74:77], v[234:237], v[210:213], v[74:77]
	v_mfma_f32_16x16x32_bf16 v[70:73], v[226:229], v[218:221], v[70:73]
	v_mfma_f32_16x16x32_bf16 v[66:69], v[234:237], v[218:221], v[66:69]
	v_mfma_f32_16x16x32_bf16 v[94:97], v[230:233], v[198:201], v[94:97]
	v_mfma_f32_16x16x32_bf16 v[90:93], v[238:241], v[198:201], v[90:93]
	v_mfma_f32_16x16x32_bf16 v[86:89], v[230:233], v[206:209], v[86:89]
	v_mfma_f32_16x16x32_bf16 v[82:85], v[238:241], v[206:209], v[82:85]
	v_mfma_f32_16x16x32_bf16 v[78:81], v[230:233], v[214:217], v[78:81]
	v_mfma_f32_16x16x32_bf16 v[74:77], v[238:241], v[214:217], v[74:77]
	v_mfma_f32_16x16x32_bf16 v[70:73], v[230:233], v[222:225], v[70:73]
	v_mfma_f32_16x16x32_bf16 v[66:69], v[238:241], v[222:225], v[66:69]
	s_mov_b64 s[24:25], 0x8200180
	v_readfirstlane_b32 s11, v172
	v_lshl_add_u64 v[164:165], v[152:153], 0, s[24:25]
	s_mov_b32 m0, s11
	s_mov_b64 s[24:25], 0x8300180
	v_readfirstlane_b32 s11, v173
	s_barrier
; #define WAIT_V(n) asm volatile("s_waitcnt vmcnt(%0)" ::"n"(n) : "memory")
; #define WAIT_L(n) asm volatile("s_waitcnt lgkmcnt(%0)" ::"n"(n) : "memory")
; #define SBAR() __builtin_amdgcn_sched_barrier(0)
; #define LDA8(dst, b, h) _Pragma("unroll") for (int m = 0; m < 4; ++m) _Pragma("unroll") for (int k = 0; k < 2; ++k) \
;     dst[m][k] = *(const bf16x8*)(abase + SAo(b, h) + m * 2048 + k * 1024)
; #define LDB8(dst, b, h) _Pragma("unroll") for (int n = 0; n < 2; ++n) _Pragma("unroll") for (int k = 0; k < 2; ++k) \
;     dst[n][k] = *(const bf16x8*)(bbase + SAo(b, h) + n * 2048 + k * 1024)
; #define BAR8 __builtin_amdgcn_s_barrier()
; __device__ __forceinline__ void gemm_main8(const u16* __restrict__ Ab, int lda, const u16* __restrict__ Bb, int ldb, int K,
;                                            char* shm, f32x4 (&acc)[2][2][4][2]) {
;     ...
;     LDB8(B1, 1, 1); STG_B(1, 0, t + 3);
;     BAR8; WAIT_L(0); MMA8(0, 1, At, B1); BAR8;
;     LDA8(At, 1, 1); STG_A(1, 0, t + 3);
;     BAR8; WAIT_L(0); MMA8(1, 0, At, B0); BAR8; SBAR();
;     STG_B(1, 1, t + 3);
;     WAIT_V(6); BAR8; MMA8(1, 1, At, B1); BAR8;
;   }
;   { LDB8(B0, 0, 0); LDA8(At, 0, 0); STG_A(1, 1, nt - 1);
;     BAR8; WAIT_L(0); MMA8(0, 0, At, B0); BAR8;
	ds_read_b128 v[194:197], v0 offset:49152
	ds_read_b128 v[198:201], v0 offset:50176
	ds_read_b128 v[202:205], v0 offset:51200
	ds_read_b128 v[206:209], v0 offset:52224
	ds_read_b128 v[210:213], v0 offset:53248
	ds_read_b128 v[214:217], v0 offset:54272
	ds_read_b128 v[218:221], v0 offset:55296
	ds_read_b128 v[222:225], v0 offset:56320
	global_load_lds_dwordx4 v[164:165], off
	v_lshl_add_u64 v[152:153], v[152:153], 0, s[24:25]
	s_mov_b32 m0, s11
	s_nop 0
	global_load_lds_dwordx4 v[152:153], off
	s_barrier
	s_waitcnt lgkmcnt(0)
	s_waitcnt lgkmcnt(0)
	v_mfma_f32_16x16x32_bf16 v[62:65], v[178:181], v[194:197], v[62:65]
	v_mfma_f32_16x16x32_bf16 v[58:61], v[186:189], v[194:197], v[58:61]
	v_mfma_f32_16x16x32_bf16 v[54:57], v[178:181], v[202:205], v[54:57]
	v_mfma_f32_16x16x32_bf16 v[50:53], v[186:189], v[202:205], v[50:53]
	v_mfma_f32_16x16x32_bf16 v[46:49], v[178:181], v[210:213], v[46:49]
	v_mfma_f32_16x16x32_bf16 v[42:45], v[186:189], v[210:213], v[42:45]
	v_mfma_f32_16x16x32_bf16 v[38:41], v[178:181], v[218:221], v[38:41]
	v_mfma_f32_16x16x32_bf16 v[34:37], v[186:189], v[218:221], v[34:37]
	v_mfma_f32_16x16x32_bf16 v[62:65], v[182:185], v[198:201], v[62:65]
	v_mfma_f32_16x16x32_bf16 v[58:61], v[190:193], v[198:201], v[58:61]
	v_mfma_f32_16x16x32_bf16 v[54:57], v[182:185], v[206:209], v[54:57]
	v_mfma_f32_16x16x32_bf16 v[50:53], v[190:193], v[206:209], v[50:53]
	v_mfma_f32_16x16x32_bf16 v[46:49], v[182:185], v[214:217], v[46:49]
	v_mfma_f32_16x16x32_bf16 v[42:45], v[190:193], v[214:217], v[42:45]
	v_mfma_f32_16x16x32_bf16 v[38:41], v[182:185], v[222:225], v[38:41]
	v_mfma_f32_16x16x32_bf16 v[34:37], v[190:193], v[222:225], v[34:37]
	s_barrier
	s_mov_b64 s[24:25], 0x17700180
	v_readfirstlane_b32 s11, v174
	v_lshl_add_u64 v[152:153], v[154:155], 0, s[24:25]
	s_mov_b32 m0, s11
	s_mov_b64 s[24:25], 0x17900180
	v_readfirstlane_b32 s11, v175
	global_load_lds_dwordx4 v[152:153], off
	v_lshl_add_u64 v[152:153], v[154:155], 0, s[24:25]
	s_mov_b32 m0, s11
	s_nop 0
	global_load_lds_dwordx4 v[152:153], off
	s_waitcnt vmcnt(6)
	s_barrier
	v_mfma_f32_16x16x32_bf16 v[30:33], v[226:229], v[194:197], v[30:33]
	v_mfma_f32_16x16x32_bf16 v[26:29], v[234:237], v[194:197], v[26:29]
	v_mfma_f32_16x16x32_bf16 v[22:25], v[226:229], v[202:205], v[22:25]
	v_mfma_f32_16x16x32_bf16 v[18:21], v[234:237], v[202:205], v[18:21]
	v_mfma_f32_16x16x32_bf16 v[14:17], v[226:229], v[210:213], v[14:17]
	v_mfma_f32_16x16x32_bf16 v[10:13], v[234:237], v[210:213], v[10:13]
	v_mfma_f32_16x16x32_bf16 v[6:9], v[226:229], v[218:221], v[6:9]
	v_mfma_f32_16x16x32_bf16 v[2:5], v[234:237], v[218:221], v[2:5]
	v_mfma_f32_16x16x32_bf16 v[30:33], v[230:233], v[198:201], v[30:33]
	v_mfma_f32_16x16x32_bf16 v[26:29], v[238:241], v[198:201], v[26:29]
	v_mfma_f32_16x16x32_bf16 v[22:25], v[230:233], v[206:209], v[22:25]
	v_mfma_f32_16x16x32_bf16 v[18:21], v[238:241], v[206:209], v[18:21]
	v_mfma_f32_16x16x32_bf16 v[14:17], v[230:233], v[214:217], v[14:17]
	v_mfma_f32_16x16x32_bf16 v[10:13], v[238:241], v[214:217], v[10:13]
	v_mfma_f32_16x16x32_bf16 v[6:9], v[230:233], v[222:225], v[6:9]
	v_mfma_f32_16x16x32_bf16 v[2:5], v[238:241], v[222:225], v[2:5]
	s_add_i32 s10, s10, 2
	s_add_u32 s20, s20, 0x100
	s_addc_u32 s21, s21, 0
	s_cmpk_lt_u32 s10, 0x7c
	s_barrier
	s_cbranch_scc1 .LBB0_662
	s_mov_b64 s[10:11], 0x203f80
	v_lshl_add_u64 v[152:153], v[130:131], 0, s[10:11]
	v_readfirstlane_b32 s10, v176
	s_mov_b32 m0, s10
	s_mov_b64 s[10:11], 0x303f80
	v_lshl_add_u64 v[130:131], v[130:131], 0, s[10:11]
	v_readfirstlane_b32 s10, v177
	ds_read_b128 v[132:135], v140
	ds_read_b128 v[142:145], v140 offset:1024
	ds_read_b128 v[146:149], v140 offset:2048
	ds_read_b128 v[172:175], v140 offset:3072
	ds_read_b128 v[178:181], v0
	ds_read_b128 v[182:185], v0 offset:1024
	ds_read_b128 v[186:189], v0 offset:2048
	ds_read_b128 v[190:193], v0 offset:3072
	ds_read_b128 v[194:197], v0 offset:4096
	ds_read_b128 v[198:201], v0 offset:5120
	ds_read_b128 v[202:205], v0 offset:6144
	ds_read_b128 v[206:209], v0 offset:7168
	global_load_lds_dwordx4 v[152:153], off
	s_mov_b32 m0, s10
	s_nop 0
	global_load_lds_dwordx4 v[130:131], off
	s_barrier
	s_waitcnt lgkmcnt(0)
	s_waitcnt lgkmcnt(0)
	v_mfma_f32_16x16x32_bf16 v[126:129], v[132:135], v[178:181], v[126:129]
	v_mfma_f32_16x16x32_bf16 v[122:125], v[146:149], v[178:181], v[122:125]
	v_mfma_f32_16x16x32_bf16 v[118:121], v[132:135], v[186:189], v[118:121]
	v_mfma_f32_16x16x32_bf16 v[114:117], v[146:149], v[186:189], v[114:117]
	v_mfma_f32_16x16x32_bf16 v[110:113], v[132:135], v[194:197], v[110:113]
	v_mfma_f32_16x16x32_bf16 v[106:109], v[146:149], v[194:197], v[106:109]
	v_mfma_f32_16x16x32_bf16 v[102:105], v[132:135], v[202:205], v[102:105]
	v_mfma_f32_16x16x32_bf16 v[98:101], v[146:149], v[202:205], v[98:101]
	v_mfma_f32_16x16x32_bf16 v[126:129], v[142:145], v[182:185], v[126:129]
	v_mfma_f32_16x16x32_bf16 v[122:125], v[172:175], v[182:185], v[122:125]
	v_mfma_f32_16x16x32_bf16 v[118:121], v[142:145], v[190:193], v[118:121]
	v_mfma_f32_16x16x32_bf16 v[114:117], v[172:175], v[190:193], v[114:117]
	v_mfma_f32_16x16x32_bf16 v[110:113], v[142:145], v[198:201], v[110:113]
	v_mfma_f32_16x16x32_bf16 v[106:109], v[172:175], v[198:201], v[106:109]
	v_mfma_f32_16x16x32_bf16 v[102:105], v[142:145], v[206:209], v[102:105]
	v_mfma_f32_16x16x32_bf16 v[98:101], v[172:175], v[206:209], v[98:101]
	s_barrier
	ds_read_b128 v[210:213], v140 offset:16384
	ds_read_b128 v[214:217], v140 offset:17408
	ds_read_b128 v[218:221], v140 offset:18432
	ds_read_b128 v[222:225], v140 offset:19456
	s_barrier
; #define WAIT_V(n) asm volatile("s_waitcnt vmcnt(%0)" ::"n"(n) : "memory")
; #define WAIT_L(n) asm volatile("s_waitcnt lgkmcnt(%0)" ::"n"(n) : "memory")
; #define LDA8(dst, b, h) _Pragma("unroll") for (int m = 0; m < 4; ++m) _Pragma("unroll") for (int k = 0; k < 2; ++k) \
;     dst[m][k] = *(const bf16x8*)(abase + SAo(b, h) + m * 2048 + k * 1024)
; #define LDB8(dst, b, h) _Pragma("unroll") for (int n = 0; n < 2; ++n) _Pragma("unroll") for (int k = 0; k < 2; ++k) \
;     dst[n][k] = *(const bf16x8*)(bbase + SAo(b, h) + n * 2048 + k * 1024)
; #define BAR8 __builtin_amdgcn_s_barrier()
; __device__ __forceinline__ void gemm_main8(const u16* __restrict__ Ab, int lda, const u16* __restrict__ Bb, int ldb, int K,
;                                            char* shm, f32x4 (&acc)[2][2][4][2]) {
;     ...
;     LDB8(B1, 0, 1); BAR8; WAIT_L(0); MMA8(0, 1, At, B1); BAR8;
;     LDA8(At, 0, 1); WAIT_V(4); BAR8; WAIT_L(0); MMA8(1, 0, At, B0); MMA8(1, 1, At, B1); BAR8; }
;   { LDB8(B0, 1, 0); LDA8(At, 1, 0); WAIT_V(2); BAR8; WAIT_L(0); MMA8(0, 0, At, B0); BAR8;
	s_waitcnt lgkmcnt(0)
	s_waitcnt lgkmcnt(0)
	v_mfma_f32_16x16x32_bf16 v[94:97], v[210:213], v[178:181], v[94:97]
	v_mfma_f32_16x16x32_bf16 v[90:93], v[218:221], v[178:181], v[90:93]
	v_mfma_f32_16x16x32_bf16 v[86:89], v[210:213], v[186:189], v[86:89]
	v_mfma_f32_16x16x32_bf16 v[82:85], v[218:221], v[186:189], v[82:85]
	v_mfma_f32_16x16x32_bf16 v[78:81], v[210:213], v[194:197], v[78:81]
	v_mfma_f32_16x16x32_bf16 v[74:77], v[218:221], v[194:197], v[74:77]
	v_mfma_f32_16x16x32_bf16 v[70:73], v[210:213], v[202:205], v[70:73]
	v_mfma_f32_16x16x32_bf16 v[66:69], v[218:221], v[202:205], v[66:69]
	v_mfma_f32_16x16x32_bf16 v[94:97], v[214:217], v[182:185], v[94:97]
	v_mfma_f32_16x16x32_bf16 v[90:93], v[222:225], v[182:185], v[90:93]
	v_mfma_f32_16x16x32_bf16 v[86:89], v[214:217], v[190:193], v[86:89]
	v_mfma_f32_16x16x32_bf16 v[82:85], v[222:225], v[190:193], v[82:85]
	v_mfma_f32_16x16x32_bf16 v[78:81], v[214:217], v[198:201], v[78:81]
	v_mfma_f32_16x16x32_bf16 v[74:77], v[222:225], v[198:201], v[74:77]
	v_mfma_f32_16x16x32_bf16 v[70:73], v[214:217], v[206:209], v[70:73]
	v_mfma_f32_16x16x32_bf16 v[66:69], v[222:225], v[206:209], v[66:69]
	s_barrier
	ds_read_b128 v[176:179], v0 offset:16384
	ds_read_b128 v[180:183], v0 offset:17408
	ds_read_b128 v[184:187], v0 offset:18432
	ds_read_b128 v[188:191], v0 offset:19456
	ds_read_b128 v[192:195], v0 offset:20480
	ds_read_b128 v[196:199], v0 offset:21504
	ds_read_b128 v[200:203], v0 offset:22528
	ds_read_b128 v[204:207], v0 offset:23552
	s_waitcnt vmcnt(4)
	s_barrier
	s_waitcnt lgkmcnt(0)
	s_waitcnt lgkmcnt(0)
	v_mfma_f32_16x16x32_bf16 v[46:49], v[132:135], v[192:195], v[46:49]
	v_mfma_f32_16x16x32_bf16 v[42:45], v[146:149], v[192:195], v[42:45]
	v_mfma_f32_16x16x32_bf16 v[62:65], v[132:135], v[176:179], v[62:65]
	v_mfma_f32_16x16x32_bf16 v[58:61], v[146:149], v[176:179], v[58:61]
	v_mfma_f32_16x16x32_bf16 v[54:57], v[132:135], v[184:187], v[54:57]
	v_mfma_f32_16x16x32_bf16 v[50:53], v[146:149], v[184:187], v[50:53]
	v_mfma_f32_16x16x32_bf16 v[46:49], v[142:145], v[196:199], v[46:49]
	v_mfma_f32_16x16x32_bf16 v[42:45], v[172:175], v[196:199], v[42:45]
	v_mfma_f32_16x16x32_bf16 v[38:41], v[132:135], v[200:203], v[38:41]
	v_mfma_f32_16x16x32_bf16 v[34:37], v[146:149], v[200:203], v[34:37]
	v_mfma_f32_16x16x32_bf16 v[226:229], v[142:145], v[180:183], v[62:65]
	v_mfma_f32_16x16x32_bf16 v[230:233], v[172:175], v[180:183], v[58:61]
	v_mfma_f32_16x16x32_bf16 v[234:237], v[142:145], v[188:191], v[54:57]
	v_mfma_f32_16x16x32_bf16 v[238:241], v[172:175], v[188:191], v[50:53]
	v_mfma_f32_16x16x32_bf16 v[130:133], v[142:145], v[204:207], v[38:41]
	v_mfma_f32_16x16x32_bf16 v[142:145], v[172:175], v[204:207], v[34:37]
	v_mfma_f32_16x16x32_bf16 v[30:33], v[210:213], v[176:179], v[30:33]
	v_mfma_f32_16x16x32_bf16 v[26:29], v[218:221], v[176:179], v[26:29]
	v_mfma_f32_16x16x32_bf16 v[22:25], v[210:213], v[184:187], v[22:25]
	v_mfma_f32_16x16x32_bf16 v[18:21], v[218:221], v[184:187], v[18:21]
	v_mfma_f32_16x16x32_bf16 v[14:17], v[210:213], v[192:195], v[14:17]
	v_mfma_f32_16x16x32_bf16 v[10:13], v[218:221], v[192:195], v[10:13]
	v_mfma_f32_16x16x32_bf16 v[6:9], v[210:213], v[200:203], v[6:9]
	v_mfma_f32_16x16x32_bf16 v[2:5], v[218:221], v[200:203], v[2:5]
	v_mfma_f32_16x16x32_bf16 v[146:149], v[214:217], v[180:183], v[30:33]
	v_mfma_f32_16x16x32_bf16 v[172:175], v[222:225], v[180:183], v[26:29]
	v_mfma_f32_16x16x32_bf16 v[176:179], v[214:217], v[188:191], v[22:25]
	v_mfma_f32_16x16x32_bf16 v[180:183], v[222:225], v[188:191], v[18:21]
	v_mfma_f32_16x16x32_bf16 v[184:187], v[214:217], v[196:199], v[14:17]
	v_mfma_f32_16x16x32_bf16 v[188:191], v[222:225], v[196:199], v[10:13]
	v_mfma_f32_16x16x32_bf16 v[192:195], v[214:217], v[204:207], v[6:9]
	v_mfma_f32_16x16x32_bf16 v[196:199], v[222:225], v[204:207], v[2:5]
	s_barrier
	ds_read_b128 v[10:13], v140 offset:32768
	ds_read_b128 v[14:17], v140 offset:33792
	ds_read_b128 v[200:203], v140 offset:34816
	ds_read_b128 v[204:207], v140 offset:35840
	ds_read_b128 v[26:29], v0 offset:32768
	ds_read_b128 v[34:37], v0 offset:33792
	ds_read_b128 v[58:61], v0 offset:34816
	ds_read_b128 v[62:65], v0 offset:35840
	ds_read_b128 v[208:211], v0 offset:36864
	ds_read_b128 v[212:215], v0 offset:37888
	ds_read_b128 v[216:219], v0 offset:38912
	ds_read_b128 v[220:223], v0 offset:39936
	s_waitcnt vmcnt(2)
	s_barrier
; #define WAIT_V(n) asm volatile("s_waitcnt vmcnt(%0)" ::"n"(n) : "memory")
; #define WAIT_L(n) asm volatile("s_waitcnt lgkmcnt(%0)" ::"n"(n) : "memory")
; #define LDA8(dst, b, h) _Pragma("unroll") for (int m = 0; m < 4; ++m) _Pragma("unroll") for (int k = 0; k < 2; ++k) \
;     dst[m][k] = *(const bf16x8*)(abase + SAo(b, h) + m * 2048 + k * 1024)
; #define LDB8(dst, b, h) _Pragma("unroll") for (int n = 0; n < 2; ++n) _Pragma("unroll") for (int k = 0; k < 2; ++k) \
;     dst[n][k] = *(const bf16x8*)(bbase + SAo(b, h) + n * 2048 + k * 1024)
; #define BAR8 __builtin_amdgcn_s_barrier()
; __device__ __forceinline__ void gemm_main8(const u16* __restrict__ Ab, int lda, const u16* __restrict__ Bb, int ldb, int K,
;                                            char* shm, f32x4 (&acc)[2][2][4][2]) {
;     ...
;   { LDB8(B0, 1, 0); LDA8(At, 1, 0); WAIT_V(2); BAR8; WAIT_L(0); MMA8(0, 0, At, B0); BAR8;
;     LDB8(B1, 1, 1); WAIT_V(0); BAR8; WAIT_L(0); MMA8(0, 1, At, B1); BAR8;
;     LDA8(At, 1, 1); BAR8; WAIT_L(0); MMA8(1, 0, At, B0); MMA8(1, 1, At, B1); BAR8; }
;   if (wr == 0) BAR8;
	s_waitcnt lgkmcnt(0)
	s_waitcnt lgkmcnt(0)
	v_mfma_f32_16x16x32_bf16 v[2:5], v[10:13], v[26:29], v[126:129]
	v_mfma_f32_16x16x32_bf16 v[50:53], v[14:17], v[34:37], v[2:5]
	v_mfma_f32_16x16x32_bf16 v[2:5], v[200:203], v[26:29], v[122:125]
	v_mfma_f32_16x16x32_bf16 v[54:57], v[204:207], v[34:37], v[2:5]
	v_mfma_f32_16x16x32_bf16 v[2:5], v[10:13], v[58:61], v[118:121]
	v_mfma_f32_16x16x32_bf16 v[30:33], v[14:17], v[62:65], v[2:5]
	v_mfma_f32_16x16x32_bf16 v[2:5], v[200:203], v[58:61], v[114:117]
	v_mfma_f32_16x16x32_bf16 v[38:41], v[204:207], v[62:65], v[2:5]
	v_mfma_f32_16x16x32_bf16 v[2:5], v[10:13], v[208:211], v[110:113]
	v_mfma_f32_16x16x32_bf16 v[18:21], v[14:17], v[212:215], v[2:5]
	v_mfma_f32_16x16x32_bf16 v[2:5], v[200:203], v[208:211], v[106:109]
	v_mfma_f32_16x16x32_bf16 v[22:25], v[204:207], v[212:215], v[2:5]
	v_mfma_f32_16x16x32_bf16 v[2:5], v[10:13], v[216:219], v[102:105]
	v_mfma_f32_16x16x32_bf16 v[6:9], v[200:203], v[216:219], v[98:101]
	v_mfma_f32_16x16x32_bf16 v[2:5], v[14:17], v[220:223], v[2:5]
	v_mfma_f32_16x16x32_bf16 v[6:9], v[204:207], v[220:223], v[6:9]
	s_barrier
	ds_read_b128 v[242:245], v140 offset:49152
	ds_read_b128 v[246:249], v140 offset:50176
	ds_read_b128 v[250:253], v140 offset:51200
	ds_read_b128 v[168:171], v140 offset:52224
	s_waitcnt vmcnt(0)
	s_barrier
	s_waitcnt lgkmcnt(0)
	s_waitcnt lgkmcnt(0)
	v_mfma_f32_16x16x32_bf16 v[94:97], v[242:245], v[26:29], v[94:97]
	v_mfma_f32_16x16x32_bf16 v[26:29], v[250:253], v[26:29], v[90:93]
	v_mfma_f32_16x16x32_bf16 v[118:121], v[168:171], v[34:37], v[26:29]
	v_mfma_f32_16x16x32_bf16 v[26:29], v[242:245], v[58:61], v[86:89]
	v_mfma_f32_16x16x32_bf16 v[98:101], v[246:249], v[62:65], v[26:29]
	v_mfma_f32_16x16x32_bf16 v[26:29], v[250:253], v[58:61], v[82:85]
	v_mfma_f32_16x16x32_bf16 v[102:105], v[168:171], v[62:65], v[26:29]
	v_mfma_f32_16x16x32_bf16 v[26:29], v[242:245], v[208:211], v[78:81]
	v_mfma_f32_16x16x32_bf16 v[82:85], v[246:249], v[212:215], v[26:29]
	v_mfma_f32_16x16x32_bf16 v[26:29], v[250:253], v[208:211], v[74:77]
	v_mfma_f32_16x16x32_bf16 v[90:93], v[168:171], v[212:215], v[26:29]
	v_mfma_f32_16x16x32_bf16 v[26:29], v[242:245], v[216:219], v[70:73]
	v_mfma_f32_16x16x32_bf16 v[58:61], v[246:249], v[220:223], v[26:29]
	v_mfma_f32_16x16x32_bf16 v[26:29], v[250:253], v[216:219], v[66:69]
	v_mfma_f32_16x16x32_bf16 v[114:117], v[246:249], v[34:37], v[94:97]
	v_mfma_f32_16x16x32_bf16 v[62:65], v[168:171], v[220:223], v[26:29]
	s_barrier
	ds_read_b128 v[74:77], v0 offset:49152
	ds_read_b128 v[78:81], v0 offset:50176
	ds_read_b128 v[110:113], v0 offset:51200
	ds_read_b128 v[208:211], v0 offset:52224
	ds_read_b128 v[212:215], v0 offset:53248
	ds_read_b128 v[216:219], v0 offset:54272
	ds_read_b128 v[220:223], v0 offset:55296
	ds_read_b128 v[152:155], v0 offset:56320
	s_barrier
	s_waitcnt lgkmcnt(0)
	s_waitcnt lgkmcnt(0)
	v_mfma_f32_16x16x32_bf16 v[26:29], v[10:13], v[74:77], v[226:229]
	v_mfma_f32_16x16x32_bf16 v[86:89], v[14:17], v[78:81], v[26:29]
	v_mfma_f32_16x16x32_bf16 v[26:29], v[200:203], v[74:77], v[230:233]
	v_mfma_f32_16x16x32_bf16 v[94:97], v[204:207], v[78:81], v[26:29]
	v_mfma_f32_16x16x32_bf16 v[26:29], v[10:13], v[110:113], v[234:237]
	v_mfma_f32_16x16x32_bf16 v[66:69], v[14:17], v[208:211], v[26:29]
	v_mfma_f32_16x16x32_bf16 v[26:29], v[200:203], v[110:113], v[238:241]
	v_mfma_f32_16x16x32_bf16 v[70:73], v[204:207], v[208:211], v[26:29]
	v_mfma_f32_16x16x32_bf16 v[26:29], v[10:13], v[212:215], v[46:49]
	v_mfma_f32_16x16x32_bf16 v[10:13], v[10:13], v[220:223], v[130:133]
	v_mfma_f32_16x16x32_bf16 v[26:29], v[14:17], v[216:219], v[26:29]
	v_mfma_f32_16x16x32_bf16 v[34:37], v[200:203], v[212:215], v[42:45]
	v_mfma_f32_16x16x32_bf16 v[10:13], v[14:17], v[152:155], v[10:13]
	v_mfma_f32_16x16x32_bf16 v[14:17], v[200:203], v[220:223], v[142:145]
	v_mfma_f32_16x16x32_bf16 v[34:37], v[204:207], v[216:219], v[34:37]
	v_mfma_f32_16x16x32_bf16 v[14:17], v[204:207], v[152:155], v[14:17]
	v_mfma_f32_16x16x32_bf16 v[42:45], v[242:245], v[74:77], v[146:149]
	v_mfma_f32_16x16x32_bf16 v[122:125], v[246:249], v[78:81], v[42:45]
	v_mfma_f32_16x16x32_bf16 v[42:45], v[250:253], v[74:77], v[172:175]
	v_mfma_f32_16x16x32_bf16 v[126:129], v[168:171], v[78:81], v[42:45]
	v_mfma_f32_16x16x32_bf16 v[42:45], v[242:245], v[110:113], v[176:179]
	v_mfma_f32_16x16x32_bf16 v[106:109], v[246:249], v[208:211], v[42:45]
	v_mfma_f32_16x16x32_bf16 v[42:45], v[250:253], v[110:113], v[180:183]
	v_mfma_f32_16x16x32_bf16 v[110:113], v[168:171], v[208:211], v[42:45]
	v_mfma_f32_16x16x32_bf16 v[42:45], v[242:245], v[212:215], v[184:187]
	v_mfma_f32_16x16x32_bf16 v[74:77], v[246:249], v[216:219], v[42:45]
	v_mfma_f32_16x16x32_bf16 v[42:45], v[250:253], v[212:215], v[188:191]
	v_mfma_f32_16x16x32_bf16 v[78:81], v[168:171], v[216:219], v[42:45]
	v_mfma_f32_16x16x32_bf16 v[42:45], v[242:245], v[220:223], v[192:195]
	v_mfma_f32_16x16x32_bf16 v[46:49], v[246:249], v[152:155], v[42:45]
	v_mfma_f32_16x16x32_bf16 v[42:45], v[250:253], v[220:223], v[196:199]
	v_mfma_f32_16x16x32_bf16 v[42:45], v[168:171], v[152:155], v[42:45]
	v_cmp_gt_u32_e32 vcc, s97, v139
	s_barrier
	s_and_saveexec_b64 s[10:11], vcc
	s_cbranch_execz .LBB0_658
	s_barrier
	s_branch .LBB0_658

; #define WAIT_V(n) asm volatile("s_waitcnt vmcnt(%0)" ::"n"(n) : "memory")
; #define WAIT_L(n) asm volatile("s_waitcnt lgkmcnt(%0)" ::"n"(n) : "memory")
; #define SBAR() __builtin_amdgcn_sched_barrier(0)
; #define LDA8(dst, b, h) _Pragma("unroll") for (int m = 0; m < 4; ++m) _Pragma("unroll") for (int k = 0; k < 2; ++k) \
;     dst[m][k] = *(const bf16x8*)(abase + SAo(b, h) + m * 2048 + k * 1024)
; #define LDB8(dst, b, h) _Pragma("unroll") for (int n = 0; n < 2; ++n) _Pragma("unroll") for (int k = 0; k < 2; ++k) \
;     dst[n][k] = *(const bf16x8*)(bbase + SAo(b, h) + n * 2048 + k * 1024)
; #define BAR8 __builtin_amdgcn_s_barrier()
; __device__ __forceinline__ void gemm_main8(const u16* __restrict__ Ab, int lda, const u16* __restrict__ Bb, int ldb, int K,
;                                            char* shm, f32x4 (&acc)[2][2][4][2]) {
;     ...
;     LDB8(B0, 0, 0); SBAR(); LDA8(At, 0, 0); STG_A(1, 1, t + 1);
;     WAIT_L(8); BAR8; WAIT_L(0); MMA8(0, 0, At, B0); BAR8; SBAR();
;     LDB8(B1, 0, 1); STG_B(0, 0, t + 2);
;     BAR8; WAIT_L(0); MMA8(0, 1, At, B1); BAR8;
;     LDA8(At, 0, 1); STG_A(0, 0, t + 2);
;     BAR8; WAIT_L(0); MMA8(1, 0, At, B0); BAR8; SBAR();
;     STG_B(0, 1, t + 2);
;     WAIT_V(6); BAR8; MMA8(1, 1, At, B1); BAR8;
.LBB0_816:
	ds_read_b128 v[152:155], v137
	ds_read_b128 v[176:179], v137 offset:1024
	ds_read_b128 v[180:183], v137 offset:2048
	ds_read_b128 v[184:187], v137 offset:3072
	v_add_u32_e32 v173, 0xc000, v138
	v_lshl_add_u64 v[164:165], s[24:25], 0, v[0:1]
	v_readfirstlane_b32 s11, v173
	v_add_u32_e32 v174, 0xe000, v138
	v_lshl_add_u64 v[166:167], v[164:165], 0, s[54:55]
	s_mov_b32 m0, s11
	v_readfirstlane_b32 s11, v174
	ds_read_b128 v[188:191], v136
	ds_read_b128 v[192:195], v136 offset:1024
	ds_read_b128 v[196:199], v136 offset:2048
	ds_read_b128 v[200:203], v136 offset:3072
	ds_read_b128 v[204:207], v136 offset:4096
	ds_read_b128 v[208:211], v136 offset:5120
	ds_read_b128 v[212:215], v136 offset:6144
	ds_read_b128 v[216:219], v136 offset:7168
	global_load_lds_dwordx4 v[166:167], off
	v_lshl_add_u64 v[166:167], v[164:165], 0, s[56:57]
	s_mov_b32 m0, s11
	s_nop 0
	global_load_lds_dwordx4 v[166:167], off
	s_waitcnt lgkmcnt(8)
	s_barrier
	s_waitcnt lgkmcnt(0)
	s_waitcnt lgkmcnt(0)
	v_mfma_f32_16x16x32_bf16 v[126:129], v[152:155], v[188:191], v[126:129]
	v_mfma_f32_16x16x32_bf16 v[122:125], v[180:183], v[188:191], v[122:125]
	v_mfma_f32_16x16x32_bf16 v[118:121], v[152:155], v[196:199], v[118:121]
	v_mfma_f32_16x16x32_bf16 v[114:117], v[180:183], v[196:199], v[114:117]
	v_mfma_f32_16x16x32_bf16 v[110:113], v[152:155], v[204:207], v[110:113]
	v_mfma_f32_16x16x32_bf16 v[106:109], v[180:183], v[204:207], v[106:109]
	v_mfma_f32_16x16x32_bf16 v[102:105], v[152:155], v[212:215], v[102:105]
	v_mfma_f32_16x16x32_bf16 v[98:101], v[180:183], v[212:215], v[98:101]
	v_mfma_f32_16x16x32_bf16 v[126:129], v[176:179], v[192:195], v[126:129]
	v_mfma_f32_16x16x32_bf16 v[122:125], v[184:187], v[192:195], v[122:125]
	v_mfma_f32_16x16x32_bf16 v[118:121], v[176:179], v[200:203], v[118:121]
	v_mfma_f32_16x16x32_bf16 v[114:117], v[184:187], v[200:203], v[114:117]
	v_mfma_f32_16x16x32_bf16 v[110:113], v[176:179], v[208:211], v[110:113]
	v_mfma_f32_16x16x32_bf16 v[106:109], v[184:187], v[208:211], v[106:109]
	v_mfma_f32_16x16x32_bf16 v[102:105], v[176:179], v[216:219], v[102:105]
	v_mfma_f32_16x16x32_bf16 v[98:101], v[184:187], v[216:219], v[98:101]
	s_barrier
	v_lshl_add_u64 v[166:167], s[20:21], 0, v[0:1]
	v_readfirstlane_b32 s11, v139
	v_lshl_add_u64 v[168:169], v[166:167], 0, s[70:71]
	s_mov_b32 m0, s11
	s_mov_b64 s[74:75], 0x40100
	v_readfirstlane_b32 s11, v140
	ds_read_b128 v[220:223], v137 offset:16384
	ds_read_b128 v[224:227], v137 offset:17408
	ds_read_b128 v[228:231], v137 offset:18432
	ds_read_b128 v[232:235], v137 offset:19456
	global_load_lds_dwordx4 v[168:169], off
	v_lshl_add_u64 v[168:169], v[166:167], 0, s[74:75]
	s_mov_b32 m0, s11
	s_nop 0
	global_load_lds_dwordx4 v[168:169], off
	s_barrier
	s_waitcnt lgkmcnt(0)
	s_waitcnt lgkmcnt(0)
	v_mfma_f32_16x16x32_bf16 v[94:97], v[220:223], v[188:191], v[94:97]
	v_mfma_f32_16x16x32_bf16 v[90:93], v[228:231], v[188:191], v[90:93]
	v_mfma_f32_16x16x32_bf16 v[86:89], v[220:223], v[196:199], v[86:89]
	v_mfma_f32_16x16x32_bf16 v[82:85], v[228:231], v[196:199], v[82:85]
	v_mfma_f32_16x16x32_bf16 v[78:81], v[220:223], v[204:207], v[78:81]
	v_mfma_f32_16x16x32_bf16 v[74:77], v[228:231], v[204:207], v[74:77]
	v_mfma_f32_16x16x32_bf16 v[70:73], v[220:223], v[212:215], v[70:73]
	v_mfma_f32_16x16x32_bf16 v[66:69], v[228:231], v[212:215], v[66:69]
	v_mfma_f32_16x16x32_bf16 v[94:97], v[224:227], v[192:195], v[94:97]
	v_mfma_f32_16x16x32_bf16 v[90:93], v[232:235], v[192:195], v[90:93]
	v_mfma_f32_16x16x32_bf16 v[86:89], v[224:227], v[200:203], v[86:89]
	v_mfma_f32_16x16x32_bf16 v[82:85], v[232:235], v[200:203], v[82:85]
	v_mfma_f32_16x16x32_bf16 v[78:81], v[224:227], v[208:211], v[78:81]
	v_mfma_f32_16x16x32_bf16 v[74:77], v[232:235], v[208:211], v[74:77]
	v_mfma_f32_16x16x32_bf16 v[70:73], v[224:227], v[216:219], v[70:73]
	v_mfma_f32_16x16x32_bf16 v[66:69], v[232:235], v[216:219], v[66:69]
	v_readfirstlane_b32 s11, v138
	v_lshl_add_u64 v[168:169], v[164:165], 0, s[58:59]
	s_mov_b32 m0, s11
	v_readfirstlane_b32 s11, v141
	s_barrier
	ds_read_b128 v[188:191], v136 offset:16384
	ds_read_b128 v[192:195], v136 offset:17408
	ds_read_b128 v[196:199], v136 offset:18432
	ds_read_b128 v[200:203], v136 offset:19456
	ds_read_b128 v[204:207], v136 offset:20480
	ds_read_b128 v[208:211], v136 offset:21504
	ds_read_b128 v[212:215], v136 offset:22528
	ds_read_b128 v[216:219], v136 offset:23552
	global_load_lds_dwordx4 v[168:169], off
	v_lshl_add_u64 v[168:169], v[164:165], 0, s[60:61]
	s_mov_b32 m0, s11
	s_nop 0
	global_load_lds_dwordx4 v[168:169], off
	s_barrier
	s_waitcnt lgkmcnt(0)
	s_waitcnt lgkmcnt(0)
	v_mfma_f32_16x16x32_bf16 v[62:65], v[152:155], v[188:191], v[62:65]
	v_mfma_f32_16x16x32_bf16 v[58:61], v[180:183], v[188:191], v[58:61]
	v_mfma_f32_16x16x32_bf16 v[54:57], v[152:155], v[196:199], v[54:57]
	v_mfma_f32_16x16x32_bf16 v[50:53], v[180:183], v[196:199], v[50:53]
	v_mfma_f32_16x16x32_bf16 v[46:49], v[152:155], v[204:207], v[46:49]
	v_mfma_f32_16x16x32_bf16 v[42:45], v[180:183], v[204:207], v[42:45]
	v_mfma_f32_16x16x32_bf16 v[38:41], v[152:155], v[212:215], v[38:41]
	v_mfma_f32_16x16x32_bf16 v[34:37], v[180:183], v[212:215], v[34:37]
	v_mfma_f32_16x16x32_bf16 v[62:65], v[176:179], v[192:195], v[62:65]
	v_mfma_f32_16x16x32_bf16 v[58:61], v[184:187], v[192:195], v[58:61]
	v_mfma_f32_16x16x32_bf16 v[54:57], v[176:179], v[200:203], v[54:57]
	v_mfma_f32_16x16x32_bf16 v[50:53], v[184:187], v[200:203], v[50:53]
	v_mfma_f32_16x16x32_bf16 v[46:49], v[176:179], v[208:211], v[46:49]
	v_mfma_f32_16x16x32_bf16 v[42:45], v[184:187], v[208:211], v[42:45]
	v_mfma_f32_16x16x32_bf16 v[38:41], v[176:179], v[216:219], v[38:41]
	v_mfma_f32_16x16x32_bf16 v[34:37], v[184:187], v[216:219], v[34:37]
	s_barrier
; #define WAIT_V(n) asm volatile("s_waitcnt vmcnt(%0)" ::"n"(n) : "memory")
; #define WAIT_L(n) asm volatile("s_waitcnt lgkmcnt(%0)" ::"n"(n) : "memory")
; #define SBAR() __builtin_amdgcn_sched_barrier(0)
; #define LDA8(dst, b, h) _Pragma("unroll") for (int m = 0; m < 4; ++m) _Pragma("unroll") for (int k = 0; k < 2; ++k) \
;     dst[m][k] = *(const bf16x8*)(abase + SAo(b, h) + m * 2048 + k * 1024)
; #define LDB8(dst, b, h) _Pragma("unroll") for (int n = 0; n < 2; ++n) _Pragma("unroll") for (int k = 0; k < 2; ++k) \
;     dst[n][k] = *(const bf16x8*)(bbase + SAo(b, h) + n * 2048 + k * 1024)
; #define BAR8 __builtin_amdgcn_s_barrier()
; __device__ __forceinline__ void gemm_main8(const u16* __restrict__ Ab, int lda, const u16* __restrict__ Bb, int ldb, int K,
;                                            char* shm, f32x4 (&acc)[2][2][4][2]) {
;     ...
;     STG_B(0, 1, t + 2);
;     WAIT_V(6); BAR8; MMA8(1, 1, At, B1); BAR8;
;     LDB8(B0, 1, 0); SBAR(); LDA8(At, 1, 0); STG_A(0, 1, t + 2);
;     WAIT_L(8); BAR8; WAIT_L(0); MMA8(0, 0, At, B0); BAR8; SBAR();
;     LDB8(B1, 1, 1); STG_B(1, 0, t + 3);
;     BAR8; WAIT_L(0); MMA8(0, 1, At, B1); BAR8;
;     LDA8(At, 1, 1); STG_A(1, 0, t + 3);
	s_mov_b64 s[74:75], 0x80100
	v_readfirstlane_b32 s11, v142
	v_lshl_add_u64 v[152:153], v[166:167], 0, s[74:75]
	s_mov_b32 m0, s11
	s_mov_b64 s[74:75], 0xc0100
	v_readfirstlane_b32 s11, v143
	global_load_lds_dwordx4 v[152:153], off
	v_lshl_add_u64 v[152:153], v[166:167], 0, s[74:75]
	s_mov_b32 m0, s11
	s_nop 0
	global_load_lds_dwordx4 v[152:153], off
	s_waitcnt vmcnt(6)
	s_barrier
	v_mfma_f32_16x16x32_bf16 v[30:33], v[220:223], v[188:191], v[30:33]
	v_mfma_f32_16x16x32_bf16 v[26:29], v[228:231], v[188:191], v[26:29]
	v_mfma_f32_16x16x32_bf16 v[22:25], v[220:223], v[196:199], v[22:25]
	v_mfma_f32_16x16x32_bf16 v[18:21], v[228:231], v[196:199], v[18:21]
	v_mfma_f32_16x16x32_bf16 v[14:17], v[220:223], v[204:207], v[14:17]
	v_mfma_f32_16x16x32_bf16 v[10:13], v[228:231], v[204:207], v[10:13]
	v_mfma_f32_16x16x32_bf16 v[6:9], v[220:223], v[212:215], v[6:9]
	v_mfma_f32_16x16x32_bf16 v[2:5], v[228:231], v[212:215], v[2:5]
	v_mfma_f32_16x16x32_bf16 v[30:33], v[224:227], v[192:195], v[30:33]
	v_mfma_f32_16x16x32_bf16 v[26:29], v[232:235], v[192:195], v[26:29]
	v_mfma_f32_16x16x32_bf16 v[22:25], v[224:227], v[200:203], v[22:25]
	v_mfma_f32_16x16x32_bf16 v[18:21], v[232:235], v[200:203], v[18:21]
	v_mfma_f32_16x16x32_bf16 v[14:17], v[224:227], v[208:211], v[14:17]
	v_mfma_f32_16x16x32_bf16 v[10:13], v[232:235], v[208:211], v[10:13]
	v_mfma_f32_16x16x32_bf16 v[6:9], v[224:227], v[216:219], v[6:9]
	v_mfma_f32_16x16x32_bf16 v[2:5], v[232:235], v[216:219], v[2:5]
	s_barrier
	ds_read_b128 v[152:155], v137 offset:32768
	ds_read_b128 v[176:179], v137 offset:33792
	ds_read_b128 v[180:183], v137 offset:34816
	ds_read_b128 v[184:187], v137 offset:35840
	v_readfirstlane_b32 s11, v144
	v_lshl_add_u64 v[168:169], v[164:165], 0, s[62:63]
	s_mov_b32 m0, s11
	v_readfirstlane_b32 s11, v145
	ds_read_b128 v[188:191], v136 offset:32768
	ds_read_b128 v[192:195], v136 offset:33792
	ds_read_b128 v[196:199], v136 offset:34816
	ds_read_b128 v[200:203], v136 offset:35840
	ds_read_b128 v[204:207], v136 offset:36864
	ds_read_b128 v[208:211], v136 offset:37888
	ds_read_b128 v[212:215], v136 offset:38912
	ds_read_b128 v[216:219], v136 offset:39936
	global_load_lds_dwordx4 v[168:169], off
	v_lshl_add_u64 v[168:169], v[164:165], 0, s[64:65]
	s_mov_b32 m0, s11
	s_nop 0
	global_load_lds_dwordx4 v[168:169], off
	s_waitcnt lgkmcnt(8)
	s_barrier
	s_waitcnt lgkmcnt(0)
	s_waitcnt lgkmcnt(0)
	v_mfma_f32_16x16x32_bf16 v[126:129], v[152:155], v[188:191], v[126:129]
	v_mfma_f32_16x16x32_bf16 v[122:125], v[180:183], v[188:191], v[122:125]
	v_mfma_f32_16x16x32_bf16 v[118:121], v[152:155], v[196:199], v[118:121]
	v_mfma_f32_16x16x32_bf16 v[114:117], v[180:183], v[196:199], v[114:117]
	v_mfma_f32_16x16x32_bf16 v[110:113], v[152:155], v[204:207], v[110:113]
	v_mfma_f32_16x16x32_bf16 v[106:109], v[180:183], v[204:207], v[106:109]
	v_mfma_f32_16x16x32_bf16 v[102:105], v[152:155], v[212:215], v[102:105]
	v_mfma_f32_16x16x32_bf16 v[98:101], v[180:183], v[212:215], v[98:101]
	v_mfma_f32_16x16x32_bf16 v[126:129], v[176:179], v[192:195], v[126:129]
	v_mfma_f32_16x16x32_bf16 v[122:125], v[184:187], v[192:195], v[122:125]
	v_mfma_f32_16x16x32_bf16 v[118:121], v[176:179], v[200:203], v[118:121]
	v_mfma_f32_16x16x32_bf16 v[114:117], v[184:187], v[200:203], v[114:117]
	v_mfma_f32_16x16x32_bf16 v[110:113], v[176:179], v[208:211], v[110:113]
	v_mfma_f32_16x16x32_bf16 v[106:109], v[184:187], v[208:211], v[106:109]
	v_mfma_f32_16x16x32_bf16 v[102:105], v[176:179], v[216:219], v[102:105]
	v_mfma_f32_16x16x32_bf16 v[98:101], v[184:187], v[216:219], v[98:101]
	s_barrier
	v_readfirstlane_b32 s11, v146
	v_lshl_add_u64 v[168:169], v[166:167], 0, s[8:9]
	s_mov_b32 m0, s11
	s_mov_b64 s[74:75], 0x40180
	v_readfirstlane_b32 s11, v147
	ds_read_b128 v[220:223], v137 offset:49152
	ds_read_b128 v[224:227], v137 offset:50176
	ds_read_b128 v[228:231], v137 offset:51200
	ds_read_b128 v[232:235], v137 offset:52224
	global_load_lds_dwordx4 v[168:169], off
	v_lshl_add_u64 v[168:169], v[166:167], 0, s[74:75]
	s_mov_b32 m0, s11
	s_nop 0
	global_load_lds_dwordx4 v[168:169], off
	s_barrier
	s_waitcnt lgkmcnt(0)
	s_waitcnt lgkmcnt(0)
	v_mfma_f32_16x16x32_bf16 v[94:97], v[220:223], v[188:191], v[94:97]
	v_mfma_f32_16x16x32_bf16 v[90:93], v[228:231], v[188:191], v[90:93]
	v_mfma_f32_16x16x32_bf16 v[86:89], v[220:223], v[196:199], v[86:89]
	v_mfma_f32_16x16x32_bf16 v[82:85], v[228:231], v[196:199], v[82:85]
	v_mfma_f32_16x16x32_bf16 v[78:81], v[220:223], v[204:207], v[78:81]
	v_mfma_f32_16x16x32_bf16 v[74:77], v[228:231], v[204:207], v[74:77]
	v_mfma_f32_16x16x32_bf16 v[70:73], v[220:223], v[212:215], v[70:73]
	v_mfma_f32_16x16x32_bf16 v[66:69], v[228:231], v[212:215], v[66:69]
	v_mfma_f32_16x16x32_bf16 v[94:97], v[224:227], v[192:195], v[94:97]
	v_mfma_f32_16x16x32_bf16 v[90:93], v[232:235], v[192:195], v[90:93]
	v_mfma_f32_16x16x32_bf16 v[86:89], v[224:227], v[200:203], v[86:89]
	v_mfma_f32_16x16x32_bf16 v[82:85], v[232:235], v[200:203], v[82:85]
	v_mfma_f32_16x16x32_bf16 v[78:81], v[224:227], v[208:211], v[78:81]
	v_mfma_f32_16x16x32_bf16 v[74:77], v[232:235], v[208:211], v[74:77]
	v_mfma_f32_16x16x32_bf16 v[70:73], v[224:227], v[216:219], v[70:73]
	v_mfma_f32_16x16x32_bf16 v[66:69], v[232:235], v[216:219], v[66:69]
	v_readfirstlane_b32 s11, v148
	v_lshl_add_u64 v[168:169], v[164:165], 0, s[66:67]
	s_mov_b32 m0, s11
	v_readfirstlane_b32 s11, v149
	s_barrier
	ds_read_b128 v[188:191], v136 offset:49152
	ds_read_b128 v[192:195], v136 offset:50176
	ds_read_b128 v[196:199], v136 offset:51200
	ds_read_b128 v[200:203], v136 offset:52224
	ds_read_b128 v[204:207], v136 offset:53248
	ds_read_b128 v[208:211], v136 offset:54272
	ds_read_b128 v[212:215], v136 offset:55296
	ds_read_b128 v[216:219], v136 offset:56320
	global_load_lds_dwordx4 v[168:169], off
	v_lshl_add_u64 v[164:165], v[164:165], 0, s[68:69]
	s_mov_b32 m0, s11
	s_nop 0
	global_load_lds_dwordx4 v[164:165], off
	s_barrier
; #define WAIT_V(n) asm volatile("s_waitcnt vmcnt(%0)" ::"n"(n) : "memory")
; #define WAIT_L(n) asm volatile("s_waitcnt lgkmcnt(%0)" ::"n"(n) : "memory")
; #define SBAR() __builtin_amdgcn_sched_barrier(0)
; #define LDA8(dst, b, h) _Pragma("unroll") for (int m = 0; m < 4; ++m) _Pragma("unroll") for (int k = 0; k < 2; ++k) \
;     dst[m][k] = *(const bf16x8*)(abase + SAo(b, h) + m * 2048 + k * 1024)
; #define LDB8(dst, b, h) _Pragma("unroll") for (int n = 0; n < 2; ++n) _Pragma("unroll") for (int k = 0; k < 2; ++k) \
;     dst[n][k] = *(const bf16x8*)(bbase + SAo(b, h) + n * 2048 + k * 1024)
; #define BAR8 __builtin_amdgcn_s_barrier()
; __device__ __forceinline__ void gemm_main8(const u16* __restrict__ Ab, int lda, const u16* __restrict__ Bb, int ldb, int K,
;                                            char* shm, f32x4 (&acc)[2][2][4][2]) {
;     ...
;     LDB8(B1, 1, 1); STG_B(1, 0, t + 3);
;     BAR8; WAIT_L(0); MMA8(0, 1, At, B1); BAR8;
;     LDA8(At, 1, 1); STG_A(1, 0, t + 3);
;     BAR8; WAIT_L(0); MMA8(1, 0, At, B0); BAR8; SBAR();
;     STG_B(1, 1, t + 3);
;     WAIT_V(6); BAR8; MMA8(1, 1, At, B1); BAR8;
;   }
;   { LDB8(B0, 0, 0); LDA8(At, 0, 0); STG_A(1, 1, nt - 1);
;     BAR8; WAIT_L(0); MMA8(0, 0, At, B0); BAR8;
	s_waitcnt lgkmcnt(0)
	s_waitcnt lgkmcnt(0)
	v_mfma_f32_16x16x32_bf16 v[62:65], v[152:155], v[188:191], v[62:65]
	v_mfma_f32_16x16x32_bf16 v[58:61], v[180:183], v[188:191], v[58:61]
	v_mfma_f32_16x16x32_bf16 v[54:57], v[152:155], v[196:199], v[54:57]
	v_mfma_f32_16x16x32_bf16 v[50:53], v[180:183], v[196:199], v[50:53]
	v_mfma_f32_16x16x32_bf16 v[46:49], v[152:155], v[204:207], v[46:49]
	v_mfma_f32_16x16x32_bf16 v[42:45], v[180:183], v[204:207], v[42:45]
	v_mfma_f32_16x16x32_bf16 v[38:41], v[152:155], v[212:215], v[38:41]
	v_mfma_f32_16x16x32_bf16 v[34:37], v[180:183], v[212:215], v[34:37]
	v_mfma_f32_16x16x32_bf16 v[62:65], v[176:179], v[192:195], v[62:65]
	v_mfma_f32_16x16x32_bf16 v[58:61], v[184:187], v[192:195], v[58:61]
	v_mfma_f32_16x16x32_bf16 v[54:57], v[176:179], v[200:203], v[54:57]
	v_mfma_f32_16x16x32_bf16 v[50:53], v[184:187], v[200:203], v[50:53]
	v_mfma_f32_16x16x32_bf16 v[46:49], v[176:179], v[208:211], v[46:49]
	v_mfma_f32_16x16x32_bf16 v[42:45], v[184:187], v[208:211], v[42:45]
	v_mfma_f32_16x16x32_bf16 v[38:41], v[176:179], v[216:219], v[38:41]
	v_mfma_f32_16x16x32_bf16 v[34:37], v[184:187], v[216:219], v[34:37]
	s_barrier
	s_mov_b64 s[74:75], 0x80180
	v_readfirstlane_b32 s11, v171
	v_lshl_add_u64 v[152:153], v[166:167], 0, s[74:75]
	s_mov_b32 m0, s11
	s_mov_b64 s[74:75], 0xc0180
	v_readfirstlane_b32 s11, v172
	global_load_lds_dwordx4 v[152:153], off
	v_lshl_add_u64 v[152:153], v[166:167], 0, s[74:75]
	s_mov_b32 m0, s11
	s_nop 0
	global_load_lds_dwordx4 v[152:153], off
	s_waitcnt vmcnt(6)
	s_barrier
	v_mfma_f32_16x16x32_bf16 v[30:33], v[220:223], v[188:191], v[30:33]
	v_mfma_f32_16x16x32_bf16 v[26:29], v[228:231], v[188:191], v[26:29]
	v_mfma_f32_16x16x32_bf16 v[22:25], v[220:223], v[196:199], v[22:25]
	v_mfma_f32_16x16x32_bf16 v[18:21], v[228:231], v[196:199], v[18:21]
	v_mfma_f32_16x16x32_bf16 v[14:17], v[220:223], v[204:207], v[14:17]
	v_mfma_f32_16x16x32_bf16 v[10:13], v[228:231], v[204:207], v[10:13]
	v_mfma_f32_16x16x32_bf16 v[6:9], v[220:223], v[212:215], v[6:9]
	v_mfma_f32_16x16x32_bf16 v[2:5], v[228:231], v[212:215], v[2:5]
	v_mfma_f32_16x16x32_bf16 v[30:33], v[224:227], v[192:195], v[30:33]
	v_mfma_f32_16x16x32_bf16 v[26:29], v[232:235], v[192:195], v[26:29]
	v_mfma_f32_16x16x32_bf16 v[22:25], v[224:227], v[200:203], v[22:25]
	v_mfma_f32_16x16x32_bf16 v[18:21], v[232:235], v[200:203], v[18:21]
	v_mfma_f32_16x16x32_bf16 v[14:17], v[224:227], v[208:211], v[14:17]
	v_mfma_f32_16x16x32_bf16 v[10:13], v[232:235], v[208:211], v[10:13]
	v_mfma_f32_16x16x32_bf16 v[6:9], v[224:227], v[216:219], v[6:9]
	v_mfma_f32_16x16x32_bf16 v[2:5], v[232:235], v[216:219], v[2:5]
	s_add_i32 s10, s10, 2
	s_add_u32 s20, s20, 0x100
	s_addc_u32 s21, s21, 0
	s_add_u32 s24, s24, 0x100
	s_addc_u32 s25, s25, 0
	s_cmp_lt_u32 s10, 28
	s_barrier
	s_cbranch_scc1 .LBB0_816
	s_mov_b64 s[10:11], 0x80f80
	v_lshl_add_u64 v[164:165], v[130:131], 0, s[10:11]
	v_readfirstlane_b32 s10, v173
	s_mov_b32 m0, s10
	s_mov_b64 s[10:11], 0xc0f80
	v_lshl_add_u64 v[130:131], v[130:131], 0, s[10:11]
	v_readfirstlane_b32 s10, v174
	ds_read_b128 v[138:141], v137
	ds_read_b128 v[142:145], v137 offset:1024
	ds_read_b128 v[146:149], v137 offset:2048
	ds_read_b128 v[152:155], v137 offset:3072
	ds_read_b128 v[168:171], v136
	ds_read_b128 v[176:179], v136 offset:1024
	ds_read_b128 v[180:183], v136 offset:2048
	ds_read_b128 v[184:187], v136 offset:3072
	ds_read_b128 v[188:191], v136 offset:4096
	ds_read_b128 v[192:195], v136 offset:5120
	ds_read_b128 v[196:199], v136 offset:6144
	ds_read_b128 v[200:203], v136 offset:7168
	global_load_lds_dwordx4 v[164:165], off
	s_mov_b32 m0, s10
	s_nop 0
	global_load_lds_dwordx4 v[130:131], off
	s_barrier
	s_waitcnt lgkmcnt(0)
	s_waitcnt lgkmcnt(0)
	v_mfma_f32_16x16x32_bf16 v[126:129], v[138:141], v[168:171], v[126:129]
	v_mfma_f32_16x16x32_bf16 v[118:121], v[138:141], v[180:183], v[118:121]
	v_mfma_f32_16x16x32_bf16 v[110:113], v[138:141], v[188:191], v[110:113]
	v_mfma_f32_16x16x32_bf16 v[102:105], v[138:141], v[196:199], v[102:105]
	v_mfma_f32_16x16x32_bf16 v[126:129], v[142:145], v[176:179], v[126:129]
	v_mfma_f32_16x16x32_bf16 v[122:125], v[146:149], v[168:171], v[122:125]
	v_mfma_f32_16x16x32_bf16 v[118:121], v[142:145], v[184:187], v[118:121]
	v_mfma_f32_16x16x32_bf16 v[114:117], v[146:149], v[180:183], v[114:117]
	v_mfma_f32_16x16x32_bf16 v[110:113], v[142:145], v[192:195], v[110:113]
	v_mfma_f32_16x16x32_bf16 v[106:109], v[146:149], v[188:191], v[106:109]
	v_mfma_f32_16x16x32_bf16 v[102:105], v[142:145], v[200:203], v[102:105]
	v_mfma_f32_16x16x32_bf16 v[98:101], v[146:149], v[196:199], v[98:101]
	v_mfma_f32_16x16x32_bf16 v[172:175], v[152:155], v[176:179], v[122:125]
	v_mfma_f32_16x16x32_bf16 v[204:207], v[152:155], v[184:187], v[114:117]
	v_mfma_f32_16x16x32_bf16 v[208:211], v[152:155], v[192:195], v[106:109]
	v_mfma_f32_16x16x32_bf16 v[212:215], v[152:155], v[200:203], v[98:101]
	s_barrier
	s_nop 1
	ds_read_b128 v[98:101], v137 offset:16384
	ds_read_b128 v[106:109], v137 offset:17408
	ds_read_b128 v[114:117], v137 offset:18432
	ds_read_b128 v[122:125], v137 offset:19456
	s_barrier
; #define WAIT_V(n) asm volatile("s_waitcnt vmcnt(%0)" ::"n"(n) : "memory")
; #define WAIT_L(n) asm volatile("s_waitcnt lgkmcnt(%0)" ::"n"(n) : "memory")
; #define LDA8(dst, b, h) _Pragma("unroll") for (int m = 0; m < 4; ++m) _Pragma("unroll") for (int k = 0; k < 2; ++k) \
;     dst[m][k] = *(const bf16x8*)(abase + SAo(b, h) + m * 2048 + k * 1024)
; #define LDB8(dst, b, h) _Pragma("unroll") for (int n = 0; n < 2; ++n) _Pragma("unroll") for (int k = 0; k < 2; ++k) \
;     dst[n][k] = *(const bf16x8*)(bbase + SAo(b, h) + n * 2048 + k * 1024)
; #define BAR8 __builtin_amdgcn_s_barrier()
; __device__ __forceinline__ void gemm_main8(const u16* __restrict__ Ab, int lda, const u16* __restrict__ Bb, int ldb, int K,
;                                            char* shm, f32x4 (&acc)[2][2][4][2]) {
;     ...
;     LDB8(B1, 0, 1); BAR8; WAIT_L(0); MMA8(0, 1, At, B1); BAR8;
;     LDA8(At, 0, 1); WAIT_V(4); BAR8; WAIT_L(0); MMA8(1, 0, At, B0); MMA8(1, 1, At, B1); BAR8; }
;   { LDB8(B0, 1, 0); LDA8(At, 1, 0); WAIT_V(2); BAR8; WAIT_L(0); MMA8(0, 0, At, B0); BAR8;
	s_waitcnt lgkmcnt(0)
	s_waitcnt lgkmcnt(0)
	v_mfma_f32_16x16x32_bf16 v[94:97], v[98:101], v[168:171], v[94:97]
	v_mfma_f32_16x16x32_bf16 v[86:89], v[98:101], v[180:183], v[86:89]
	v_mfma_f32_16x16x32_bf16 v[78:81], v[98:101], v[188:191], v[78:81]
	v_mfma_f32_16x16x32_bf16 v[70:73], v[98:101], v[196:199], v[70:73]
	v_mfma_f32_16x16x32_bf16 v[94:97], v[106:109], v[176:179], v[94:97]
	v_mfma_f32_16x16x32_bf16 v[90:93], v[114:117], v[168:171], v[90:93]
	v_mfma_f32_16x16x32_bf16 v[86:89], v[106:109], v[184:187], v[86:89]
	v_mfma_f32_16x16x32_bf16 v[82:85], v[114:117], v[180:183], v[82:85]
	v_mfma_f32_16x16x32_bf16 v[78:81], v[106:109], v[192:195], v[78:81]
	v_mfma_f32_16x16x32_bf16 v[74:77], v[114:117], v[188:191], v[74:77]
	v_mfma_f32_16x16x32_bf16 v[70:73], v[106:109], v[200:203], v[70:73]
	v_mfma_f32_16x16x32_bf16 v[66:69], v[114:117], v[196:199], v[66:69]
	v_mfma_f32_16x16x32_bf16 v[168:171], v[122:125], v[176:179], v[90:93]
	v_mfma_f32_16x16x32_bf16 v[176:179], v[122:125], v[184:187], v[82:85]
	v_mfma_f32_16x16x32_bf16 v[180:183], v[122:125], v[192:195], v[74:77]
	v_mfma_f32_16x16x32_bf16 v[184:187], v[122:125], v[200:203], v[66:69]
	s_barrier
	s_nop 1
	ds_read_b128 v[66:69], v136 offset:16384
	ds_read_b128 v[74:77], v136 offset:17408
	ds_read_b128 v[82:85], v136 offset:18432
	ds_read_b128 v[90:93], v136 offset:19456
	ds_read_b128 v[188:191], v136 offset:20480
	ds_read_b128 v[192:195], v136 offset:21504
	ds_read_b128 v[196:199], v136 offset:22528
	ds_read_b128 v[200:203], v136 offset:23552
	s_waitcnt vmcnt(4)
	s_barrier
	s_waitcnt lgkmcnt(0)
	s_waitcnt lgkmcnt(0)
	v_mfma_f32_16x16x32_bf16 v[62:65], v[138:141], v[66:69], v[62:65]
	v_mfma_f32_16x16x32_bf16 v[58:61], v[146:149], v[66:69], v[58:61]
	v_mfma_f32_16x16x32_bf16 v[50:53], v[146:149], v[82:85], v[50:53]
	v_mfma_f32_16x16x32_bf16 v[42:45], v[146:149], v[188:191], v[42:45]
	v_mfma_f32_16x16x32_bf16 v[34:37], v[146:149], v[196:199], v[34:37]
	v_mfma_f32_16x16x32_bf16 v[62:65], v[142:145], v[74:77], v[62:65]
	v_mfma_f32_16x16x32_bf16 v[58:61], v[152:155], v[74:77], v[58:61]
	v_mfma_f32_16x16x32_bf16 v[54:57], v[138:141], v[82:85], v[54:57]
	v_mfma_f32_16x16x32_bf16 v[50:53], v[152:155], v[90:93], v[50:53]
	v_mfma_f32_16x16x32_bf16 v[46:49], v[138:141], v[188:191], v[46:49]
	v_mfma_f32_16x16x32_bf16 v[42:45], v[152:155], v[192:195], v[42:45]
	v_mfma_f32_16x16x32_bf16 v[38:41], v[138:141], v[196:199], v[38:41]
	v_mfma_f32_16x16x32_bf16 v[34:37], v[152:155], v[200:203], v[34:37]
	v_mfma_f32_16x16x32_bf16 v[216:219], v[142:145], v[90:93], v[54:57]
	v_mfma_f32_16x16x32_bf16 v[220:223], v[142:145], v[192:195], v[46:49]
	v_mfma_f32_16x16x32_bf16 v[138:141], v[142:145], v[200:203], v[38:41]
	v_mfma_f32_16x16x32_bf16 v[26:29], v[114:117], v[66:69], v[26:29]
	v_mfma_f32_16x16x32_bf16 v[18:21], v[114:117], v[82:85], v[18:21]
	v_mfma_f32_16x16x32_bf16 v[10:13], v[114:117], v[188:191], v[10:13]
	v_mfma_f32_16x16x32_bf16 v[2:5], v[114:117], v[196:199], v[2:5]
	v_mfma_f32_16x16x32_bf16 v[30:33], v[98:101], v[66:69], v[30:33]
	v_mfma_f32_16x16x32_bf16 v[26:29], v[122:125], v[74:77], v[26:29]
	v_mfma_f32_16x16x32_bf16 v[22:25], v[98:101], v[82:85], v[22:25]
	v_mfma_f32_16x16x32_bf16 v[18:21], v[122:125], v[90:93], v[18:21]
	v_mfma_f32_16x16x32_bf16 v[14:17], v[98:101], v[188:191], v[14:17]
	v_mfma_f32_16x16x32_bf16 v[10:13], v[122:125], v[192:195], v[10:13]
	v_mfma_f32_16x16x32_bf16 v[6:9], v[98:101], v[196:199], v[6:9]
	v_mfma_f32_16x16x32_bf16 v[2:5], v[122:125], v[200:203], v[2:5]
	v_mfma_f32_16x16x32_bf16 v[142:145], v[106:109], v[74:77], v[30:33]
	v_mfma_f32_16x16x32_bf16 v[146:149], v[106:109], v[90:93], v[22:25]
	v_mfma_f32_16x16x32_bf16 v[152:155], v[106:109], v[192:195], v[14:17]
	v_mfma_f32_16x16x32_bf16 v[188:191], v[106:109], v[200:203], v[6:9]
	s_barrier
	s_nop 0
	ds_read_b128 v[6:9], v137 offset:32768
	ds_read_b128 v[14:17], v137 offset:33792
	ds_read_b128 v[192:195], v137 offset:34816
	ds_read_b128 v[196:199], v137 offset:35840
	ds_read_b128 v[22:25], v136 offset:32768
	ds_read_b128 v[30:33], v136 offset:33792
	ds_read_b128 v[38:41], v136 offset:34816
	ds_read_b128 v[46:49], v136 offset:35840
	ds_read_b128 v[54:57], v136 offset:36864
	ds_read_b128 v[200:203], v136 offset:37888
	ds_read_b128 v[224:227], v136 offset:38912
	ds_read_b128 v[228:231], v136 offset:39936
	s_waitcnt vmcnt(2)
	s_barrier
; #define WAIT_V(n) asm volatile("s_waitcnt vmcnt(%0)" ::"n"(n) : "memory")
; #define WAIT_L(n) asm volatile("s_waitcnt lgkmcnt(%0)" ::"n"(n) : "memory")
; #define LDA8(dst, b, h) _Pragma("unroll") for (int m = 0; m < 4; ++m) _Pragma("unroll") for (int k = 0; k < 2; ++k) \
;     dst[m][k] = *(const bf16x8*)(abase + SAo(b, h) + m * 2048 + k * 1024)
; #define LDB8(dst, b, h) _Pragma("unroll") for (int n = 0; n < 2; ++n) _Pragma("unroll") for (int k = 0; k < 2; ++k) \
;     dst[n][k] = *(const bf16x8*)(bbase + SAo(b, h) + n * 2048 + k * 1024)
; #define BAR8 __builtin_amdgcn_s_barrier()
; __device__ __forceinline__ void gemm_main8(const u16* __restrict__ Ab, int lda, const u16* __restrict__ Bb, int ldb, int K,
;                                            char* shm, f32x4 (&acc)[2][2][4][2]) {
;     ...
;   { LDB8(B0, 1, 0); LDA8(At, 1, 0); WAIT_V(2); BAR8; WAIT_L(0); MMA8(0, 0, At, B0); BAR8;
;     LDB8(B1, 1, 1); WAIT_V(0); BAR8; WAIT_L(0); MMA8(0, 1, At, B1); BAR8;
;     LDA8(At, 1, 1); BAR8; WAIT_L(0); MMA8(1, 0, At, B0); MMA8(1, 1, At, B1); BAR8; }
;   if (wr == 0) BAR8;
	s_waitcnt lgkmcnt(0)
	s_waitcnt lgkmcnt(0)
	v_mfma_f32_16x16x32_bf16 v[66:69], v[6:9], v[22:25], v[126:129]
	v_mfma_f32_16x16x32_bf16 v[122:125], v[14:17], v[30:33], v[66:69]
	v_mfma_f32_16x16x32_bf16 v[66:69], v[192:195], v[22:25], v[172:175]
	v_mfma_f32_16x16x32_bf16 v[114:117], v[196:199], v[30:33], v[66:69]
	v_mfma_f32_16x16x32_bf16 v[66:69], v[6:9], v[38:41], v[118:121]
	v_mfma_f32_16x16x32_bf16 v[106:109], v[14:17], v[46:49], v[66:69]
	v_mfma_f32_16x16x32_bf16 v[66:69], v[192:195], v[38:41], v[204:207]
	v_mfma_f32_16x16x32_bf16 v[98:101], v[196:199], v[46:49], v[66:69]
	v_mfma_f32_16x16x32_bf16 v[66:69], v[6:9], v[54:57], v[110:113]
	v_mfma_f32_16x16x32_bf16 v[90:93], v[14:17], v[200:203], v[66:69]
	v_mfma_f32_16x16x32_bf16 v[66:69], v[192:195], v[54:57], v[208:211]
	v_mfma_f32_16x16x32_bf16 v[82:85], v[196:199], v[200:203], v[66:69]
	v_mfma_f32_16x16x32_bf16 v[66:69], v[6:9], v[224:227], v[102:105]
	v_mfma_f32_16x16x32_bf16 v[74:77], v[14:17], v[228:231], v[66:69]
	v_mfma_f32_16x16x32_bf16 v[66:69], v[192:195], v[224:227], v[212:215]
	v_mfma_f32_16x16x32_bf16 v[66:69], v[196:199], v[228:231], v[66:69]
	s_barrier
	ds_read_b128 v[172:175], v137 offset:49152
	ds_read_b128 v[204:207], v137 offset:50176
	ds_read_b128 v[208:211], v137 offset:51200
	ds_read_b128 v[212:215], v137 offset:52224
	s_waitcnt vmcnt(0)
	s_barrier
	s_waitcnt lgkmcnt(0)
	s_waitcnt lgkmcnt(0)
	v_mfma_f32_16x16x32_bf16 v[94:97], v[172:175], v[22:25], v[94:97]
	v_mfma_f32_16x16x32_bf16 v[22:25], v[208:211], v[22:25], v[168:171]
	v_mfma_f32_16x16x32_bf16 v[118:121], v[212:215], v[30:33], v[22:25]
	v_mfma_f32_16x16x32_bf16 v[22:25], v[172:175], v[38:41], v[86:89]
	v_mfma_f32_16x16x32_bf16 v[110:113], v[204:207], v[46:49], v[22:25]
	v_mfma_f32_16x16x32_bf16 v[22:25], v[208:211], v[38:41], v[176:179]
	v_mfma_f32_16x16x32_bf16 v[102:105], v[212:215], v[46:49], v[22:25]
	v_mfma_f32_16x16x32_bf16 v[22:25], v[172:175], v[54:57], v[78:81]
	v_mfma_f32_16x16x32_bf16 v[126:129], v[204:207], v[30:33], v[94:97]
	v_mfma_f32_16x16x32_bf16 v[94:97], v[204:207], v[200:203], v[22:25]
	v_mfma_f32_16x16x32_bf16 v[22:25], v[208:211], v[54:57], v[180:183]
	v_mfma_f32_16x16x32_bf16 v[86:89], v[212:215], v[200:203], v[22:25]
	v_mfma_f32_16x16x32_bf16 v[22:25], v[172:175], v[224:227], v[70:73]
	v_mfma_f32_16x16x32_bf16 v[78:81], v[204:207], v[228:231], v[22:25]
	v_mfma_f32_16x16x32_bf16 v[22:25], v[208:211], v[224:227], v[184:187]
	v_mfma_f32_16x16x32_bf16 v[70:73], v[212:215], v[228:231], v[22:25]
	s_barrier
	ds_read_b128 v[168:171], v136 offset:49152
	ds_read_b128 v[176:179], v136 offset:50176
	ds_read_b128 v[180:183], v136 offset:51200
	ds_read_b128 v[184:187], v136 offset:52224
	ds_read_b128 v[200:203], v136 offset:53248
	ds_read_b128 v[224:227], v136 offset:54272
	ds_read_b128 v[228:231], v136 offset:55296
	ds_read_b128 v[232:235], v136 offset:56320
	s_barrier
	s_waitcnt lgkmcnt(0)
	s_waitcnt lgkmcnt(0)
	v_mfma_f32_16x16x32_bf16 v[22:25], v[6:9], v[168:171], v[62:65]
	v_mfma_f32_16x16x32_bf16 v[62:65], v[14:17], v[176:179], v[22:25]
	v_mfma_f32_16x16x32_bf16 v[22:25], v[192:195], v[168:171], v[58:61]
	v_mfma_f32_16x16x32_bf16 v[54:57], v[196:199], v[176:179], v[22:25]
	v_mfma_f32_16x16x32_bf16 v[22:25], v[6:9], v[180:183], v[216:219]
	v_mfma_f32_16x16x32_bf16 v[46:49], v[14:17], v[184:187], v[22:25]
	v_mfma_f32_16x16x32_bf16 v[22:25], v[192:195], v[180:183], v[50:53]
	v_mfma_f32_16x16x32_bf16 v[38:41], v[196:199], v[184:187], v[22:25]
	v_mfma_f32_16x16x32_bf16 v[22:25], v[6:9], v[200:203], v[220:223]
	v_mfma_f32_16x16x32_bf16 v[6:9], v[6:9], v[228:231], v[138:141]
	v_mfma_f32_16x16x32_bf16 v[30:33], v[14:17], v[224:227], v[22:25]
	v_mfma_f32_16x16x32_bf16 v[22:25], v[192:195], v[200:203], v[42:45]
	v_mfma_f32_16x16x32_bf16 v[14:17], v[14:17], v[232:235], v[6:9]
	v_mfma_f32_16x16x32_bf16 v[6:9], v[192:195], v[228:231], v[34:37]
	v_mfma_f32_16x16x32_bf16 v[22:25], v[196:199], v[224:227], v[22:25]
	v_mfma_f32_16x16x32_bf16 v[6:9], v[196:199], v[232:235], v[6:9]
	v_mfma_f32_16x16x32_bf16 v[34:37], v[172:175], v[168:171], v[142:145]
	v_mfma_f32_16x16x32_bf16 v[26:29], v[208:211], v[168:171], v[26:29]
	v_mfma_f32_16x16x32_bf16 v[18:21], v[208:211], v[180:183], v[18:21]
	v_mfma_f32_16x16x32_bf16 v[58:61], v[204:207], v[176:179], v[34:37]
	v_mfma_f32_16x16x32_bf16 v[50:53], v[212:215], v[176:179], v[26:29]
	v_mfma_f32_16x16x32_bf16 v[26:29], v[172:175], v[180:183], v[146:149]
	v_mfma_f32_16x16x32_bf16 v[34:37], v[212:215], v[184:187], v[18:21]
	v_mfma_f32_16x16x32_bf16 v[18:21], v[172:175], v[200:203], v[152:155]
	v_mfma_f32_16x16x32_bf16 v[10:13], v[208:211], v[200:203], v[10:13]
	v_mfma_f32_16x16x32_bf16 v[42:45], v[204:207], v[184:187], v[26:29]
	v_mfma_f32_16x16x32_bf16 v[26:29], v[204:207], v[224:227], v[18:21]
	v_mfma_f32_16x16x32_bf16 v[18:21], v[212:215], v[224:227], v[10:13]
	v_mfma_f32_16x16x32_bf16 v[10:13], v[172:175], v[228:231], v[188:191]
	v_mfma_f32_16x16x32_bf16 v[2:5], v[208:211], v[228:231], v[2:5]
	v_mfma_f32_16x16x32_bf16 v[10:13], v[204:207], v[232:235], v[10:13]
	v_mfma_f32_16x16x32_bf16 v[2:5], v[212:215], v[232:235], v[2:5]
	v_cmp_gt_u32_e32 vcc, s97, v135
	s_barrier
	s_and_saveexec_b64 s[10:11], vcc
	s_cbranch_execz .LBB0_812
	s_barrier
	s_branch .LBB0_812

; #define WAIT_L(n) asm volatile("s_waitcnt lgkmcnt(%0)" ::"n"(n) : "memory")
; #define SBAR() __builtin_amdgcn_sched_barrier(0)
; #define LDA8(dst, b, h) _Pragma("unroll") for (int m = 0; m < 4; ++m) _Pragma("unroll") for (int k = 0; k < 2; ++k) \
;     dst[m][k] = *(const bf16x8*)(abase + SAo(b, h) + m * 2048 + k * 1024)
; #define LDB8(dst, b, h) _Pragma("unroll") for (int n = 0; n < 2; ++n) _Pragma("unroll") for (int k = 0; k < 2; ++k) \
;     dst[n][k] = *(const bf16x8*)(bbase + SAo(b, h) + n * 2048 + k * 1024)
; #define BAR8 __builtin_amdgcn_s_barrier()
; __device__ __forceinline__ void gemm_main8(const u16* __restrict__ Ab, int lda, const u16* __restrict__ Bb, int ldb, int K,
;                                            char* shm, f32x4 (&acc)[2][2][4][2]) {
;     ...
;     LDB8(B0, 0, 0); SBAR(); LDA8(At, 0, 0); STG_A(1, 1, t + 1);
;     WAIT_L(8); BAR8; WAIT_L(0); MMA8(0, 0, At, B0); BAR8; SBAR();
;     LDB8(B1, 0, 1); STG_B(0, 0, t + 2);
;     BAR8; WAIT_L(0); MMA8(0, 1, At, B1); BAR8;
;     LDA8(At, 0, 1); STG_A(0, 0, t + 2);
;     BAR8; WAIT_L(0); MMA8(1, 0, At, B0); BAR8; SBAR();
.LBB0_905:
	ds_read_b128 v[152:155], v138
	ds_read_b128 v[164:167], v138 offset:1024
	ds_read_b128 v[176:179], v138 offset:2048
	ds_read_b128 v[180:183], v138 offset:3072
	v_add_u32_e32 v174, 0xc000, v139
	v_lshl_add_u64 v[168:169], s[28:29], 0, v[0:1]
	v_readfirstlane_b32 s11, v174
	v_add_u32_e32 v175, 0xe000, v139
	v_lshl_add_u64 v[216:217], v[168:169], 0, s[54:55]
	s_mov_b32 m0, s11
	v_readfirstlane_b32 s11, v175
	ds_read_b128 v[184:187], v137
	ds_read_b128 v[188:191], v137 offset:1024
	ds_read_b128 v[192:195], v137 offset:2048
	ds_read_b128 v[196:199], v137 offset:3072
	ds_read_b128 v[200:203], v137 offset:4096
	ds_read_b128 v[204:207], v137 offset:5120
	ds_read_b128 v[208:211], v137 offset:6144
	ds_read_b128 v[212:215], v137 offset:7168
	global_load_lds_dwordx4 v[216:217], off
	v_lshl_add_u64 v[216:217], v[168:169], 0, s[56:57]
	s_mov_b32 m0, s11
	s_nop 0
	global_load_lds_dwordx4 v[216:217], off
	s_waitcnt lgkmcnt(8)
	s_barrier
	s_waitcnt lgkmcnt(0)
	s_waitcnt lgkmcnt(0)
	v_mfma_f32_16x16x32_bf16 v[126:129], v[152:155], v[184:187], v[126:129]
	v_mfma_f32_16x16x32_bf16 v[122:125], v[176:179], v[184:187], v[122:125]
	v_mfma_f32_16x16x32_bf16 v[118:121], v[152:155], v[192:195], v[118:121]
	v_mfma_f32_16x16x32_bf16 v[114:117], v[176:179], v[192:195], v[114:117]
	v_mfma_f32_16x16x32_bf16 v[110:113], v[152:155], v[200:203], v[110:113]
	v_mfma_f32_16x16x32_bf16 v[106:109], v[176:179], v[200:203], v[106:109]
	v_mfma_f32_16x16x32_bf16 v[102:105], v[152:155], v[208:211], v[102:105]
	v_mfma_f32_16x16x32_bf16 v[98:101], v[176:179], v[208:211], v[98:101]
	v_mfma_f32_16x16x32_bf16 v[126:129], v[164:167], v[188:191], v[126:129]
	v_mfma_f32_16x16x32_bf16 v[122:125], v[180:183], v[188:191], v[122:125]
	v_mfma_f32_16x16x32_bf16 v[118:121], v[164:167], v[196:199], v[118:121]
	v_mfma_f32_16x16x32_bf16 v[114:117], v[180:183], v[196:199], v[114:117]
	v_mfma_f32_16x16x32_bf16 v[110:113], v[164:167], v[204:207], v[110:113]
	v_mfma_f32_16x16x32_bf16 v[106:109], v[180:183], v[204:207], v[106:109]
	v_mfma_f32_16x16x32_bf16 v[102:105], v[164:167], v[212:215], v[102:105]
	v_mfma_f32_16x16x32_bf16 v[98:101], v[180:183], v[212:215], v[98:101]
	s_barrier
	v_lshl_add_u64 v[232:233], s[12:13], 0, v[0:1]
	s_mov_b64 s[78:79], 0x4000100
	v_readfirstlane_b32 s11, v140
	v_lshl_add_u64 v[234:235], v[232:233], 0, s[78:79]
	s_mov_b32 m0, s11
	s_mov_b64 s[78:79], 0x4040100
	v_readfirstlane_b32 s11, v141
	ds_read_b128 v[216:219], v138 offset:16384
	ds_read_b128 v[220:223], v138 offset:17408
	ds_read_b128 v[224:227], v138 offset:18432
	ds_read_b128 v[228:231], v138 offset:19456
	global_load_lds_dwordx4 v[234:235], off
	v_lshl_add_u64 v[234:235], v[232:233], 0, s[78:79]
	s_mov_b32 m0, s11
	s_nop 0
	global_load_lds_dwordx4 v[234:235], off
	s_barrier
	s_waitcnt lgkmcnt(0)
	s_waitcnt lgkmcnt(0)
	v_mfma_f32_16x16x32_bf16 v[94:97], v[216:219], v[184:187], v[94:97]
	v_mfma_f32_16x16x32_bf16 v[90:93], v[224:227], v[184:187], v[90:93]
	v_mfma_f32_16x16x32_bf16 v[86:89], v[216:219], v[192:195], v[86:89]
	v_mfma_f32_16x16x32_bf16 v[82:85], v[224:227], v[192:195], v[82:85]
	v_mfma_f32_16x16x32_bf16 v[78:81], v[216:219], v[200:203], v[78:81]
	v_mfma_f32_16x16x32_bf16 v[74:77], v[224:227], v[200:203], v[74:77]
	v_mfma_f32_16x16x32_bf16 v[70:73], v[216:219], v[208:211], v[70:73]
	v_mfma_f32_16x16x32_bf16 v[66:69], v[224:227], v[208:211], v[66:69]
	v_mfma_f32_16x16x32_bf16 v[94:97], v[220:223], v[188:191], v[94:97]
	v_mfma_f32_16x16x32_bf16 v[90:93], v[228:231], v[188:191], v[90:93]
	v_mfma_f32_16x16x32_bf16 v[86:89], v[220:223], v[196:199], v[86:89]
	v_mfma_f32_16x16x32_bf16 v[82:85], v[228:231], v[196:199], v[82:85]
	v_mfma_f32_16x16x32_bf16 v[78:81], v[220:223], v[204:207], v[78:81]
	v_mfma_f32_16x16x32_bf16 v[74:77], v[228:231], v[204:207], v[74:77]
	v_mfma_f32_16x16x32_bf16 v[70:73], v[220:223], v[212:215], v[70:73]
	v_mfma_f32_16x16x32_bf16 v[66:69], v[228:231], v[212:215], v[66:69]
	v_readfirstlane_b32 s11, v139
	v_lshl_add_u64 v[234:235], v[168:169], 0, s[58:59]
	s_mov_b32 m0, s11
	v_readfirstlane_b32 s11, v142
	s_barrier
	ds_read_b128 v[184:187], v137 offset:16384
	ds_read_b128 v[188:191], v137 offset:17408
	ds_read_b128 v[192:195], v137 offset:18432
	ds_read_b128 v[196:199], v137 offset:19456
	ds_read_b128 v[200:203], v137 offset:20480
	ds_read_b128 v[204:207], v137 offset:21504
	ds_read_b128 v[208:211], v137 offset:22528
	ds_read_b128 v[212:215], v137 offset:23552
	global_load_lds_dwordx4 v[234:235], off
	v_lshl_add_u64 v[234:235], v[168:169], 0, s[60:61]
	s_mov_b32 m0, s11
	s_nop 0
	global_load_lds_dwordx4 v[234:235], off
	s_barrier
	s_waitcnt lgkmcnt(0)
	s_waitcnt lgkmcnt(0)
	v_mfma_f32_16x16x32_bf16 v[62:65], v[152:155], v[184:187], v[62:65]
	v_mfma_f32_16x16x32_bf16 v[58:61], v[176:179], v[184:187], v[58:61]
	v_mfma_f32_16x16x32_bf16 v[54:57], v[152:155], v[192:195], v[54:57]
	v_mfma_f32_16x16x32_bf16 v[50:53], v[176:179], v[192:195], v[50:53]
	v_mfma_f32_16x16x32_bf16 v[46:49], v[152:155], v[200:203], v[46:49]
	v_mfma_f32_16x16x32_bf16 v[42:45], v[176:179], v[200:203], v[42:45]
	v_mfma_f32_16x16x32_bf16 v[38:41], v[152:155], v[208:211], v[38:41]
	v_mfma_f32_16x16x32_bf16 v[34:37], v[176:179], v[208:211], v[34:37]
	v_mfma_f32_16x16x32_bf16 v[62:65], v[164:167], v[188:191], v[62:65]
	v_mfma_f32_16x16x32_bf16 v[58:61], v[180:183], v[188:191], v[58:61]
	v_mfma_f32_16x16x32_bf16 v[54:57], v[164:167], v[196:199], v[54:57]
	v_mfma_f32_16x16x32_bf16 v[50:53], v[180:183], v[196:199], v[50:53]
	v_mfma_f32_16x16x32_bf16 v[46:49], v[164:167], v[204:207], v[46:49]
	v_mfma_f32_16x16x32_bf16 v[42:45], v[180:183], v[204:207], v[42:45]
	v_mfma_f32_16x16x32_bf16 v[38:41], v[164:167], v[212:215], v[38:41]
	v_mfma_f32_16x16x32_bf16 v[34:37], v[180:183], v[212:215], v[34:37]
	s_barrier
; #define WAIT_V(n) asm volatile("s_waitcnt vmcnt(%0)" ::"n"(n) : "memory")
; #define WAIT_L(n) asm volatile("s_waitcnt lgkmcnt(%0)" ::"n"(n) : "memory")
; #define SBAR() __builtin_amdgcn_sched_barrier(0)
; #define LDA8(dst, b, h) _Pragma("unroll") for (int m = 0; m < 4; ++m) _Pragma("unroll") for (int k = 0; k < 2; ++k) \
;     dst[m][k] = *(const bf16x8*)(abase + SAo(b, h) + m * 2048 + k * 1024)
; #define LDB8(dst, b, h) _Pragma("unroll") for (int n = 0; n < 2; ++n) _Pragma("unroll") for (int k = 0; k < 2; ++k) \
;     dst[n][k] = *(const bf16x8*)(bbase + SAo(b, h) + n * 2048 + k * 1024)
; #define BAR8 __builtin_amdgcn_s_barrier()
; __device__ __forceinline__ void gemm_main8(const u16* __restrict__ Ab, int lda, const u16* __restrict__ Bb, int ldb, int K,
;                                            char* shm, f32x4 (&acc)[2][2][4][2]) {
;     ...
;     STG_B(0, 1, t + 2);
;     WAIT_V(6); BAR8; MMA8(1, 1, At, B1); BAR8;
;     LDB8(B0, 1, 0); SBAR(); LDA8(At, 1, 0); STG_A(0, 1, t + 2);
;     WAIT_L(8); BAR8; WAIT_L(0); MMA8(0, 0, At, B0); BAR8; SBAR();
;     LDB8(B1, 1, 1); STG_B(1, 0, t + 3);
;     BAR8; WAIT_L(0); MMA8(0, 1, At, B1); BAR8;
	s_mov_b64 s[78:79], 0x4080100
	v_readfirstlane_b32 s11, v143
	v_lshl_add_u64 v[152:153], v[232:233], 0, s[78:79]
	s_mov_b32 m0, s11
	s_mov_b64 s[78:79], 0x40c0100
	v_readfirstlane_b32 s11, v144
	global_load_lds_dwordx4 v[152:153], off
	v_lshl_add_u64 v[152:153], v[232:233], 0, s[78:79]
	s_mov_b32 m0, s11
	s_nop 0
	global_load_lds_dwordx4 v[152:153], off
	s_waitcnt vmcnt(6)
	s_barrier
	v_mfma_f32_16x16x32_bf16 v[30:33], v[216:219], v[184:187], v[30:33]
	v_mfma_f32_16x16x32_bf16 v[26:29], v[224:227], v[184:187], v[26:29]
	v_mfma_f32_16x16x32_bf16 v[22:25], v[216:219], v[192:195], v[22:25]
	v_mfma_f32_16x16x32_bf16 v[18:21], v[224:227], v[192:195], v[18:21]
	v_mfma_f32_16x16x32_bf16 v[14:17], v[216:219], v[200:203], v[14:17]
	v_mfma_f32_16x16x32_bf16 v[10:13], v[224:227], v[200:203], v[10:13]
	v_mfma_f32_16x16x32_bf16 v[6:9], v[216:219], v[208:211], v[6:9]
	v_mfma_f32_16x16x32_bf16 v[2:5], v[224:227], v[208:211], v[2:5]
	v_mfma_f32_16x16x32_bf16 v[30:33], v[220:223], v[188:191], v[30:33]
	v_mfma_f32_16x16x32_bf16 v[26:29], v[228:231], v[188:191], v[26:29]
	v_mfma_f32_16x16x32_bf16 v[22:25], v[220:223], v[196:199], v[22:25]
	v_mfma_f32_16x16x32_bf16 v[18:21], v[228:231], v[196:199], v[18:21]
	v_mfma_f32_16x16x32_bf16 v[14:17], v[220:223], v[204:207], v[14:17]
	v_mfma_f32_16x16x32_bf16 v[10:13], v[228:231], v[204:207], v[10:13]
	v_mfma_f32_16x16x32_bf16 v[6:9], v[220:223], v[212:215], v[6:9]
	v_mfma_f32_16x16x32_bf16 v[2:5], v[228:231], v[212:215], v[2:5]
	s_barrier
	ds_read_b128 v[152:155], v138 offset:32768
	ds_read_b128 v[164:167], v138 offset:33792
	ds_read_b128 v[176:179], v138 offset:34816
	ds_read_b128 v[180:183], v138 offset:35840
	v_readfirstlane_b32 s11, v145
	v_lshl_add_u64 v[216:217], v[168:169], 0, s[62:63]
	s_mov_b32 m0, s11
	v_readfirstlane_b32 s11, v146
	ds_read_b128 v[184:187], v137 offset:32768
	ds_read_b128 v[188:191], v137 offset:33792
	ds_read_b128 v[192:195], v137 offset:34816
	ds_read_b128 v[196:199], v137 offset:35840
	ds_read_b128 v[200:203], v137 offset:36864
	ds_read_b128 v[204:207], v137 offset:37888
	ds_read_b128 v[208:211], v137 offset:38912
	ds_read_b128 v[212:215], v137 offset:39936
	global_load_lds_dwordx4 v[216:217], off
	v_lshl_add_u64 v[216:217], v[168:169], 0, s[64:65]
	s_mov_b32 m0, s11
	s_nop 0
	global_load_lds_dwordx4 v[216:217], off
	s_waitcnt lgkmcnt(8)
	s_barrier
	s_waitcnt lgkmcnt(0)
	s_waitcnt lgkmcnt(0)
	v_mfma_f32_16x16x32_bf16 v[126:129], v[152:155], v[184:187], v[126:129]
	v_mfma_f32_16x16x32_bf16 v[122:125], v[176:179], v[184:187], v[122:125]
	v_mfma_f32_16x16x32_bf16 v[118:121], v[152:155], v[192:195], v[118:121]
	v_mfma_f32_16x16x32_bf16 v[114:117], v[176:179], v[192:195], v[114:117]
	v_mfma_f32_16x16x32_bf16 v[110:113], v[152:155], v[200:203], v[110:113]
	v_mfma_f32_16x16x32_bf16 v[106:109], v[176:179], v[200:203], v[106:109]
	v_mfma_f32_16x16x32_bf16 v[102:105], v[152:155], v[208:211], v[102:105]
	v_mfma_f32_16x16x32_bf16 v[98:101], v[176:179], v[208:211], v[98:101]
	v_mfma_f32_16x16x32_bf16 v[126:129], v[164:167], v[188:191], v[126:129]
	v_mfma_f32_16x16x32_bf16 v[122:125], v[180:183], v[188:191], v[122:125]
	v_mfma_f32_16x16x32_bf16 v[118:121], v[164:167], v[196:199], v[118:121]
	v_mfma_f32_16x16x32_bf16 v[114:117], v[180:183], v[196:199], v[114:117]
	v_mfma_f32_16x16x32_bf16 v[110:113], v[164:167], v[204:207], v[110:113]
	v_mfma_f32_16x16x32_bf16 v[106:109], v[180:183], v[204:207], v[106:109]
	v_mfma_f32_16x16x32_bf16 v[102:105], v[164:167], v[212:215], v[102:105]
	v_mfma_f32_16x16x32_bf16 v[98:101], v[180:183], v[212:215], v[98:101]
	s_barrier
	s_mov_b64 s[78:79], 0x4000180
	v_readfirstlane_b32 s11, v147
	v_lshl_add_u64 v[234:235], v[232:233], 0, s[78:79]
	s_mov_b32 m0, s11
	s_mov_b64 s[78:79], 0x4040180
	v_readfirstlane_b32 s11, v148
	ds_read_b128 v[216:219], v138 offset:49152
	ds_read_b128 v[220:223], v138 offset:50176
	ds_read_b128 v[224:227], v138 offset:51200
	ds_read_b128 v[228:231], v138 offset:52224
	global_load_lds_dwordx4 v[234:235], off
	v_lshl_add_u64 v[234:235], v[232:233], 0, s[78:79]
	s_mov_b32 m0, s11
	s_nop 0
	global_load_lds_dwordx4 v[234:235], off
	s_barrier
	s_waitcnt lgkmcnt(0)
	s_waitcnt lgkmcnt(0)
	v_mfma_f32_16x16x32_bf16 v[94:97], v[216:219], v[184:187], v[94:97]
	v_mfma_f32_16x16x32_bf16 v[90:93], v[224:227], v[184:187], v[90:93]
	v_mfma_f32_16x16x32_bf16 v[86:89], v[216:219], v[192:195], v[86:89]
	v_mfma_f32_16x16x32_bf16 v[82:85], v[224:227], v[192:195], v[82:85]
	v_mfma_f32_16x16x32_bf16 v[78:81], v[216:219], v[200:203], v[78:81]
	v_mfma_f32_16x16x32_bf16 v[74:77], v[224:227], v[200:203], v[74:77]
	v_mfma_f32_16x16x32_bf16 v[70:73], v[216:219], v[208:211], v[70:73]
	v_mfma_f32_16x16x32_bf16 v[66:69], v[224:227], v[208:211], v[66:69]
	v_mfma_f32_16x16x32_bf16 v[94:97], v[220:223], v[188:191], v[94:97]
	v_mfma_f32_16x16x32_bf16 v[90:93], v[228:231], v[188:191], v[90:93]
	v_mfma_f32_16x16x32_bf16 v[86:89], v[220:223], v[196:199], v[86:89]
	v_mfma_f32_16x16x32_bf16 v[82:85], v[228:231], v[196:199], v[82:85]
	v_mfma_f32_16x16x32_bf16 v[78:81], v[220:223], v[204:207], v[78:81]
	v_mfma_f32_16x16x32_bf16 v[74:77], v[228:231], v[204:207], v[74:77]
	v_mfma_f32_16x16x32_bf16 v[70:73], v[220:223], v[212:215], v[70:73]
	v_mfma_f32_16x16x32_bf16 v[66:69], v[228:231], v[212:215], v[66:69]
	v_readfirstlane_b32 s11, v149
	v_lshl_add_u64 v[234:235], v[168:169], 0, s[66:67]
	s_mov_b32 m0, s11
	v_readfirstlane_b32 s11, v171
	s_barrier
; #define WAIT_V(n) asm volatile("s_waitcnt vmcnt(%0)" ::"n"(n) : "memory")
; #define WAIT_L(n) asm volatile("s_waitcnt lgkmcnt(%0)" ::"n"(n) : "memory")
; #define SBAR() __builtin_amdgcn_sched_barrier(0)
; #define LDA8(dst, b, h) _Pragma("unroll") for (int m = 0; m < 4; ++m) _Pragma("unroll") for (int k = 0; k < 2; ++k) \
;     dst[m][k] = *(const bf16x8*)(abase + SAo(b, h) + m * 2048 + k * 1024)
; #define LDB8(dst, b, h) _Pragma("unroll") for (int n = 0; n < 2; ++n) _Pragma("unroll") for (int k = 0; k < 2; ++k) \
;     dst[n][k] = *(const bf16x8*)(bbase + SAo(b, h) + n * 2048 + k * 1024)
; #define BAR8 __builtin_amdgcn_s_barrier()
; __device__ __forceinline__ void gemm_main8(const u16* __restrict__ Ab, int lda, const u16* __restrict__ Bb, int ldb, int K,
;                                            char* shm, f32x4 (&acc)[2][2][4][2]) {
;     ...
;     LDA8(At, 1, 1); STG_A(1, 0, t + 3);
;     BAR8; WAIT_L(0); MMA8(1, 0, At, B0); BAR8; SBAR();
;     STG_B(1, 1, t + 3);
;     WAIT_V(6); BAR8; MMA8(1, 1, At, B1); BAR8;
;   }
;   { LDB8(B0, 0, 0); LDA8(At, 0, 0); STG_A(1, 1, nt - 1);
;     BAR8; WAIT_L(0); MMA8(0, 0, At, B0); BAR8;
;     LDB8(B1, 0, 1); BAR8; WAIT_L(0); MMA8(0, 1, At, B1); BAR8;
	ds_read_b128 v[184:187], v137 offset:49152
	ds_read_b128 v[188:191], v137 offset:50176
	ds_read_b128 v[192:195], v137 offset:51200
	ds_read_b128 v[196:199], v137 offset:52224
	ds_read_b128 v[200:203], v137 offset:53248
	ds_read_b128 v[204:207], v137 offset:54272
	ds_read_b128 v[208:211], v137 offset:55296
	ds_read_b128 v[212:215], v137 offset:56320
	global_load_lds_dwordx4 v[234:235], off
	v_lshl_add_u64 v[168:169], v[168:169], 0, s[68:69]
	s_mov_b32 m0, s11
	s_nop 0
	global_load_lds_dwordx4 v[168:169], off
	s_barrier
	s_waitcnt lgkmcnt(0)
	s_waitcnt lgkmcnt(0)
	v_mfma_f32_16x16x32_bf16 v[62:65], v[152:155], v[184:187], v[62:65]
	v_mfma_f32_16x16x32_bf16 v[58:61], v[176:179], v[184:187], v[58:61]
	v_mfma_f32_16x16x32_bf16 v[54:57], v[152:155], v[192:195], v[54:57]
	v_mfma_f32_16x16x32_bf16 v[50:53], v[176:179], v[192:195], v[50:53]
	v_mfma_f32_16x16x32_bf16 v[46:49], v[152:155], v[200:203], v[46:49]
	v_mfma_f32_16x16x32_bf16 v[42:45], v[176:179], v[200:203], v[42:45]
	v_mfma_f32_16x16x32_bf16 v[38:41], v[152:155], v[208:211], v[38:41]
	v_mfma_f32_16x16x32_bf16 v[34:37], v[176:179], v[208:211], v[34:37]
	v_mfma_f32_16x16x32_bf16 v[62:65], v[164:167], v[188:191], v[62:65]
	v_mfma_f32_16x16x32_bf16 v[58:61], v[180:183], v[188:191], v[58:61]
	v_mfma_f32_16x16x32_bf16 v[54:57], v[164:167], v[196:199], v[54:57]
	v_mfma_f32_16x16x32_bf16 v[50:53], v[180:183], v[196:199], v[50:53]
	v_mfma_f32_16x16x32_bf16 v[46:49], v[164:167], v[204:207], v[46:49]
	v_mfma_f32_16x16x32_bf16 v[42:45], v[180:183], v[204:207], v[42:45]
	v_mfma_f32_16x16x32_bf16 v[38:41], v[164:167], v[212:215], v[38:41]
	v_mfma_f32_16x16x32_bf16 v[34:37], v[180:183], v[212:215], v[34:37]
	s_barrier
	s_mov_b64 s[78:79], 0x4080180
	v_readfirstlane_b32 s11, v172
	v_lshl_add_u64 v[152:153], v[232:233], 0, s[78:79]
	s_mov_b32 m0, s11
	s_mov_b64 s[78:79], 0x40c0180
	v_readfirstlane_b32 s11, v173
	global_load_lds_dwordx4 v[152:153], off
	v_lshl_add_u64 v[152:153], v[232:233], 0, s[78:79]
	s_mov_b32 m0, s11
	s_nop 0
	global_load_lds_dwordx4 v[152:153], off
	s_waitcnt vmcnt(6)
	s_barrier
	v_mfma_f32_16x16x32_bf16 v[30:33], v[216:219], v[184:187], v[30:33]
	v_mfma_f32_16x16x32_bf16 v[26:29], v[224:227], v[184:187], v[26:29]
	v_mfma_f32_16x16x32_bf16 v[22:25], v[216:219], v[192:195], v[22:25]
	v_mfma_f32_16x16x32_bf16 v[18:21], v[224:227], v[192:195], v[18:21]
	v_mfma_f32_16x16x32_bf16 v[14:17], v[216:219], v[200:203], v[14:17]
	v_mfma_f32_16x16x32_bf16 v[10:13], v[224:227], v[200:203], v[10:13]
	v_mfma_f32_16x16x32_bf16 v[6:9], v[216:219], v[208:211], v[6:9]
	v_mfma_f32_16x16x32_bf16 v[2:5], v[224:227], v[208:211], v[2:5]
	v_mfma_f32_16x16x32_bf16 v[30:33], v[220:223], v[188:191], v[30:33]
	v_mfma_f32_16x16x32_bf16 v[26:29], v[228:231], v[188:191], v[26:29]
	v_mfma_f32_16x16x32_bf16 v[22:25], v[220:223], v[196:199], v[22:25]
	v_mfma_f32_16x16x32_bf16 v[18:21], v[228:231], v[196:199], v[18:21]
	v_mfma_f32_16x16x32_bf16 v[14:17], v[220:223], v[204:207], v[14:17]
	v_mfma_f32_16x16x32_bf16 v[10:13], v[228:231], v[204:207], v[10:13]
	v_mfma_f32_16x16x32_bf16 v[6:9], v[220:223], v[212:215], v[6:9]
	v_mfma_f32_16x16x32_bf16 v[2:5], v[228:231], v[212:215], v[2:5]
	s_add_i32 s10, s10, 2
	s_add_u32 s12, s12, 0x100
	s_addc_u32 s13, s13, 0
	s_add_u32 s28, s28, 0x100
	s_addc_u32 s29, s29, 0
	s_cmp_lt_u32 s10, 28
	s_barrier
	s_cbranch_scc1 .LBB0_905
	s_mov_b64 s[10:11], 0x80f80
	v_lshl_add_u64 v[148:149], v[130:131], 0, s[10:11]
	v_readfirstlane_b32 s10, v174
	s_mov_b32 m0, s10
	s_mov_b64 s[10:11], 0xc0f80
	v_lshl_add_u64 v[130:131], v[130:131], 0, s[10:11]
	v_readfirstlane_b32 s10, v175
	ds_read_b128 v[140:143], v138
	ds_read_b128 v[144:147], v138 offset:1024
	ds_read_b128 v[152:155], v138 offset:2048
	ds_read_b128 v[164:167], v138 offset:3072
	ds_read_b128 v[168:171], v137
	ds_read_b128 v[176:179], v137 offset:1024
	ds_read_b128 v[180:183], v137 offset:2048
	ds_read_b128 v[184:187], v137 offset:3072
	ds_read_b128 v[188:191], v137 offset:4096
	ds_read_b128 v[192:195], v137 offset:5120
	ds_read_b128 v[196:199], v137 offset:6144
	ds_read_b128 v[200:203], v137 offset:7168
	global_load_lds_dwordx4 v[148:149], off
	s_mov_b32 m0, s10
	s_nop 0
	global_load_lds_dwordx4 v[130:131], off
	s_barrier
	s_waitcnt lgkmcnt(0)
	s_waitcnt lgkmcnt(0)
	v_mfma_f32_16x16x32_bf16 v[126:129], v[140:143], v[168:171], v[126:129]
	v_mfma_f32_16x16x32_bf16 v[118:121], v[140:143], v[180:183], v[118:121]
	v_mfma_f32_16x16x32_bf16 v[114:117], v[152:155], v[180:183], v[114:117]
	v_mfma_f32_16x16x32_bf16 v[102:105], v[140:143], v[196:199], v[102:105]
	v_mfma_f32_16x16x32_bf16 v[98:101], v[152:155], v[196:199], v[98:101]
	v_mfma_f32_16x16x32_bf16 v[126:129], v[144:147], v[176:179], v[126:129]
	v_mfma_f32_16x16x32_bf16 v[122:125], v[152:155], v[168:171], v[122:125]
	v_mfma_f32_16x16x32_bf16 v[118:121], v[144:147], v[184:187], v[118:121]
	v_mfma_f32_16x16x32_bf16 v[114:117], v[164:167], v[184:187], v[114:117]
	v_mfma_f32_16x16x32_bf16 v[110:113], v[140:143], v[188:191], v[110:113]
	v_mfma_f32_16x16x32_bf16 v[106:109], v[152:155], v[188:191], v[106:109]
	v_mfma_f32_16x16x32_bf16 v[102:105], v[144:147], v[200:203], v[102:105]
	v_mfma_f32_16x16x32_bf16 v[98:101], v[164:167], v[200:203], v[98:101]
	v_mfma_f32_16x16x32_bf16 v[172:175], v[164:167], v[176:179], v[122:125]
	v_mfma_f32_16x16x32_bf16 v[204:207], v[144:147], v[192:195], v[110:113]
	v_mfma_f32_16x16x32_bf16 v[208:211], v[164:167], v[192:195], v[106:109]
	s_barrier
	s_nop 0
	ds_read_b128 v[106:109], v138 offset:16384
	ds_read_b128 v[110:113], v138 offset:17408
	ds_read_b128 v[122:125], v138 offset:18432
	ds_read_b128 v[212:215], v138 offset:19456
	s_barrier
; #define WAIT_V(n) asm volatile("s_waitcnt vmcnt(%0)" ::"n"(n) : "memory")
; #define WAIT_L(n) asm volatile("s_waitcnt lgkmcnt(%0)" ::"n"(n) : "memory")
; #define LDA8(dst, b, h) _Pragma("unroll") for (int m = 0; m < 4; ++m) _Pragma("unroll") for (int k = 0; k < 2; ++k) \
;     dst[m][k] = *(const bf16x8*)(abase + SAo(b, h) + m * 2048 + k * 1024)
; #define LDB8(dst, b, h) _Pragma("unroll") for (int n = 0; n < 2; ++n) _Pragma("unroll") for (int k = 0; k < 2; ++k) \
;     dst[n][k] = *(const bf16x8*)(bbase + SAo(b, h) + n * 2048 + k * 1024)
; #define BAR8 __builtin_amdgcn_s_barrier()
; __device__ __forceinline__ void gemm_main8(const u16* __restrict__ Ab, int lda, const u16* __restrict__ Bb, int ldb, int K,
;                                            char* shm, f32x4 (&acc)[2][2][4][2]) {
;     ...
;     LDB8(B1, 0, 1); BAR8; WAIT_L(0); MMA8(0, 1, At, B1); BAR8;
;     LDA8(At, 0, 1); WAIT_V(4); BAR8; WAIT_L(0); MMA8(1, 0, At, B0); MMA8(1, 1, At, B1); BAR8; }
;   { LDB8(B0, 1, 0); LDA8(At, 1, 0); WAIT_V(2); BAR8; WAIT_L(0); MMA8(0, 0, At, B0); BAR8;
	s_waitcnt lgkmcnt(0)
	s_waitcnt lgkmcnt(0)
	v_mfma_f32_16x16x32_bf16 v[86:89], v[106:109], v[180:183], v[86:89]
	v_mfma_f32_16x16x32_bf16 v[82:85], v[122:125], v[180:183], v[82:85]
	v_mfma_f32_16x16x32_bf16 v[70:73], v[106:109], v[196:199], v[70:73]
	v_mfma_f32_16x16x32_bf16 v[94:97], v[106:109], v[168:171], v[94:97]
	v_mfma_f32_16x16x32_bf16 v[90:93], v[122:125], v[168:171], v[90:93]
	v_mfma_f32_16x16x32_bf16 v[86:89], v[110:113], v[184:187], v[86:89]
	v_mfma_f32_16x16x32_bf16 v[82:85], v[212:215], v[184:187], v[82:85]
	v_mfma_f32_16x16x32_bf16 v[78:81], v[106:109], v[188:191], v[78:81]
	v_mfma_f32_16x16x32_bf16 v[74:77], v[122:125], v[188:191], v[74:77]
	v_mfma_f32_16x16x32_bf16 v[70:73], v[110:113], v[200:203], v[70:73]
	v_mfma_f32_16x16x32_bf16 v[66:69], v[122:125], v[196:199], v[66:69]
	v_mfma_f32_16x16x32_bf16 v[216:219], v[110:113], v[176:179], v[94:97]
	v_mfma_f32_16x16x32_bf16 v[168:171], v[212:215], v[176:179], v[90:93]
	v_mfma_f32_16x16x32_bf16 v[176:179], v[110:113], v[192:195], v[78:81]
	v_mfma_f32_16x16x32_bf16 v[180:183], v[212:215], v[192:195], v[74:77]
	v_mfma_f32_16x16x32_bf16 v[184:187], v[212:215], v[200:203], v[66:69]
	s_barrier
	s_nop 0
	ds_read_b128 v[66:69], v137 offset:16384
	ds_read_b128 v[74:77], v137 offset:17408
	ds_read_b128 v[78:81], v137 offset:18432
	ds_read_b128 v[90:93], v137 offset:19456
	ds_read_b128 v[94:97], v137 offset:20480
	ds_read_b128 v[188:191], v137 offset:21504
	ds_read_b128 v[192:195], v137 offset:22528
	ds_read_b128 v[196:199], v137 offset:23552
	s_waitcnt vmcnt(4)
	s_barrier
	s_waitcnt lgkmcnt(0)
	s_waitcnt lgkmcnt(0)
	v_mfma_f32_16x16x32_bf16 v[62:65], v[140:143], v[66:69], v[62:65]
	v_mfma_f32_16x16x32_bf16 v[54:57], v[140:143], v[78:81], v[54:57]
	v_mfma_f32_16x16x32_bf16 v[50:53], v[152:155], v[78:81], v[50:53]
	v_mfma_f32_16x16x32_bf16 v[38:41], v[140:143], v[192:195], v[38:41]
	v_mfma_f32_16x16x32_bf16 v[34:37], v[152:155], v[192:195], v[34:37]
	v_mfma_f32_16x16x32_bf16 v[62:65], v[144:147], v[74:77], v[62:65]
	v_mfma_f32_16x16x32_bf16 v[58:61], v[152:155], v[66:69], v[58:61]
	v_mfma_f32_16x16x32_bf16 v[54:57], v[144:147], v[90:93], v[54:57]
	v_mfma_f32_16x16x32_bf16 v[50:53], v[164:167], v[90:93], v[50:53]
	v_mfma_f32_16x16x32_bf16 v[46:49], v[140:143], v[94:97], v[46:49]
	v_mfma_f32_16x16x32_bf16 v[42:45], v[152:155], v[94:97], v[42:45]
	v_mfma_f32_16x16x32_bf16 v[38:41], v[144:147], v[196:199], v[38:41]
	v_mfma_f32_16x16x32_bf16 v[34:37], v[164:167], v[196:199], v[34:37]
	v_mfma_f32_16x16x32_bf16 v[200:203], v[164:167], v[74:77], v[58:61]
	v_mfma_f32_16x16x32_bf16 v[220:223], v[144:147], v[188:191], v[46:49]
	v_mfma_f32_16x16x32_bf16 v[224:227], v[164:167], v[188:191], v[42:45]
	v_mfma_f32_16x16x32_bf16 v[22:25], v[106:109], v[78:81], v[22:25]
	v_mfma_f32_16x16x32_bf16 v[18:21], v[122:125], v[78:81], v[18:21]
	v_mfma_f32_16x16x32_bf16 v[6:9], v[106:109], v[192:195], v[6:9]
	v_mfma_f32_16x16x32_bf16 v[30:33], v[106:109], v[66:69], v[30:33]
	v_mfma_f32_16x16x32_bf16 v[26:29], v[122:125], v[66:69], v[26:29]
	v_mfma_f32_16x16x32_bf16 v[22:25], v[110:113], v[90:93], v[22:25]
	v_mfma_f32_16x16x32_bf16 v[18:21], v[212:215], v[90:93], v[18:21]
	v_mfma_f32_16x16x32_bf16 v[14:17], v[106:109], v[94:97], v[14:17]
	v_mfma_f32_16x16x32_bf16 v[10:13], v[122:125], v[94:97], v[10:13]
	v_mfma_f32_16x16x32_bf16 v[6:9], v[110:113], v[196:199], v[6:9]
	v_mfma_f32_16x16x32_bf16 v[2:5], v[122:125], v[192:195], v[2:5]
	v_mfma_f32_16x16x32_bf16 v[140:143], v[110:113], v[74:77], v[30:33]
	v_mfma_f32_16x16x32_bf16 v[144:147], v[212:215], v[74:77], v[26:29]
	v_mfma_f32_16x16x32_bf16 v[152:155], v[110:113], v[188:191], v[14:17]
	v_mfma_f32_16x16x32_bf16 v[164:167], v[212:215], v[188:191], v[10:13]
	v_mfma_f32_16x16x32_bf16 v[188:191], v[212:215], v[196:199], v[2:5]
	s_barrier
	s_nop 0
	ds_read_b128 v[2:5], v138 offset:32768
	ds_read_b128 v[10:13], v138 offset:33792
	ds_read_b128 v[14:17], v138 offset:34816
	ds_read_b128 v[192:195], v138 offset:35840
	ds_read_b128 v[26:29], v137 offset:32768
	ds_read_b128 v[30:33], v137 offset:33792
	ds_read_b128 v[42:45], v137 offset:34816
	ds_read_b128 v[46:49], v137 offset:35840
	ds_read_b128 v[58:61], v137 offset:36864
	ds_read_b128 v[66:69], v137 offset:37888
	ds_read_b128 v[196:199], v137 offset:38912
	ds_read_b128 v[212:215], v137 offset:39936
	s_waitcnt vmcnt(2)
	s_barrier
; #define WAIT_V(n) asm volatile("s_waitcnt vmcnt(%0)" ::"n"(n) : "memory")
; #define WAIT_L(n) asm volatile("s_waitcnt lgkmcnt(%0)" ::"n"(n) : "memory")
; #define LDA8(dst, b, h) _Pragma("unroll") for (int m = 0; m < 4; ++m) _Pragma("unroll") for (int k = 0; k < 2; ++k) \
;     dst[m][k] = *(const bf16x8*)(abase + SAo(b, h) + m * 2048 + k * 1024)
; #define LDB8(dst, b, h) _Pragma("unroll") for (int n = 0; n < 2; ++n) _Pragma("unroll") for (int k = 0; k < 2; ++k) \
;     dst[n][k] = *(const bf16x8*)(bbase + SAo(b, h) + n * 2048 + k * 1024)
; #define BAR8 __builtin_amdgcn_s_barrier()
; __device__ __forceinline__ void gemm_main8(const u16* __restrict__ Ab, int lda, const u16* __restrict__ Bb, int ldb, int K,
;                                            char* shm, f32x4 (&acc)[2][2][4][2]) {
;     ...
;   { LDB8(B0, 1, 0); LDA8(At, 1, 0); WAIT_V(2); BAR8; WAIT_L(0); MMA8(0, 0, At, B0); BAR8;
;     LDB8(B1, 1, 1); WAIT_V(0); BAR8; WAIT_L(0); MMA8(0, 1, At, B1); BAR8;
;     LDA8(At, 1, 1); BAR8; WAIT_L(0); MMA8(1, 0, At, B0); MMA8(1, 1, At, B1); BAR8; }
;   if (wr == 0) BAR8;
	s_waitcnt lgkmcnt(0)
	s_waitcnt lgkmcnt(0)
	v_mfma_f32_16x16x32_bf16 v[74:77], v[2:5], v[26:29], v[126:129]
	v_mfma_f32_16x16x32_bf16 v[122:125], v[10:13], v[30:33], v[74:77]
	v_mfma_f32_16x16x32_bf16 v[74:77], v[14:17], v[26:29], v[172:175]
	v_mfma_f32_16x16x32_bf16 v[126:129], v[192:195], v[30:33], v[74:77]
	v_mfma_f32_16x16x32_bf16 v[74:77], v[2:5], v[42:45], v[118:121]
	v_mfma_f32_16x16x32_bf16 v[106:109], v[10:13], v[46:49], v[74:77]
	v_mfma_f32_16x16x32_bf16 v[74:77], v[14:17], v[42:45], v[114:117]
	v_mfma_f32_16x16x32_bf16 v[110:113], v[192:195], v[46:49], v[74:77]
	v_mfma_f32_16x16x32_bf16 v[74:77], v[2:5], v[58:61], v[204:207]
	v_mfma_f32_16x16x32_bf16 v[90:93], v[10:13], v[66:69], v[74:77]
	v_mfma_f32_16x16x32_bf16 v[74:77], v[14:17], v[58:61], v[208:211]
	v_mfma_f32_16x16x32_bf16 v[94:97], v[192:195], v[66:69], v[74:77]
	v_mfma_f32_16x16x32_bf16 v[74:77], v[2:5], v[196:199], v[102:105]
	v_mfma_f32_16x16x32_bf16 v[78:81], v[14:17], v[196:199], v[98:101]
	v_mfma_f32_16x16x32_bf16 v[74:77], v[10:13], v[212:215], v[74:77]
	v_mfma_f32_16x16x32_bf16 v[78:81], v[192:195], v[212:215], v[78:81]
	s_barrier
	ds_read_b128 v[172:175], v138 offset:49152
	ds_read_b128 v[204:207], v138 offset:50176
	ds_read_b128 v[208:211], v138 offset:51200
	ds_read_b128 v[228:231], v138 offset:52224
	s_waitcnt vmcnt(0)
	s_barrier
	s_waitcnt lgkmcnt(0)
	s_waitcnt lgkmcnt(0)
	v_mfma_f32_16x16x32_bf16 v[98:101], v[172:175], v[26:29], v[216:219]
	v_mfma_f32_16x16x32_bf16 v[26:29], v[208:211], v[26:29], v[168:171]
	v_mfma_f32_16x16x32_bf16 v[118:121], v[228:231], v[30:33], v[26:29]
	v_mfma_f32_16x16x32_bf16 v[26:29], v[172:175], v[42:45], v[86:89]
	v_mfma_f32_16x16x32_bf16 v[114:117], v[204:207], v[30:33], v[98:101]
	v_mfma_f32_16x16x32_bf16 v[98:101], v[204:207], v[46:49], v[26:29]
	v_mfma_f32_16x16x32_bf16 v[26:29], v[208:211], v[42:45], v[82:85]
	v_mfma_f32_16x16x32_bf16 v[102:105], v[228:231], v[46:49], v[26:29]
	v_mfma_f32_16x16x32_bf16 v[26:29], v[172:175], v[58:61], v[176:179]
	v_mfma_f32_16x16x32_bf16 v[82:85], v[204:207], v[66:69], v[26:29]
	v_mfma_f32_16x16x32_bf16 v[26:29], v[208:211], v[58:61], v[180:183]
	v_mfma_f32_16x16x32_bf16 v[86:89], v[228:231], v[66:69], v[26:29]
	v_mfma_f32_16x16x32_bf16 v[26:29], v[172:175], v[196:199], v[70:73]
	v_mfma_f32_16x16x32_bf16 v[66:69], v[204:207], v[212:215], v[26:29]
	v_mfma_f32_16x16x32_bf16 v[26:29], v[208:211], v[196:199], v[184:187]
	v_mfma_f32_16x16x32_bf16 v[70:73], v[228:231], v[212:215], v[26:29]
	s_barrier
	ds_read_b128 v[168:171], v137 offset:49152
	ds_read_b128 v[176:179], v137 offset:50176
	ds_read_b128 v[180:183], v137 offset:51200
	ds_read_b128 v[184:187], v137 offset:52224
	ds_read_b128 v[196:199], v137 offset:53248
	ds_read_b128 v[212:215], v137 offset:54272
	ds_read_b128 v[216:219], v137 offset:55296
	ds_read_b128 v[232:235], v137 offset:56320
	s_barrier
	s_waitcnt lgkmcnt(0)
	s_waitcnt lgkmcnt(0)
	v_mfma_f32_16x16x32_bf16 v[26:29], v[2:5], v[168:171], v[62:65]
	v_mfma_f32_16x16x32_bf16 v[58:61], v[10:13], v[176:179], v[26:29]
	v_mfma_f32_16x16x32_bf16 v[26:29], v[14:17], v[168:171], v[200:203]
	v_mfma_f32_16x16x32_bf16 v[62:65], v[192:195], v[176:179], v[26:29]
	v_mfma_f32_16x16x32_bf16 v[26:29], v[2:5], v[180:183], v[54:57]
	v_mfma_f32_16x16x32_bf16 v[42:45], v[10:13], v[184:187], v[26:29]
	v_mfma_f32_16x16x32_bf16 v[26:29], v[14:17], v[180:183], v[50:53]
	v_mfma_f32_16x16x32_bf16 v[46:49], v[192:195], v[184:187], v[26:29]
	v_mfma_f32_16x16x32_bf16 v[26:29], v[2:5], v[196:199], v[220:223]
	v_mfma_f32_16x16x32_bf16 v[2:5], v[2:5], v[216:219], v[38:41]
	v_mfma_f32_16x16x32_bf16 v[26:29], v[10:13], v[212:215], v[26:29]
	v_mfma_f32_16x16x32_bf16 v[30:33], v[14:17], v[196:199], v[224:227]
	v_mfma_f32_16x16x32_bf16 v[10:13], v[10:13], v[232:235], v[2:5]
	v_mfma_f32_16x16x32_bf16 v[2:5], v[14:17], v[216:219], v[34:37]
	v_mfma_f32_16x16x32_bf16 v[30:33], v[192:195], v[212:215], v[30:33]
	v_mfma_f32_16x16x32_bf16 v[14:17], v[192:195], v[232:235], v[2:5]
	v_mfma_f32_16x16x32_bf16 v[2:5], v[172:175], v[168:171], v[140:143]
	v_mfma_f32_16x16x32_bf16 v[54:57], v[204:207], v[176:179], v[2:5]
	v_mfma_f32_16x16x32_bf16 v[2:5], v[208:211], v[168:171], v[144:147]
	v_mfma_f32_16x16x32_bf16 v[50:53], v[228:231], v[176:179], v[2:5]
	v_mfma_f32_16x16x32_bf16 v[2:5], v[172:175], v[180:183], v[22:25]
	v_mfma_f32_16x16x32_bf16 v[34:37], v[204:207], v[184:187], v[2:5]
	v_mfma_f32_16x16x32_bf16 v[2:5], v[208:211], v[180:183], v[18:21]
	v_mfma_f32_16x16x32_bf16 v[38:41], v[228:231], v[184:187], v[2:5]
	v_mfma_f32_16x16x32_bf16 v[2:5], v[172:175], v[196:199], v[152:155]
	v_mfma_f32_16x16x32_bf16 v[18:21], v[204:207], v[212:215], v[2:5]
	v_mfma_f32_16x16x32_bf16 v[2:5], v[208:211], v[196:199], v[164:167]
	v_mfma_f32_16x16x32_bf16 v[22:25], v[228:231], v[212:215], v[2:5]
	v_mfma_f32_16x16x32_bf16 v[2:5], v[172:175], v[216:219], v[6:9]
	v_mfma_f32_16x16x32_bf16 v[6:9], v[208:211], v[216:219], v[188:191]
	v_mfma_f32_16x16x32_bf16 v[2:5], v[204:207], v[232:235], v[2:5]
	v_mfma_f32_16x16x32_bf16 v[6:9], v[228:231], v[232:235], v[6:9]
	v_cmp_gt_u32_e64 s[12:13], s97, v136
	s_barrier
	s_and_saveexec_b64 s[10:11], s[12:13]
	s_cbranch_execz .LBB0_901
	s_barrier
	s_branch .LBB0_901

; #define WAIT_L(n) asm volatile("s_waitcnt lgkmcnt(%0)" ::"n"(n) : "memory")
; #define SBAR() __builtin_amdgcn_sched_barrier(0)
; #define LDA8(dst, b, h) _Pragma("unroll") for (int m = 0; m < 4; ++m) _Pragma("unroll") for (int k = 0; k < 2; ++k) \
;     dst[m][k] = *(const bf16x8*)(abase + SAo(b, h) + m * 2048 + k * 1024)
; #define LDB8(dst, b, h) _Pragma("unroll") for (int n = 0; n < 2; ++n) _Pragma("unroll") for (int k = 0; k < 2; ++k) \
;     dst[n][k] = *(const bf16x8*)(bbase + SAo(b, h) + n * 2048 + k * 1024)
; #define BAR8 __builtin_amdgcn_s_barrier()
; __device__ __forceinline__ void gemm_main8(const u16* __restrict__ Ab, int lda, const u16* __restrict__ Bb, int ldb, int K,
;                                            char* shm, f32x4 (&acc)[2][2][4][2]) {
;     ...
;     LDB8(B0, 0, 0); SBAR(); LDA8(At, 0, 0); STG_A(1, 1, t + 1);
;     WAIT_L(8); BAR8; WAIT_L(0); MMA8(0, 0, At, B0); BAR8; SBAR();
;     LDB8(B1, 0, 1); STG_B(0, 0, t + 2);
;     BAR8; WAIT_L(0); MMA8(0, 1, At, B1); BAR8;
;     LDA8(At, 0, 1); STG_A(0, 0, t + 2);
;     BAR8; WAIT_L(0); MMA8(1, 0, At, B0); BAR8; SBAR();
.LBB0_951:
	ds_read_b128 v[152:155], v137
	ds_read_b128 v[164:167], v137 offset:1024
	ds_read_b128 v[176:179], v137 offset:2048
	ds_read_b128 v[180:183], v137 offset:3072
	v_add_u32_e32 v173, 0xc000, v138
	v_lshl_add_u64 v[168:169], s[20:21], 0, v[0:1]
	s_mov_b64 s[78:79], 0x17460080
	v_readfirstlane_b32 s25, v173
	v_lshl_add_u64 v[174:175], v[168:169], 0, s[78:79]
	s_mov_b32 m0, s25
	ds_read_b128 v[184:187], v136
	ds_read_b128 v[188:191], v136 offset:1024
	ds_read_b128 v[192:195], v136 offset:2048
	ds_read_b128 v[196:199], v136 offset:3072
	ds_read_b128 v[200:203], v136 offset:4096
	ds_read_b128 v[204:207], v136 offset:5120
	ds_read_b128 v[208:211], v136 offset:6144
	ds_read_b128 v[212:215], v136 offset:7168
	global_load_lds_dwordx4 v[174:175], off
	v_add_u32_e32 v174, 0xe000, v138
	s_mov_b64 s[78:79], 0x17510080
	v_readfirstlane_b32 s25, v174
	v_lshl_add_u64 v[216:217], v[168:169], 0, s[78:79]
	s_mov_b32 m0, s25
	s_nop 0
	global_load_lds_dwordx4 v[216:217], off
	s_waitcnt lgkmcnt(8)
	s_barrier
	s_waitcnt lgkmcnt(0)
	s_waitcnt lgkmcnt(0)
	v_mfma_f32_16x16x32_bf16 v[126:129], v[152:155], v[184:187], v[126:129]
	v_mfma_f32_16x16x32_bf16 v[122:125], v[176:179], v[184:187], v[122:125]
	v_mfma_f32_16x16x32_bf16 v[118:121], v[152:155], v[192:195], v[118:121]
	v_mfma_f32_16x16x32_bf16 v[114:117], v[176:179], v[192:195], v[114:117]
	v_mfma_f32_16x16x32_bf16 v[110:113], v[152:155], v[200:203], v[110:113]
	v_mfma_f32_16x16x32_bf16 v[106:109], v[176:179], v[200:203], v[106:109]
	v_mfma_f32_16x16x32_bf16 v[102:105], v[152:155], v[208:211], v[102:105]
	v_mfma_f32_16x16x32_bf16 v[98:101], v[176:179], v[208:211], v[98:101]
	v_mfma_f32_16x16x32_bf16 v[126:129], v[164:167], v[188:191], v[126:129]
	v_mfma_f32_16x16x32_bf16 v[122:125], v[180:183], v[188:191], v[122:125]
	v_mfma_f32_16x16x32_bf16 v[118:121], v[164:167], v[196:199], v[118:121]
	v_mfma_f32_16x16x32_bf16 v[114:117], v[180:183], v[196:199], v[114:117]
	v_mfma_f32_16x16x32_bf16 v[110:113], v[164:167], v[204:207], v[110:113]
	v_mfma_f32_16x16x32_bf16 v[106:109], v[180:183], v[204:207], v[106:109]
	v_mfma_f32_16x16x32_bf16 v[102:105], v[164:167], v[212:215], v[102:105]
	v_mfma_f32_16x16x32_bf16 v[98:101], v[180:183], v[212:215], v[98:101]
	s_barrier
	v_lshl_add_u64 v[232:233], s[18:19], 0, v[0:1]
	s_mov_b64 s[78:79], 0x6c00100
	v_readfirstlane_b32 s25, v139
	v_lshl_add_u64 v[234:235], v[232:233], 0, s[78:79]
	s_mov_b32 m0, s25
	s_mov_b64 s[78:79], 0x6cb0100
	v_readfirstlane_b32 s25, v140
	ds_read_b128 v[216:219], v137 offset:16384
	ds_read_b128 v[220:223], v137 offset:17408
	ds_read_b128 v[224:227], v137 offset:18432
	ds_read_b128 v[228:231], v137 offset:19456
	global_load_lds_dwordx4 v[234:235], off
	v_lshl_add_u64 v[234:235], v[232:233], 0, s[78:79]
	s_mov_b32 m0, s25
	s_nop 0
	global_load_lds_dwordx4 v[234:235], off
	s_barrier
	s_waitcnt lgkmcnt(0)
	s_waitcnt lgkmcnt(0)
	v_mfma_f32_16x16x32_bf16 v[94:97], v[216:219], v[184:187], v[94:97]
	v_mfma_f32_16x16x32_bf16 v[90:93], v[224:227], v[184:187], v[90:93]
	v_mfma_f32_16x16x32_bf16 v[86:89], v[216:219], v[192:195], v[86:89]
	v_mfma_f32_16x16x32_bf16 v[82:85], v[224:227], v[192:195], v[82:85]
	v_mfma_f32_16x16x32_bf16 v[78:81], v[216:219], v[200:203], v[78:81]
	v_mfma_f32_16x16x32_bf16 v[74:77], v[224:227], v[200:203], v[74:77]
	v_mfma_f32_16x16x32_bf16 v[70:73], v[216:219], v[208:211], v[70:73]
	v_mfma_f32_16x16x32_bf16 v[66:69], v[224:227], v[208:211], v[66:69]
	v_mfma_f32_16x16x32_bf16 v[94:97], v[220:223], v[188:191], v[94:97]
	v_mfma_f32_16x16x32_bf16 v[90:93], v[228:231], v[188:191], v[90:93]
	v_mfma_f32_16x16x32_bf16 v[86:89], v[220:223], v[196:199], v[86:89]
	v_mfma_f32_16x16x32_bf16 v[82:85], v[228:231], v[196:199], v[82:85]
	v_mfma_f32_16x16x32_bf16 v[78:81], v[220:223], v[204:207], v[78:81]
	v_mfma_f32_16x16x32_bf16 v[74:77], v[228:231], v[204:207], v[74:77]
	v_mfma_f32_16x16x32_bf16 v[70:73], v[220:223], v[212:215], v[70:73]
	v_mfma_f32_16x16x32_bf16 v[66:69], v[228:231], v[212:215], v[66:69]
	v_readfirstlane_b32 s25, v138
	v_lshl_add_u64 v[234:235], v[168:169], 0, s[30:31]
	s_mov_b32 m0, s25
	s_mov_b64 s[78:79], 0x173b0100
	v_readfirstlane_b32 s25, v141
	s_barrier
	ds_read_b128 v[184:187], v136 offset:16384
	ds_read_b128 v[188:191], v136 offset:17408
	ds_read_b128 v[192:195], v136 offset:18432
	ds_read_b128 v[196:199], v136 offset:19456
	ds_read_b128 v[200:203], v136 offset:20480
	ds_read_b128 v[204:207], v136 offset:21504
	ds_read_b128 v[208:211], v136 offset:22528
	ds_read_b128 v[212:215], v136 offset:23552
	global_load_lds_dwordx4 v[234:235], off
	v_lshl_add_u64 v[234:235], v[168:169], 0, s[78:79]
	s_mov_b32 m0, s25
	s_nop 0
	global_load_lds_dwordx4 v[234:235], off
	s_barrier
	s_waitcnt lgkmcnt(0)
	s_waitcnt lgkmcnt(0)
	v_mfma_f32_16x16x32_bf16 v[62:65], v[152:155], v[184:187], v[62:65]
	v_mfma_f32_16x16x32_bf16 v[58:61], v[176:179], v[184:187], v[58:61]
	v_mfma_f32_16x16x32_bf16 v[54:57], v[152:155], v[192:195], v[54:57]
	v_mfma_f32_16x16x32_bf16 v[50:53], v[176:179], v[192:195], v[50:53]
	v_mfma_f32_16x16x32_bf16 v[46:49], v[152:155], v[200:203], v[46:49]
	v_mfma_f32_16x16x32_bf16 v[42:45], v[176:179], v[200:203], v[42:45]
	v_mfma_f32_16x16x32_bf16 v[38:41], v[152:155], v[208:211], v[38:41]
	v_mfma_f32_16x16x32_bf16 v[34:37], v[176:179], v[208:211], v[34:37]
	v_mfma_f32_16x16x32_bf16 v[62:65], v[164:167], v[188:191], v[62:65]
	v_mfma_f32_16x16x32_bf16 v[58:61], v[180:183], v[188:191], v[58:61]
	v_mfma_f32_16x16x32_bf16 v[54:57], v[164:167], v[196:199], v[54:57]
	v_mfma_f32_16x16x32_bf16 v[50:53], v[180:183], v[196:199], v[50:53]
	v_mfma_f32_16x16x32_bf16 v[46:49], v[164:167], v[204:207], v[46:49]
	v_mfma_f32_16x16x32_bf16 v[42:45], v[180:183], v[204:207], v[42:45]
	v_mfma_f32_16x16x32_bf16 v[38:41], v[164:167], v[212:215], v[38:41]
	v_mfma_f32_16x16x32_bf16 v[34:37], v[180:183], v[212:215], v[34:37]
	s_barrier
; #define WAIT_V(n) asm volatile("s_waitcnt vmcnt(%0)" ::"n"(n) : "memory")
; #define WAIT_L(n) asm volatile("s_waitcnt lgkmcnt(%0)" ::"n"(n) : "memory")
; #define SBAR() __builtin_amdgcn_sched_barrier(0)
; #define LDA8(dst, b, h) _Pragma("unroll") for (int m = 0; m < 4; ++m) _Pragma("unroll") for (int k = 0; k < 2; ++k) \
;     dst[m][k] = *(const bf16x8*)(abase + SAo(b, h) + m * 2048 + k * 1024)
; #define LDB8(dst, b, h) _Pragma("unroll") for (int n = 0; n < 2; ++n) _Pragma("unroll") for (int k = 0; k < 2; ++k) \
;     dst[n][k] = *(const bf16x8*)(bbase + SAo(b, h) + n * 2048 + k * 1024)
; #define BAR8 __builtin_amdgcn_s_barrier()
; __device__ __forceinline__ void gemm_main8(const u16* __restrict__ Ab, int lda, const u16* __restrict__ Bb, int ldb, int K,
;                                            char* shm, f32x4 (&acc)[2][2][4][2]) {
;     ...
;     STG_B(0, 1, t + 2);
;     WAIT_V(6); BAR8; MMA8(1, 1, At, B1); BAR8;
;     LDB8(B0, 1, 0); SBAR(); LDA8(At, 1, 0); STG_A(0, 1, t + 2);
;     WAIT_L(8); BAR8; WAIT_L(0); MMA8(0, 0, At, B0); BAR8; SBAR();
;     LDB8(B1, 1, 1); STG_B(1, 0, t + 3);
;     BAR8; WAIT_L(0); MMA8(0, 1, At, B1); BAR8;
	s_mov_b64 s[78:79], 0x6d60100
	v_readfirstlane_b32 s25, v142
	v_lshl_add_u64 v[152:153], v[232:233], 0, s[78:79]
	s_mov_b32 m0, s25
	s_mov_b64 s[78:79], 0x6e10100
	v_readfirstlane_b32 s25, v143
	global_load_lds_dwordx4 v[152:153], off
	v_lshl_add_u64 v[152:153], v[232:233], 0, s[78:79]
	s_mov_b32 m0, s25
	s_nop 0
	global_load_lds_dwordx4 v[152:153], off
	s_waitcnt vmcnt(6)
	s_barrier
	v_mfma_f32_16x16x32_bf16 v[30:33], v[216:219], v[184:187], v[30:33]
	v_mfma_f32_16x16x32_bf16 v[26:29], v[224:227], v[184:187], v[26:29]
	v_mfma_f32_16x16x32_bf16 v[22:25], v[216:219], v[192:195], v[22:25]
	v_mfma_f32_16x16x32_bf16 v[18:21], v[224:227], v[192:195], v[18:21]
	v_mfma_f32_16x16x32_bf16 v[14:17], v[216:219], v[200:203], v[14:17]
	v_mfma_f32_16x16x32_bf16 v[10:13], v[224:227], v[200:203], v[10:13]
	v_mfma_f32_16x16x32_bf16 v[6:9], v[216:219], v[208:211], v[6:9]
	v_mfma_f32_16x16x32_bf16 v[2:5], v[224:227], v[208:211], v[2:5]
	v_mfma_f32_16x16x32_bf16 v[30:33], v[220:223], v[188:191], v[30:33]
	v_mfma_f32_16x16x32_bf16 v[26:29], v[228:231], v[188:191], v[26:29]
	v_mfma_f32_16x16x32_bf16 v[22:25], v[220:223], v[196:199], v[22:25]
	v_mfma_f32_16x16x32_bf16 v[18:21], v[228:231], v[196:199], v[18:21]
	v_mfma_f32_16x16x32_bf16 v[14:17], v[220:223], v[204:207], v[14:17]
	v_mfma_f32_16x16x32_bf16 v[10:13], v[228:231], v[204:207], v[10:13]
	v_mfma_f32_16x16x32_bf16 v[6:9], v[220:223], v[212:215], v[6:9]
	v_mfma_f32_16x16x32_bf16 v[2:5], v[228:231], v[212:215], v[2:5]
	s_barrier
	ds_read_b128 v[152:155], v137 offset:32768
	ds_read_b128 v[164:167], v137 offset:33792
	ds_read_b128 v[176:179], v137 offset:34816
	ds_read_b128 v[180:183], v137 offset:35840
	s_mov_b64 s[78:79], 0x17460100
	v_readfirstlane_b32 s25, v144
	v_lshl_add_u64 v[216:217], v[168:169], 0, s[78:79]
	s_mov_b32 m0, s25
	s_mov_b64 s[78:79], 0x17510100
	v_readfirstlane_b32 s25, v145
	ds_read_b128 v[184:187], v136 offset:32768
	ds_read_b128 v[188:191], v136 offset:33792
	ds_read_b128 v[192:195], v136 offset:34816
	ds_read_b128 v[196:199], v136 offset:35840
	ds_read_b128 v[200:203], v136 offset:36864
	ds_read_b128 v[204:207], v136 offset:37888
	ds_read_b128 v[208:211], v136 offset:38912
	ds_read_b128 v[212:215], v136 offset:39936
	global_load_lds_dwordx4 v[216:217], off
	v_lshl_add_u64 v[216:217], v[168:169], 0, s[78:79]
	s_mov_b32 m0, s25
	s_nop 0
	global_load_lds_dwordx4 v[216:217], off
	s_waitcnt lgkmcnt(8)
	s_barrier
	s_waitcnt lgkmcnt(0)
	s_waitcnt lgkmcnt(0)
	v_mfma_f32_16x16x32_bf16 v[126:129], v[152:155], v[184:187], v[126:129]
	v_mfma_f32_16x16x32_bf16 v[122:125], v[176:179], v[184:187], v[122:125]
	v_mfma_f32_16x16x32_bf16 v[118:121], v[152:155], v[192:195], v[118:121]
	v_mfma_f32_16x16x32_bf16 v[114:117], v[176:179], v[192:195], v[114:117]
	v_mfma_f32_16x16x32_bf16 v[110:113], v[152:155], v[200:203], v[110:113]
	v_mfma_f32_16x16x32_bf16 v[106:109], v[176:179], v[200:203], v[106:109]
	v_mfma_f32_16x16x32_bf16 v[102:105], v[152:155], v[208:211], v[102:105]
	v_mfma_f32_16x16x32_bf16 v[98:101], v[176:179], v[208:211], v[98:101]
	v_mfma_f32_16x16x32_bf16 v[126:129], v[164:167], v[188:191], v[126:129]
	v_mfma_f32_16x16x32_bf16 v[122:125], v[180:183], v[188:191], v[122:125]
	v_mfma_f32_16x16x32_bf16 v[118:121], v[164:167], v[196:199], v[118:121]
	v_mfma_f32_16x16x32_bf16 v[114:117], v[180:183], v[196:199], v[114:117]
	v_mfma_f32_16x16x32_bf16 v[110:113], v[164:167], v[204:207], v[110:113]
	v_mfma_f32_16x16x32_bf16 v[106:109], v[180:183], v[204:207], v[106:109]
	v_mfma_f32_16x16x32_bf16 v[102:105], v[164:167], v[212:215], v[102:105]
	v_mfma_f32_16x16x32_bf16 v[98:101], v[180:183], v[212:215], v[98:101]
	s_barrier
	s_mov_b64 s[78:79], 0x6c00180
	v_readfirstlane_b32 s25, v146
	v_lshl_add_u64 v[234:235], v[232:233], 0, s[78:79]
	s_mov_b32 m0, s25
	s_mov_b64 s[78:79], 0x6cb0180
	v_readfirstlane_b32 s25, v147
	ds_read_b128 v[216:219], v137 offset:49152
	ds_read_b128 v[220:223], v137 offset:50176
	ds_read_b128 v[224:227], v137 offset:51200
	ds_read_b128 v[228:231], v137 offset:52224
	global_load_lds_dwordx4 v[234:235], off
	v_lshl_add_u64 v[234:235], v[232:233], 0, s[78:79]
	s_mov_b32 m0, s25
	s_nop 0
	global_load_lds_dwordx4 v[234:235], off
	s_barrier
	s_waitcnt lgkmcnt(0)
	s_waitcnt lgkmcnt(0)
	v_mfma_f32_16x16x32_bf16 v[94:97], v[216:219], v[184:187], v[94:97]
	v_mfma_f32_16x16x32_bf16 v[90:93], v[224:227], v[184:187], v[90:93]
	v_mfma_f32_16x16x32_bf16 v[86:89], v[216:219], v[192:195], v[86:89]
	v_mfma_f32_16x16x32_bf16 v[82:85], v[224:227], v[192:195], v[82:85]
	v_mfma_f32_16x16x32_bf16 v[78:81], v[216:219], v[200:203], v[78:81]
	v_mfma_f32_16x16x32_bf16 v[74:77], v[224:227], v[200:203], v[74:77]
	v_mfma_f32_16x16x32_bf16 v[70:73], v[216:219], v[208:211], v[70:73]
	v_mfma_f32_16x16x32_bf16 v[66:69], v[224:227], v[208:211], v[66:69]
	v_mfma_f32_16x16x32_bf16 v[94:97], v[220:223], v[188:191], v[94:97]
	v_mfma_f32_16x16x32_bf16 v[90:93], v[228:231], v[188:191], v[90:93]
	v_mfma_f32_16x16x32_bf16 v[86:89], v[220:223], v[196:199], v[86:89]
	v_mfma_f32_16x16x32_bf16 v[82:85], v[228:231], v[196:199], v[82:85]
	v_mfma_f32_16x16x32_bf16 v[78:81], v[220:223], v[204:207], v[78:81]
	v_mfma_f32_16x16x32_bf16 v[74:77], v[228:231], v[204:207], v[74:77]
	v_mfma_f32_16x16x32_bf16 v[70:73], v[220:223], v[212:215], v[70:73]
	v_mfma_f32_16x16x32_bf16 v[66:69], v[228:231], v[212:215], v[66:69]
	v_readfirstlane_b32 s25, v148
	v_lshl_add_u64 v[234:235], v[168:169], 0, s[16:17]
	s_mov_b32 m0, s25
	s_mov_b64 s[78:79], 0x173b0180
	v_readfirstlane_b32 s25, v149
	s_barrier
; #define WAIT_V(n) asm volatile("s_waitcnt vmcnt(%0)" ::"n"(n) : "memory")
; #define WAIT_L(n) asm volatile("s_waitcnt lgkmcnt(%0)" ::"n"(n) : "memory")
; #define SBAR() __builtin_amdgcn_sched_barrier(0)
; #define LDA8(dst, b, h) _Pragma("unroll") for (int m = 0; m < 4; ++m) _Pragma("unroll") for (int k = 0; k < 2; ++k) \
;     dst[m][k] = *(const bf16x8*)(abase + SAo(b, h) + m * 2048 + k * 1024)
; #define LDB8(dst, b, h) _Pragma("unroll") for (int n = 0; n < 2; ++n) _Pragma("unroll") for (int k = 0; k < 2; ++k) \
;     dst[n][k] = *(const bf16x8*)(bbase + SAo(b, h) + n * 2048 + k * 1024)
; #define BAR8 __builtin_amdgcn_s_barrier()
; __device__ __forceinline__ void gemm_main8(const u16* __restrict__ Ab, int lda, const u16* __restrict__ Bb, int ldb, int K,
;                                            char* shm, f32x4 (&acc)[2][2][4][2]) {
;     ...
;     LDA8(At, 1, 1); STG_A(1, 0, t + 3);
;     BAR8; WAIT_L(0); MMA8(1, 0, At, B0); BAR8; SBAR();
;     STG_B(1, 1, t + 3);
;     WAIT_V(6); BAR8; MMA8(1, 1, At, B1); BAR8;
;   }
;   { LDB8(B0, 0, 0); LDA8(At, 0, 0); STG_A(1, 1, nt - 1);
;     BAR8; WAIT_L(0); MMA8(0, 0, At, B0); BAR8;
;     LDB8(B1, 0, 1); BAR8; WAIT_L(0); MMA8(0, 1, At, B1); BAR8;
	ds_read_b128 v[184:187], v136 offset:49152
	ds_read_b128 v[188:191], v136 offset:50176
	ds_read_b128 v[192:195], v136 offset:51200
	ds_read_b128 v[196:199], v136 offset:52224
	ds_read_b128 v[200:203], v136 offset:53248
	ds_read_b128 v[204:207], v136 offset:54272
	ds_read_b128 v[208:211], v136 offset:55296
	ds_read_b128 v[212:215], v136 offset:56320
	global_load_lds_dwordx4 v[234:235], off
	v_lshl_add_u64 v[168:169], v[168:169], 0, s[78:79]
	s_mov_b32 m0, s25
	s_nop 0
	global_load_lds_dwordx4 v[168:169], off
	s_barrier
	s_waitcnt lgkmcnt(0)
	s_waitcnt lgkmcnt(0)
	v_mfma_f32_16x16x32_bf16 v[62:65], v[152:155], v[184:187], v[62:65]
	v_mfma_f32_16x16x32_bf16 v[58:61], v[176:179], v[184:187], v[58:61]
	v_mfma_f32_16x16x32_bf16 v[54:57], v[152:155], v[192:195], v[54:57]
	v_mfma_f32_16x16x32_bf16 v[50:53], v[176:179], v[192:195], v[50:53]
	v_mfma_f32_16x16x32_bf16 v[46:49], v[152:155], v[200:203], v[46:49]
	v_mfma_f32_16x16x32_bf16 v[42:45], v[176:179], v[200:203], v[42:45]
	v_mfma_f32_16x16x32_bf16 v[38:41], v[152:155], v[208:211], v[38:41]
	v_mfma_f32_16x16x32_bf16 v[34:37], v[176:179], v[208:211], v[34:37]
	v_mfma_f32_16x16x32_bf16 v[62:65], v[164:167], v[188:191], v[62:65]
	v_mfma_f32_16x16x32_bf16 v[58:61], v[180:183], v[188:191], v[58:61]
	v_mfma_f32_16x16x32_bf16 v[54:57], v[164:167], v[196:199], v[54:57]
	v_mfma_f32_16x16x32_bf16 v[50:53], v[180:183], v[196:199], v[50:53]
	v_mfma_f32_16x16x32_bf16 v[46:49], v[164:167], v[204:207], v[46:49]
	v_mfma_f32_16x16x32_bf16 v[42:45], v[180:183], v[204:207], v[42:45]
	v_mfma_f32_16x16x32_bf16 v[38:41], v[164:167], v[212:215], v[38:41]
	v_mfma_f32_16x16x32_bf16 v[34:37], v[180:183], v[212:215], v[34:37]
	s_barrier
	s_mov_b64 s[78:79], 0x6d60180
	v_readfirstlane_b32 s25, v171
	v_lshl_add_u64 v[152:153], v[232:233], 0, s[78:79]
	s_mov_b32 m0, s25
	s_mov_b64 s[78:79], 0x6e10180
	v_readfirstlane_b32 s25, v172
	global_load_lds_dwordx4 v[152:153], off
	v_lshl_add_u64 v[152:153], v[232:233], 0, s[78:79]
	s_mov_b32 m0, s25
	s_nop 0
	global_load_lds_dwordx4 v[152:153], off
	s_waitcnt vmcnt(6)
	s_barrier
	v_mfma_f32_16x16x32_bf16 v[30:33], v[216:219], v[184:187], v[30:33]
	v_mfma_f32_16x16x32_bf16 v[26:29], v[224:227], v[184:187], v[26:29]
	v_mfma_f32_16x16x32_bf16 v[22:25], v[216:219], v[192:195], v[22:25]
	v_mfma_f32_16x16x32_bf16 v[18:21], v[224:227], v[192:195], v[18:21]
	v_mfma_f32_16x16x32_bf16 v[14:17], v[216:219], v[200:203], v[14:17]
	v_mfma_f32_16x16x32_bf16 v[10:13], v[224:227], v[200:203], v[10:13]
	v_mfma_f32_16x16x32_bf16 v[6:9], v[216:219], v[208:211], v[6:9]
	v_mfma_f32_16x16x32_bf16 v[2:5], v[224:227], v[208:211], v[2:5]
	v_mfma_f32_16x16x32_bf16 v[30:33], v[220:223], v[188:191], v[30:33]
	v_mfma_f32_16x16x32_bf16 v[26:29], v[228:231], v[188:191], v[26:29]
	v_mfma_f32_16x16x32_bf16 v[22:25], v[220:223], v[196:199], v[22:25]
	v_mfma_f32_16x16x32_bf16 v[18:21], v[228:231], v[196:199], v[18:21]
	v_mfma_f32_16x16x32_bf16 v[14:17], v[220:223], v[204:207], v[14:17]
	v_mfma_f32_16x16x32_bf16 v[10:13], v[228:231], v[204:207], v[10:13]
	v_mfma_f32_16x16x32_bf16 v[6:9], v[220:223], v[212:215], v[6:9]
	v_mfma_f32_16x16x32_bf16 v[2:5], v[228:231], v[212:215], v[2:5]
	s_add_i32 s24, s24, 2
	s_add_u32 s18, s18, 0x100
	s_addc_u32 s19, s19, 0
	s_add_u32 s20, s20, 0x100
	s_addc_u32 s21, s21, 0
	s_cmpk_lt_u32 s24, 0x54
	s_barrier
	s_cbranch_scc1 .LBB0_951
	s_mov_b64 s[18:19], 0x162b80
	v_lshl_add_u64 v[200:201], v[130:131], 0, s[18:19]
	v_readfirstlane_b32 s18, v173
	s_mov_b32 m0, s18
	s_mov_b64 s[18:19], 0x212b80
	v_lshl_add_u64 v[130:131], v[130:131], 0, s[18:19]
	v_readfirstlane_b32 s18, v174
	ds_read_b128 v[138:141], v137
	ds_read_b128 v[142:145], v137 offset:1024
	ds_read_b128 v[146:149], v137 offset:2048
	ds_read_b128 v[152:155], v137 offset:3072
	ds_read_b128 v[164:167], v136
	ds_read_b128 v[168:171], v136 offset:1024
	ds_read_b128 v[176:179], v136 offset:2048
	ds_read_b128 v[180:183], v136 offset:3072
	ds_read_b128 v[184:187], v136 offset:4096
	ds_read_b128 v[188:191], v136 offset:5120
	ds_read_b128 v[192:195], v136 offset:6144
	ds_read_b128 v[196:199], v136 offset:7168
	global_load_lds_dwordx4 v[200:201], off
	s_mov_b32 m0, s18
	s_nop 0
	global_load_lds_dwordx4 v[130:131], off
	s_barrier
	s_waitcnt lgkmcnt(0)
	s_waitcnt lgkmcnt(0)
	v_mfma_f32_16x16x32_bf16 v[126:129], v[138:141], v[164:167], v[126:129]
	v_mfma_f32_16x16x32_bf16 v[118:121], v[138:141], v[176:179], v[118:121]
	v_mfma_f32_16x16x32_bf16 v[110:113], v[138:141], v[184:187], v[110:113]
	v_mfma_f32_16x16x32_bf16 v[102:105], v[138:141], v[192:195], v[102:105]
	v_mfma_f32_16x16x32_bf16 v[126:129], v[142:145], v[168:171], v[126:129]
	v_mfma_f32_16x16x32_bf16 v[122:125], v[146:149], v[164:167], v[122:125]
	v_mfma_f32_16x16x32_bf16 v[118:121], v[142:145], v[180:183], v[118:121]
	v_mfma_f32_16x16x32_bf16 v[114:117], v[146:149], v[176:179], v[114:117]
	v_mfma_f32_16x16x32_bf16 v[110:113], v[142:145], v[188:191], v[110:113]
	v_mfma_f32_16x16x32_bf16 v[106:109], v[146:149], v[184:187], v[106:109]
	v_mfma_f32_16x16x32_bf16 v[102:105], v[142:145], v[196:199], v[102:105]
	v_mfma_f32_16x16x32_bf16 v[98:101], v[146:149], v[192:195], v[98:101]
	v_mfma_f32_16x16x32_bf16 v[172:175], v[152:155], v[168:171], v[122:125]
	v_mfma_f32_16x16x32_bf16 v[200:203], v[152:155], v[180:183], v[114:117]
	v_mfma_f32_16x16x32_bf16 v[204:207], v[152:155], v[188:191], v[106:109]
	v_mfma_f32_16x16x32_bf16 v[208:211], v[152:155], v[196:199], v[98:101]
	s_barrier
	s_nop 1
	ds_read_b128 v[98:101], v137 offset:16384
	ds_read_b128 v[106:109], v137 offset:17408
	ds_read_b128 v[114:117], v137 offset:18432
	ds_read_b128 v[122:125], v137 offset:19456
	s_barrier
; #define WAIT_V(n) asm volatile("s_waitcnt vmcnt(%0)" ::"n"(n) : "memory")
; #define WAIT_L(n) asm volatile("s_waitcnt lgkmcnt(%0)" ::"n"(n) : "memory")
; #define LDA8(dst, b, h) _Pragma("unroll") for (int m = 0; m < 4; ++m) _Pragma("unroll") for (int k = 0; k < 2; ++k) \
;     dst[m][k] = *(const bf16x8*)(abase + SAo(b, h) + m * 2048 + k * 1024)
; #define LDB8(dst, b, h) _Pragma("unroll") for (int n = 0; n < 2; ++n) _Pragma("unroll") for (int k = 0; k < 2; ++k) \
;     dst[n][k] = *(const bf16x8*)(bbase + SAo(b, h) + n * 2048 + k * 1024)
; #define BAR8 __builtin_amdgcn_s_barrier()
; __device__ __forceinline__ void gemm_main8(const u16* __restrict__ Ab, int lda, const u16* __restrict__ Bb, int ldb, int K,
;                                            char* shm, f32x4 (&acc)[2][2][4][2]) {
;     ...
;     LDB8(B1, 0, 1); BAR8; WAIT_L(0); MMA8(0, 1, At, B1); BAR8;
;     LDA8(At, 0, 1); WAIT_V(4); BAR8; WAIT_L(0); MMA8(1, 0, At, B0); MMA8(1, 1, At, B1); BAR8; }
;   { LDB8(B0, 1, 0); LDA8(At, 1, 0); WAIT_V(2); BAR8; WAIT_L(0); MMA8(0, 0, At, B0); BAR8;
	s_waitcnt lgkmcnt(0)
	s_waitcnt lgkmcnt(0)
	v_mfma_f32_16x16x32_bf16 v[94:97], v[98:101], v[164:167], v[94:97]
	v_mfma_f32_16x16x32_bf16 v[86:89], v[98:101], v[176:179], v[86:89]
	v_mfma_f32_16x16x32_bf16 v[78:81], v[98:101], v[184:187], v[78:81]
	v_mfma_f32_16x16x32_bf16 v[70:73], v[98:101], v[192:195], v[70:73]
	v_mfma_f32_16x16x32_bf16 v[94:97], v[106:109], v[168:171], v[94:97]
	v_mfma_f32_16x16x32_bf16 v[90:93], v[114:117], v[164:167], v[90:93]
	v_mfma_f32_16x16x32_bf16 v[86:89], v[106:109], v[180:183], v[86:89]
	v_mfma_f32_16x16x32_bf16 v[82:85], v[114:117], v[176:179], v[82:85]
	v_mfma_f32_16x16x32_bf16 v[78:81], v[106:109], v[188:191], v[78:81]
	v_mfma_f32_16x16x32_bf16 v[74:77], v[114:117], v[184:187], v[74:77]
	v_mfma_f32_16x16x32_bf16 v[70:73], v[106:109], v[196:199], v[70:73]
	v_mfma_f32_16x16x32_bf16 v[66:69], v[114:117], v[192:195], v[66:69]
	v_mfma_f32_16x16x32_bf16 v[164:167], v[122:125], v[168:171], v[90:93]
	v_mfma_f32_16x16x32_bf16 v[168:171], v[122:125], v[180:183], v[82:85]
	v_mfma_f32_16x16x32_bf16 v[176:179], v[122:125], v[188:191], v[74:77]
	v_mfma_f32_16x16x32_bf16 v[180:183], v[122:125], v[196:199], v[66:69]
	s_barrier
	s_nop 1
	ds_read_b128 v[66:69], v136 offset:16384
	ds_read_b128 v[74:77], v136 offset:17408
	ds_read_b128 v[82:85], v136 offset:18432
	ds_read_b128 v[90:93], v136 offset:19456
	ds_read_b128 v[184:187], v136 offset:20480
	ds_read_b128 v[188:191], v136 offset:21504
	ds_read_b128 v[192:195], v136 offset:22528
	ds_read_b128 v[196:199], v136 offset:23552
	s_waitcnt vmcnt(4)
	s_barrier
	s_waitcnt lgkmcnt(0)
	s_waitcnt lgkmcnt(0)
	v_mfma_f32_16x16x32_bf16 v[62:65], v[138:141], v[66:69], v[62:65]
	v_mfma_f32_16x16x32_bf16 v[58:61], v[146:149], v[66:69], v[58:61]
	v_mfma_f32_16x16x32_bf16 v[50:53], v[146:149], v[82:85], v[50:53]
	v_mfma_f32_16x16x32_bf16 v[42:45], v[146:149], v[184:187], v[42:45]
	v_mfma_f32_16x16x32_bf16 v[34:37], v[146:149], v[192:195], v[34:37]
	v_mfma_f32_16x16x32_bf16 v[62:65], v[142:145], v[74:77], v[62:65]
	v_mfma_f32_16x16x32_bf16 v[58:61], v[152:155], v[74:77], v[58:61]
	v_mfma_f32_16x16x32_bf16 v[54:57], v[138:141], v[82:85], v[54:57]
	v_mfma_f32_16x16x32_bf16 v[50:53], v[152:155], v[90:93], v[50:53]
	v_mfma_f32_16x16x32_bf16 v[46:49], v[138:141], v[184:187], v[46:49]
	v_mfma_f32_16x16x32_bf16 v[42:45], v[152:155], v[188:191], v[42:45]
	v_mfma_f32_16x16x32_bf16 v[38:41], v[138:141], v[192:195], v[38:41]
	v_mfma_f32_16x16x32_bf16 v[34:37], v[152:155], v[196:199], v[34:37]
	v_mfma_f32_16x16x32_bf16 v[212:215], v[142:145], v[90:93], v[54:57]
	v_mfma_f32_16x16x32_bf16 v[216:219], v[142:145], v[188:191], v[46:49]
	v_mfma_f32_16x16x32_bf16 v[138:141], v[142:145], v[196:199], v[38:41]
	v_mfma_f32_16x16x32_bf16 v[26:29], v[114:117], v[66:69], v[26:29]
	v_mfma_f32_16x16x32_bf16 v[18:21], v[114:117], v[82:85], v[18:21]
	v_mfma_f32_16x16x32_bf16 v[10:13], v[114:117], v[184:187], v[10:13]
	v_mfma_f32_16x16x32_bf16 v[2:5], v[114:117], v[192:195], v[2:5]
	v_mfma_f32_16x16x32_bf16 v[30:33], v[98:101], v[66:69], v[30:33]
	v_mfma_f32_16x16x32_bf16 v[26:29], v[122:125], v[74:77], v[26:29]
	v_mfma_f32_16x16x32_bf16 v[22:25], v[98:101], v[82:85], v[22:25]
	v_mfma_f32_16x16x32_bf16 v[18:21], v[122:125], v[90:93], v[18:21]
	v_mfma_f32_16x16x32_bf16 v[14:17], v[98:101], v[184:187], v[14:17]
	v_mfma_f32_16x16x32_bf16 v[10:13], v[122:125], v[188:191], v[10:13]
	v_mfma_f32_16x16x32_bf16 v[6:9], v[98:101], v[192:195], v[6:9]
	v_mfma_f32_16x16x32_bf16 v[2:5], v[122:125], v[196:199], v[2:5]
	v_mfma_f32_16x16x32_bf16 v[142:145], v[106:109], v[74:77], v[30:33]
	v_mfma_f32_16x16x32_bf16 v[146:149], v[106:109], v[90:93], v[22:25]
	v_mfma_f32_16x16x32_bf16 v[152:155], v[106:109], v[188:191], v[14:17]
	v_mfma_f32_16x16x32_bf16 v[184:187], v[106:109], v[196:199], v[6:9]
	s_barrier
	s_nop 0
	ds_read_b128 v[6:9], v137 offset:32768
	ds_read_b128 v[14:17], v137 offset:33792
	ds_read_b128 v[188:191], v137 offset:34816
	ds_read_b128 v[192:195], v137 offset:35840
	ds_read_b128 v[22:25], v136 offset:32768
	ds_read_b128 v[30:33], v136 offset:33792
	ds_read_b128 v[38:41], v136 offset:34816
	ds_read_b128 v[46:49], v136 offset:35840
	ds_read_b128 v[54:57], v136 offset:36864
	ds_read_b128 v[196:199], v136 offset:37888
	ds_read_b128 v[220:223], v136 offset:38912
	ds_read_b128 v[224:227], v136 offset:39936
	s_waitcnt vmcnt(2)
	s_barrier
; #define WAIT_V(n) asm volatile("s_waitcnt vmcnt(%0)" ::"n"(n) : "memory")
; #define WAIT_L(n) asm volatile("s_waitcnt lgkmcnt(%0)" ::"n"(n) : "memory")
; #define LDA8(dst, b, h) _Pragma("unroll") for (int m = 0; m < 4; ++m) _Pragma("unroll") for (int k = 0; k < 2; ++k) \
;     dst[m][k] = *(const bf16x8*)(abase + SAo(b, h) + m * 2048 + k * 1024)
; #define LDB8(dst, b, h) _Pragma("unroll") for (int n = 0; n < 2; ++n) _Pragma("unroll") for (int k = 0; k < 2; ++k) \
;     dst[n][k] = *(const bf16x8*)(bbase + SAo(b, h) + n * 2048 + k * 1024)
; #define BAR8 __builtin_amdgcn_s_barrier()
; __device__ __forceinline__ void gemm_main8(const u16* __restrict__ Ab, int lda, const u16* __restrict__ Bb, int ldb, int K,
;                                            char* shm, f32x4 (&acc)[2][2][4][2]) {
;     ...
;   { LDB8(B0, 1, 0); LDA8(At, 1, 0); WAIT_V(2); BAR8; WAIT_L(0); MMA8(0, 0, At, B0); BAR8;
;     LDB8(B1, 1, 1); WAIT_V(0); BAR8; WAIT_L(0); MMA8(0, 1, At, B1); BAR8;
;     LDA8(At, 1, 1); BAR8; WAIT_L(0); MMA8(1, 0, At, B0); MMA8(1, 1, At, B1); BAR8; }
;   if (wr == 0) BAR8;
	s_waitcnt lgkmcnt(0)
	s_waitcnt lgkmcnt(0)
	v_mfma_f32_16x16x32_bf16 v[66:69], v[6:9], v[22:25], v[126:129]
	v_mfma_f32_16x16x32_bf16 v[122:125], v[14:17], v[30:33], v[66:69]
	v_mfma_f32_16x16x32_bf16 v[66:69], v[188:191], v[22:25], v[172:175]
	v_mfma_f32_16x16x32_bf16 v[114:117], v[192:195], v[30:33], v[66:69]
	v_mfma_f32_16x16x32_bf16 v[66:69], v[6:9], v[38:41], v[118:121]
	v_mfma_f32_16x16x32_bf16 v[106:109], v[14:17], v[46:49], v[66:69]
	v_mfma_f32_16x16x32_bf16 v[66:69], v[188:191], v[38:41], v[200:203]
	v_mfma_f32_16x16x32_bf16 v[98:101], v[192:195], v[46:49], v[66:69]
	v_mfma_f32_16x16x32_bf16 v[66:69], v[6:9], v[54:57], v[110:113]
	v_mfma_f32_16x16x32_bf16 v[90:93], v[14:17], v[196:199], v[66:69]
	v_mfma_f32_16x16x32_bf16 v[66:69], v[188:191], v[54:57], v[204:207]
	v_mfma_f32_16x16x32_bf16 v[82:85], v[192:195], v[196:199], v[66:69]
	v_mfma_f32_16x16x32_bf16 v[66:69], v[6:9], v[220:223], v[102:105]
	v_mfma_f32_16x16x32_bf16 v[74:77], v[14:17], v[224:227], v[66:69]
	v_mfma_f32_16x16x32_bf16 v[66:69], v[188:191], v[220:223], v[208:211]
	v_mfma_f32_16x16x32_bf16 v[66:69], v[192:195], v[224:227], v[66:69]
	s_barrier
	ds_read_b128 v[172:175], v137 offset:49152
	ds_read_b128 v[200:203], v137 offset:50176
	ds_read_b128 v[204:207], v137 offset:51200
	ds_read_b128 v[208:211], v137 offset:52224
	s_waitcnt vmcnt(0)
	s_barrier
	s_waitcnt lgkmcnt(0)
	s_waitcnt lgkmcnt(0)
	v_mfma_f32_16x16x32_bf16 v[94:97], v[172:175], v[22:25], v[94:97]
	v_mfma_f32_16x16x32_bf16 v[22:25], v[204:207], v[22:25], v[164:167]
	v_mfma_f32_16x16x32_bf16 v[118:121], v[208:211], v[30:33], v[22:25]
	v_mfma_f32_16x16x32_bf16 v[22:25], v[172:175], v[38:41], v[86:89]
	v_mfma_f32_16x16x32_bf16 v[110:113], v[200:203], v[46:49], v[22:25]
	v_mfma_f32_16x16x32_bf16 v[22:25], v[204:207], v[38:41], v[168:171]
	v_mfma_f32_16x16x32_bf16 v[102:105], v[208:211], v[46:49], v[22:25]
	v_mfma_f32_16x16x32_bf16 v[22:25], v[172:175], v[54:57], v[78:81]
	v_mfma_f32_16x16x32_bf16 v[126:129], v[200:203], v[30:33], v[94:97]
	v_mfma_f32_16x16x32_bf16 v[94:97], v[200:203], v[196:199], v[22:25]
	v_mfma_f32_16x16x32_bf16 v[22:25], v[204:207], v[54:57], v[176:179]
	v_mfma_f32_16x16x32_bf16 v[86:89], v[208:211], v[196:199], v[22:25]
	v_mfma_f32_16x16x32_bf16 v[22:25], v[172:175], v[220:223], v[70:73]
	v_mfma_f32_16x16x32_bf16 v[78:81], v[200:203], v[224:227], v[22:25]
	v_mfma_f32_16x16x32_bf16 v[22:25], v[204:207], v[220:223], v[180:183]
	v_mfma_f32_16x16x32_bf16 v[70:73], v[208:211], v[224:227], v[22:25]
	s_barrier
	ds_read_b128 v[164:167], v136 offset:49152
	ds_read_b128 v[168:171], v136 offset:50176
	ds_read_b128 v[176:179], v136 offset:51200
	ds_read_b128 v[180:183], v136 offset:52224
	ds_read_b128 v[196:199], v136 offset:53248
	ds_read_b128 v[220:223], v136 offset:54272
	ds_read_b128 v[224:227], v136 offset:55296
	ds_read_b128 v[228:231], v136 offset:56320
	s_barrier
	s_waitcnt lgkmcnt(0)
	s_waitcnt lgkmcnt(0)
	v_mfma_f32_16x16x32_bf16 v[22:25], v[6:9], v[164:167], v[62:65]
	v_mfma_f32_16x16x32_bf16 v[62:65], v[14:17], v[168:171], v[22:25]
	v_mfma_f32_16x16x32_bf16 v[22:25], v[188:191], v[164:167], v[58:61]
	v_mfma_f32_16x16x32_bf16 v[54:57], v[192:195], v[168:171], v[22:25]
	v_mfma_f32_16x16x32_bf16 v[22:25], v[6:9], v[176:179], v[212:215]
	v_mfma_f32_16x16x32_bf16 v[46:49], v[14:17], v[180:183], v[22:25]
	v_mfma_f32_16x16x32_bf16 v[22:25], v[188:191], v[176:179], v[50:53]
	v_mfma_f32_16x16x32_bf16 v[38:41], v[192:195], v[180:183], v[22:25]
	v_mfma_f32_16x16x32_bf16 v[22:25], v[6:9], v[196:199], v[216:219]
	v_mfma_f32_16x16x32_bf16 v[6:9], v[6:9], v[224:227], v[138:141]
	v_mfma_f32_16x16x32_bf16 v[30:33], v[14:17], v[220:223], v[22:25]
	v_mfma_f32_16x16x32_bf16 v[22:25], v[188:191], v[196:199], v[42:45]
	v_mfma_f32_16x16x32_bf16 v[14:17], v[14:17], v[228:231], v[6:9]
	v_mfma_f32_16x16x32_bf16 v[6:9], v[188:191], v[224:227], v[34:37]
	v_mfma_f32_16x16x32_bf16 v[22:25], v[192:195], v[220:223], v[22:25]
	v_mfma_f32_16x16x32_bf16 v[6:9], v[192:195], v[228:231], v[6:9]
	v_mfma_f32_16x16x32_bf16 v[34:37], v[172:175], v[164:167], v[142:145]
	v_mfma_f32_16x16x32_bf16 v[26:29], v[204:207], v[164:167], v[26:29]
	v_mfma_f32_16x16x32_bf16 v[18:21], v[204:207], v[176:179], v[18:21]
	v_mfma_f32_16x16x32_bf16 v[58:61], v[200:203], v[168:171], v[34:37]
	v_mfma_f32_16x16x32_bf16 v[50:53], v[208:211], v[168:171], v[26:29]
	v_mfma_f32_16x16x32_bf16 v[26:29], v[172:175], v[176:179], v[146:149]
	v_mfma_f32_16x16x32_bf16 v[34:37], v[208:211], v[180:183], v[18:21]
	v_mfma_f32_16x16x32_bf16 v[18:21], v[172:175], v[196:199], v[152:155]
	v_mfma_f32_16x16x32_bf16 v[10:13], v[204:207], v[196:199], v[10:13]
	v_mfma_f32_16x16x32_bf16 v[42:45], v[200:203], v[180:183], v[26:29]
	v_mfma_f32_16x16x32_bf16 v[26:29], v[200:203], v[220:223], v[18:21]
	v_mfma_f32_16x16x32_bf16 v[18:21], v[208:211], v[220:223], v[10:13]
	v_mfma_f32_16x16x32_bf16 v[10:13], v[172:175], v[224:227], v[184:187]
	v_mfma_f32_16x16x32_bf16 v[2:5], v[204:207], v[224:227], v[2:5]
	v_mfma_f32_16x16x32_bf16 v[10:13], v[200:203], v[228:231], v[10:13]
	v_mfma_f32_16x16x32_bf16 v[2:5], v[208:211], v[228:231], v[2:5]
	v_cmp_gt_u32_e32 vcc, s97, v135
	s_barrier
	s_and_saveexec_b64 s[18:19], vcc
	s_cbranch_execz .LBB0_947
	s_barrier
	s_branch .LBB0_947
